# v3 + non-temporal (nt) cache hint on the write-once f32 residual-stream stores of the EpiResid/EpiPle epilogues
# baseline (speedup 1.0000x reference)
.LBB0_217:
	v_lshl_add_u32 v180, s44, 8, v184
	v_lshl_or_b32 v176, s43, 8, v186
	s_cmpk_lt_i32 s44, 0x100
	v_ashrrev_i32_e32 v181, 31, v180
	s_cselect_b32 s3, s24, s26
	s_cselect_b32 s2, s25, s27
	v_lshlrev_b64 v[128:129], 12, v[180:181]
	v_ashrrev_i32_e32 v177, 31, v176
	v_lshl_add_u64 v[128:129], s[2:3], 0, v[128:129]
	v_lshlrev_b64 v[130:131], 2, v[176:177]
	v_lshl_add_u64 v[128:129], v[128:129], 0, v[130:131]
	global_load_dwordx4 v[188:191], v[128:129], off
	global_load_dwordx4 v[192:195], v[128:129], off offset:64
	global_load_dwordx4 v[148:151], v[128:129], off offset:512
	global_load_dwordx4 v[144:147], v[128:129], off offset:576
	v_and_b32_e32 v129, 64, v203
	v_xor_b32_e32 v128, 16, v203
	v_add_u32_e32 v129, 64, v129
	v_cmp_lt_i32_e32 vcc, v128, v129
	v_or_b32_e32 v182, 16, v180
	v_ashrrev_i32_e32 v183, 31, v182
	v_cndmask_b32_e32 v128, v203, v128, vcc
	v_lshlrev_b32_e32 v163, 2, v128
	v_xor_b32_e32 v128, 32, v203
	v_cmp_lt_i32_e32 vcc, v128, v129
	v_lshl_add_u64 v[178:179], s[2:3], 0, v[130:131]
	v_readlane_b32 s52, v248, 48
	v_cndmask_b32_e32 v128, v203, v128, vcc
	v_lshlrev_b32_e32 v162, 2, v128
	v_lshlrev_b64 v[128:129], 10, v[180:181]
	v_lshl_add_u64 v[154:155], v[128:129], 0, v[176:177]
	v_lshlrev_b64 v[128:129], 12, v[182:183]
	v_lshl_add_u64 v[128:129], v[178:179], 0, v[128:129]
	global_load_dwordx4 v[140:143], v[128:129], off
	global_load_dwordx4 v[136:139], v[128:129], off offset:64
	global_load_dwordx4 v[132:135], v[128:129], off offset:512
	s_nop 0
	global_load_dwordx4 v[128:131], v[128:129], off offset:576
	v_readlane_b32 s66, v248, 62
	v_readlane_b32 s67, v248, 63
	s_lshl_b32 s16, s43, 2
	s_ashr_i32 s17, s16, 31
	v_readlane_b32 s53, v248, 49
	v_readlane_b32 s54, v248, 50
	v_readlane_b32 s55, v248, 51
	v_readlane_b32 s56, v248, 52
	v_readlane_b32 s57, v248, 53
	v_readlane_b32 s58, v248, 54
	v_readlane_b32 s59, v248, 55
	v_readlane_b32 s60, v248, 56
	v_readlane_b32 s61, v248, 57
	v_readlane_b32 s62, v248, 58
	v_readlane_b32 s63, v248, 59
	v_readlane_b32 s64, v248, 60
	v_readlane_b32 s65, v248, 61
	s_waitcnt vmcnt(0)
	v_pk_fma_f32 v[190:191], v[126:127], 0.5, v[190:191] op_sel_hi:[1,0,1]
	v_pk_fma_f32 v[188:189], v[124:125], 0.5, v[188:189] op_sel_hi:[1,0,1]
	v_lshl_add_u64 v[124:125], v[154:155], 2, s[66:67]
	v_lshlrev_b64 v[154:155], 1, v[154:155]
	v_cvt_pk_f16_f32 v126, v188, v189
	v_cvt_pk_f16_f32 v127, v190, v191
	v_lshl_add_u64 v[156:157], s[48:49], 0, v[154:155]
	global_store_dwordx4 v[124:125], v[188:191], off nt
	global_store_dwordx2 v[156:157], v[126:127], off
	v_mul_f32_e32 v126, v189, v189
	v_mul_f32_e32 v127, v191, v191
	v_fmac_f32_e32 v126, v188, v188
	v_fmac_f32_e32 v127, v190, v190
	v_pk_fma_f32 v[122:123], v[122:123], 0.5, v[194:195] op_sel_hi:[1,0,1]
	v_pk_fma_f32 v[120:121], v[120:121], 0.5, v[192:193] op_sel_hi:[1,0,1]
	v_add_f32_e32 v164, v126, v127
	global_store_dwordx4 v[124:125], v[120:123], off offset:64 nt
	v_cvt_pk_f16_f32 v126, v120, v121
	v_or_b32_e32 v156, 32, v154
	v_mul_f32_e32 v121, v121, v121
	v_fmac_f32_e32 v121, v120, v120
	v_mul_f32_e32 v120, v123, v123
	v_mov_b32_e32 v157, v155
	v_fmac_f32_e32 v120, v122, v122
	v_cvt_pk_f16_f32 v127, v122, v123
	v_lshl_add_u64 v[156:157], s[48:49], 0, v[156:157]
	v_add_f32_e32 v120, v121, v120
	v_pk_fma_f32 v[118:119], v[118:119], 0.5, v[150:151] op_sel_hi:[1,0,1]
	v_pk_fma_f32 v[116:117], v[116:117], 0.5, v[148:149] op_sel_hi:[1,0,1]
	global_store_dwordx2 v[156:157], v[126:127], off
	v_add_f32_e32 v126, v164, v120
	global_store_dwordx4 v[124:125], v[116:119], off offset:512 nt
	v_cvt_pk_f16_f32 v120, v116, v117
	v_or_b32_e32 v122, 0x100, v154
	v_mul_f32_e32 v117, v117, v117
	v_fmac_f32_e32 v117, v116, v116
	v_mul_f32_e32 v116, v119, v119
	v_mov_b32_e32 v123, v155
	v_fmac_f32_e32 v116, v118, v118
	v_cvt_pk_f16_f32 v121, v118, v119
	v_lshl_add_u64 v[122:123], s[48:49], 0, v[122:123]
	v_add_f32_e32 v116, v117, v116
	v_pk_fma_f32 v[114:115], v[114:115], 0.5, v[146:147] op_sel_hi:[1,0,1]
	v_pk_fma_f32 v[112:113], v[112:113], 0.5, v[144:145] op_sel_hi:[1,0,1]
	global_store_dwordx2 v[122:123], v[120:121], off
	v_add_f32_e32 v120, v126, v116
	global_store_dwordx4 v[124:125], v[112:115], off offset:576 nt
	v_cvt_pk_f16_f32 v116, v112, v113
	v_or_b32_e32 v154, 0x120, v154
	v_mul_f32_e32 v113, v113, v113
	v_fmac_f32_e32 v113, v112, v112
	v_mul_f32_e32 v112, v115, v115
	v_fmac_f32_e32 v112, v114, v114
	v_add_f32_e32 v112, v113, v112
	v_add_f32_e32 v112, v120, v112
	ds_bpermute_b32 v113, v163, v112
	v_cvt_pk_f16_f32 v117, v114, v115
	v_lshl_add_u64 v[118:119], s[48:49], 0, v[154:155]
	global_store_dwordx2 v[118:119], v[116:117], off
	s_waitcnt lgkmcnt(0)
	v_add_f32_e32 v112, v112, v113
	ds_bpermute_b32 v113, v162, v112
	s_and_saveexec_b64 s[2:3], s[6:7]
	v_readlane_b32 s46, v254, 16
	v_readlane_b32 s47, v254, 17
	s_cbranch_execz .LBB0_219
	s_waitcnt lgkmcnt(0)
	v_add_f32_e32 v114, v112, v113
	v_lshlrev_b64 v[112:113], 6, v[180:181]
	v_lshl_add_u64 v[112:113], s[46:47], 0, v[112:113]
	v_lshl_add_u64 v[112:113], s[16:17], 2, v[112:113]
	s_lshl_b32 s92, s39, 2
	v_lshl_add_u64 v[112:113], v[112:113], 0, s[92:93]
	v_readlane_b32 s73, v250, 34
	global_store_dword v[112:113], v114, off
.LBB0_219:
	s_or_b64 exec, exec, s[2:3]
	v_or_b32_e32 v144, 32, v180
	v_ashrrev_i32_e32 v145, 31, v144
	s_waitcnt lgkmcnt(0)
	v_lshlrev_b64 v[112:113], 12, v[144:145]
	v_lshl_add_u64 v[112:113], v[178:179], 0, v[112:113]
	global_load_dwordx4 v[124:127], v[112:113], off
	global_load_dwordx4 v[120:123], v[112:113], off offset:64
	global_load_dwordx4 v[116:119], v[112:113], off offset:512
	s_nop 0
	global_load_dwordx4 v[112:115], v[112:113], off offset:576
	v_lshlrev_b64 v[146:147], 10, v[182:183]
	v_readlane_b32 s52, v248, 48
	v_lshl_add_u64 v[146:147], v[146:147], 0, v[176:177]
	v_readlane_b32 s66, v248, 62
	v_readlane_b32 s67, v248, 63
	v_pk_fma_f32 v[110:111], v[110:111], 0.5, v[142:143] op_sel_hi:[1,0,1]
	v_pk_fma_f32 v[108:109], v[108:109], 0.5, v[140:141] op_sel_hi:[1,0,1]
	v_lshl_add_u64 v[140:141], v[146:147], 2, s[66:67]
	global_store_dwordx4 v[140:141], v[108:111], off nt
	v_cvt_pk_f16_f32 v142, v108, v109
	v_lshlrev_b64 v[146:147], 1, v[146:147]
	v_mul_f32_e32 v109, v109, v109
	v_fmac_f32_e32 v109, v108, v108
	v_mul_f32_e32 v108, v111, v111
	v_cvt_pk_f16_f32 v143, v110, v111
	v_lshl_add_u64 v[148:149], s[48:49], 0, v[146:147]
	v_fmac_f32_e32 v108, v110, v110
	v_pk_fma_f32 v[106:107], v[106:107], 0.5, v[138:139] op_sel_hi:[1,0,1]
	v_pk_fma_f32 v[104:105], v[104:105], 0.5, v[136:137] op_sel_hi:[1,0,1]
	global_store_dwordx2 v[148:149], v[142:143], off
	v_add_f32_e32 v142, v109, v108
	global_store_dwordx4 v[140:141], v[104:107], off offset:64 nt
	v_cvt_pk_f16_f32 v108, v104, v105
	v_or_b32_e32 v110, 32, v146
	v_mul_f32_e32 v105, v105, v105
	v_fmac_f32_e32 v105, v104, v104
	v_mul_f32_e32 v104, v107, v107
	v_mov_b32_e32 v111, v147
	v_fmac_f32_e32 v104, v106, v106
	v_cvt_pk_f16_f32 v109, v106, v107
	v_lshl_add_u64 v[110:111], s[48:49], 0, v[110:111]
	v_add_f32_e32 v104, v105, v104
	v_pk_fma_f32 v[102:103], v[102:103], 0.5, v[134:135] op_sel_hi:[1,0,1]
	v_pk_fma_f32 v[100:101], v[100:101], 0.5, v[132:133] op_sel_hi:[1,0,1]
	global_store_dwordx2 v[110:111], v[108:109], off
	v_add_f32_e32 v108, v142, v104
	global_store_dwordx4 v[140:141], v[100:103], off offset:512 nt
	v_cvt_pk_f16_f32 v104, v100, v101
	v_pk_fma_f32 v[98:99], v[98:99], 0.5, v[130:131] op_sel_hi:[1,0,1]
	v_mul_f32_e32 v101, v101, v101
	v_fmac_f32_e32 v101, v100, v100
	v_mul_f32_e32 v100, v103, v103
	v_fmac_f32_e32 v100, v102, v102
	v_pk_fma_f32 v[96:97], v[96:97], 0.5, v[128:129] op_sel_hi:[1,0,1]
	v_cvt_pk_f16_f32 v105, v102, v103
	v_add_f32_e32 v100, v101, v100
	v_mul_f32_e32 v101, v97, v97
	v_mul_f32_e32 v102, v99, v99
	v_fmac_f32_e32 v101, v96, v96
	v_fmac_f32_e32 v102, v98, v98
	v_add_f32_e32 v100, v108, v100
	v_add_f32_e32 v101, v101, v102
	v_add_f32_e32 v102, v100, v101
	ds_bpermute_b32 v103, v163, v102
	v_or_b32_e32 v106, 0x100, v146
	v_mov_b32_e32 v107, v147
	v_lshl_add_u64 v[100:101], s[48:49], 0, v[106:107]
	global_store_dwordx2 v[100:101], v[104:105], off
	global_store_dwordx4 v[140:141], v[96:99], off offset:576 nt
	v_cvt_pk_f16_f32 v100, v96, v97
	v_or_b32_e32 v146, 0x120, v146
	s_waitcnt lgkmcnt(0)
	v_add_f32_e32 v96, v102, v103
	ds_bpermute_b32 v97, v162, v96
	v_cvt_pk_f16_f32 v101, v98, v99
	v_lshl_add_u64 v[98:99], s[48:49], 0, v[146:147]
	v_readlane_b32 s53, v248, 49
	v_readlane_b32 s54, v248, 50
	v_readlane_b32 s55, v248, 51
	v_readlane_b32 s56, v248, 52
	v_readlane_b32 s57, v248, 53
	v_readlane_b32 s58, v248, 54
	v_readlane_b32 s59, v248, 55
	v_readlane_b32 s60, v248, 56
	v_readlane_b32 s61, v248, 57
	v_readlane_b32 s62, v248, 58
	v_readlane_b32 s63, v248, 59
	v_readlane_b32 s64, v248, 60
	v_readlane_b32 s65, v248, 61
	global_store_dwordx2 v[98:99], v[100:101], off
	s_and_saveexec_b64 s[2:3], s[6:7]
	s_cbranch_execz .LBB0_221
	s_waitcnt lgkmcnt(0)
	v_add_f32_e32 v98, v96, v97
	v_lshlrev_b64 v[96:97], 6, v[182:183]
	v_lshl_add_u64 v[96:97], s[46:47], 0, v[96:97]
	v_lshl_add_u64 v[96:97], s[16:17], 2, v[96:97]
	s_lshl_b32 s92, s39, 2
	v_lshl_add_u64 v[96:97], v[96:97], 0, s[92:93]
	v_readlane_b32 s73, v250, 34
	global_store_dword v[96:97], v98, off
.LBB0_221:
	s_or_b64 exec, exec, s[2:3]
	v_or_b32_e32 v128, 48, v180
	v_ashrrev_i32_e32 v129, 31, v128
	s_waitcnt lgkmcnt(0)
	v_lshlrev_b64 v[96:97], 12, v[128:129]
	v_lshl_add_u64 v[96:97], v[178:179], 0, v[96:97]
	global_load_dwordx4 v[108:111], v[96:97], off
	global_load_dwordx4 v[104:107], v[96:97], off offset:64
	global_load_dwordx4 v[100:103], v[96:97], off offset:512
	s_nop 0
	global_load_dwordx4 v[96:99], v[96:97], off offset:576
	v_lshlrev_b64 v[130:131], 10, v[144:145]
	v_readlane_b32 s52, v248, 48
	v_lshl_add_u64 v[130:131], v[130:131], 0, v[176:177]
	v_readlane_b32 s66, v248, 62
	v_readlane_b32 s67, v248, 63
	s_waitcnt vmcnt(15)
	v_pk_fma_f32 v[94:95], v[94:95], 0.5, v[126:127] op_sel_hi:[1,0,1]
	v_pk_fma_f32 v[92:93], v[92:93], 0.5, v[124:125] op_sel_hi:[1,0,1]
	v_lshl_add_u64 v[124:125], v[130:131], 2, s[66:67]
	global_store_dwordx4 v[124:125], v[92:95], off nt
	v_cvt_pk_f16_f32 v126, v92, v93
	v_lshlrev_b64 v[130:131], 1, v[130:131]
	v_mul_f32_e32 v93, v93, v93
	v_fmac_f32_e32 v93, v92, v92
	v_mul_f32_e32 v92, v95, v95
	v_cvt_pk_f16_f32 v127, v94, v95
	v_lshl_add_u64 v[132:133], s[48:49], 0, v[130:131]
	v_fmac_f32_e32 v92, v94, v94
	s_waitcnt vmcnt(15)
	v_pk_fma_f32 v[90:91], v[90:91], 0.5, v[122:123] op_sel_hi:[1,0,1]
	v_pk_fma_f32 v[88:89], v[88:89], 0.5, v[120:121] op_sel_hi:[1,0,1]
	global_store_dwordx2 v[132:133], v[126:127], off
	v_add_f32_e32 v126, v93, v92
	global_store_dwordx4 v[124:125], v[88:91], off offset:64 nt
	v_cvt_pk_f16_f32 v92, v88, v89
	v_or_b32_e32 v94, 32, v130
	v_mul_f32_e32 v89, v89, v89
	v_fmac_f32_e32 v89, v88, v88
	v_mul_f32_e32 v88, v91, v91
	v_mov_b32_e32 v95, v131
	v_fmac_f32_e32 v88, v90, v90
	v_cvt_pk_f16_f32 v93, v90, v91
	v_lshl_add_u64 v[94:95], s[48:49], 0, v[94:95]
	v_add_f32_e32 v88, v89, v88
	s_waitcnt vmcnt(16)
	v_pk_fma_f32 v[86:87], v[86:87], 0.5, v[118:119] op_sel_hi:[1,0,1]
	v_pk_fma_f32 v[84:85], v[84:85], 0.5, v[116:117] op_sel_hi:[1,0,1]
	global_store_dwordx2 v[94:95], v[92:93], off
	v_add_f32_e32 v92, v126, v88
	global_store_dwordx4 v[124:125], v[84:87], off offset:512 nt
	v_cvt_pk_f16_f32 v88, v84, v85
	s_waitcnt vmcnt(17)
	v_pk_fma_f32 v[82:83], v[82:83], 0.5, v[114:115] op_sel_hi:[1,0,1]
	v_mul_f32_e32 v85, v85, v85
	v_fmac_f32_e32 v85, v84, v84
	v_mul_f32_e32 v84, v87, v87
	v_fmac_f32_e32 v84, v86, v86
	v_pk_fma_f32 v[80:81], v[80:81], 0.5, v[112:113] op_sel_hi:[1,0,1]
	v_cvt_pk_f16_f32 v89, v86, v87
	v_add_f32_e32 v84, v85, v84
	v_mul_f32_e32 v85, v81, v81
	v_mul_f32_e32 v86, v83, v83
	v_fmac_f32_e32 v85, v80, v80
	v_fmac_f32_e32 v86, v82, v82
	v_add_f32_e32 v84, v92, v84
	v_add_f32_e32 v85, v85, v86
	v_add_f32_e32 v86, v84, v85
	ds_bpermute_b32 v87, v163, v86
	v_or_b32_e32 v90, 0x100, v130
	v_mov_b32_e32 v91, v131
	v_lshl_add_u64 v[84:85], s[48:49], 0, v[90:91]
	global_store_dwordx2 v[84:85], v[88:89], off
	global_store_dwordx4 v[124:125], v[80:83], off offset:576 nt
	v_cvt_pk_f16_f32 v84, v80, v81
	v_or_b32_e32 v130, 0x120, v130
	s_waitcnt lgkmcnt(0)
	v_add_f32_e32 v80, v86, v87
	ds_bpermute_b32 v81, v162, v80
	v_cvt_pk_f16_f32 v85, v82, v83
	v_lshl_add_u64 v[82:83], s[48:49], 0, v[130:131]
	v_readlane_b32 s53, v248, 49
	v_readlane_b32 s54, v248, 50
	v_readlane_b32 s55, v248, 51
	v_readlane_b32 s56, v248, 52
	v_readlane_b32 s57, v248, 53
	v_readlane_b32 s58, v248, 54
	v_readlane_b32 s59, v248, 55
	v_readlane_b32 s60, v248, 56
	v_readlane_b32 s61, v248, 57
	v_readlane_b32 s62, v248, 58
	v_readlane_b32 s63, v248, 59
	v_readlane_b32 s64, v248, 60
	v_readlane_b32 s65, v248, 61
	global_store_dwordx2 v[82:83], v[84:85], off
	s_mov_b64 s[2:3], exec
	v_mov_b64_e32 v[154:155], v[158:159]
	s_and_b64 s[18:19], s[2:3], s[6:7]
	v_mov_b64_e32 v[156:157], v[160:161]
	s_mov_b64 exec, s[18:19]
	s_cbranch_execz .LBB0_223
	s_waitcnt lgkmcnt(0)
	v_add_f32_e32 v82, v80, v81
	v_lshlrev_b64 v[80:81], 6, v[144:145]
	v_lshl_add_u64 v[80:81], s[46:47], 0, v[80:81]
	v_lshl_add_u64 v[80:81], s[16:17], 2, v[80:81]
	s_lshl_b32 s92, s39, 2
	v_lshl_add_u64 v[80:81], v[80:81], 0, s[92:93]
	v_readlane_b32 s73, v250, 34
	global_store_dword v[80:81], v82, off
.LBB0_223:
	s_or_b64 exec, exec, s[2:3]
	v_add_u32_e32 v112, 0x80, v180
	v_ashrrev_i32_e32 v113, 31, v112
	s_waitcnt lgkmcnt(0)
	v_lshlrev_b64 v[80:81], 12, v[112:113]
	v_lshl_add_u64 v[80:81], v[178:179], 0, v[80:81]
	global_load_dwordx4 v[92:95], v[80:81], off
	global_load_dwordx4 v[88:91], v[80:81], off offset:64
	global_load_dwordx4 v[84:87], v[80:81], off offset:512
	s_nop 0
	global_load_dwordx4 v[80:83], v[80:81], off offset:576
	v_lshlrev_b64 v[114:115], 10, v[128:129]
	v_readlane_b32 s52, v248, 48
	v_lshl_add_u64 v[114:115], v[114:115], 0, v[176:177]
	v_readlane_b32 s66, v248, 62
	v_readlane_b32 s67, v248, 63
	s_waitcnt vmcnt(15)
	v_pk_fma_f32 v[78:79], v[78:79], 0.5, v[110:111] op_sel_hi:[1,0,1]
	v_pk_fma_f32 v[76:77], v[76:77], 0.5, v[108:109] op_sel_hi:[1,0,1]
	v_lshl_add_u64 v[108:109], v[114:115], 2, s[66:67]
	global_store_dwordx4 v[108:109], v[76:79], off nt
	v_cvt_pk_f16_f32 v110, v76, v77
	v_lshlrev_b64 v[114:115], 1, v[114:115]
	v_mul_f32_e32 v77, v77, v77
	v_fmac_f32_e32 v77, v76, v76
	v_mul_f32_e32 v76, v79, v79
	v_cvt_pk_f16_f32 v111, v78, v79
	v_lshl_add_u64 v[116:117], s[48:49], 0, v[114:115]
	v_fmac_f32_e32 v76, v78, v78
	s_waitcnt vmcnt(15)
	v_pk_fma_f32 v[74:75], v[74:75], 0.5, v[106:107] op_sel_hi:[1,0,1]
	v_pk_fma_f32 v[72:73], v[72:73], 0.5, v[104:105] op_sel_hi:[1,0,1]
	global_store_dwordx2 v[116:117], v[110:111], off
	v_add_f32_e32 v110, v77, v76
	global_store_dwordx4 v[108:109], v[72:75], off offset:64 nt
	v_cvt_pk_f16_f32 v76, v72, v73
	v_or_b32_e32 v78, 32, v114
	v_mul_f32_e32 v73, v73, v73
	v_fmac_f32_e32 v73, v72, v72
	v_mul_f32_e32 v72, v75, v75
	v_mov_b32_e32 v79, v115
	v_fmac_f32_e32 v72, v74, v74
	v_cvt_pk_f16_f32 v77, v74, v75
	v_lshl_add_u64 v[78:79], s[48:49], 0, v[78:79]
	v_add_f32_e32 v72, v73, v72
	s_waitcnt vmcnt(16)
	v_pk_fma_f32 v[70:71], v[70:71], 0.5, v[102:103] op_sel_hi:[1,0,1]
	v_pk_fma_f32 v[68:69], v[68:69], 0.5, v[100:101] op_sel_hi:[1,0,1]
	global_store_dwordx2 v[78:79], v[76:77], off
	v_add_f32_e32 v76, v110, v72
	global_store_dwordx4 v[108:109], v[68:71], off offset:512 nt
	v_cvt_pk_f16_f32 v72, v68, v69
	s_waitcnt vmcnt(17)
	v_pk_fma_f32 v[66:67], v[66:67], 0.5, v[98:99] op_sel_hi:[1,0,1]
	v_mul_f32_e32 v69, v69, v69
	v_fmac_f32_e32 v69, v68, v68
	v_mul_f32_e32 v68, v71, v71
	v_fmac_f32_e32 v68, v70, v70
	v_pk_fma_f32 v[64:65], v[64:65], 0.5, v[96:97] op_sel_hi:[1,0,1]
	v_cvt_pk_f16_f32 v73, v70, v71
	v_add_f32_e32 v68, v69, v68
	v_mul_f32_e32 v69, v65, v65
	v_mul_f32_e32 v70, v67, v67
	v_fmac_f32_e32 v69, v64, v64
	v_fmac_f32_e32 v70, v66, v66
	v_add_f32_e32 v68, v76, v68
	v_add_f32_e32 v69, v69, v70
	v_add_f32_e32 v70, v68, v69
	ds_bpermute_b32 v71, v163, v70
	v_or_b32_e32 v74, 0x100, v114
	v_mov_b32_e32 v75, v115
	v_lshl_add_u64 v[68:69], s[48:49], 0, v[74:75]
	global_store_dwordx2 v[68:69], v[72:73], off
	global_store_dwordx4 v[108:109], v[64:67], off offset:576 nt
	v_cvt_pk_f16_f32 v68, v64, v65
	v_or_b32_e32 v114, 0x120, v114
	s_waitcnt lgkmcnt(0)
	v_add_f32_e32 v64, v70, v71
	ds_bpermute_b32 v65, v162, v64
	v_cvt_pk_f16_f32 v69, v66, v67
	v_lshl_add_u64 v[66:67], s[48:49], 0, v[114:115]
	v_readlane_b32 s53, v248, 49
	v_readlane_b32 s54, v248, 50
	v_readlane_b32 s55, v248, 51
	v_readlane_b32 s56, v248, 52
	v_readlane_b32 s57, v248, 53
	v_readlane_b32 s58, v248, 54
	v_readlane_b32 s59, v248, 55
	v_readlane_b32 s60, v248, 56
	v_readlane_b32 s61, v248, 57
	v_readlane_b32 s62, v248, 58
	v_readlane_b32 s63, v248, 59
	v_readlane_b32 s64, v248, 60
	v_readlane_b32 s65, v248, 61
	global_store_dwordx2 v[66:67], v[68:69], off
	s_and_saveexec_b64 s[2:3], s[6:7]
	s_cbranch_execz .LBB0_225
	s_waitcnt lgkmcnt(0)
	v_add_f32_e32 v66, v64, v65
	v_lshlrev_b64 v[64:65], 6, v[128:129]
	v_lshl_add_u64 v[64:65], s[46:47], 0, v[64:65]
	v_lshl_add_u64 v[64:65], s[16:17], 2, v[64:65]
	s_lshl_b32 s92, s39, 2
	v_lshl_add_u64 v[64:65], v[64:65], 0, s[92:93]
	v_readlane_b32 s73, v250, 34
	global_store_dword v[64:65], v66, off
.LBB0_225:
	s_or_b64 exec, exec, s[2:3]
	v_or_b32_e32 v96, 16, v112
	v_ashrrev_i32_e32 v97, 31, v96
	s_waitcnt lgkmcnt(0)
	v_lshlrev_b64 v[64:65], 12, v[96:97]
	v_lshl_add_u64 v[64:65], v[178:179], 0, v[64:65]
	global_load_dwordx4 v[76:79], v[64:65], off
	global_load_dwordx4 v[72:75], v[64:65], off offset:64
	global_load_dwordx4 v[68:71], v[64:65], off offset:512
	s_nop 0
	global_load_dwordx4 v[64:67], v[64:65], off offset:576
	v_lshlrev_b64 v[98:99], 10, v[112:113]
	v_readlane_b32 s52, v248, 48
	v_lshl_add_u64 v[98:99], v[98:99], 0, v[176:177]
	v_readlane_b32 s66, v248, 62
	v_readlane_b32 s67, v248, 63
	s_waitcnt vmcnt(15)
	v_pk_fma_f32 v[62:63], v[62:63], 0.5, v[94:95] op_sel_hi:[1,0,1]
	v_pk_fma_f32 v[60:61], v[60:61], 0.5, v[92:93] op_sel_hi:[1,0,1]
	v_lshl_add_u64 v[92:93], v[98:99], 2, s[66:67]
	global_store_dwordx4 v[92:93], v[60:63], off nt
	v_cvt_pk_f16_f32 v94, v60, v61
	v_lshlrev_b64 v[98:99], 1, v[98:99]
	v_mul_f32_e32 v61, v61, v61
	v_fmac_f32_e32 v61, v60, v60
	v_mul_f32_e32 v60, v63, v63
	v_cvt_pk_f16_f32 v95, v62, v63
	v_lshl_add_u64 v[100:101], s[48:49], 0, v[98:99]
	v_fmac_f32_e32 v60, v62, v62
	s_waitcnt vmcnt(15)
	v_pk_fma_f32 v[58:59], v[58:59], 0.5, v[90:91] op_sel_hi:[1,0,1]
	v_pk_fma_f32 v[56:57], v[56:57], 0.5, v[88:89] op_sel_hi:[1,0,1]
	global_store_dwordx2 v[100:101], v[94:95], off
	v_add_f32_e32 v94, v61, v60
	global_store_dwordx4 v[92:93], v[56:59], off offset:64 nt
	v_cvt_pk_f16_f32 v60, v56, v57
	v_or_b32_e32 v62, 32, v98
	v_mul_f32_e32 v57, v57, v57
	v_fmac_f32_e32 v57, v56, v56
	v_mul_f32_e32 v56, v59, v59
	v_mov_b32_e32 v63, v99
	v_fmac_f32_e32 v56, v58, v58
	v_cvt_pk_f16_f32 v61, v58, v59
	v_lshl_add_u64 v[62:63], s[48:49], 0, v[62:63]
	v_add_f32_e32 v56, v57, v56
	s_waitcnt vmcnt(16)
	v_pk_fma_f32 v[54:55], v[54:55], 0.5, v[86:87] op_sel_hi:[1,0,1]
	v_pk_fma_f32 v[52:53], v[52:53], 0.5, v[84:85] op_sel_hi:[1,0,1]
	global_store_dwordx2 v[62:63], v[60:61], off
	v_add_f32_e32 v60, v94, v56
	global_store_dwordx4 v[92:93], v[52:55], off offset:512 nt
	v_cvt_pk_f16_f32 v56, v52, v53
	s_waitcnt vmcnt(17)
	v_pk_fma_f32 v[50:51], v[50:51], 0.5, v[82:83] op_sel_hi:[1,0,1]
	v_mul_f32_e32 v53, v53, v53
	v_fmac_f32_e32 v53, v52, v52
	v_mul_f32_e32 v52, v55, v55
	v_fmac_f32_e32 v52, v54, v54
	v_pk_fma_f32 v[48:49], v[48:49], 0.5, v[80:81] op_sel_hi:[1,0,1]
	v_cvt_pk_f16_f32 v57, v54, v55
	v_add_f32_e32 v52, v53, v52
	v_mul_f32_e32 v53, v49, v49
	v_mul_f32_e32 v54, v51, v51
	v_fmac_f32_e32 v53, v48, v48
	v_fmac_f32_e32 v54, v50, v50
	v_add_f32_e32 v52, v60, v52
	v_add_f32_e32 v53, v53, v54
	v_add_f32_e32 v54, v52, v53
	ds_bpermute_b32 v55, v163, v54
	v_or_b32_e32 v58, 0x100, v98
	v_mov_b32_e32 v59, v99
	v_lshl_add_u64 v[52:53], s[48:49], 0, v[58:59]
	global_store_dwordx2 v[52:53], v[56:57], off
	global_store_dwordx4 v[92:93], v[48:51], off offset:576 nt
	v_cvt_pk_f16_f32 v52, v48, v49
	v_or_b32_e32 v98, 0x120, v98
	s_waitcnt lgkmcnt(0)
	v_add_f32_e32 v48, v54, v55
	ds_bpermute_b32 v49, v162, v48
	v_cvt_pk_f16_f32 v53, v50, v51
	v_lshl_add_u64 v[50:51], s[48:49], 0, v[98:99]
	v_readlane_b32 s53, v248, 49
	v_readlane_b32 s54, v248, 50
	v_readlane_b32 s55, v248, 51
	v_readlane_b32 s56, v248, 52
	v_readlane_b32 s57, v248, 53
	v_readlane_b32 s58, v248, 54
	v_readlane_b32 s59, v248, 55
	v_readlane_b32 s60, v248, 56
	v_readlane_b32 s61, v248, 57
	v_readlane_b32 s62, v248, 58
	v_readlane_b32 s63, v248, 59
	v_readlane_b32 s64, v248, 60
	v_readlane_b32 s65, v248, 61
	global_store_dwordx2 v[50:51], v[52:53], off
	s_and_saveexec_b64 s[2:3], s[6:7]
	s_cbranch_execz .LBB0_227
	s_waitcnt lgkmcnt(0)
	v_add_f32_e32 v50, v48, v49
	v_lshlrev_b64 v[48:49], 6, v[112:113]
	v_lshl_add_u64 v[48:49], s[46:47], 0, v[48:49]
	v_lshl_add_u64 v[48:49], s[16:17], 2, v[48:49]
	s_lshl_b32 s92, s39, 2
	v_lshl_add_u64 v[48:49], v[48:49], 0, s[92:93]
	v_readlane_b32 s73, v250, 34
	global_store_dword v[48:49], v50, off
.LBB0_227:
	s_or_b64 exec, exec, s[2:3]
	v_or_b32_e32 v80, 32, v112
	v_ashrrev_i32_e32 v81, 31, v80
	s_waitcnt lgkmcnt(0)
	v_lshlrev_b64 v[48:49], 12, v[80:81]
	v_lshl_add_u64 v[48:49], v[178:179], 0, v[48:49]
	global_load_dwordx4 v[60:63], v[48:49], off
	global_load_dwordx4 v[56:59], v[48:49], off offset:64
	global_load_dwordx4 v[52:55], v[48:49], off offset:512
	s_nop 0
	global_load_dwordx4 v[48:51], v[48:49], off offset:576
	v_lshlrev_b64 v[82:83], 10, v[96:97]
	v_readlane_b32 s52, v248, 48
	v_lshl_add_u64 v[82:83], v[82:83], 0, v[176:177]
	v_readlane_b32 s66, v248, 62
	v_readlane_b32 s67, v248, 63
	s_waitcnt vmcnt(15)
	v_pk_fma_f32 v[46:47], v[46:47], 0.5, v[78:79] op_sel_hi:[1,0,1]
	v_pk_fma_f32 v[44:45], v[44:45], 0.5, v[76:77] op_sel_hi:[1,0,1]
	v_lshl_add_u64 v[76:77], v[82:83], 2, s[66:67]
	global_store_dwordx4 v[76:77], v[44:47], off nt
	v_cvt_pk_f16_f32 v78, v44, v45
	v_lshlrev_b64 v[82:83], 1, v[82:83]
	v_mul_f32_e32 v45, v45, v45
	v_fmac_f32_e32 v45, v44, v44
	v_mul_f32_e32 v44, v47, v47
	v_cvt_pk_f16_f32 v79, v46, v47
	v_lshl_add_u64 v[84:85], s[48:49], 0, v[82:83]
	v_fmac_f32_e32 v44, v46, v46
	s_waitcnt vmcnt(15)
	v_pk_fma_f32 v[42:43], v[42:43], 0.5, v[74:75] op_sel_hi:[1,0,1]
	v_pk_fma_f32 v[40:41], v[40:41], 0.5, v[72:73] op_sel_hi:[1,0,1]
	global_store_dwordx2 v[84:85], v[78:79], off
	v_add_f32_e32 v78, v45, v44
	global_store_dwordx4 v[76:77], v[40:43], off offset:64 nt
	v_cvt_pk_f16_f32 v44, v40, v41
	v_or_b32_e32 v46, 32, v82
	v_mul_f32_e32 v41, v41, v41
	v_fmac_f32_e32 v41, v40, v40
	v_mul_f32_e32 v40, v43, v43
	v_mov_b32_e32 v47, v83
	v_fmac_f32_e32 v40, v42, v42
	v_cvt_pk_f16_f32 v45, v42, v43
	v_lshl_add_u64 v[46:47], s[48:49], 0, v[46:47]
	v_add_f32_e32 v40, v41, v40
	s_waitcnt vmcnt(16)
	v_pk_fma_f32 v[38:39], v[38:39], 0.5, v[70:71] op_sel_hi:[1,0,1]
	v_pk_fma_f32 v[36:37], v[36:37], 0.5, v[68:69] op_sel_hi:[1,0,1]
	global_store_dwordx2 v[46:47], v[44:45], off
	v_add_f32_e32 v44, v78, v40
	global_store_dwordx4 v[76:77], v[36:39], off offset:512 nt
	v_cvt_pk_f16_f32 v40, v36, v37
	s_waitcnt vmcnt(17)
	v_pk_fma_f32 v[34:35], v[34:35], 0.5, v[66:67] op_sel_hi:[1,0,1]
	v_mul_f32_e32 v37, v37, v37
	v_fmac_f32_e32 v37, v36, v36
	v_mul_f32_e32 v36, v39, v39
	v_fmac_f32_e32 v36, v38, v38
	v_pk_fma_f32 v[32:33], v[32:33], 0.5, v[64:65] op_sel_hi:[1,0,1]
	v_cvt_pk_f16_f32 v41, v38, v39
	v_add_f32_e32 v36, v37, v36
	v_mul_f32_e32 v37, v33, v33
	v_mul_f32_e32 v38, v35, v35
	v_fmac_f32_e32 v37, v32, v32
	v_fmac_f32_e32 v38, v34, v34
	v_add_f32_e32 v36, v44, v36
	v_add_f32_e32 v37, v37, v38
	v_add_f32_e32 v38, v36, v37
	ds_bpermute_b32 v39, v163, v38
	v_or_b32_e32 v42, 0x100, v82
	v_mov_b32_e32 v43, v83
	v_lshl_add_u64 v[36:37], s[48:49], 0, v[42:43]
	global_store_dwordx2 v[36:37], v[40:41], off
	global_store_dwordx4 v[76:77], v[32:35], off offset:576 nt
	v_cvt_pk_f16_f32 v36, v32, v33
	v_or_b32_e32 v82, 0x120, v82
	s_waitcnt lgkmcnt(0)
	v_add_f32_e32 v32, v38, v39
	ds_bpermute_b32 v33, v162, v32
	v_cvt_pk_f16_f32 v37, v34, v35
	v_lshl_add_u64 v[34:35], s[48:49], 0, v[82:83]
	v_readlane_b32 s53, v248, 49
	v_readlane_b32 s54, v248, 50
	v_readlane_b32 s55, v248, 51
	v_readlane_b32 s56, v248, 52
	v_readlane_b32 s57, v248, 53
	v_readlane_b32 s58, v248, 54
	v_readlane_b32 s59, v248, 55
	v_readlane_b32 s60, v248, 56
	v_readlane_b32 s61, v248, 57
	v_readlane_b32 s62, v248, 58
	v_readlane_b32 s63, v248, 59
	v_readlane_b32 s64, v248, 60
	v_readlane_b32 s65, v248, 61
	global_store_dwordx2 v[34:35], v[36:37], off
	s_and_saveexec_b64 s[2:3], s[6:7]
	s_cbranch_execz .LBB0_229
	s_waitcnt lgkmcnt(0)
	v_add_f32_e32 v34, v32, v33
	v_lshlrev_b64 v[32:33], 6, v[96:97]
	v_lshl_add_u64 v[32:33], s[46:47], 0, v[32:33]
	v_lshl_add_u64 v[32:33], s[16:17], 2, v[32:33]
	s_lshl_b32 s92, s39, 2
	v_lshl_add_u64 v[32:33], v[32:33], 0, s[92:93]
	v_readlane_b32 s73, v250, 34
	global_store_dword v[32:33], v34, off
.LBB0_229:
	s_or_b64 exec, exec, s[2:3]
	v_or_b32_e32 v64, 48, v112
	v_ashrrev_i32_e32 v65, 31, v64
	s_waitcnt lgkmcnt(0)
	v_lshlrev_b64 v[32:33], 12, v[64:65]
	v_lshl_add_u64 v[32:33], v[178:179], 0, v[32:33]
	global_load_dwordx4 v[44:47], v[32:33], off
	global_load_dwordx4 v[40:43], v[32:33], off offset:64
	global_load_dwordx4 v[36:39], v[32:33], off offset:512
	s_nop 0
	global_load_dwordx4 v[32:35], v[32:33], off offset:576
	v_lshlrev_b64 v[66:67], 10, v[80:81]
	v_readlane_b32 s52, v248, 48
	v_lshl_add_u64 v[66:67], v[66:67], 0, v[176:177]
	v_readlane_b32 s66, v248, 62
	v_readlane_b32 s67, v248, 63
	s_waitcnt vmcnt(15)
	v_pk_fma_f32 v[30:31], v[30:31], 0.5, v[62:63] op_sel_hi:[1,0,1]
	v_pk_fma_f32 v[28:29], v[28:29], 0.5, v[60:61] op_sel_hi:[1,0,1]
	v_lshl_add_u64 v[60:61], v[66:67], 2, s[66:67]
	global_store_dwordx4 v[60:61], v[28:31], off nt
	v_cvt_pk_f16_f32 v62, v28, v29
	v_lshlrev_b64 v[66:67], 1, v[66:67]
	v_mul_f32_e32 v29, v29, v29
	v_fmac_f32_e32 v29, v28, v28
	v_mul_f32_e32 v28, v31, v31
	v_cvt_pk_f16_f32 v63, v30, v31
	v_lshl_add_u64 v[68:69], s[48:49], 0, v[66:67]
	v_fmac_f32_e32 v28, v30, v30
	s_waitcnt vmcnt(15)
	v_pk_fma_f32 v[26:27], v[26:27], 0.5, v[58:59] op_sel_hi:[1,0,1]
	v_pk_fma_f32 v[24:25], v[24:25], 0.5, v[56:57] op_sel_hi:[1,0,1]
	global_store_dwordx2 v[68:69], v[62:63], off
	v_add_f32_e32 v62, v29, v28
	global_store_dwordx4 v[60:61], v[24:27], off offset:64 nt
	v_cvt_pk_f16_f32 v28, v24, v25
	v_or_b32_e32 v30, 32, v66
	v_mul_f32_e32 v25, v25, v25
	v_fmac_f32_e32 v25, v24, v24
	v_mul_f32_e32 v24, v27, v27
	v_mov_b32_e32 v31, v67
	v_fmac_f32_e32 v24, v26, v26
	v_cvt_pk_f16_f32 v29, v26, v27
	v_lshl_add_u64 v[30:31], s[48:49], 0, v[30:31]
	v_add_f32_e32 v24, v25, v24
	s_waitcnt vmcnt(16)
	v_pk_fma_f32 v[22:23], v[22:23], 0.5, v[54:55] op_sel_hi:[1,0,1]
	v_pk_fma_f32 v[20:21], v[20:21], 0.5, v[52:53] op_sel_hi:[1,0,1]
	global_store_dwordx2 v[30:31], v[28:29], off
	v_add_f32_e32 v28, v62, v24
	global_store_dwordx4 v[60:61], v[20:23], off offset:512 nt
	v_cvt_pk_f16_f32 v24, v20, v21
	s_waitcnt vmcnt(17)
	v_pk_fma_f32 v[18:19], v[18:19], 0.5, v[50:51] op_sel_hi:[1,0,1]
	v_mul_f32_e32 v21, v21, v21
	v_fmac_f32_e32 v21, v20, v20
	v_mul_f32_e32 v20, v23, v23
	v_fmac_f32_e32 v20, v22, v22
	v_pk_fma_f32 v[16:17], v[16:17], 0.5, v[48:49] op_sel_hi:[1,0,1]
	v_cvt_pk_f16_f32 v25, v22, v23
	v_add_f32_e32 v20, v21, v20
	v_mul_f32_e32 v21, v17, v17
	v_mul_f32_e32 v22, v19, v19
	v_fmac_f32_e32 v21, v16, v16
	v_fmac_f32_e32 v22, v18, v18
	v_add_f32_e32 v20, v28, v20
	v_add_f32_e32 v21, v21, v22
	v_add_f32_e32 v22, v20, v21
	ds_bpermute_b32 v23, v163, v22
	v_or_b32_e32 v26, 0x100, v66
	v_mov_b32_e32 v27, v67
	v_lshl_add_u64 v[20:21], s[48:49], 0, v[26:27]
	global_store_dwordx2 v[20:21], v[24:25], off
	global_store_dwordx4 v[60:61], v[16:19], off offset:576 nt
	v_cvt_pk_f16_f32 v20, v16, v17
	v_or_b32_e32 v66, 0x120, v66
	s_waitcnt lgkmcnt(0)
	v_add_f32_e32 v16, v22, v23
	ds_bpermute_b32 v17, v162, v16
	v_cvt_pk_f16_f32 v21, v18, v19
	v_lshl_add_u64 v[18:19], s[48:49], 0, v[66:67]
	v_readlane_b32 s53, v248, 49
	v_readlane_b32 s54, v248, 50
	v_readlane_b32 s55, v248, 51
	v_readlane_b32 s56, v248, 52
	v_readlane_b32 s57, v248, 53
	v_readlane_b32 s58, v248, 54
	v_readlane_b32 s59, v248, 55
	v_readlane_b32 s60, v248, 56
	v_readlane_b32 s61, v248, 57
	v_readlane_b32 s62, v248, 58
	v_readlane_b32 s63, v248, 59
	v_readlane_b32 s64, v248, 60
	v_readlane_b32 s65, v248, 61
	global_store_dwordx2 v[18:19], v[20:21], off
	s_and_saveexec_b64 s[2:3], s[6:7]
	s_cbranch_execz .LBB0_231
	s_waitcnt lgkmcnt(0)
	v_add_f32_e32 v18, v16, v17
	v_lshlrev_b64 v[16:17], 6, v[80:81]
	v_lshl_add_u64 v[16:17], s[46:47], 0, v[16:17]
	v_lshl_add_u64 v[16:17], s[16:17], 2, v[16:17]
	s_lshl_b32 s92, s39, 2
	v_lshl_add_u64 v[16:17], v[16:17], 0, s[92:93]
	v_readlane_b32 s73, v250, 34
	global_store_dword v[16:17], v18, off
.LBB0_231:
	s_or_b64 exec, exec, s[2:3]
	s_waitcnt lgkmcnt(0)
	v_lshlrev_b64 v[16:17], 10, v[64:65]
	v_readlane_b32 s52, v248, 48
	v_lshl_add_u64 v[16:17], v[16:17], 0, v[176:177]
	v_readlane_b32 s66, v248, 62
	v_readlane_b32 s67, v248, 63
	s_waitcnt vmcnt(11)
	v_pk_fma_f32 v[14:15], v[14:15], 0.5, v[46:47] op_sel_hi:[1,0,1]
	v_pk_fma_f32 v[12:13], v[12:13], 0.5, v[44:45] op_sel_hi:[1,0,1]
	v_lshl_add_u64 v[18:19], v[16:17], 2, s[66:67]
	global_store_dwordx4 v[18:19], v[12:15], off nt
	v_cvt_pk_f16_f32 v20, v12, v13
	v_lshlrev_b64 v[16:17], 1, v[16:17]
	v_mul_f32_e32 v13, v13, v13
	v_fmac_f32_e32 v13, v12, v12
	v_mul_f32_e32 v12, v15, v15
	v_cvt_pk_f16_f32 v21, v14, v15
	v_lshl_add_u64 v[22:23], s[48:49], 0, v[16:17]
	v_fmac_f32_e32 v12, v14, v14
	s_waitcnt vmcnt(11)
	v_pk_fma_f32 v[10:11], v[10:11], 0.5, v[42:43] op_sel_hi:[1,0,1]
	v_pk_fma_f32 v[8:9], v[8:9], 0.5, v[40:41] op_sel_hi:[1,0,1]
	global_store_dwordx2 v[22:23], v[20:21], off
	v_add_f32_e32 v20, v13, v12
	global_store_dwordx4 v[18:19], v[8:11], off offset:64 nt
	v_cvt_pk_f16_f32 v12, v8, v9
	v_or_b32_e32 v14, 32, v16
	v_mul_f32_e32 v9, v9, v9
	v_fmac_f32_e32 v9, v8, v8
	v_mul_f32_e32 v8, v11, v11
	v_mov_b32_e32 v15, v17
	v_fmac_f32_e32 v8, v10, v10
	v_cvt_pk_f16_f32 v13, v10, v11
	v_lshl_add_u64 v[14:15], s[48:49], 0, v[14:15]
	v_add_f32_e32 v8, v9, v8
	s_waitcnt vmcnt(12)
	v_pk_fma_f32 v[6:7], v[6:7], 0.5, v[38:39] op_sel_hi:[1,0,1]
	v_pk_fma_f32 v[4:5], v[4:5], 0.5, v[36:37] op_sel_hi:[1,0,1]
	global_store_dwordx2 v[14:15], v[12:13], off
	v_add_f32_e32 v12, v20, v8
	global_store_dwordx4 v[18:19], v[4:7], off offset:512 nt
	v_cvt_pk_f16_f32 v8, v4, v5
	s_waitcnt vmcnt(13)
	v_pk_fma_f32 v[2:3], v[2:3], 0.5, v[34:35] op_sel_hi:[1,0,1]
	v_mul_f32_e32 v5, v5, v5
	v_fmac_f32_e32 v5, v4, v4
	v_mul_f32_e32 v4, v7, v7
	v_fmac_f32_e32 v4, v6, v6
	v_pk_fma_f32 v[0:1], v[0:1], 0.5, v[32:33] op_sel_hi:[1,0,1]
	v_cvt_pk_f16_f32 v9, v6, v7
	v_add_f32_e32 v4, v5, v4
	v_mul_f32_e32 v5, v1, v1
	v_mul_f32_e32 v6, v3, v3
	v_fmac_f32_e32 v5, v0, v0
	v_fmac_f32_e32 v6, v2, v2
	v_add_f32_e32 v4, v12, v4
	v_add_f32_e32 v5, v5, v6
	v_add_f32_e32 v6, v4, v5
	ds_bpermute_b32 v7, v163, v6
	v_or_b32_e32 v10, 0x100, v16
	v_mov_b32_e32 v11, v17
	v_lshl_add_u64 v[4:5], s[48:49], 0, v[10:11]
	global_store_dwordx2 v[4:5], v[8:9], off
	global_store_dwordx4 v[18:19], v[0:3], off offset:576 nt
	v_cvt_pk_f16_f32 v4, v0, v1
	v_or_b32_e32 v16, 0x120, v16
	s_waitcnt lgkmcnt(0)
	v_add_f32_e32 v0, v6, v7
	ds_bpermute_b32 v1, v162, v0
	v_cvt_pk_f16_f32 v5, v2, v3
	v_lshl_add_u64 v[2:3], s[48:49], 0, v[16:17]
	v_readlane_b32 s53, v248, 49
	v_readlane_b32 s54, v248, 50
	v_readlane_b32 s55, v248, 51
	v_readlane_b32 s56, v248, 52
	v_readlane_b32 s57, v248, 53
	v_readlane_b32 s58, v248, 54
	v_readlane_b32 s59, v248, 55
	v_readlane_b32 s60, v248, 56
	v_readlane_b32 s61, v248, 57
	v_readlane_b32 s62, v248, 58
	v_readlane_b32 s63, v248, 59
	v_readlane_b32 s64, v248, 60
	v_readlane_b32 s65, v248, 61
	global_store_dwordx2 v[2:3], v[4:5], off
	s_and_saveexec_b64 s[2:3], s[6:7]
	s_cbranch_execz .LBB0_233
	s_waitcnt lgkmcnt(0)
	v_add_f32_e32 v2, v0, v1
	v_lshlrev_b64 v[0:1], 6, v[64:65]
	v_lshl_add_u64 v[0:1], s[46:47], 0, v[0:1]
	v_lshl_add_u64 v[0:1], s[16:17], 2, v[0:1]
	s_lshl_b32 s92, s39, 2
	v_lshl_add_u64 v[0:1], v[0:1], 0, s[92:93]
	v_readlane_b32 s73, v250, 34
	global_store_dword v[0:1], v2, off

.LBB0_339:
	v_lshl_add_u32 v180, s45, 8, v184
	v_lshl_or_b32 v176, s44, 8, v186
	s_cmpk_lt_i32 s45, 0x100
	v_ashrrev_i32_e32 v181, 31, v180
	s_cselect_b32 s3, s24, s26
	s_cselect_b32 s2, s25, s27
	v_lshlrev_b64 v[128:129], 12, v[180:181]
	v_ashrrev_i32_e32 v177, 31, v176
	v_lshl_add_u64 v[128:129], s[2:3], 0, v[128:129]
	v_lshlrev_b64 v[130:131], 2, v[176:177]
	v_lshl_add_u64 v[128:129], v[128:129], 0, v[130:131]
	global_load_dwordx4 v[154:157], v[128:129], off
	global_load_dwordx4 v[188:191], v[128:129], off offset:64
	global_load_dwordx4 v[148:151], v[128:129], off offset:512
	global_load_dwordx4 v[144:147], v[128:129], off offset:576
	v_and_b32_e32 v129, 64, v203
	v_xor_b32_e32 v128, 16, v203
	v_add_u32_e32 v129, 64, v129
	v_cmp_lt_i32_e32 vcc, v128, v129
	v_or_b32_e32 v182, 16, v180
	v_ashrrev_i32_e32 v183, 31, v182
	v_cndmask_b32_e32 v128, v203, v128, vcc
	v_lshlrev_b32_e32 v163, 2, v128
	v_xor_b32_e32 v128, 32, v203
	v_cmp_lt_i32_e32 vcc, v128, v129
	v_lshl_add_u64 v[178:179], s[2:3], 0, v[130:131]
	v_readlane_b32 s52, v248, 48
	v_cndmask_b32_e32 v128, v203, v128, vcc
	v_lshlrev_b32_e32 v162, 2, v128
	v_lshlrev_b64 v[128:129], 10, v[180:181]
	v_lshl_add_u64 v[164:165], v[128:129], 0, v[176:177]
	v_lshlrev_b64 v[128:129], 12, v[182:183]
	v_lshl_add_u64 v[128:129], v[178:179], 0, v[128:129]
	global_load_dwordx4 v[140:143], v[128:129], off
	global_load_dwordx4 v[136:139], v[128:129], off offset:64
	global_load_dwordx4 v[132:135], v[128:129], off offset:512
	s_nop 0
	global_load_dwordx4 v[128:131], v[128:129], off offset:576
	v_readlane_b32 s66, v248, 62
	v_readlane_b32 s67, v248, 63
	v_readlane_b32 s2, v253, 24
	v_readlane_b32 s3, v253, 25
	s_lshl_b32 s16, s44, 2
	s_ashr_i32 s17, s16, 31
	v_readlane_b32 s53, v248, 49
	v_readlane_b32 s54, v248, 50
	v_readlane_b32 s55, v248, 51
	v_readlane_b32 s56, v248, 52
	v_readlane_b32 s57, v248, 53
	v_readlane_b32 s58, v248, 54
	v_readlane_b32 s59, v248, 55
	v_readlane_b32 s60, v248, 56
	v_readlane_b32 s61, v248, 57
	v_readlane_b32 s62, v248, 58
	v_readlane_b32 s63, v248, 59
	v_readlane_b32 s64, v248, 60
	v_readlane_b32 s65, v248, 61
	s_waitcnt vmcnt(0)
	v_pk_fma_f32 v[156:157], v[126:127], 0.5, v[156:157] op_sel_hi:[1,0,1]
	v_pk_fma_f32 v[154:155], v[124:125], 0.5, v[154:155] op_sel_hi:[1,0,1]
	v_lshl_add_u64 v[124:125], v[164:165], 2, s[66:67]
	v_lshlrev_b64 v[164:165], 1, v[164:165]
	v_cvt_pk_f16_f32 v126, v154, v155
	v_cvt_pk_f16_f32 v127, v156, v157
	v_lshl_add_u64 v[166:167], s[2:3], 0, v[164:165]
	global_store_dwordx4 v[124:125], v[154:157], off nt
	global_store_dwordx2 v[166:167], v[126:127], off
	v_mul_f32_e32 v126, v155, v155
	v_mul_f32_e32 v127, v157, v157
	v_fmac_f32_e32 v126, v154, v154
	v_fmac_f32_e32 v127, v156, v156
	v_pk_fma_f32 v[122:123], v[122:123], 0.5, v[190:191] op_sel_hi:[1,0,1]
	v_pk_fma_f32 v[120:121], v[120:121], 0.5, v[188:189] op_sel_hi:[1,0,1]
	v_add_f32_e32 v156, v126, v127
	global_store_dwordx4 v[124:125], v[120:123], off offset:64 nt
	v_cvt_pk_f16_f32 v126, v120, v121
	v_or_b32_e32 v154, 32, v164
	v_mul_f32_e32 v121, v121, v121
	v_fmac_f32_e32 v121, v120, v120
	v_mul_f32_e32 v120, v123, v123
	v_mov_b32_e32 v155, v165
	v_fmac_f32_e32 v120, v122, v122
	v_cvt_pk_f16_f32 v127, v122, v123
	v_lshl_add_u64 v[154:155], s[2:3], 0, v[154:155]
	v_add_f32_e32 v120, v121, v120
	v_pk_fma_f32 v[118:119], v[118:119], 0.5, v[150:151] op_sel_hi:[1,0,1]
	v_pk_fma_f32 v[116:117], v[116:117], 0.5, v[148:149] op_sel_hi:[1,0,1]
	global_store_dwordx2 v[154:155], v[126:127], off
	v_add_f32_e32 v126, v156, v120
	global_store_dwordx4 v[124:125], v[116:119], off offset:512 nt
	v_cvt_pk_f16_f32 v120, v116, v117
	v_or_b32_e32 v122, 0x100, v164
	v_mul_f32_e32 v117, v117, v117
	v_fmac_f32_e32 v117, v116, v116
	v_mul_f32_e32 v116, v119, v119
	v_mov_b32_e32 v123, v165
	v_fmac_f32_e32 v116, v118, v118
	v_cvt_pk_f16_f32 v121, v118, v119
	v_lshl_add_u64 v[122:123], s[2:3], 0, v[122:123]
	v_add_f32_e32 v116, v117, v116
	v_pk_fma_f32 v[114:115], v[114:115], 0.5, v[146:147] op_sel_hi:[1,0,1]
	v_pk_fma_f32 v[112:113], v[112:113], 0.5, v[144:145] op_sel_hi:[1,0,1]
	global_store_dwordx2 v[122:123], v[120:121], off
	v_add_f32_e32 v120, v126, v116
	global_store_dwordx4 v[124:125], v[112:115], off offset:576 nt
	v_cvt_pk_f16_f32 v116, v112, v113
	v_or_b32_e32 v164, 0x120, v164
	v_mul_f32_e32 v113, v113, v113
	v_fmac_f32_e32 v113, v112, v112
	v_mul_f32_e32 v112, v115, v115
	v_fmac_f32_e32 v112, v114, v114
	v_add_f32_e32 v112, v113, v112
	v_add_f32_e32 v112, v120, v112
	ds_bpermute_b32 v113, v163, v112
	v_cvt_pk_f16_f32 v117, v114, v115
	v_lshl_add_u64 v[118:119], s[2:3], 0, v[164:165]
	global_store_dwordx2 v[118:119], v[116:117], off
	s_waitcnt lgkmcnt(0)
	v_add_f32_e32 v112, v112, v113
	ds_bpermute_b32 v113, v162, v112
	s_and_saveexec_b64 s[2:3], s[6:7]
	v_readlane_b32 s46, v254, 16
	v_readlane_b32 s47, v254, 17
	s_cbranch_execz .LBB0_341
	s_waitcnt lgkmcnt(0)
	v_add_f32_e32 v114, v112, v113
	v_lshlrev_b64 v[112:113], 6, v[180:181]
	v_lshl_add_u64 v[112:113], s[46:47], 0, v[112:113]
	v_lshl_add_u64 v[112:113], s[16:17], 2, v[112:113]
	s_lshl_b32 s92, s40, 2
	v_lshl_add_u64 v[112:113], v[112:113], 0, s[92:93]
	v_readlane_b32 s73, v250, 34
	global_store_dword v[112:113], v114, off
.LBB0_341:
	s_or_b64 exec, exec, s[2:3]
	v_or_b32_e32 v144, 32, v180
	v_ashrrev_i32_e32 v145, 31, v144
	s_waitcnt lgkmcnt(0)
	v_lshlrev_b64 v[112:113], 12, v[144:145]
	v_lshl_add_u64 v[112:113], v[178:179], 0, v[112:113]
	global_load_dwordx4 v[124:127], v[112:113], off
	global_load_dwordx4 v[120:123], v[112:113], off offset:64
	global_load_dwordx4 v[116:119], v[112:113], off offset:512
	s_nop 0
	global_load_dwordx4 v[112:115], v[112:113], off offset:576
	v_lshlrev_b64 v[146:147], 10, v[182:183]
	v_readlane_b32 s52, v248, 48
	v_lshl_add_u64 v[146:147], v[146:147], 0, v[176:177]
	v_readlane_b32 s66, v248, 62
	v_readlane_b32 s67, v248, 63
	v_pk_fma_f32 v[110:111], v[110:111], 0.5, v[142:143] op_sel_hi:[1,0,1]
	v_pk_fma_f32 v[108:109], v[108:109], 0.5, v[140:141] op_sel_hi:[1,0,1]
	v_lshl_add_u64 v[140:141], v[146:147], 2, s[66:67]
	global_store_dwordx4 v[140:141], v[108:111], off nt
	v_cvt_pk_f16_f32 v142, v108, v109
	v_readlane_b32 s2, v253, 24
	v_mul_f32_e32 v109, v109, v109
	v_lshlrev_b64 v[146:147], 1, v[146:147]
	v_readlane_b32 s3, v253, 25
	v_fmac_f32_e32 v109, v108, v108
	v_mul_f32_e32 v108, v111, v111
	v_cvt_pk_f16_f32 v143, v110, v111
	v_lshl_add_u64 v[148:149], s[2:3], 0, v[146:147]
	v_fmac_f32_e32 v108, v110, v110
	v_pk_fma_f32 v[106:107], v[106:107], 0.5, v[138:139] op_sel_hi:[1,0,1]
	v_pk_fma_f32 v[104:105], v[104:105], 0.5, v[136:137] op_sel_hi:[1,0,1]
	global_store_dwordx2 v[148:149], v[142:143], off
	v_add_f32_e32 v142, v109, v108
	global_store_dwordx4 v[140:141], v[104:107], off offset:64 nt
	v_cvt_pk_f16_f32 v108, v104, v105
	v_or_b32_e32 v110, 32, v146
	v_mul_f32_e32 v105, v105, v105
	v_fmac_f32_e32 v105, v104, v104
	v_mul_f32_e32 v104, v107, v107
	v_mov_b32_e32 v111, v147
	v_fmac_f32_e32 v104, v106, v106
	v_cvt_pk_f16_f32 v109, v106, v107
	v_lshl_add_u64 v[110:111], s[2:3], 0, v[110:111]
	v_add_f32_e32 v104, v105, v104
	v_pk_fma_f32 v[102:103], v[102:103], 0.5, v[134:135] op_sel_hi:[1,0,1]
	v_pk_fma_f32 v[100:101], v[100:101], 0.5, v[132:133] op_sel_hi:[1,0,1]
	global_store_dwordx2 v[110:111], v[108:109], off
	v_add_f32_e32 v108, v142, v104
	global_store_dwordx4 v[140:141], v[100:103], off offset:512 nt
	v_cvt_pk_f16_f32 v104, v100, v101
	v_pk_fma_f32 v[98:99], v[98:99], 0.5, v[130:131] op_sel_hi:[1,0,1]
	v_mul_f32_e32 v101, v101, v101
	v_fmac_f32_e32 v101, v100, v100
	v_mul_f32_e32 v100, v103, v103
	v_fmac_f32_e32 v100, v102, v102
	v_pk_fma_f32 v[96:97], v[96:97], 0.5, v[128:129] op_sel_hi:[1,0,1]
	v_cvt_pk_f16_f32 v105, v102, v103
	v_add_f32_e32 v100, v101, v100
	v_mul_f32_e32 v101, v97, v97
	v_mul_f32_e32 v102, v99, v99
	v_fmac_f32_e32 v101, v96, v96
	v_fmac_f32_e32 v102, v98, v98
	v_add_f32_e32 v100, v108, v100
	v_add_f32_e32 v101, v101, v102
	v_add_f32_e32 v102, v100, v101
	ds_bpermute_b32 v103, v163, v102
	v_or_b32_e32 v106, 0x100, v146
	v_mov_b32_e32 v107, v147
	v_lshl_add_u64 v[100:101], s[2:3], 0, v[106:107]
	global_store_dwordx2 v[100:101], v[104:105], off
	global_store_dwordx4 v[140:141], v[96:99], off offset:576 nt
	v_cvt_pk_f16_f32 v100, v96, v97
	v_or_b32_e32 v146, 0x120, v146
	s_waitcnt lgkmcnt(0)
	v_add_f32_e32 v96, v102, v103
	ds_bpermute_b32 v97, v162, v96
	v_cvt_pk_f16_f32 v101, v98, v99
	v_lshl_add_u64 v[98:99], s[2:3], 0, v[146:147]
	v_readlane_b32 s53, v248, 49
	v_readlane_b32 s54, v248, 50
	v_readlane_b32 s55, v248, 51
	v_readlane_b32 s56, v248, 52
	v_readlane_b32 s57, v248, 53
	v_readlane_b32 s58, v248, 54
	v_readlane_b32 s59, v248, 55
	v_readlane_b32 s60, v248, 56
	v_readlane_b32 s61, v248, 57
	v_readlane_b32 s62, v248, 58
	v_readlane_b32 s63, v248, 59
	v_readlane_b32 s64, v248, 60
	v_readlane_b32 s65, v248, 61
	global_store_dwordx2 v[98:99], v[100:101], off
	s_and_saveexec_b64 s[2:3], s[6:7]
	s_cbranch_execz .LBB0_343
	s_waitcnt lgkmcnt(0)
	v_add_f32_e32 v98, v96, v97
	v_lshlrev_b64 v[96:97], 6, v[182:183]
	v_lshl_add_u64 v[96:97], s[46:47], 0, v[96:97]
	v_lshl_add_u64 v[96:97], s[16:17], 2, v[96:97]
	s_lshl_b32 s92, s40, 2
	v_lshl_add_u64 v[96:97], v[96:97], 0, s[92:93]
	v_readlane_b32 s73, v250, 34
	global_store_dword v[96:97], v98, off
.LBB0_343:
	s_or_b64 exec, exec, s[2:3]
	v_or_b32_e32 v128, 48, v180
	v_ashrrev_i32_e32 v129, 31, v128
	s_waitcnt lgkmcnt(0)
	v_lshlrev_b64 v[96:97], 12, v[128:129]
	v_lshl_add_u64 v[96:97], v[178:179], 0, v[96:97]
	global_load_dwordx4 v[108:111], v[96:97], off
	global_load_dwordx4 v[104:107], v[96:97], off offset:64
	global_load_dwordx4 v[100:103], v[96:97], off offset:512
	s_nop 0
	global_load_dwordx4 v[96:99], v[96:97], off offset:576
	v_lshlrev_b64 v[130:131], 10, v[144:145]
	v_readlane_b32 s52, v248, 48
	v_lshl_add_u64 v[130:131], v[130:131], 0, v[176:177]
	v_readlane_b32 s66, v248, 62
	v_readlane_b32 s67, v248, 63
	s_waitcnt vmcnt(15)
	v_pk_fma_f32 v[94:95], v[94:95], 0.5, v[126:127] op_sel_hi:[1,0,1]
	v_pk_fma_f32 v[92:93], v[92:93], 0.5, v[124:125] op_sel_hi:[1,0,1]
	v_lshl_add_u64 v[124:125], v[130:131], 2, s[66:67]
	global_store_dwordx4 v[124:125], v[92:95], off nt
	v_cvt_pk_f16_f32 v126, v92, v93
	v_readlane_b32 s2, v253, 24
	v_mul_f32_e32 v93, v93, v93
	v_lshlrev_b64 v[130:131], 1, v[130:131]
	v_readlane_b32 s3, v253, 25
	v_fmac_f32_e32 v93, v92, v92
	v_mul_f32_e32 v92, v95, v95
	v_cvt_pk_f16_f32 v127, v94, v95
	v_lshl_add_u64 v[132:133], s[2:3], 0, v[130:131]
	v_fmac_f32_e32 v92, v94, v94
	s_waitcnt vmcnt(15)
	v_pk_fma_f32 v[90:91], v[90:91], 0.5, v[122:123] op_sel_hi:[1,0,1]
	v_pk_fma_f32 v[88:89], v[88:89], 0.5, v[120:121] op_sel_hi:[1,0,1]
	global_store_dwordx2 v[132:133], v[126:127], off
	v_add_f32_e32 v126, v93, v92
	global_store_dwordx4 v[124:125], v[88:91], off offset:64 nt
	v_cvt_pk_f16_f32 v92, v88, v89
	v_or_b32_e32 v94, 32, v130
	v_mul_f32_e32 v89, v89, v89
	v_fmac_f32_e32 v89, v88, v88
	v_mul_f32_e32 v88, v91, v91
	v_mov_b32_e32 v95, v131
	v_fmac_f32_e32 v88, v90, v90
	v_cvt_pk_f16_f32 v93, v90, v91
	v_lshl_add_u64 v[94:95], s[2:3], 0, v[94:95]
	v_add_f32_e32 v88, v89, v88
	s_waitcnt vmcnt(16)
	v_pk_fma_f32 v[86:87], v[86:87], 0.5, v[118:119] op_sel_hi:[1,0,1]
	v_pk_fma_f32 v[84:85], v[84:85], 0.5, v[116:117] op_sel_hi:[1,0,1]
	global_store_dwordx2 v[94:95], v[92:93], off
	v_add_f32_e32 v92, v126, v88
	global_store_dwordx4 v[124:125], v[84:87], off offset:512 nt
	v_cvt_pk_f16_f32 v88, v84, v85
	s_waitcnt vmcnt(17)
	v_pk_fma_f32 v[82:83], v[82:83], 0.5, v[114:115] op_sel_hi:[1,0,1]
	v_mul_f32_e32 v85, v85, v85
	v_fmac_f32_e32 v85, v84, v84
	v_mul_f32_e32 v84, v87, v87
	v_fmac_f32_e32 v84, v86, v86
	v_pk_fma_f32 v[80:81], v[80:81], 0.5, v[112:113] op_sel_hi:[1,0,1]
	v_cvt_pk_f16_f32 v89, v86, v87
	v_add_f32_e32 v84, v85, v84
	v_mul_f32_e32 v85, v81, v81
	v_mul_f32_e32 v86, v83, v83
	v_fmac_f32_e32 v85, v80, v80
	v_fmac_f32_e32 v86, v82, v82
	v_add_f32_e32 v84, v92, v84
	v_add_f32_e32 v85, v85, v86
	v_add_f32_e32 v86, v84, v85
	ds_bpermute_b32 v87, v163, v86
	v_or_b32_e32 v90, 0x100, v130
	v_mov_b32_e32 v91, v131
	v_lshl_add_u64 v[84:85], s[2:3], 0, v[90:91]
	global_store_dwordx2 v[84:85], v[88:89], off
	global_store_dwordx4 v[124:125], v[80:83], off offset:576 nt
	v_cvt_pk_f16_f32 v84, v80, v81
	v_or_b32_e32 v130, 0x120, v130
	s_waitcnt lgkmcnt(0)
	v_add_f32_e32 v80, v86, v87
	ds_bpermute_b32 v81, v162, v80
	v_cvt_pk_f16_f32 v85, v82, v83
	v_lshl_add_u64 v[82:83], s[2:3], 0, v[130:131]
	v_readlane_b32 s53, v248, 49
	v_readlane_b32 s54, v248, 50
	v_readlane_b32 s55, v248, 51
	v_readlane_b32 s56, v248, 52
	v_readlane_b32 s57, v248, 53
	v_readlane_b32 s58, v248, 54
	v_readlane_b32 s59, v248, 55
	v_readlane_b32 s60, v248, 56
	v_readlane_b32 s61, v248, 57
	v_readlane_b32 s62, v248, 58
	v_readlane_b32 s63, v248, 59
	v_readlane_b32 s64, v248, 60
	v_readlane_b32 s65, v248, 61
	global_store_dwordx2 v[82:83], v[84:85], off
	s_mov_b64 s[2:3], exec
	v_mov_b64_e32 v[154:155], v[158:159]
	s_and_b64 s[18:19], s[2:3], s[6:7]
	v_mov_b64_e32 v[156:157], v[160:161]
	s_mov_b64 exec, s[18:19]
	s_cbranch_execz .LBB0_345
	s_waitcnt lgkmcnt(0)
	v_add_f32_e32 v82, v80, v81
	v_lshlrev_b64 v[80:81], 6, v[144:145]
	v_lshl_add_u64 v[80:81], s[46:47], 0, v[80:81]
	v_lshl_add_u64 v[80:81], s[16:17], 2, v[80:81]
	s_lshl_b32 s92, s40, 2
	v_lshl_add_u64 v[80:81], v[80:81], 0, s[92:93]
	v_readlane_b32 s73, v250, 34
	global_store_dword v[80:81], v82, off
.LBB0_345:
	s_or_b64 exec, exec, s[2:3]
	v_add_u32_e32 v112, 0x80, v180
	v_ashrrev_i32_e32 v113, 31, v112
	s_waitcnt lgkmcnt(0)
	v_lshlrev_b64 v[80:81], 12, v[112:113]
	v_lshl_add_u64 v[80:81], v[178:179], 0, v[80:81]
	global_load_dwordx4 v[92:95], v[80:81], off
	global_load_dwordx4 v[88:91], v[80:81], off offset:64
	global_load_dwordx4 v[84:87], v[80:81], off offset:512
	s_nop 0
	global_load_dwordx4 v[80:83], v[80:81], off offset:576
	v_lshlrev_b64 v[114:115], 10, v[128:129]
	v_readlane_b32 s52, v248, 48
	v_lshl_add_u64 v[114:115], v[114:115], 0, v[176:177]
	v_readlane_b32 s66, v248, 62
	v_readlane_b32 s67, v248, 63
	s_waitcnt vmcnt(15)
	v_pk_fma_f32 v[78:79], v[78:79], 0.5, v[110:111] op_sel_hi:[1,0,1]
	v_pk_fma_f32 v[76:77], v[76:77], 0.5, v[108:109] op_sel_hi:[1,0,1]
	v_lshl_add_u64 v[108:109], v[114:115], 2, s[66:67]
	global_store_dwordx4 v[108:109], v[76:79], off nt
	v_cvt_pk_f16_f32 v110, v76, v77
	v_readlane_b32 s2, v253, 24
	v_mul_f32_e32 v77, v77, v77
	v_lshlrev_b64 v[114:115], 1, v[114:115]
	v_readlane_b32 s3, v253, 25
	v_fmac_f32_e32 v77, v76, v76
	v_mul_f32_e32 v76, v79, v79
	v_cvt_pk_f16_f32 v111, v78, v79
	v_lshl_add_u64 v[116:117], s[2:3], 0, v[114:115]
	v_fmac_f32_e32 v76, v78, v78
	s_waitcnt vmcnt(15)
	v_pk_fma_f32 v[74:75], v[74:75], 0.5, v[106:107] op_sel_hi:[1,0,1]
	v_pk_fma_f32 v[72:73], v[72:73], 0.5, v[104:105] op_sel_hi:[1,0,1]
	global_store_dwordx2 v[116:117], v[110:111], off
	v_add_f32_e32 v110, v77, v76
	global_store_dwordx4 v[108:109], v[72:75], off offset:64 nt
	v_cvt_pk_f16_f32 v76, v72, v73
	v_or_b32_e32 v78, 32, v114
	v_mul_f32_e32 v73, v73, v73
	v_fmac_f32_e32 v73, v72, v72
	v_mul_f32_e32 v72, v75, v75
	v_mov_b32_e32 v79, v115
	v_fmac_f32_e32 v72, v74, v74
	v_cvt_pk_f16_f32 v77, v74, v75
	v_lshl_add_u64 v[78:79], s[2:3], 0, v[78:79]
	v_add_f32_e32 v72, v73, v72
	s_waitcnt vmcnt(16)
	v_pk_fma_f32 v[70:71], v[70:71], 0.5, v[102:103] op_sel_hi:[1,0,1]
	v_pk_fma_f32 v[68:69], v[68:69], 0.5, v[100:101] op_sel_hi:[1,0,1]
	global_store_dwordx2 v[78:79], v[76:77], off
	v_add_f32_e32 v76, v110, v72
	global_store_dwordx4 v[108:109], v[68:71], off offset:512 nt
	v_cvt_pk_f16_f32 v72, v68, v69
	s_waitcnt vmcnt(17)
	v_pk_fma_f32 v[66:67], v[66:67], 0.5, v[98:99] op_sel_hi:[1,0,1]
	v_mul_f32_e32 v69, v69, v69
	v_fmac_f32_e32 v69, v68, v68
	v_mul_f32_e32 v68, v71, v71
	v_fmac_f32_e32 v68, v70, v70
	v_pk_fma_f32 v[64:65], v[64:65], 0.5, v[96:97] op_sel_hi:[1,0,1]
	v_cvt_pk_f16_f32 v73, v70, v71
	v_add_f32_e32 v68, v69, v68
	v_mul_f32_e32 v69, v65, v65
	v_mul_f32_e32 v70, v67, v67
	v_fmac_f32_e32 v69, v64, v64
	v_fmac_f32_e32 v70, v66, v66
	v_add_f32_e32 v68, v76, v68
	v_add_f32_e32 v69, v69, v70
	v_add_f32_e32 v70, v68, v69
	ds_bpermute_b32 v71, v163, v70
	v_or_b32_e32 v74, 0x100, v114
	v_mov_b32_e32 v75, v115
	v_lshl_add_u64 v[68:69], s[2:3], 0, v[74:75]
	global_store_dwordx2 v[68:69], v[72:73], off
	global_store_dwordx4 v[108:109], v[64:67], off offset:576 nt
	v_cvt_pk_f16_f32 v68, v64, v65
	v_or_b32_e32 v114, 0x120, v114
	s_waitcnt lgkmcnt(0)
	v_add_f32_e32 v64, v70, v71
	ds_bpermute_b32 v65, v162, v64
	v_cvt_pk_f16_f32 v69, v66, v67
	v_lshl_add_u64 v[66:67], s[2:3], 0, v[114:115]
	v_readlane_b32 s53, v248, 49
	v_readlane_b32 s54, v248, 50
	v_readlane_b32 s55, v248, 51
	v_readlane_b32 s56, v248, 52
	v_readlane_b32 s57, v248, 53
	v_readlane_b32 s58, v248, 54
	v_readlane_b32 s59, v248, 55
	v_readlane_b32 s60, v248, 56
	v_readlane_b32 s61, v248, 57
	v_readlane_b32 s62, v248, 58
	v_readlane_b32 s63, v248, 59
	v_readlane_b32 s64, v248, 60
	v_readlane_b32 s65, v248, 61
	global_store_dwordx2 v[66:67], v[68:69], off
	s_and_saveexec_b64 s[2:3], s[6:7]
	s_cbranch_execz .LBB0_347
	s_waitcnt lgkmcnt(0)
	v_add_f32_e32 v66, v64, v65
	v_lshlrev_b64 v[64:65], 6, v[128:129]
	v_lshl_add_u64 v[64:65], s[46:47], 0, v[64:65]
	v_lshl_add_u64 v[64:65], s[16:17], 2, v[64:65]
	s_lshl_b32 s92, s40, 2
	v_lshl_add_u64 v[64:65], v[64:65], 0, s[92:93]
	v_readlane_b32 s73, v250, 34
	global_store_dword v[64:65], v66, off
.LBB0_347:
	s_or_b64 exec, exec, s[2:3]
	v_or_b32_e32 v96, 16, v112
	v_ashrrev_i32_e32 v97, 31, v96
	s_waitcnt lgkmcnt(0)
	v_lshlrev_b64 v[64:65], 12, v[96:97]
	v_lshl_add_u64 v[64:65], v[178:179], 0, v[64:65]
	global_load_dwordx4 v[76:79], v[64:65], off
	global_load_dwordx4 v[72:75], v[64:65], off offset:64
	global_load_dwordx4 v[68:71], v[64:65], off offset:512
	s_nop 0
	global_load_dwordx4 v[64:67], v[64:65], off offset:576
	v_lshlrev_b64 v[98:99], 10, v[112:113]
	v_readlane_b32 s52, v248, 48
	v_lshl_add_u64 v[98:99], v[98:99], 0, v[176:177]
	v_readlane_b32 s66, v248, 62
	v_readlane_b32 s67, v248, 63
	s_waitcnt vmcnt(15)
	v_pk_fma_f32 v[62:63], v[62:63], 0.5, v[94:95] op_sel_hi:[1,0,1]
	v_pk_fma_f32 v[60:61], v[60:61], 0.5, v[92:93] op_sel_hi:[1,0,1]
	v_lshl_add_u64 v[92:93], v[98:99], 2, s[66:67]
	global_store_dwordx4 v[92:93], v[60:63], off nt
	v_cvt_pk_f16_f32 v94, v60, v61
	v_readlane_b32 s2, v253, 24
	v_mul_f32_e32 v61, v61, v61
	v_lshlrev_b64 v[98:99], 1, v[98:99]
	v_readlane_b32 s3, v253, 25
	v_fmac_f32_e32 v61, v60, v60
	v_mul_f32_e32 v60, v63, v63
	v_cvt_pk_f16_f32 v95, v62, v63
	v_lshl_add_u64 v[100:101], s[2:3], 0, v[98:99]
	v_fmac_f32_e32 v60, v62, v62
	s_waitcnt vmcnt(15)
	v_pk_fma_f32 v[58:59], v[58:59], 0.5, v[90:91] op_sel_hi:[1,0,1]
	v_pk_fma_f32 v[56:57], v[56:57], 0.5, v[88:89] op_sel_hi:[1,0,1]
	global_store_dwordx2 v[100:101], v[94:95], off
	v_add_f32_e32 v94, v61, v60
	global_store_dwordx4 v[92:93], v[56:59], off offset:64 nt
	v_cvt_pk_f16_f32 v60, v56, v57
	v_or_b32_e32 v62, 32, v98
	v_mul_f32_e32 v57, v57, v57
	v_fmac_f32_e32 v57, v56, v56
	v_mul_f32_e32 v56, v59, v59
	v_mov_b32_e32 v63, v99
	v_fmac_f32_e32 v56, v58, v58
	v_cvt_pk_f16_f32 v61, v58, v59
	v_lshl_add_u64 v[62:63], s[2:3], 0, v[62:63]
	v_add_f32_e32 v56, v57, v56
	s_waitcnt vmcnt(16)
	v_pk_fma_f32 v[54:55], v[54:55], 0.5, v[86:87] op_sel_hi:[1,0,1]
	v_pk_fma_f32 v[52:53], v[52:53], 0.5, v[84:85] op_sel_hi:[1,0,1]
	global_store_dwordx2 v[62:63], v[60:61], off
	v_add_f32_e32 v60, v94, v56
	global_store_dwordx4 v[92:93], v[52:55], off offset:512 nt
	v_cvt_pk_f16_f32 v56, v52, v53
	s_waitcnt vmcnt(17)
	v_pk_fma_f32 v[50:51], v[50:51], 0.5, v[82:83] op_sel_hi:[1,0,1]
	v_mul_f32_e32 v53, v53, v53
	v_fmac_f32_e32 v53, v52, v52
	v_mul_f32_e32 v52, v55, v55
	v_fmac_f32_e32 v52, v54, v54
	v_pk_fma_f32 v[48:49], v[48:49], 0.5, v[80:81] op_sel_hi:[1,0,1]
	v_cvt_pk_f16_f32 v57, v54, v55
	v_add_f32_e32 v52, v53, v52
	v_mul_f32_e32 v53, v49, v49
	v_mul_f32_e32 v54, v51, v51
	v_fmac_f32_e32 v53, v48, v48
	v_fmac_f32_e32 v54, v50, v50
	v_add_f32_e32 v52, v60, v52
	v_add_f32_e32 v53, v53, v54
	v_add_f32_e32 v54, v52, v53
	ds_bpermute_b32 v55, v163, v54
	v_or_b32_e32 v58, 0x100, v98
	v_mov_b32_e32 v59, v99
	v_lshl_add_u64 v[52:53], s[2:3], 0, v[58:59]
	global_store_dwordx2 v[52:53], v[56:57], off
	global_store_dwordx4 v[92:93], v[48:51], off offset:576 nt
	v_cvt_pk_f16_f32 v52, v48, v49
	v_or_b32_e32 v98, 0x120, v98
	s_waitcnt lgkmcnt(0)
	v_add_f32_e32 v48, v54, v55
	ds_bpermute_b32 v49, v162, v48
	v_cvt_pk_f16_f32 v53, v50, v51
	v_lshl_add_u64 v[50:51], s[2:3], 0, v[98:99]
	v_readlane_b32 s53, v248, 49
	v_readlane_b32 s54, v248, 50
	v_readlane_b32 s55, v248, 51
	v_readlane_b32 s56, v248, 52
	v_readlane_b32 s57, v248, 53
	v_readlane_b32 s58, v248, 54
	v_readlane_b32 s59, v248, 55
	v_readlane_b32 s60, v248, 56
	v_readlane_b32 s61, v248, 57
	v_readlane_b32 s62, v248, 58
	v_readlane_b32 s63, v248, 59
	v_readlane_b32 s64, v248, 60
	v_readlane_b32 s65, v248, 61
	global_store_dwordx2 v[50:51], v[52:53], off
	s_and_saveexec_b64 s[2:3], s[6:7]
	s_cbranch_execz .LBB0_349
	s_waitcnt lgkmcnt(0)
	v_add_f32_e32 v50, v48, v49
	v_lshlrev_b64 v[48:49], 6, v[112:113]
	v_lshl_add_u64 v[48:49], s[46:47], 0, v[48:49]
	v_lshl_add_u64 v[48:49], s[16:17], 2, v[48:49]
	s_lshl_b32 s92, s40, 2
	v_lshl_add_u64 v[48:49], v[48:49], 0, s[92:93]
	v_readlane_b32 s73, v250, 34
	global_store_dword v[48:49], v50, off
.LBB0_349:
	s_or_b64 exec, exec, s[2:3]
	v_or_b32_e32 v80, 32, v112
	v_ashrrev_i32_e32 v81, 31, v80
	s_waitcnt lgkmcnt(0)
	v_lshlrev_b64 v[48:49], 12, v[80:81]
	v_lshl_add_u64 v[48:49], v[178:179], 0, v[48:49]
	global_load_dwordx4 v[60:63], v[48:49], off
	global_load_dwordx4 v[56:59], v[48:49], off offset:64
	global_load_dwordx4 v[52:55], v[48:49], off offset:512
	s_nop 0
	global_load_dwordx4 v[48:51], v[48:49], off offset:576
	v_lshlrev_b64 v[82:83], 10, v[96:97]
	v_readlane_b32 s52, v248, 48
	v_lshl_add_u64 v[82:83], v[82:83], 0, v[176:177]
	v_readlane_b32 s66, v248, 62
	v_readlane_b32 s67, v248, 63
	s_waitcnt vmcnt(15)
	v_pk_fma_f32 v[46:47], v[46:47], 0.5, v[78:79] op_sel_hi:[1,0,1]
	v_pk_fma_f32 v[44:45], v[44:45], 0.5, v[76:77] op_sel_hi:[1,0,1]
	v_lshl_add_u64 v[76:77], v[82:83], 2, s[66:67]
	global_store_dwordx4 v[76:77], v[44:47], off nt
	v_cvt_pk_f16_f32 v78, v44, v45
	v_readlane_b32 s2, v253, 24
	v_mul_f32_e32 v45, v45, v45
	v_lshlrev_b64 v[82:83], 1, v[82:83]
	v_readlane_b32 s3, v253, 25
	v_fmac_f32_e32 v45, v44, v44
	v_mul_f32_e32 v44, v47, v47
	v_cvt_pk_f16_f32 v79, v46, v47
	v_lshl_add_u64 v[84:85], s[2:3], 0, v[82:83]
	v_fmac_f32_e32 v44, v46, v46
	s_waitcnt vmcnt(15)
	v_pk_fma_f32 v[42:43], v[42:43], 0.5, v[74:75] op_sel_hi:[1,0,1]
	v_pk_fma_f32 v[40:41], v[40:41], 0.5, v[72:73] op_sel_hi:[1,0,1]
	global_store_dwordx2 v[84:85], v[78:79], off
	v_add_f32_e32 v78, v45, v44
	global_store_dwordx4 v[76:77], v[40:43], off offset:64 nt
	v_cvt_pk_f16_f32 v44, v40, v41
	v_or_b32_e32 v46, 32, v82
	v_mul_f32_e32 v41, v41, v41
	v_fmac_f32_e32 v41, v40, v40
	v_mul_f32_e32 v40, v43, v43
	v_mov_b32_e32 v47, v83
	v_fmac_f32_e32 v40, v42, v42
	v_cvt_pk_f16_f32 v45, v42, v43
	v_lshl_add_u64 v[46:47], s[2:3], 0, v[46:47]
	v_add_f32_e32 v40, v41, v40
	s_waitcnt vmcnt(16)
	v_pk_fma_f32 v[38:39], v[38:39], 0.5, v[70:71] op_sel_hi:[1,0,1]
	v_pk_fma_f32 v[36:37], v[36:37], 0.5, v[68:69] op_sel_hi:[1,0,1]
	global_store_dwordx2 v[46:47], v[44:45], off
	v_add_f32_e32 v44, v78, v40
	global_store_dwordx4 v[76:77], v[36:39], off offset:512 nt
	v_cvt_pk_f16_f32 v40, v36, v37
	s_waitcnt vmcnt(17)
	v_pk_fma_f32 v[34:35], v[34:35], 0.5, v[66:67] op_sel_hi:[1,0,1]
	v_mul_f32_e32 v37, v37, v37
	v_fmac_f32_e32 v37, v36, v36
	v_mul_f32_e32 v36, v39, v39
	v_fmac_f32_e32 v36, v38, v38
	v_pk_fma_f32 v[32:33], v[32:33], 0.5, v[64:65] op_sel_hi:[1,0,1]
	v_cvt_pk_f16_f32 v41, v38, v39
	v_add_f32_e32 v36, v37, v36
	v_mul_f32_e32 v37, v33, v33
	v_mul_f32_e32 v38, v35, v35
	v_fmac_f32_e32 v37, v32, v32
	v_fmac_f32_e32 v38, v34, v34
	v_add_f32_e32 v36, v44, v36
	v_add_f32_e32 v37, v37, v38
	v_add_f32_e32 v38, v36, v37
	ds_bpermute_b32 v39, v163, v38
	v_or_b32_e32 v42, 0x100, v82
	v_mov_b32_e32 v43, v83
	v_lshl_add_u64 v[36:37], s[2:3], 0, v[42:43]
	global_store_dwordx2 v[36:37], v[40:41], off
	global_store_dwordx4 v[76:77], v[32:35], off offset:576 nt
	v_cvt_pk_f16_f32 v36, v32, v33
	v_or_b32_e32 v82, 0x120, v82
	s_waitcnt lgkmcnt(0)
	v_add_f32_e32 v32, v38, v39
	ds_bpermute_b32 v33, v162, v32
	v_cvt_pk_f16_f32 v37, v34, v35
	v_lshl_add_u64 v[34:35], s[2:3], 0, v[82:83]
	v_readlane_b32 s53, v248, 49
	v_readlane_b32 s54, v248, 50
	v_readlane_b32 s55, v248, 51
	v_readlane_b32 s56, v248, 52
	v_readlane_b32 s57, v248, 53
	v_readlane_b32 s58, v248, 54
	v_readlane_b32 s59, v248, 55
	v_readlane_b32 s60, v248, 56
	v_readlane_b32 s61, v248, 57
	v_readlane_b32 s62, v248, 58
	v_readlane_b32 s63, v248, 59
	v_readlane_b32 s64, v248, 60
	v_readlane_b32 s65, v248, 61
	global_store_dwordx2 v[34:35], v[36:37], off
	s_and_saveexec_b64 s[2:3], s[6:7]
	s_cbranch_execz .LBB0_351
	s_waitcnt lgkmcnt(0)
	v_add_f32_e32 v34, v32, v33
	v_lshlrev_b64 v[32:33], 6, v[96:97]
	v_lshl_add_u64 v[32:33], s[46:47], 0, v[32:33]
	v_lshl_add_u64 v[32:33], s[16:17], 2, v[32:33]
	s_lshl_b32 s92, s40, 2
	v_lshl_add_u64 v[32:33], v[32:33], 0, s[92:93]
	v_readlane_b32 s73, v250, 34
	global_store_dword v[32:33], v34, off
.LBB0_351:
	s_or_b64 exec, exec, s[2:3]
	v_or_b32_e32 v64, 48, v112
	v_ashrrev_i32_e32 v65, 31, v64
	s_waitcnt lgkmcnt(0)
	v_lshlrev_b64 v[32:33], 12, v[64:65]
	v_lshl_add_u64 v[32:33], v[178:179], 0, v[32:33]
	global_load_dwordx4 v[44:47], v[32:33], off
	global_load_dwordx4 v[40:43], v[32:33], off offset:64
	global_load_dwordx4 v[36:39], v[32:33], off offset:512
	s_nop 0
	global_load_dwordx4 v[32:35], v[32:33], off offset:576
	v_lshlrev_b64 v[66:67], 10, v[80:81]
	v_readlane_b32 s52, v248, 48
	v_lshl_add_u64 v[66:67], v[66:67], 0, v[176:177]
	v_readlane_b32 s66, v248, 62
	v_readlane_b32 s67, v248, 63
	s_waitcnt vmcnt(15)
	v_pk_fma_f32 v[30:31], v[30:31], 0.5, v[62:63] op_sel_hi:[1,0,1]
	v_pk_fma_f32 v[28:29], v[28:29], 0.5, v[60:61] op_sel_hi:[1,0,1]
	v_lshl_add_u64 v[60:61], v[66:67], 2, s[66:67]
	global_store_dwordx4 v[60:61], v[28:31], off nt
	v_cvt_pk_f16_f32 v62, v28, v29
	v_readlane_b32 s2, v253, 24
	v_mul_f32_e32 v29, v29, v29
	v_lshlrev_b64 v[66:67], 1, v[66:67]
	v_readlane_b32 s3, v253, 25
	v_fmac_f32_e32 v29, v28, v28
	v_mul_f32_e32 v28, v31, v31
	v_cvt_pk_f16_f32 v63, v30, v31
	v_lshl_add_u64 v[68:69], s[2:3], 0, v[66:67]
	v_fmac_f32_e32 v28, v30, v30
	s_waitcnt vmcnt(15)
	v_pk_fma_f32 v[26:27], v[26:27], 0.5, v[58:59] op_sel_hi:[1,0,1]
	v_pk_fma_f32 v[24:25], v[24:25], 0.5, v[56:57] op_sel_hi:[1,0,1]
	global_store_dwordx2 v[68:69], v[62:63], off
	v_add_f32_e32 v62, v29, v28
	global_store_dwordx4 v[60:61], v[24:27], off offset:64 nt
	v_cvt_pk_f16_f32 v28, v24, v25
	v_or_b32_e32 v30, 32, v66
	v_mul_f32_e32 v25, v25, v25
	v_fmac_f32_e32 v25, v24, v24
	v_mul_f32_e32 v24, v27, v27
	v_mov_b32_e32 v31, v67
	v_fmac_f32_e32 v24, v26, v26
	v_cvt_pk_f16_f32 v29, v26, v27
	v_lshl_add_u64 v[30:31], s[2:3], 0, v[30:31]
	v_add_f32_e32 v24, v25, v24
	s_waitcnt vmcnt(16)
	v_pk_fma_f32 v[22:23], v[22:23], 0.5, v[54:55] op_sel_hi:[1,0,1]
	v_pk_fma_f32 v[20:21], v[20:21], 0.5, v[52:53] op_sel_hi:[1,0,1]
	global_store_dwordx2 v[30:31], v[28:29], off
	v_add_f32_e32 v28, v62, v24
	global_store_dwordx4 v[60:61], v[20:23], off offset:512 nt
	v_cvt_pk_f16_f32 v24, v20, v21
	s_waitcnt vmcnt(17)
	v_pk_fma_f32 v[18:19], v[18:19], 0.5, v[50:51] op_sel_hi:[1,0,1]
	v_mul_f32_e32 v21, v21, v21
	v_fmac_f32_e32 v21, v20, v20
	v_mul_f32_e32 v20, v23, v23
	v_fmac_f32_e32 v20, v22, v22
	v_pk_fma_f32 v[16:17], v[16:17], 0.5, v[48:49] op_sel_hi:[1,0,1]
	v_cvt_pk_f16_f32 v25, v22, v23
	v_add_f32_e32 v20, v21, v20
	v_mul_f32_e32 v21, v17, v17
	v_mul_f32_e32 v22, v19, v19
	v_fmac_f32_e32 v21, v16, v16
	v_fmac_f32_e32 v22, v18, v18
	v_add_f32_e32 v20, v28, v20
	v_add_f32_e32 v21, v21, v22
	v_add_f32_e32 v22, v20, v21
	ds_bpermute_b32 v23, v163, v22
	v_or_b32_e32 v26, 0x100, v66
	v_mov_b32_e32 v27, v67
	v_lshl_add_u64 v[20:21], s[2:3], 0, v[26:27]
	global_store_dwordx2 v[20:21], v[24:25], off
	global_store_dwordx4 v[60:61], v[16:19], off offset:576 nt
	v_cvt_pk_f16_f32 v20, v16, v17
	v_or_b32_e32 v66, 0x120, v66
	s_waitcnt lgkmcnt(0)
	v_add_f32_e32 v16, v22, v23
	ds_bpermute_b32 v17, v162, v16
	v_cvt_pk_f16_f32 v21, v18, v19
	v_lshl_add_u64 v[18:19], s[2:3], 0, v[66:67]
	v_readlane_b32 s53, v248, 49
	v_readlane_b32 s54, v248, 50
	v_readlane_b32 s55, v248, 51
	v_readlane_b32 s56, v248, 52
	v_readlane_b32 s57, v248, 53
	v_readlane_b32 s58, v248, 54
	v_readlane_b32 s59, v248, 55
	v_readlane_b32 s60, v248, 56
	v_readlane_b32 s61, v248, 57
	v_readlane_b32 s62, v248, 58
	v_readlane_b32 s63, v248, 59
	v_readlane_b32 s64, v248, 60
	v_readlane_b32 s65, v248, 61
	global_store_dwordx2 v[18:19], v[20:21], off
	s_and_saveexec_b64 s[2:3], s[6:7]
	s_cbranch_execz .LBB0_353
	s_waitcnt lgkmcnt(0)
	v_add_f32_e32 v18, v16, v17
	v_lshlrev_b64 v[16:17], 6, v[80:81]
	v_lshl_add_u64 v[16:17], s[46:47], 0, v[16:17]
	v_lshl_add_u64 v[16:17], s[16:17], 2, v[16:17]
	s_lshl_b32 s92, s40, 2
	v_lshl_add_u64 v[16:17], v[16:17], 0, s[92:93]
	v_readlane_b32 s73, v250, 34
	global_store_dword v[16:17], v18, off
.LBB0_353:
	s_or_b64 exec, exec, s[2:3]
	s_waitcnt lgkmcnt(0)
	v_lshlrev_b64 v[16:17], 10, v[64:65]
	v_readlane_b32 s52, v248, 48
	v_lshl_add_u64 v[16:17], v[16:17], 0, v[176:177]
	v_readlane_b32 s66, v248, 62
	v_readlane_b32 s67, v248, 63
	s_waitcnt vmcnt(11)
	v_pk_fma_f32 v[14:15], v[14:15], 0.5, v[46:47] op_sel_hi:[1,0,1]
	v_pk_fma_f32 v[12:13], v[12:13], 0.5, v[44:45] op_sel_hi:[1,0,1]
	v_lshl_add_u64 v[18:19], v[16:17], 2, s[66:67]
	global_store_dwordx4 v[18:19], v[12:15], off nt
	v_cvt_pk_f16_f32 v20, v12, v13
	v_readlane_b32 s2, v253, 24
	v_mul_f32_e32 v13, v13, v13
	v_lshlrev_b64 v[16:17], 1, v[16:17]
	v_readlane_b32 s3, v253, 25
	v_fmac_f32_e32 v13, v12, v12
	v_mul_f32_e32 v12, v15, v15
	v_cvt_pk_f16_f32 v21, v14, v15
	v_lshl_add_u64 v[22:23], s[2:3], 0, v[16:17]
	v_fmac_f32_e32 v12, v14, v14
	s_waitcnt vmcnt(11)
	v_pk_fma_f32 v[10:11], v[10:11], 0.5, v[42:43] op_sel_hi:[1,0,1]
	v_pk_fma_f32 v[8:9], v[8:9], 0.5, v[40:41] op_sel_hi:[1,0,1]
	global_store_dwordx2 v[22:23], v[20:21], off
	v_add_f32_e32 v20, v13, v12
	global_store_dwordx4 v[18:19], v[8:11], off offset:64 nt
	v_cvt_pk_f16_f32 v12, v8, v9
	v_or_b32_e32 v14, 32, v16
	v_mul_f32_e32 v9, v9, v9
	v_fmac_f32_e32 v9, v8, v8
	v_mul_f32_e32 v8, v11, v11
	v_mov_b32_e32 v15, v17
	v_fmac_f32_e32 v8, v10, v10
	v_cvt_pk_f16_f32 v13, v10, v11
	v_lshl_add_u64 v[14:15], s[2:3], 0, v[14:15]
	v_add_f32_e32 v8, v9, v8
	s_waitcnt vmcnt(12)
	v_pk_fma_f32 v[6:7], v[6:7], 0.5, v[38:39] op_sel_hi:[1,0,1]
	v_pk_fma_f32 v[4:5], v[4:5], 0.5, v[36:37] op_sel_hi:[1,0,1]
	global_store_dwordx2 v[14:15], v[12:13], off
	v_add_f32_e32 v12, v20, v8
	global_store_dwordx4 v[18:19], v[4:7], off offset:512 nt
	v_cvt_pk_f16_f32 v8, v4, v5
	s_waitcnt vmcnt(13)
	v_pk_fma_f32 v[2:3], v[2:3], 0.5, v[34:35] op_sel_hi:[1,0,1]
	v_mul_f32_e32 v5, v5, v5
	v_fmac_f32_e32 v5, v4, v4
	v_mul_f32_e32 v4, v7, v7
	v_fmac_f32_e32 v4, v6, v6
	v_pk_fma_f32 v[0:1], v[0:1], 0.5, v[32:33] op_sel_hi:[1,0,1]
	v_cvt_pk_f16_f32 v9, v6, v7
	v_add_f32_e32 v4, v5, v4
	v_mul_f32_e32 v5, v1, v1
	v_mul_f32_e32 v6, v3, v3
	v_fmac_f32_e32 v5, v0, v0
	v_fmac_f32_e32 v6, v2, v2
	v_add_f32_e32 v4, v12, v4
	v_add_f32_e32 v5, v5, v6
	v_add_f32_e32 v6, v4, v5
	ds_bpermute_b32 v7, v163, v6
	v_or_b32_e32 v10, 0x100, v16
	v_mov_b32_e32 v11, v17
	v_lshl_add_u64 v[4:5], s[2:3], 0, v[10:11]
	global_store_dwordx2 v[4:5], v[8:9], off
	global_store_dwordx4 v[18:19], v[0:3], off offset:576 nt
	v_cvt_pk_f16_f32 v4, v0, v1
	v_or_b32_e32 v16, 0x120, v16
	s_waitcnt lgkmcnt(0)
	v_add_f32_e32 v0, v6, v7
	ds_bpermute_b32 v1, v162, v0
	v_cvt_pk_f16_f32 v5, v2, v3
	v_lshl_add_u64 v[2:3], s[2:3], 0, v[16:17]
	v_readlane_b32 s53, v248, 49
	v_readlane_b32 s54, v248, 50
	v_readlane_b32 s55, v248, 51
	v_readlane_b32 s56, v248, 52
	v_readlane_b32 s57, v248, 53
	v_readlane_b32 s58, v248, 54
	v_readlane_b32 s59, v248, 55
	v_readlane_b32 s60, v248, 56
	v_readlane_b32 s61, v248, 57
	v_readlane_b32 s62, v248, 58
	v_readlane_b32 s63, v248, 59
	v_readlane_b32 s64, v248, 60
	v_readlane_b32 s65, v248, 61
	global_store_dwordx2 v[2:3], v[4:5], off
	s_and_saveexec_b64 s[2:3], s[6:7]
	s_cbranch_execz .LBB0_355
	s_waitcnt lgkmcnt(0)
	v_add_f32_e32 v2, v0, v1
	v_lshlrev_b64 v[0:1], 6, v[64:65]
	v_lshl_add_u64 v[0:1], s[46:47], 0, v[0:1]
	v_lshl_add_u64 v[0:1], s[16:17], 2, v[0:1]
	s_lshl_b32 s92, s40, 2
	v_lshl_add_u64 v[0:1], v[0:1], 0, s[92:93]
	v_readlane_b32 s73, v250, 34
	global_store_dword v[0:1], v2, off

.LBB0_582:
	v_lshl_add_u32 v180, s41, 8, v188
	v_lshl_or_b32 v176, s40, 8, v190
	v_ashrrev_i32_e32 v181, 31, v180
	v_readlane_b32 s52, v248, 48
	v_lshlrev_b64 v[128:129], 12, v[180:181]
	v_readlane_b32 s66, v248, 62
	v_readlane_b32 s67, v248, 63
	v_ashrrev_i32_e32 v177, 31, v176
	v_lshlrev_b64 v[130:131], 2, v[176:177]
	v_lshl_add_u64 v[128:129], s[66:67], 0, v[128:129]
	v_lshl_add_u64 v[186:187], v[128:129], 0, v[130:131]
	global_load_dwordx4 v[154:157], v[186:187], off
	global_load_dwordx4 v[164:167], v[186:187], off offset:64
	global_load_dwordx4 v[148:151], v[186:187], off offset:512
	global_load_dwordx4 v[144:147], v[186:187], off offset:576
	v_and_b32_e32 v129, 64, v203
	v_xor_b32_e32 v128, 16, v203
	v_add_u32_e32 v129, 64, v129
	v_cmp_lt_i32_e32 vcc, v128, v129
	v_or_b32_e32 v182, 16, v180
	v_ashrrev_i32_e32 v183, 31, v182
	v_cndmask_b32_e32 v128, v203, v128, vcc
	v_lshlrev_b32_e32 v163, 2, v128
	v_xor_b32_e32 v128, 32, v203
	v_cmp_lt_i32_e32 vcc, v128, v129
	v_lshl_add_u64 v[178:179], s[66:67], 0, v[130:131]
	v_readlane_b32 s2, v253, 24
	v_cndmask_b32_e32 v128, v203, v128, vcc
	v_lshlrev_b32_e32 v162, 2, v128
	v_lshlrev_b64 v[128:129], 10, v[180:181]
	v_lshl_add_u64 v[192:193], v[128:129], 0, v[176:177]
	v_lshlrev_b64 v[128:129], 12, v[182:183]
	v_lshl_add_u64 v[184:185], v[178:179], 0, v[128:129]
	global_load_dwordx4 v[140:143], v[184:185], off
	global_load_dwordx4 v[136:139], v[184:185], off offset:64
	global_load_dwordx4 v[132:135], v[184:185], off offset:512
	global_load_dwordx4 v[128:131], v[184:185], off offset:576
	v_readlane_b32 s3, v253, 25
	s_lshl_b32 s20, s40, 2
	s_ashr_i32 s21, s20, 31
	v_readlane_b32 s53, v248, 49
	v_readlane_b32 s54, v248, 50
	v_readlane_b32 s55, v248, 51
	v_readlane_b32 s56, v248, 52
	v_readlane_b32 s57, v248, 53
	v_readlane_b32 s58, v248, 54
	v_readlane_b32 s59, v248, 55
	v_readlane_b32 s60, v248, 56
	v_readlane_b32 s61, v248, 57
	v_readlane_b32 s62, v248, 58
	v_readlane_b32 s63, v248, 59
	v_readlane_b32 s64, v248, 60
	v_readlane_b32 s65, v248, 61
	s_waitcnt vmcnt(0)
	v_pk_add_f32 v[126:127], v[126:127], v[156:157]
	v_pk_add_f32 v[124:125], v[124:125], v[154:155]
	global_store_dwordx4 v[186:187], v[124:127], off nt
	v_cvt_pk_f16_f32 v154, v124, v125
	v_lshlrev_b64 v[156:157], 1, v[192:193]
	v_mul_f32_e32 v125, v125, v125
	v_fmac_f32_e32 v125, v124, v124
	v_mul_f32_e32 v124, v127, v127
	v_cvt_pk_f16_f32 v155, v126, v127
	v_lshl_add_u64 v[192:193], s[2:3], 0, v[156:157]
	v_fmac_f32_e32 v124, v126, v126
	v_pk_add_f32 v[122:123], v[122:123], v[166:167]
	v_pk_add_f32 v[120:121], v[120:121], v[164:165]
	global_store_dwordx2 v[192:193], v[154:155], off
	v_add_f32_e32 v154, v125, v124
	global_store_dwordx4 v[186:187], v[120:123], off offset:64 nt
	v_cvt_pk_f16_f32 v124, v120, v121
	v_or_b32_e32 v126, 32, v156
	v_mul_f32_e32 v121, v121, v121
	v_fmac_f32_e32 v121, v120, v120
	v_mul_f32_e32 v120, v123, v123
	v_mov_b32_e32 v127, v157
	v_fmac_f32_e32 v120, v122, v122
	v_cvt_pk_f16_f32 v125, v122, v123
	v_lshl_add_u64 v[126:127], s[2:3], 0, v[126:127]
	v_add_f32_e32 v120, v121, v120
	v_pk_add_f32 v[118:119], v[118:119], v[150:151]
	v_pk_add_f32 v[116:117], v[116:117], v[148:149]
	global_store_dwordx2 v[126:127], v[124:125], off
	v_add_f32_e32 v124, v154, v120
	global_store_dwordx4 v[186:187], v[116:119], off offset:512 nt
	v_cvt_pk_f16_f32 v120, v116, v117
	v_or_b32_e32 v122, 0x100, v156
	v_mul_f32_e32 v117, v117, v117
	v_fmac_f32_e32 v117, v116, v116
	v_mul_f32_e32 v116, v119, v119
	v_mov_b32_e32 v123, v157
	v_fmac_f32_e32 v116, v118, v118
	v_cvt_pk_f16_f32 v121, v118, v119
	v_lshl_add_u64 v[122:123], s[2:3], 0, v[122:123]
	v_add_f32_e32 v116, v117, v116
	v_pk_add_f32 v[114:115], v[114:115], v[146:147]
	v_pk_add_f32 v[112:113], v[112:113], v[144:145]
	global_store_dwordx2 v[122:123], v[120:121], off
	v_add_f32_e32 v120, v124, v116
	global_store_dwordx4 v[186:187], v[112:115], off offset:576 nt
	v_cvt_pk_f16_f32 v116, v112, v113
	v_or_b32_e32 v156, 0x120, v156
	v_mul_f32_e32 v113, v113, v113
	v_fmac_f32_e32 v113, v112, v112
	v_mul_f32_e32 v112, v115, v115
	v_fmac_f32_e32 v112, v114, v114
	v_add_f32_e32 v112, v113, v112
	v_add_f32_e32 v112, v120, v112
	ds_bpermute_b32 v113, v163, v112
	v_cvt_pk_f16_f32 v117, v114, v115
	v_lshl_add_u64 v[118:119], s[2:3], 0, v[156:157]
	global_store_dwordx2 v[118:119], v[116:117], off
	s_waitcnt lgkmcnt(0)
	v_add_f32_e32 v112, v112, v113
	ds_bpermute_b32 v113, v162, v112
	s_and_saveexec_b64 s[2:3], s[6:7]
	v_readlane_b32 s46, v254, 16
	v_readlane_b32 s42, v254, 18
	v_readlane_b32 s47, v254, 17
	v_readlane_b32 s43, v254, 19
	s_cbranch_execz .LBB0_584
	s_waitcnt lgkmcnt(0)
	v_add_f32_e32 v114, v112, v113
	v_lshlrev_b64 v[112:113], 6, v[180:181]
	v_lshl_add_u64 v[112:113], s[46:47], 0, v[112:113]
	v_lshl_add_u64 v[112:113], s[20:21], 2, v[112:113]
	s_lshl_b32 s92, s38, 2
	v_lshl_add_u64 v[112:113], v[112:113], 0, s[92:93]
	global_store_dword v[112:113], v114, off
.LBB0_584:
	s_or_b64 exec, exec, s[2:3]
	v_or_b32_e32 v144, 32, v180
	v_ashrrev_i32_e32 v145, 31, v144
	s_waitcnt lgkmcnt(0)
	v_lshlrev_b64 v[112:113], 12, v[144:145]
	v_lshl_add_u64 v[146:147], v[178:179], 0, v[112:113]
	global_load_dwordx4 v[124:127], v[146:147], off
	global_load_dwordx4 v[120:123], v[146:147], off offset:64
	global_load_dwordx4 v[116:119], v[146:147], off offset:512
	global_load_dwordx4 v[112:115], v[146:147], off offset:576
	v_lshlrev_b64 v[148:149], 10, v[182:183]
	v_pk_add_f32 v[110:111], v[110:111], v[142:143]
	v_pk_add_f32 v[108:109], v[108:109], v[140:141]
	v_lshl_add_u64 v[148:149], v[148:149], 0, v[176:177]
	global_store_dwordx4 v[184:185], v[108:111], off nt
	v_cvt_pk_f16_f32 v140, v108, v109
	v_readlane_b32 s2, v253, 24
	v_mul_f32_e32 v109, v109, v109
	v_lshlrev_b64 v[142:143], 1, v[148:149]
	v_readlane_b32 s3, v253, 25
	v_fmac_f32_e32 v109, v108, v108
	v_mul_f32_e32 v108, v111, v111
	v_cvt_pk_f16_f32 v141, v110, v111
	v_lshl_add_u64 v[148:149], s[2:3], 0, v[142:143]
	v_fmac_f32_e32 v108, v110, v110
	v_pk_add_f32 v[106:107], v[106:107], v[138:139]
	v_pk_add_f32 v[104:105], v[104:105], v[136:137]
	global_store_dwordx2 v[148:149], v[140:141], off
	v_add_f32_e32 v140, v109, v108
	global_store_dwordx4 v[184:185], v[104:107], off offset:64 nt
	v_cvt_pk_f16_f32 v108, v104, v105
	v_or_b32_e32 v110, 32, v142
	v_mul_f32_e32 v105, v105, v105
	v_fmac_f32_e32 v105, v104, v104
	v_mul_f32_e32 v104, v107, v107
	v_mov_b32_e32 v111, v143
	v_fmac_f32_e32 v104, v106, v106
	v_cvt_pk_f16_f32 v109, v106, v107
	v_lshl_add_u64 v[110:111], s[2:3], 0, v[110:111]
	v_add_f32_e32 v104, v105, v104
	v_pk_add_f32 v[102:103], v[102:103], v[134:135]
	v_pk_add_f32 v[100:101], v[100:101], v[132:133]
	global_store_dwordx2 v[110:111], v[108:109], off
	v_add_f32_e32 v108, v140, v104
	global_store_dwordx4 v[184:185], v[100:103], off offset:512 nt
	v_cvt_pk_f16_f32 v104, v100, v101
	v_pk_add_f32 v[98:99], v[98:99], v[130:131]
	v_mul_f32_e32 v101, v101, v101
	v_fmac_f32_e32 v101, v100, v100
	v_mul_f32_e32 v100, v103, v103
	v_fmac_f32_e32 v100, v102, v102
	v_pk_add_f32 v[96:97], v[96:97], v[128:129]
	v_cvt_pk_f16_f32 v105, v102, v103
	v_add_f32_e32 v100, v101, v100
	v_mul_f32_e32 v101, v97, v97
	v_mul_f32_e32 v102, v99, v99
	v_fmac_f32_e32 v101, v96, v96
	v_fmac_f32_e32 v102, v98, v98
	v_add_f32_e32 v100, v108, v100
	v_add_f32_e32 v101, v101, v102
	v_add_f32_e32 v102, v100, v101
	ds_bpermute_b32 v103, v163, v102
	v_or_b32_e32 v106, 0x100, v142
	v_mov_b32_e32 v107, v143
	v_lshl_add_u64 v[100:101], s[2:3], 0, v[106:107]
	global_store_dwordx2 v[100:101], v[104:105], off
	global_store_dwordx4 v[184:185], v[96:99], off offset:576 nt
	v_cvt_pk_f16_f32 v100, v96, v97
	v_or_b32_e32 v142, 0x120, v142
	s_waitcnt lgkmcnt(0)
	v_add_f32_e32 v96, v102, v103
	ds_bpermute_b32 v97, v162, v96
	v_cvt_pk_f16_f32 v101, v98, v99
	v_lshl_add_u64 v[98:99], s[2:3], 0, v[142:143]
	global_store_dwordx2 v[98:99], v[100:101], off
	s_and_saveexec_b64 s[2:3], s[6:7]
	s_cbranch_execz .LBB0_586
	s_waitcnt lgkmcnt(0)
	v_add_f32_e32 v98, v96, v97
	v_lshlrev_b64 v[96:97], 6, v[182:183]
	v_lshl_add_u64 v[96:97], s[46:47], 0, v[96:97]
	v_lshl_add_u64 v[96:97], s[20:21], 2, v[96:97]
	s_lshl_b32 s92, s38, 2
	v_lshl_add_u64 v[96:97], v[96:97], 0, s[92:93]
	global_store_dword v[96:97], v98, off
.LBB0_586:
	s_or_b64 exec, exec, s[2:3]
	v_or_b32_e32 v128, 48, v180
	v_ashrrev_i32_e32 v129, 31, v128
	s_waitcnt lgkmcnt(0)
	v_lshlrev_b64 v[96:97], 12, v[128:129]
	v_lshl_add_u64 v[130:131], v[178:179], 0, v[96:97]
	global_load_dwordx4 v[108:111], v[130:131], off
	global_load_dwordx4 v[104:107], v[130:131], off offset:64
	global_load_dwordx4 v[100:103], v[130:131], off offset:512
	global_load_dwordx4 v[96:99], v[130:131], off offset:576
	v_lshlrev_b64 v[132:133], 10, v[144:145]
	s_waitcnt vmcnt(15)
	v_pk_add_f32 v[94:95], v[94:95], v[126:127]
	v_pk_add_f32 v[92:93], v[92:93], v[124:125]
	v_lshl_add_u64 v[132:133], v[132:133], 0, v[176:177]
	global_store_dwordx4 v[146:147], v[92:95], off nt
	v_cvt_pk_f16_f32 v124, v92, v93
	v_readlane_b32 s2, v253, 24
	v_mul_f32_e32 v93, v93, v93
	v_lshlrev_b64 v[126:127], 1, v[132:133]
	v_readlane_b32 s3, v253, 25
	v_fmac_f32_e32 v93, v92, v92
	v_mul_f32_e32 v92, v95, v95
	v_cvt_pk_f16_f32 v125, v94, v95
	v_lshl_add_u64 v[132:133], s[2:3], 0, v[126:127]
	v_fmac_f32_e32 v92, v94, v94
	s_waitcnt vmcnt(15)
	v_pk_add_f32 v[90:91], v[90:91], v[122:123]
	v_pk_add_f32 v[88:89], v[88:89], v[120:121]
	global_store_dwordx2 v[132:133], v[124:125], off
	v_add_f32_e32 v124, v93, v92
	global_store_dwordx4 v[146:147], v[88:91], off offset:64 nt
	v_cvt_pk_f16_f32 v92, v88, v89
	v_or_b32_e32 v94, 32, v126
	v_mul_f32_e32 v89, v89, v89
	v_fmac_f32_e32 v89, v88, v88
	v_mul_f32_e32 v88, v91, v91
	v_mov_b32_e32 v95, v127
	v_fmac_f32_e32 v88, v90, v90
	v_cvt_pk_f16_f32 v93, v90, v91
	v_lshl_add_u64 v[94:95], s[2:3], 0, v[94:95]
	v_add_f32_e32 v88, v89, v88
	s_waitcnt vmcnt(16)
	v_pk_add_f32 v[86:87], v[86:87], v[118:119]
	v_pk_add_f32 v[84:85], v[84:85], v[116:117]
	global_store_dwordx2 v[94:95], v[92:93], off
	v_add_f32_e32 v92, v124, v88
	global_store_dwordx4 v[146:147], v[84:87], off offset:512 nt
	v_cvt_pk_f16_f32 v88, v84, v85
	s_waitcnt vmcnt(17)
	v_pk_add_f32 v[82:83], v[82:83], v[114:115]
	v_mul_f32_e32 v85, v85, v85
	v_fmac_f32_e32 v85, v84, v84
	v_mul_f32_e32 v84, v87, v87
	v_fmac_f32_e32 v84, v86, v86
	v_pk_add_f32 v[80:81], v[80:81], v[112:113]
	v_cvt_pk_f16_f32 v89, v86, v87
	v_add_f32_e32 v84, v85, v84
	v_mul_f32_e32 v85, v81, v81
	v_mul_f32_e32 v86, v83, v83
	v_fmac_f32_e32 v85, v80, v80
	v_fmac_f32_e32 v86, v82, v82
	v_add_f32_e32 v84, v92, v84
	v_add_f32_e32 v85, v85, v86
	v_add_f32_e32 v86, v84, v85
	ds_bpermute_b32 v87, v163, v86
	v_or_b32_e32 v90, 0x100, v126
	v_mov_b32_e32 v91, v127
	v_lshl_add_u64 v[84:85], s[2:3], 0, v[90:91]
	global_store_dwordx2 v[84:85], v[88:89], off
	global_store_dwordx4 v[146:147], v[80:83], off offset:576 nt
	v_cvt_pk_f16_f32 v84, v80, v81
	v_or_b32_e32 v126, 0x120, v126
	s_waitcnt lgkmcnt(0)
	v_add_f32_e32 v80, v86, v87
	ds_bpermute_b32 v81, v162, v80
	v_cvt_pk_f16_f32 v85, v82, v83
	v_lshl_add_u64 v[82:83], s[2:3], 0, v[126:127]
	global_store_dwordx2 v[82:83], v[84:85], off
	s_mov_b64 s[2:3], exec
	v_mov_b64_e32 v[154:155], v[158:159]
	s_and_b64 s[22:23], s[2:3], s[6:7]
	v_mov_b64_e32 v[156:157], v[160:161]
	s_mov_b64 exec, s[22:23]
	s_cbranch_execz .LBB0_588
	s_waitcnt lgkmcnt(0)
	v_add_f32_e32 v82, v80, v81
	v_lshlrev_b64 v[80:81], 6, v[144:145]
	v_lshl_add_u64 v[80:81], s[46:47], 0, v[80:81]
	v_lshl_add_u64 v[80:81], s[20:21], 2, v[80:81]
	s_lshl_b32 s92, s38, 2
	v_lshl_add_u64 v[80:81], v[80:81], 0, s[92:93]
	global_store_dword v[80:81], v82, off
.LBB0_588:
	s_or_b64 exec, exec, s[2:3]
	v_add_u32_e32 v112, 0x80, v180
	v_ashrrev_i32_e32 v113, 31, v112
	s_waitcnt lgkmcnt(0)
	v_lshlrev_b64 v[80:81], 12, v[112:113]
	v_lshl_add_u64 v[114:115], v[178:179], 0, v[80:81]
	global_load_dwordx4 v[92:95], v[114:115], off
	global_load_dwordx4 v[88:91], v[114:115], off offset:64
	global_load_dwordx4 v[84:87], v[114:115], off offset:512
	global_load_dwordx4 v[80:83], v[114:115], off offset:576
	v_lshlrev_b64 v[116:117], 10, v[128:129]
	s_waitcnt vmcnt(15)
	v_pk_add_f32 v[78:79], v[78:79], v[110:111]
	v_pk_add_f32 v[76:77], v[76:77], v[108:109]
	v_lshl_add_u64 v[116:117], v[116:117], 0, v[176:177]
	global_store_dwordx4 v[130:131], v[76:79], off nt
	v_cvt_pk_f16_f32 v108, v76, v77
	v_readlane_b32 s2, v253, 24
	v_mul_f32_e32 v77, v77, v77
	v_lshlrev_b64 v[110:111], 1, v[116:117]
	v_readlane_b32 s3, v253, 25
	v_fmac_f32_e32 v77, v76, v76
	v_mul_f32_e32 v76, v79, v79
	v_cvt_pk_f16_f32 v109, v78, v79
	v_lshl_add_u64 v[116:117], s[2:3], 0, v[110:111]
	v_fmac_f32_e32 v76, v78, v78
	s_waitcnt vmcnt(15)
	v_pk_add_f32 v[74:75], v[74:75], v[106:107]
	v_pk_add_f32 v[72:73], v[72:73], v[104:105]
	global_store_dwordx2 v[116:117], v[108:109], off
	v_add_f32_e32 v108, v77, v76
	global_store_dwordx4 v[130:131], v[72:75], off offset:64 nt
	v_cvt_pk_f16_f32 v76, v72, v73
	v_or_b32_e32 v78, 32, v110
	v_mul_f32_e32 v73, v73, v73
	v_fmac_f32_e32 v73, v72, v72
	v_mul_f32_e32 v72, v75, v75
	v_mov_b32_e32 v79, v111
	v_fmac_f32_e32 v72, v74, v74
	v_cvt_pk_f16_f32 v77, v74, v75
	v_lshl_add_u64 v[78:79], s[2:3], 0, v[78:79]
	v_add_f32_e32 v72, v73, v72
	s_waitcnt vmcnt(16)
	v_pk_add_f32 v[70:71], v[70:71], v[102:103]
	v_pk_add_f32 v[68:69], v[68:69], v[100:101]
	global_store_dwordx2 v[78:79], v[76:77], off
	v_add_f32_e32 v76, v108, v72
	global_store_dwordx4 v[130:131], v[68:71], off offset:512 nt
	v_cvt_pk_f16_f32 v72, v68, v69
	s_waitcnt vmcnt(17)
	v_pk_add_f32 v[66:67], v[66:67], v[98:99]
	v_mul_f32_e32 v69, v69, v69
	v_fmac_f32_e32 v69, v68, v68
	v_mul_f32_e32 v68, v71, v71
	v_fmac_f32_e32 v68, v70, v70
	v_pk_add_f32 v[64:65], v[64:65], v[96:97]
	v_cvt_pk_f16_f32 v73, v70, v71
	v_add_f32_e32 v68, v69, v68
	v_mul_f32_e32 v69, v65, v65
	v_mul_f32_e32 v70, v67, v67
	v_fmac_f32_e32 v69, v64, v64
	v_fmac_f32_e32 v70, v66, v66
	v_add_f32_e32 v68, v76, v68
	v_add_f32_e32 v69, v69, v70
	v_add_f32_e32 v70, v68, v69
	ds_bpermute_b32 v71, v163, v70
	v_or_b32_e32 v74, 0x100, v110
	v_mov_b32_e32 v75, v111
	v_lshl_add_u64 v[68:69], s[2:3], 0, v[74:75]
	global_store_dwordx2 v[68:69], v[72:73], off
	global_store_dwordx4 v[130:131], v[64:67], off offset:576 nt
	v_cvt_pk_f16_f32 v68, v64, v65
	v_or_b32_e32 v110, 0x120, v110
	s_waitcnt lgkmcnt(0)
	v_add_f32_e32 v64, v70, v71
	ds_bpermute_b32 v65, v162, v64
	v_cvt_pk_f16_f32 v69, v66, v67
	v_lshl_add_u64 v[66:67], s[2:3], 0, v[110:111]
	global_store_dwordx2 v[66:67], v[68:69], off
	s_and_saveexec_b64 s[2:3], s[6:7]
	s_cbranch_execz .LBB0_590
	s_waitcnt lgkmcnt(0)
	v_add_f32_e32 v66, v64, v65
	v_lshlrev_b64 v[64:65], 6, v[128:129]
	v_lshl_add_u64 v[64:65], s[46:47], 0, v[64:65]
	v_lshl_add_u64 v[64:65], s[20:21], 2, v[64:65]
	s_lshl_b32 s92, s38, 2
	v_lshl_add_u64 v[64:65], v[64:65], 0, s[92:93]
	global_store_dword v[64:65], v66, off
.LBB0_590:
	s_or_b64 exec, exec, s[2:3]
	v_or_b32_e32 v96, 16, v112
	v_ashrrev_i32_e32 v97, 31, v96
	s_waitcnt lgkmcnt(0)
	v_lshlrev_b64 v[64:65], 12, v[96:97]
	v_lshl_add_u64 v[98:99], v[178:179], 0, v[64:65]
	global_load_dwordx4 v[76:79], v[98:99], off
	global_load_dwordx4 v[72:75], v[98:99], off offset:64
	global_load_dwordx4 v[68:71], v[98:99], off offset:512
	global_load_dwordx4 v[64:67], v[98:99], off offset:576
	v_lshlrev_b64 v[100:101], 10, v[112:113]
	s_waitcnt vmcnt(15)
	v_pk_add_f32 v[62:63], v[62:63], v[94:95]
	v_pk_add_f32 v[60:61], v[60:61], v[92:93]
	v_lshl_add_u64 v[100:101], v[100:101], 0, v[176:177]
	global_store_dwordx4 v[114:115], v[60:63], off nt
	v_cvt_pk_f16_f32 v92, v60, v61
	v_readlane_b32 s2, v253, 24
	v_mul_f32_e32 v61, v61, v61
	v_lshlrev_b64 v[94:95], 1, v[100:101]
	v_readlane_b32 s3, v253, 25
	v_fmac_f32_e32 v61, v60, v60
	v_mul_f32_e32 v60, v63, v63
	v_cvt_pk_f16_f32 v93, v62, v63
	v_lshl_add_u64 v[100:101], s[2:3], 0, v[94:95]
	v_fmac_f32_e32 v60, v62, v62
	s_waitcnt vmcnt(15)
	v_pk_add_f32 v[58:59], v[58:59], v[90:91]
	v_pk_add_f32 v[56:57], v[56:57], v[88:89]
	global_store_dwordx2 v[100:101], v[92:93], off
	v_add_f32_e32 v92, v61, v60
	global_store_dwordx4 v[114:115], v[56:59], off offset:64 nt
	v_cvt_pk_f16_f32 v60, v56, v57
	v_or_b32_e32 v62, 32, v94
	v_mul_f32_e32 v57, v57, v57
	v_fmac_f32_e32 v57, v56, v56
	v_mul_f32_e32 v56, v59, v59
	v_mov_b32_e32 v63, v95
	v_fmac_f32_e32 v56, v58, v58
	v_cvt_pk_f16_f32 v61, v58, v59
	v_lshl_add_u64 v[62:63], s[2:3], 0, v[62:63]
	v_add_f32_e32 v56, v57, v56
	s_waitcnt vmcnt(16)
	v_pk_add_f32 v[54:55], v[54:55], v[86:87]
	v_pk_add_f32 v[52:53], v[52:53], v[84:85]
	global_store_dwordx2 v[62:63], v[60:61], off
	v_add_f32_e32 v60, v92, v56
	global_store_dwordx4 v[114:115], v[52:55], off offset:512 nt
	v_cvt_pk_f16_f32 v56, v52, v53
	s_waitcnt vmcnt(17)
	v_pk_add_f32 v[50:51], v[50:51], v[82:83]
	v_mul_f32_e32 v53, v53, v53
	v_fmac_f32_e32 v53, v52, v52
	v_mul_f32_e32 v52, v55, v55
	v_fmac_f32_e32 v52, v54, v54
	v_pk_add_f32 v[48:49], v[48:49], v[80:81]
	v_cvt_pk_f16_f32 v57, v54, v55
	v_add_f32_e32 v52, v53, v52
	v_mul_f32_e32 v53, v49, v49
	v_mul_f32_e32 v54, v51, v51
	v_fmac_f32_e32 v53, v48, v48
	v_fmac_f32_e32 v54, v50, v50
	v_add_f32_e32 v52, v60, v52
	v_add_f32_e32 v53, v53, v54
	v_add_f32_e32 v54, v52, v53
	ds_bpermute_b32 v55, v163, v54
	v_or_b32_e32 v58, 0x100, v94
	v_mov_b32_e32 v59, v95
	v_lshl_add_u64 v[52:53], s[2:3], 0, v[58:59]
	global_store_dwordx2 v[52:53], v[56:57], off
	global_store_dwordx4 v[114:115], v[48:51], off offset:576 nt
	v_cvt_pk_f16_f32 v52, v48, v49
	v_or_b32_e32 v94, 0x120, v94
	s_waitcnt lgkmcnt(0)
	v_add_f32_e32 v48, v54, v55
	ds_bpermute_b32 v49, v162, v48
	v_cvt_pk_f16_f32 v53, v50, v51
	v_lshl_add_u64 v[50:51], s[2:3], 0, v[94:95]
	global_store_dwordx2 v[50:51], v[52:53], off
	s_and_saveexec_b64 s[2:3], s[6:7]
	s_cbranch_execz .LBB0_592
	s_waitcnt lgkmcnt(0)
	v_add_f32_e32 v50, v48, v49
	v_lshlrev_b64 v[48:49], 6, v[112:113]
	v_lshl_add_u64 v[48:49], s[46:47], 0, v[48:49]
	v_lshl_add_u64 v[48:49], s[20:21], 2, v[48:49]
	s_lshl_b32 s92, s38, 2
	v_lshl_add_u64 v[48:49], v[48:49], 0, s[92:93]
	global_store_dword v[48:49], v50, off
.LBB0_592:
	s_or_b64 exec, exec, s[2:3]
	v_or_b32_e32 v80, 32, v112
	v_ashrrev_i32_e32 v81, 31, v80
	s_waitcnt lgkmcnt(0)
	v_lshlrev_b64 v[48:49], 12, v[80:81]
	v_lshl_add_u64 v[82:83], v[178:179], 0, v[48:49]
	global_load_dwordx4 v[60:63], v[82:83], off
	global_load_dwordx4 v[56:59], v[82:83], off offset:64
	global_load_dwordx4 v[52:55], v[82:83], off offset:512
	global_load_dwordx4 v[48:51], v[82:83], off offset:576
	v_lshlrev_b64 v[84:85], 10, v[96:97]
	s_waitcnt vmcnt(15)
	v_pk_add_f32 v[46:47], v[46:47], v[78:79]
	v_pk_add_f32 v[44:45], v[44:45], v[76:77]
	v_lshl_add_u64 v[84:85], v[84:85], 0, v[176:177]
	global_store_dwordx4 v[98:99], v[44:47], off nt
	v_cvt_pk_f16_f32 v76, v44, v45
	v_readlane_b32 s2, v253, 24
	v_mul_f32_e32 v45, v45, v45
	v_lshlrev_b64 v[78:79], 1, v[84:85]
	v_readlane_b32 s3, v253, 25
	v_fmac_f32_e32 v45, v44, v44
	v_mul_f32_e32 v44, v47, v47
	v_cvt_pk_f16_f32 v77, v46, v47
	v_lshl_add_u64 v[84:85], s[2:3], 0, v[78:79]
	v_fmac_f32_e32 v44, v46, v46
	s_waitcnt vmcnt(15)
	v_pk_add_f32 v[42:43], v[42:43], v[74:75]
	v_pk_add_f32 v[40:41], v[40:41], v[72:73]
	global_store_dwordx2 v[84:85], v[76:77], off
	v_add_f32_e32 v76, v45, v44
	global_store_dwordx4 v[98:99], v[40:43], off offset:64 nt
	v_cvt_pk_f16_f32 v44, v40, v41
	v_or_b32_e32 v46, 32, v78
	v_mul_f32_e32 v41, v41, v41
	v_fmac_f32_e32 v41, v40, v40
	v_mul_f32_e32 v40, v43, v43
	v_mov_b32_e32 v47, v79
	v_fmac_f32_e32 v40, v42, v42
	v_cvt_pk_f16_f32 v45, v42, v43
	v_lshl_add_u64 v[46:47], s[2:3], 0, v[46:47]
	v_add_f32_e32 v40, v41, v40
	s_waitcnt vmcnt(16)
	v_pk_add_f32 v[38:39], v[38:39], v[70:71]
	v_pk_add_f32 v[36:37], v[36:37], v[68:69]
	global_store_dwordx2 v[46:47], v[44:45], off
	v_add_f32_e32 v44, v76, v40
	global_store_dwordx4 v[98:99], v[36:39], off offset:512 nt
	v_cvt_pk_f16_f32 v40, v36, v37
	s_waitcnt vmcnt(17)
	v_pk_add_f32 v[34:35], v[34:35], v[66:67]
	v_mul_f32_e32 v37, v37, v37
	v_fmac_f32_e32 v37, v36, v36
	v_mul_f32_e32 v36, v39, v39
	v_fmac_f32_e32 v36, v38, v38
	v_pk_add_f32 v[32:33], v[32:33], v[64:65]
	v_cvt_pk_f16_f32 v41, v38, v39
	v_add_f32_e32 v36, v37, v36
	v_mul_f32_e32 v37, v33, v33
	v_mul_f32_e32 v38, v35, v35
	v_fmac_f32_e32 v37, v32, v32
	v_fmac_f32_e32 v38, v34, v34
	v_add_f32_e32 v36, v44, v36
	v_add_f32_e32 v37, v37, v38
	v_add_f32_e32 v38, v36, v37
	ds_bpermute_b32 v39, v163, v38
	v_or_b32_e32 v42, 0x100, v78
	v_mov_b32_e32 v43, v79
	v_lshl_add_u64 v[36:37], s[2:3], 0, v[42:43]
	global_store_dwordx2 v[36:37], v[40:41], off
	global_store_dwordx4 v[98:99], v[32:35], off offset:576 nt
	v_cvt_pk_f16_f32 v36, v32, v33
	v_or_b32_e32 v78, 0x120, v78
	s_waitcnt lgkmcnt(0)
	v_add_f32_e32 v32, v38, v39
	ds_bpermute_b32 v33, v162, v32
	v_cvt_pk_f16_f32 v37, v34, v35
	v_lshl_add_u64 v[34:35], s[2:3], 0, v[78:79]
	global_store_dwordx2 v[34:35], v[36:37], off
	s_and_saveexec_b64 s[2:3], s[6:7]
	s_cbranch_execz .LBB0_594
	s_waitcnt lgkmcnt(0)
	v_add_f32_e32 v34, v32, v33
	v_lshlrev_b64 v[32:33], 6, v[96:97]
	v_lshl_add_u64 v[32:33], s[46:47], 0, v[32:33]
	v_lshl_add_u64 v[32:33], s[20:21], 2, v[32:33]
	s_lshl_b32 s92, s38, 2
	v_lshl_add_u64 v[32:33], v[32:33], 0, s[92:93]
	global_store_dword v[32:33], v34, off
.LBB0_594:
	s_or_b64 exec, exec, s[2:3]
	v_or_b32_e32 v64, 48, v112
	v_ashrrev_i32_e32 v65, 31, v64
	s_waitcnt lgkmcnt(0)
	v_lshlrev_b64 v[32:33], 12, v[64:65]
	v_lshl_add_u64 v[66:67], v[178:179], 0, v[32:33]
	global_load_dwordx4 v[44:47], v[66:67], off
	global_load_dwordx4 v[40:43], v[66:67], off offset:64
	global_load_dwordx4 v[36:39], v[66:67], off offset:512
	global_load_dwordx4 v[32:35], v[66:67], off offset:576
	v_lshlrev_b64 v[68:69], 10, v[80:81]
	s_waitcnt vmcnt(15)
	v_pk_add_f32 v[30:31], v[30:31], v[62:63]
	v_pk_add_f32 v[28:29], v[28:29], v[60:61]
	v_lshl_add_u64 v[68:69], v[68:69], 0, v[176:177]
	global_store_dwordx4 v[82:83], v[28:31], off nt
	v_cvt_pk_f16_f32 v60, v28, v29
	v_readlane_b32 s2, v253, 24
	v_mul_f32_e32 v29, v29, v29
	v_lshlrev_b64 v[62:63], 1, v[68:69]
	v_readlane_b32 s3, v253, 25
	v_fmac_f32_e32 v29, v28, v28
	v_mul_f32_e32 v28, v31, v31
	v_cvt_pk_f16_f32 v61, v30, v31
	v_lshl_add_u64 v[68:69], s[2:3], 0, v[62:63]
	v_fmac_f32_e32 v28, v30, v30
	s_waitcnt vmcnt(15)
	v_pk_add_f32 v[26:27], v[26:27], v[58:59]
	v_pk_add_f32 v[24:25], v[24:25], v[56:57]
	global_store_dwordx2 v[68:69], v[60:61], off
	v_add_f32_e32 v60, v29, v28
	global_store_dwordx4 v[82:83], v[24:27], off offset:64 nt
	v_cvt_pk_f16_f32 v28, v24, v25
	v_or_b32_e32 v30, 32, v62
	v_mul_f32_e32 v25, v25, v25
	v_fmac_f32_e32 v25, v24, v24
	v_mul_f32_e32 v24, v27, v27
	v_mov_b32_e32 v31, v63
	v_fmac_f32_e32 v24, v26, v26
	v_cvt_pk_f16_f32 v29, v26, v27
	v_lshl_add_u64 v[30:31], s[2:3], 0, v[30:31]
	v_add_f32_e32 v24, v25, v24
	s_waitcnt vmcnt(16)
	v_pk_add_f32 v[22:23], v[22:23], v[54:55]
	v_pk_add_f32 v[20:21], v[20:21], v[52:53]
	global_store_dwordx2 v[30:31], v[28:29], off
	v_add_f32_e32 v28, v60, v24
	global_store_dwordx4 v[82:83], v[20:23], off offset:512 nt
	v_cvt_pk_f16_f32 v24, v20, v21
	s_waitcnt vmcnt(17)
	v_pk_add_f32 v[18:19], v[18:19], v[50:51]
	v_mul_f32_e32 v21, v21, v21
	v_fmac_f32_e32 v21, v20, v20
	v_mul_f32_e32 v20, v23, v23
	v_fmac_f32_e32 v20, v22, v22
	v_pk_add_f32 v[16:17], v[16:17], v[48:49]
	v_cvt_pk_f16_f32 v25, v22, v23
	v_add_f32_e32 v20, v21, v20
	v_mul_f32_e32 v21, v17, v17
	v_mul_f32_e32 v22, v19, v19
	v_fmac_f32_e32 v21, v16, v16
	v_fmac_f32_e32 v22, v18, v18
	v_add_f32_e32 v20, v28, v20
	v_add_f32_e32 v21, v21, v22
	v_add_f32_e32 v22, v20, v21
	ds_bpermute_b32 v23, v163, v22
	v_or_b32_e32 v26, 0x100, v62
	v_mov_b32_e32 v27, v63
	v_lshl_add_u64 v[20:21], s[2:3], 0, v[26:27]
	global_store_dwordx2 v[20:21], v[24:25], off
	global_store_dwordx4 v[82:83], v[16:19], off offset:576 nt
	v_cvt_pk_f16_f32 v20, v16, v17
	v_or_b32_e32 v62, 0x120, v62
	s_waitcnt lgkmcnt(0)
	v_add_f32_e32 v16, v22, v23
	ds_bpermute_b32 v17, v162, v16
	v_cvt_pk_f16_f32 v21, v18, v19
	v_lshl_add_u64 v[18:19], s[2:3], 0, v[62:63]
	global_store_dwordx2 v[18:19], v[20:21], off
	s_and_saveexec_b64 s[2:3], s[6:7]
	s_cbranch_execz .LBB0_596
	s_waitcnt lgkmcnt(0)
	v_add_f32_e32 v18, v16, v17
	v_lshlrev_b64 v[16:17], 6, v[80:81]
	v_lshl_add_u64 v[16:17], s[46:47], 0, v[16:17]
	v_lshl_add_u64 v[16:17], s[20:21], 2, v[16:17]
	s_lshl_b32 s92, s38, 2
	v_lshl_add_u64 v[16:17], v[16:17], 0, s[92:93]
	global_store_dword v[16:17], v18, off
.LBB0_596:
	s_or_b64 exec, exec, s[2:3]
	s_waitcnt lgkmcnt(0)
	v_lshlrev_b64 v[16:17], 10, v[64:65]
	s_waitcnt vmcnt(11)
	v_pk_add_f32 v[14:15], v[14:15], v[46:47]
	v_pk_add_f32 v[12:13], v[12:13], v[44:45]
	v_lshl_add_u64 v[16:17], v[16:17], 0, v[176:177]
	global_store_dwordx4 v[66:67], v[12:15], off nt
	v_cvt_pk_f16_f32 v18, v12, v13
	v_readlane_b32 s2, v253, 24
	v_mul_f32_e32 v13, v13, v13
	v_lshlrev_b64 v[16:17], 1, v[16:17]
	v_readlane_b32 s3, v253, 25
	v_fmac_f32_e32 v13, v12, v12
	v_mul_f32_e32 v12, v15, v15
	v_cvt_pk_f16_f32 v19, v14, v15
	v_lshl_add_u64 v[20:21], s[2:3], 0, v[16:17]
	v_fmac_f32_e32 v12, v14, v14
	s_waitcnt vmcnt(11)
	v_pk_add_f32 v[10:11], v[10:11], v[42:43]
	v_pk_add_f32 v[8:9], v[8:9], v[40:41]
	global_store_dwordx2 v[20:21], v[18:19], off
	v_add_f32_e32 v18, v13, v12
	global_store_dwordx4 v[66:67], v[8:11], off offset:64 nt
	v_cvt_pk_f16_f32 v12, v8, v9
	v_or_b32_e32 v14, 32, v16
	v_mul_f32_e32 v9, v9, v9
	v_fmac_f32_e32 v9, v8, v8
	v_mul_f32_e32 v8, v11, v11
	v_mov_b32_e32 v15, v17
	v_fmac_f32_e32 v8, v10, v10
	v_cvt_pk_f16_f32 v13, v10, v11
	v_lshl_add_u64 v[14:15], s[2:3], 0, v[14:15]
	v_add_f32_e32 v8, v9, v8
	s_waitcnt vmcnt(12)
	v_pk_add_f32 v[6:7], v[6:7], v[38:39]
	v_pk_add_f32 v[4:5], v[4:5], v[36:37]
	global_store_dwordx2 v[14:15], v[12:13], off
	v_add_f32_e32 v12, v18, v8
	global_store_dwordx4 v[66:67], v[4:7], off offset:512 nt
	v_cvt_pk_f16_f32 v8, v4, v5
	s_waitcnt vmcnt(13)
	v_pk_add_f32 v[2:3], v[2:3], v[34:35]
	v_mul_f32_e32 v5, v5, v5
	v_fmac_f32_e32 v5, v4, v4
	v_mul_f32_e32 v4, v7, v7
	v_fmac_f32_e32 v4, v6, v6
	v_pk_add_f32 v[0:1], v[0:1], v[32:33]
	v_cvt_pk_f16_f32 v9, v6, v7
	v_add_f32_e32 v4, v5, v4
	v_mul_f32_e32 v5, v1, v1
	v_mul_f32_e32 v6, v3, v3
	v_fmac_f32_e32 v5, v0, v0
	v_fmac_f32_e32 v6, v2, v2
	v_add_f32_e32 v4, v12, v4
	v_add_f32_e32 v5, v5, v6
	v_add_f32_e32 v6, v4, v5
	ds_bpermute_b32 v7, v163, v6
	v_or_b32_e32 v10, 0x100, v16
	v_mov_b32_e32 v11, v17
	v_lshl_add_u64 v[4:5], s[2:3], 0, v[10:11]
	global_store_dwordx2 v[4:5], v[8:9], off
	global_store_dwordx4 v[66:67], v[0:3], off offset:576 nt
	v_cvt_pk_f16_f32 v4, v0, v1
	v_or_b32_e32 v16, 0x120, v16
	s_waitcnt lgkmcnt(0)
	v_add_f32_e32 v0, v6, v7
	ds_bpermute_b32 v1, v162, v0
	v_cvt_pk_f16_f32 v5, v2, v3
	v_lshl_add_u64 v[2:3], s[2:3], 0, v[16:17]
	global_store_dwordx2 v[2:3], v[4:5], off
	s_and_saveexec_b64 s[2:3], s[6:7]
	s_cbranch_execz .LBB0_598
	s_waitcnt lgkmcnt(0)
	v_add_f32_e32 v2, v0, v1
	v_lshlrev_b64 v[0:1], 6, v[64:65]
	v_lshl_add_u64 v[0:1], s[46:47], 0, v[0:1]
	v_lshl_add_u64 v[0:1], s[20:21], 2, v[0:1]
	s_lshl_b32 s92, s38, 2
	v_lshl_add_u64 v[0:1], v[0:1], 0, s[92:93]
	global_store_dword v[0:1], v2, off

.LBB0_748:
	v_lshl_add_u32 v180, s43, 8, v188
	v_lshl_or_b32 v176, s42, 8, v190
	v_ashrrev_i32_e32 v181, 31, v180
	v_readlane_b32 s52, v248, 48
	v_lshlrev_b64 v[128:129], 12, v[180:181]
	v_readlane_b32 s66, v248, 62
	v_readlane_b32 s67, v248, 63
	v_ashrrev_i32_e32 v177, 31, v176
	v_lshlrev_b64 v[130:131], 2, v[176:177]
	v_lshl_add_u64 v[128:129], s[66:67], 0, v[128:129]
	v_lshl_add_u64 v[186:187], v[128:129], 0, v[130:131]
	global_load_dwordx4 v[154:157], v[186:187], off
	global_load_dwordx4 v[164:167], v[186:187], off offset:64
	global_load_dwordx4 v[148:151], v[186:187], off offset:512
	global_load_dwordx4 v[144:147], v[186:187], off offset:576
	v_and_b32_e32 v129, 64, v203
	v_xor_b32_e32 v128, 16, v203
	v_add_u32_e32 v129, 64, v129
	v_cmp_lt_i32_e32 vcc, v128, v129
	v_or_b32_e32 v182, 16, v180
	v_ashrrev_i32_e32 v183, 31, v182
	v_cndmask_b32_e32 v128, v203, v128, vcc
	v_lshlrev_b32_e32 v163, 2, v128
	v_xor_b32_e32 v128, 32, v203
	v_cmp_lt_i32_e32 vcc, v128, v129
	v_lshl_add_u64 v[178:179], s[66:67], 0, v[130:131]
	v_readlane_b32 s2, v253, 24
	v_cndmask_b32_e32 v128, v203, v128, vcc
	v_lshlrev_b32_e32 v162, 2, v128
	v_lshlrev_b64 v[128:129], 10, v[180:181]
	v_lshl_add_u64 v[192:193], v[128:129], 0, v[176:177]
	v_lshlrev_b64 v[128:129], 12, v[182:183]
	v_lshl_add_u64 v[184:185], v[178:179], 0, v[128:129]
	global_load_dwordx4 v[140:143], v[184:185], off
	global_load_dwordx4 v[136:139], v[184:185], off offset:64
	global_load_dwordx4 v[132:135], v[184:185], off offset:512
	global_load_dwordx4 v[128:131], v[184:185], off offset:576
	v_readlane_b32 s3, v253, 25
	s_lshl_b32 s18, s42, 2
	s_ashr_i32 s19, s18, 31
	v_readlane_b32 s53, v248, 49
	v_readlane_b32 s54, v248, 50
	v_readlane_b32 s55, v248, 51
	v_readlane_b32 s56, v248, 52
	v_readlane_b32 s57, v248, 53
	v_readlane_b32 s58, v248, 54
	v_readlane_b32 s59, v248, 55
	v_readlane_b32 s60, v248, 56
	v_readlane_b32 s61, v248, 57
	v_readlane_b32 s62, v248, 58
	v_readlane_b32 s63, v248, 59
	v_readlane_b32 s64, v248, 60
	v_readlane_b32 s65, v248, 61
	s_waitcnt vmcnt(0)
	v_pk_fma_f32 v[126:127], v[126:127], 0.5, v[156:157] op_sel_hi:[1,0,1]
	v_pk_fma_f32 v[124:125], v[124:125], 0.5, v[154:155] op_sel_hi:[1,0,1]
	global_store_dwordx4 v[186:187], v[124:127], off nt
	v_cvt_pk_f16_f32 v154, v124, v125
	v_lshlrev_b64 v[156:157], 1, v[192:193]
	v_mul_f32_e32 v125, v125, v125
	v_fmac_f32_e32 v125, v124, v124
	v_mul_f32_e32 v124, v127, v127
	v_cvt_pk_f16_f32 v155, v126, v127
	v_lshl_add_u64 v[192:193], s[2:3], 0, v[156:157]
	v_fmac_f32_e32 v124, v126, v126
	v_pk_fma_f32 v[122:123], v[122:123], 0.5, v[166:167] op_sel_hi:[1,0,1]
	v_pk_fma_f32 v[120:121], v[120:121], 0.5, v[164:165] op_sel_hi:[1,0,1]
	global_store_dwordx2 v[192:193], v[154:155], off
	v_add_f32_e32 v154, v125, v124
	global_store_dwordx4 v[186:187], v[120:123], off offset:64 nt
	v_cvt_pk_f16_f32 v124, v120, v121
	v_or_b32_e32 v126, 32, v156
	v_mul_f32_e32 v121, v121, v121
	v_fmac_f32_e32 v121, v120, v120
	v_mul_f32_e32 v120, v123, v123
	v_mov_b32_e32 v127, v157
	v_fmac_f32_e32 v120, v122, v122
	v_cvt_pk_f16_f32 v125, v122, v123
	v_lshl_add_u64 v[126:127], s[2:3], 0, v[126:127]
	v_add_f32_e32 v120, v121, v120
	v_pk_fma_f32 v[118:119], v[118:119], 0.5, v[150:151] op_sel_hi:[1,0,1]
	v_pk_fma_f32 v[116:117], v[116:117], 0.5, v[148:149] op_sel_hi:[1,0,1]
	global_store_dwordx2 v[126:127], v[124:125], off
	v_add_f32_e32 v124, v154, v120
	global_store_dwordx4 v[186:187], v[116:119], off offset:512 nt
	v_cvt_pk_f16_f32 v120, v116, v117
	v_or_b32_e32 v122, 0x100, v156
	v_mul_f32_e32 v117, v117, v117
	v_fmac_f32_e32 v117, v116, v116
	v_mul_f32_e32 v116, v119, v119
	v_mov_b32_e32 v123, v157
	v_fmac_f32_e32 v116, v118, v118
	v_cvt_pk_f16_f32 v121, v118, v119
	v_lshl_add_u64 v[122:123], s[2:3], 0, v[122:123]
	v_add_f32_e32 v116, v117, v116
	v_pk_fma_f32 v[114:115], v[114:115], 0.5, v[146:147] op_sel_hi:[1,0,1]
	v_pk_fma_f32 v[112:113], v[112:113], 0.5, v[144:145] op_sel_hi:[1,0,1]
	global_store_dwordx2 v[122:123], v[120:121], off
	v_add_f32_e32 v120, v124, v116
	global_store_dwordx4 v[186:187], v[112:115], off offset:576 nt
	v_cvt_pk_f16_f32 v116, v112, v113
	v_or_b32_e32 v156, 0x120, v156
	v_mul_f32_e32 v113, v113, v113
	v_fmac_f32_e32 v113, v112, v112
	v_mul_f32_e32 v112, v115, v115
	v_fmac_f32_e32 v112, v114, v114
	v_add_f32_e32 v112, v113, v112
	v_add_f32_e32 v112, v120, v112
	ds_bpermute_b32 v113, v163, v112
	v_cvt_pk_f16_f32 v117, v114, v115
	v_lshl_add_u64 v[118:119], s[2:3], 0, v[156:157]
	global_store_dwordx2 v[118:119], v[116:117], off
	s_waitcnt lgkmcnt(0)
	v_add_f32_e32 v112, v112, v113
	ds_bpermute_b32 v113, v162, v112
	s_and_saveexec_b64 s[2:3], s[6:7]
	s_cbranch_execz .LBB0_750
	s_waitcnt lgkmcnt(0)
	v_add_f32_e32 v114, v112, v113
	v_lshlrev_b64 v[112:113], 6, v[180:181]
	v_lshl_add_u64 v[112:113], s[46:47], 0, v[112:113]
	v_lshl_add_u64 v[112:113], s[18:19], 2, v[112:113]
	s_lshl_b32 s92, s38, 2
	v_lshl_add_u64 v[112:113], v[112:113], 0, s[92:93]
	global_store_dword v[112:113], v114, off
;     __device__ __forceinline__ void operator()(const Acc& acc, const Unit& u, int wr, int wc, int fr, int fq) const {
;     ...
;         for (int i = 0; i < 8; ++i) {
;             const int ai = i >> 2, m = i & 3;
;             const int row = row0 + ai * HALF + m * 16; const size_t off = (size_t)row * D + col0; float sq = 0.f;
;             if (i + 1 < 8) { const size_t offn = (size_t)(row0 + ((i + 1) >> 2) * HALF + ((i + 1) & 3) * 16) * D + col0;
; #pragma unroll
;                 for (int k = 0; k < 4; ++k) rn[k] = *(const f32x4*)(res + offn + (k >> 1) * HALF + (k & 1) * 16); }
; #pragma unroll
;             for (int bj = 0; bj < 2; ++bj)
; #pragma unroll
;                 for (int n = 0; n < 2; ++n) { const size_t o = off + bj * HALF + n * 16; const f32x4 v = rc[bj * 2 + n] + acc[ai][bj][m][n] * alpha;
;                     *(f32x4*)(out + o) = v; u32x2 w; w.x = pk2h(v.x, v.y); w.y = pk2h(v.z, v.w); *(u32x2*)(o16 + o) = w; sq += (v.x * v.x + v.y * v.y) + (v.z * v.z + v.w * v.w); }
;             sq += __shfl_xor(sq, 16); sq += __shfl_xor(sq, 32);
;             if (fq == 0) ss[(size_t)row * 16 + u.pn * 4 + wc] = sq;
.LBB0_750:
	s_or_b64 exec, exec, s[2:3]
	v_or_b32_e32 v144, 32, v180
	v_ashrrev_i32_e32 v145, 31, v144
	s_waitcnt lgkmcnt(0)
	v_lshlrev_b64 v[112:113], 12, v[144:145]
	v_lshl_add_u64 v[146:147], v[178:179], 0, v[112:113]
	global_load_dwordx4 v[124:127], v[146:147], off
	global_load_dwordx4 v[120:123], v[146:147], off offset:64
	global_load_dwordx4 v[116:119], v[146:147], off offset:512
	global_load_dwordx4 v[112:115], v[146:147], off offset:576
	v_lshlrev_b64 v[148:149], 10, v[182:183]
	v_pk_fma_f32 v[110:111], v[110:111], 0.5, v[142:143] op_sel_hi:[1,0,1]
	v_pk_fma_f32 v[108:109], v[108:109], 0.5, v[140:141] op_sel_hi:[1,0,1]
	v_lshl_add_u64 v[148:149], v[148:149], 0, v[176:177]
	global_store_dwordx4 v[184:185], v[108:111], off nt
	v_cvt_pk_f16_f32 v140, v108, v109
	v_readlane_b32 s2, v253, 24
	v_mul_f32_e32 v109, v109, v109
	v_lshlrev_b64 v[142:143], 1, v[148:149]
	v_readlane_b32 s3, v253, 25
	v_fmac_f32_e32 v109, v108, v108
	v_mul_f32_e32 v108, v111, v111
	v_cvt_pk_f16_f32 v141, v110, v111
	v_lshl_add_u64 v[148:149], s[2:3], 0, v[142:143]
	v_fmac_f32_e32 v108, v110, v110
	v_pk_fma_f32 v[106:107], v[106:107], 0.5, v[138:139] op_sel_hi:[1,0,1]
	v_pk_fma_f32 v[104:105], v[104:105], 0.5, v[136:137] op_sel_hi:[1,0,1]
	global_store_dwordx2 v[148:149], v[140:141], off
	v_add_f32_e32 v140, v109, v108
	global_store_dwordx4 v[184:185], v[104:107], off offset:64 nt
	v_cvt_pk_f16_f32 v108, v104, v105
	v_or_b32_e32 v110, 32, v142
	v_mul_f32_e32 v105, v105, v105
	v_fmac_f32_e32 v105, v104, v104
	v_mul_f32_e32 v104, v107, v107
	v_mov_b32_e32 v111, v143
	v_fmac_f32_e32 v104, v106, v106
	v_cvt_pk_f16_f32 v109, v106, v107
	v_lshl_add_u64 v[110:111], s[2:3], 0, v[110:111]
	v_add_f32_e32 v104, v105, v104
	v_pk_fma_f32 v[102:103], v[102:103], 0.5, v[134:135] op_sel_hi:[1,0,1]
	v_pk_fma_f32 v[100:101], v[100:101], 0.5, v[132:133] op_sel_hi:[1,0,1]
	global_store_dwordx2 v[110:111], v[108:109], off
	v_add_f32_e32 v108, v140, v104
	global_store_dwordx4 v[184:185], v[100:103], off offset:512 nt
	v_cvt_pk_f16_f32 v104, v100, v101
	v_pk_fma_f32 v[98:99], v[98:99], 0.5, v[130:131] op_sel_hi:[1,0,1]
	v_mul_f32_e32 v101, v101, v101
	v_fmac_f32_e32 v101, v100, v100
	v_mul_f32_e32 v100, v103, v103
	v_fmac_f32_e32 v100, v102, v102
	v_pk_fma_f32 v[96:97], v[96:97], 0.5, v[128:129] op_sel_hi:[1,0,1]
	v_cvt_pk_f16_f32 v105, v102, v103
	v_add_f32_e32 v100, v101, v100
	v_mul_f32_e32 v101, v97, v97
	v_mul_f32_e32 v102, v99, v99
	v_fmac_f32_e32 v101, v96, v96
	v_fmac_f32_e32 v102, v98, v98
	v_add_f32_e32 v100, v108, v100
	v_add_f32_e32 v101, v101, v102
	v_add_f32_e32 v102, v100, v101
	ds_bpermute_b32 v103, v163, v102
	v_or_b32_e32 v106, 0x100, v142
	v_mov_b32_e32 v107, v143
	v_lshl_add_u64 v[100:101], s[2:3], 0, v[106:107]
	global_store_dwordx2 v[100:101], v[104:105], off
	global_store_dwordx4 v[184:185], v[96:99], off offset:576 nt
	v_cvt_pk_f16_f32 v100, v96, v97
	v_or_b32_e32 v142, 0x120, v142
	s_waitcnt lgkmcnt(0)
	v_add_f32_e32 v96, v102, v103
	ds_bpermute_b32 v97, v162, v96
	v_cvt_pk_f16_f32 v101, v98, v99
	v_lshl_add_u64 v[98:99], s[2:3], 0, v[142:143]
	global_store_dwordx2 v[98:99], v[100:101], off
	s_and_saveexec_b64 s[2:3], s[6:7]
	s_cbranch_execz .LBB0_752
	s_waitcnt lgkmcnt(0)
	v_add_f32_e32 v98, v96, v97
	v_lshlrev_b64 v[96:97], 6, v[182:183]
	v_lshl_add_u64 v[96:97], s[46:47], 0, v[96:97]
	v_lshl_add_u64 v[96:97], s[18:19], 2, v[96:97]
	s_lshl_b32 s92, s38, 2
	v_lshl_add_u64 v[96:97], v[96:97], 0, s[92:93]
	global_store_dword v[96:97], v98, off
.LBB0_752:
	s_or_b64 exec, exec, s[2:3]
	v_or_b32_e32 v128, 48, v180
	v_ashrrev_i32_e32 v129, 31, v128
	s_waitcnt lgkmcnt(0)
	v_lshlrev_b64 v[96:97], 12, v[128:129]
	v_lshl_add_u64 v[130:131], v[178:179], 0, v[96:97]
	global_load_dwordx4 v[108:111], v[130:131], off
	global_load_dwordx4 v[104:107], v[130:131], off offset:64
	global_load_dwordx4 v[100:103], v[130:131], off offset:512
	global_load_dwordx4 v[96:99], v[130:131], off offset:576
	v_lshlrev_b64 v[132:133], 10, v[144:145]
	s_waitcnt vmcnt(15)
	v_pk_fma_f32 v[94:95], v[94:95], 0.5, v[126:127] op_sel_hi:[1,0,1]
	v_pk_fma_f32 v[92:93], v[92:93], 0.5, v[124:125] op_sel_hi:[1,0,1]
	v_lshl_add_u64 v[132:133], v[132:133], 0, v[176:177]
	global_store_dwordx4 v[146:147], v[92:95], off nt
	v_cvt_pk_f16_f32 v124, v92, v93
	v_readlane_b32 s2, v253, 24
	v_mul_f32_e32 v93, v93, v93
	v_lshlrev_b64 v[126:127], 1, v[132:133]
	v_readlane_b32 s3, v253, 25
	v_fmac_f32_e32 v93, v92, v92
	v_mul_f32_e32 v92, v95, v95
	v_cvt_pk_f16_f32 v125, v94, v95
	v_lshl_add_u64 v[132:133], s[2:3], 0, v[126:127]
	v_fmac_f32_e32 v92, v94, v94
	s_waitcnt vmcnt(15)
	v_pk_fma_f32 v[90:91], v[90:91], 0.5, v[122:123] op_sel_hi:[1,0,1]
	v_pk_fma_f32 v[88:89], v[88:89], 0.5, v[120:121] op_sel_hi:[1,0,1]
	global_store_dwordx2 v[132:133], v[124:125], off
	v_add_f32_e32 v124, v93, v92
	global_store_dwordx4 v[146:147], v[88:91], off offset:64 nt
	v_cvt_pk_f16_f32 v92, v88, v89
	v_or_b32_e32 v94, 32, v126
	v_mul_f32_e32 v89, v89, v89
	v_fmac_f32_e32 v89, v88, v88
	v_mul_f32_e32 v88, v91, v91
	v_mov_b32_e32 v95, v127
	v_fmac_f32_e32 v88, v90, v90
	v_cvt_pk_f16_f32 v93, v90, v91
	v_lshl_add_u64 v[94:95], s[2:3], 0, v[94:95]
	v_add_f32_e32 v88, v89, v88
	s_waitcnt vmcnt(16)
	v_pk_fma_f32 v[86:87], v[86:87], 0.5, v[118:119] op_sel_hi:[1,0,1]
	v_pk_fma_f32 v[84:85], v[84:85], 0.5, v[116:117] op_sel_hi:[1,0,1]
	global_store_dwordx2 v[94:95], v[92:93], off
	v_add_f32_e32 v92, v124, v88
	global_store_dwordx4 v[146:147], v[84:87], off offset:512 nt
	v_cvt_pk_f16_f32 v88, v84, v85
	s_waitcnt vmcnt(17)
	v_pk_fma_f32 v[82:83], v[82:83], 0.5, v[114:115] op_sel_hi:[1,0,1]
	v_mul_f32_e32 v85, v85, v85
	v_fmac_f32_e32 v85, v84, v84
	v_mul_f32_e32 v84, v87, v87
	v_fmac_f32_e32 v84, v86, v86
	v_pk_fma_f32 v[80:81], v[80:81], 0.5, v[112:113] op_sel_hi:[1,0,1]
	v_cvt_pk_f16_f32 v89, v86, v87
	v_add_f32_e32 v84, v85, v84
	v_mul_f32_e32 v85, v81, v81
	v_mul_f32_e32 v86, v83, v83
	v_fmac_f32_e32 v85, v80, v80
	v_fmac_f32_e32 v86, v82, v82
	v_add_f32_e32 v84, v92, v84
	v_add_f32_e32 v85, v85, v86
	v_add_f32_e32 v86, v84, v85
	ds_bpermute_b32 v87, v163, v86
	v_or_b32_e32 v90, 0x100, v126
	v_mov_b32_e32 v91, v127
	v_lshl_add_u64 v[84:85], s[2:3], 0, v[90:91]
	global_store_dwordx2 v[84:85], v[88:89], off
	global_store_dwordx4 v[146:147], v[80:83], off offset:576 nt
	v_cvt_pk_f16_f32 v84, v80, v81
	v_or_b32_e32 v126, 0x120, v126
	s_waitcnt lgkmcnt(0)
	v_add_f32_e32 v80, v86, v87
	ds_bpermute_b32 v81, v162, v80
	v_cvt_pk_f16_f32 v85, v82, v83
	v_lshl_add_u64 v[82:83], s[2:3], 0, v[126:127]
	global_store_dwordx2 v[82:83], v[84:85], off
	s_mov_b64 s[2:3], exec
	v_mov_b64_e32 v[154:155], v[158:159]
	s_and_b64 s[20:21], s[2:3], s[6:7]
	v_mov_b64_e32 v[156:157], v[160:161]
	s_mov_b64 exec, s[20:21]
	s_cbranch_execz .LBB0_754
	s_waitcnt lgkmcnt(0)
	v_add_f32_e32 v82, v80, v81
	v_lshlrev_b64 v[80:81], 6, v[144:145]
	v_lshl_add_u64 v[80:81], s[46:47], 0, v[80:81]
	v_lshl_add_u64 v[80:81], s[18:19], 2, v[80:81]
	s_lshl_b32 s92, s38, 2
	v_lshl_add_u64 v[80:81], v[80:81], 0, s[92:93]
	global_store_dword v[80:81], v82, off
;     __device__ __forceinline__ void operator()(const Acc& acc, const Unit& u, int wr, int wc, int fr, int fq) const {
;     ...
;         for (int i = 0; i < 8; ++i) {
;             const int ai = i >> 2, m = i & 3;
;             const int row = row0 + ai * HALF + m * 16; const size_t off = (size_t)row * D + col0; float sq = 0.f;
;             if (i + 1 < 8) { const size_t offn = (size_t)(row0 + ((i + 1) >> 2) * HALF + ((i + 1) & 3) * 16) * D + col0;
; #pragma unroll
;                 for (int k = 0; k < 4; ++k) rn[k] = *(const f32x4*)(res + offn + (k >> 1) * HALF + (k & 1) * 16); }
; #pragma unroll
;             for (int bj = 0; bj < 2; ++bj)
; #pragma unroll
;                 for (int n = 0; n < 2; ++n) { const size_t o = off + bj * HALF + n * 16; const f32x4 v = rc[bj * 2 + n] + acc[ai][bj][m][n] * alpha;
;                     *(f32x4*)(out + o) = v; u32x2 w; w.x = pk2h(v.x, v.y); w.y = pk2h(v.z, v.w); *(u32x2*)(o16 + o) = w; sq += (v.x * v.x + v.y * v.y) + (v.z * v.z + v.w * v.w); }
;             sq += __shfl_xor(sq, 16); sq += __shfl_xor(sq, 32);
;             if (fq == 0) ss[(size_t)row * 16 + u.pn * 4 + wc] = sq;
.LBB0_754:
	s_or_b64 exec, exec, s[2:3]
	v_add_u32_e32 v112, 0x80, v180
	v_ashrrev_i32_e32 v113, 31, v112
	s_waitcnt lgkmcnt(0)
	v_lshlrev_b64 v[80:81], 12, v[112:113]
	v_lshl_add_u64 v[114:115], v[178:179], 0, v[80:81]
	global_load_dwordx4 v[92:95], v[114:115], off
	global_load_dwordx4 v[88:91], v[114:115], off offset:64
	global_load_dwordx4 v[84:87], v[114:115], off offset:512
	global_load_dwordx4 v[80:83], v[114:115], off offset:576
	v_lshlrev_b64 v[116:117], 10, v[128:129]
	s_waitcnt vmcnt(15)
	v_pk_fma_f32 v[78:79], v[78:79], 0.5, v[110:111] op_sel_hi:[1,0,1]
	v_pk_fma_f32 v[76:77], v[76:77], 0.5, v[108:109] op_sel_hi:[1,0,1]
	v_lshl_add_u64 v[116:117], v[116:117], 0, v[176:177]
	global_store_dwordx4 v[130:131], v[76:79], off nt
	v_cvt_pk_f16_f32 v108, v76, v77
	v_readlane_b32 s2, v253, 24
	v_mul_f32_e32 v77, v77, v77
	v_lshlrev_b64 v[110:111], 1, v[116:117]
	v_readlane_b32 s3, v253, 25
	v_fmac_f32_e32 v77, v76, v76
	v_mul_f32_e32 v76, v79, v79
	v_cvt_pk_f16_f32 v109, v78, v79
	v_lshl_add_u64 v[116:117], s[2:3], 0, v[110:111]
	v_fmac_f32_e32 v76, v78, v78
	s_waitcnt vmcnt(15)
	v_pk_fma_f32 v[74:75], v[74:75], 0.5, v[106:107] op_sel_hi:[1,0,1]
	v_pk_fma_f32 v[72:73], v[72:73], 0.5, v[104:105] op_sel_hi:[1,0,1]
	global_store_dwordx2 v[116:117], v[108:109], off
	v_add_f32_e32 v108, v77, v76
	global_store_dwordx4 v[130:131], v[72:75], off offset:64 nt
	v_cvt_pk_f16_f32 v76, v72, v73
	v_or_b32_e32 v78, 32, v110
	v_mul_f32_e32 v73, v73, v73
	v_fmac_f32_e32 v73, v72, v72
	v_mul_f32_e32 v72, v75, v75
	v_mov_b32_e32 v79, v111
	v_fmac_f32_e32 v72, v74, v74
	v_cvt_pk_f16_f32 v77, v74, v75
	v_lshl_add_u64 v[78:79], s[2:3], 0, v[78:79]
	v_add_f32_e32 v72, v73, v72
	s_waitcnt vmcnt(16)
	v_pk_fma_f32 v[70:71], v[70:71], 0.5, v[102:103] op_sel_hi:[1,0,1]
	v_pk_fma_f32 v[68:69], v[68:69], 0.5, v[100:101] op_sel_hi:[1,0,1]
	global_store_dwordx2 v[78:79], v[76:77], off
	v_add_f32_e32 v76, v108, v72
	global_store_dwordx4 v[130:131], v[68:71], off offset:512 nt
	v_cvt_pk_f16_f32 v72, v68, v69
	s_waitcnt vmcnt(17)
	v_pk_fma_f32 v[66:67], v[66:67], 0.5, v[98:99] op_sel_hi:[1,0,1]
	v_mul_f32_e32 v69, v69, v69
	v_fmac_f32_e32 v69, v68, v68
	v_mul_f32_e32 v68, v71, v71
	v_fmac_f32_e32 v68, v70, v70
	v_pk_fma_f32 v[64:65], v[64:65], 0.5, v[96:97] op_sel_hi:[1,0,1]
	v_cvt_pk_f16_f32 v73, v70, v71
	v_add_f32_e32 v68, v69, v68
	v_mul_f32_e32 v69, v65, v65
	v_mul_f32_e32 v70, v67, v67
	v_fmac_f32_e32 v69, v64, v64
	v_fmac_f32_e32 v70, v66, v66
	v_add_f32_e32 v68, v76, v68
	v_add_f32_e32 v69, v69, v70
	v_add_f32_e32 v70, v68, v69
	ds_bpermute_b32 v71, v163, v70
	v_or_b32_e32 v74, 0x100, v110
	v_mov_b32_e32 v75, v111
	v_lshl_add_u64 v[68:69], s[2:3], 0, v[74:75]
	global_store_dwordx2 v[68:69], v[72:73], off
	global_store_dwordx4 v[130:131], v[64:67], off offset:576 nt
	v_cvt_pk_f16_f32 v68, v64, v65
	v_or_b32_e32 v110, 0x120, v110
	s_waitcnt lgkmcnt(0)
	v_add_f32_e32 v64, v70, v71
	ds_bpermute_b32 v65, v162, v64
	v_cvt_pk_f16_f32 v69, v66, v67
	v_lshl_add_u64 v[66:67], s[2:3], 0, v[110:111]
	global_store_dwordx2 v[66:67], v[68:69], off
	s_and_saveexec_b64 s[2:3], s[6:7]
	s_cbranch_execz .LBB0_756
	s_waitcnt lgkmcnt(0)
	v_add_f32_e32 v66, v64, v65
	v_lshlrev_b64 v[64:65], 6, v[128:129]
	v_lshl_add_u64 v[64:65], s[46:47], 0, v[64:65]
	v_lshl_add_u64 v[64:65], s[18:19], 2, v[64:65]
	s_lshl_b32 s92, s38, 2
	v_lshl_add_u64 v[64:65], v[64:65], 0, s[92:93]
	global_store_dword v[64:65], v66, off
.LBB0_756:
	s_or_b64 exec, exec, s[2:3]
	v_or_b32_e32 v96, 16, v112
	v_ashrrev_i32_e32 v97, 31, v96
	s_waitcnt lgkmcnt(0)
	v_lshlrev_b64 v[64:65], 12, v[96:97]
	v_lshl_add_u64 v[98:99], v[178:179], 0, v[64:65]
	global_load_dwordx4 v[76:79], v[98:99], off
	global_load_dwordx4 v[72:75], v[98:99], off offset:64
	global_load_dwordx4 v[68:71], v[98:99], off offset:512
	global_load_dwordx4 v[64:67], v[98:99], off offset:576
	v_lshlrev_b64 v[100:101], 10, v[112:113]
	s_waitcnt vmcnt(15)
	v_pk_fma_f32 v[62:63], v[62:63], 0.5, v[94:95] op_sel_hi:[1,0,1]
	v_pk_fma_f32 v[60:61], v[60:61], 0.5, v[92:93] op_sel_hi:[1,0,1]
	v_lshl_add_u64 v[100:101], v[100:101], 0, v[176:177]
	global_store_dwordx4 v[114:115], v[60:63], off nt
	v_cvt_pk_f16_f32 v92, v60, v61
	v_readlane_b32 s2, v253, 24
	v_mul_f32_e32 v61, v61, v61
	v_lshlrev_b64 v[94:95], 1, v[100:101]
	v_readlane_b32 s3, v253, 25
	v_fmac_f32_e32 v61, v60, v60
	v_mul_f32_e32 v60, v63, v63
	v_cvt_pk_f16_f32 v93, v62, v63
	v_lshl_add_u64 v[100:101], s[2:3], 0, v[94:95]
	v_fmac_f32_e32 v60, v62, v62
	s_waitcnt vmcnt(15)
	v_pk_fma_f32 v[58:59], v[58:59], 0.5, v[90:91] op_sel_hi:[1,0,1]
	v_pk_fma_f32 v[56:57], v[56:57], 0.5, v[88:89] op_sel_hi:[1,0,1]
	global_store_dwordx2 v[100:101], v[92:93], off
	v_add_f32_e32 v92, v61, v60
	global_store_dwordx4 v[114:115], v[56:59], off offset:64 nt
	v_cvt_pk_f16_f32 v60, v56, v57
	v_or_b32_e32 v62, 32, v94
	v_mul_f32_e32 v57, v57, v57
	v_fmac_f32_e32 v57, v56, v56
	v_mul_f32_e32 v56, v59, v59
	v_mov_b32_e32 v63, v95
	v_fmac_f32_e32 v56, v58, v58
	v_cvt_pk_f16_f32 v61, v58, v59
	v_lshl_add_u64 v[62:63], s[2:3], 0, v[62:63]
	v_add_f32_e32 v56, v57, v56
	s_waitcnt vmcnt(16)
	v_pk_fma_f32 v[54:55], v[54:55], 0.5, v[86:87] op_sel_hi:[1,0,1]
	v_pk_fma_f32 v[52:53], v[52:53], 0.5, v[84:85] op_sel_hi:[1,0,1]
	global_store_dwordx2 v[62:63], v[60:61], off
	v_add_f32_e32 v60, v92, v56
	global_store_dwordx4 v[114:115], v[52:55], off offset:512 nt
	v_cvt_pk_f16_f32 v56, v52, v53
	s_waitcnt vmcnt(17)
	v_pk_fma_f32 v[50:51], v[50:51], 0.5, v[82:83] op_sel_hi:[1,0,1]
	v_mul_f32_e32 v53, v53, v53
	v_fmac_f32_e32 v53, v52, v52
	v_mul_f32_e32 v52, v55, v55
	v_fmac_f32_e32 v52, v54, v54
	v_pk_fma_f32 v[48:49], v[48:49], 0.5, v[80:81] op_sel_hi:[1,0,1]
	v_cvt_pk_f16_f32 v57, v54, v55
	v_add_f32_e32 v52, v53, v52
	v_mul_f32_e32 v53, v49, v49
	v_mul_f32_e32 v54, v51, v51
	v_fmac_f32_e32 v53, v48, v48
	v_fmac_f32_e32 v54, v50, v50
	v_add_f32_e32 v52, v60, v52
	v_add_f32_e32 v53, v53, v54
	v_add_f32_e32 v54, v52, v53
	ds_bpermute_b32 v55, v163, v54
	v_or_b32_e32 v58, 0x100, v94
	v_mov_b32_e32 v59, v95
	v_lshl_add_u64 v[52:53], s[2:3], 0, v[58:59]
	global_store_dwordx2 v[52:53], v[56:57], off
	global_store_dwordx4 v[114:115], v[48:51], off offset:576 nt
	v_cvt_pk_f16_f32 v52, v48, v49
	v_or_b32_e32 v94, 0x120, v94
	s_waitcnt lgkmcnt(0)
	v_add_f32_e32 v48, v54, v55
	ds_bpermute_b32 v49, v162, v48
	v_cvt_pk_f16_f32 v53, v50, v51
	v_lshl_add_u64 v[50:51], s[2:3], 0, v[94:95]
	global_store_dwordx2 v[50:51], v[52:53], off
	s_and_saveexec_b64 s[2:3], s[6:7]
	s_cbranch_execz .LBB0_758
	s_waitcnt lgkmcnt(0)
	v_add_f32_e32 v50, v48, v49
	v_lshlrev_b64 v[48:49], 6, v[112:113]
	v_lshl_add_u64 v[48:49], s[46:47], 0, v[48:49]
	v_lshl_add_u64 v[48:49], s[18:19], 2, v[48:49]
	s_lshl_b32 s92, s38, 2
	v_lshl_add_u64 v[48:49], v[48:49], 0, s[92:93]
	global_store_dword v[48:49], v50, off
;     __device__ __forceinline__ void operator()(const Acc& acc, const Unit& u, int wr, int wc, int fr, int fq) const {
;     ...
;         for (int i = 0; i < 8; ++i) {
;             const int ai = i >> 2, m = i & 3;
;             const int row = row0 + ai * HALF + m * 16; const size_t off = (size_t)row * D + col0; float sq = 0.f;
;             if (i + 1 < 8) { const size_t offn = (size_t)(row0 + ((i + 1) >> 2) * HALF + ((i + 1) & 3) * 16) * D + col0;
; #pragma unroll
;                 for (int k = 0; k < 4; ++k) rn[k] = *(const f32x4*)(res + offn + (k >> 1) * HALF + (k & 1) * 16); }
; #pragma unroll
;             for (int bj = 0; bj < 2; ++bj)
; #pragma unroll
;                 for (int n = 0; n < 2; ++n) { const size_t o = off + bj * HALF + n * 16; const f32x4 v = rc[bj * 2 + n] + acc[ai][bj][m][n] * alpha;
;                     *(f32x4*)(out + o) = v; u32x2 w; w.x = pk2h(v.x, v.y); w.y = pk2h(v.z, v.w); *(u32x2*)(o16 + o) = w; sq += (v.x * v.x + v.y * v.y) + (v.z * v.z + v.w * v.w); }
;             sq += __shfl_xor(sq, 16); sq += __shfl_xor(sq, 32);
;             if (fq == 0) ss[(size_t)row * 16 + u.pn * 4 + wc] = sq;
.LBB0_758:
	s_or_b64 exec, exec, s[2:3]
	v_or_b32_e32 v80, 32, v112
	v_ashrrev_i32_e32 v81, 31, v80
	s_waitcnt lgkmcnt(0)
	v_lshlrev_b64 v[48:49], 12, v[80:81]
	v_lshl_add_u64 v[82:83], v[178:179], 0, v[48:49]
	global_load_dwordx4 v[60:63], v[82:83], off
	global_load_dwordx4 v[56:59], v[82:83], off offset:64
	global_load_dwordx4 v[52:55], v[82:83], off offset:512
	global_load_dwordx4 v[48:51], v[82:83], off offset:576
	v_lshlrev_b64 v[84:85], 10, v[96:97]
	s_waitcnt vmcnt(15)
	v_pk_fma_f32 v[46:47], v[46:47], 0.5, v[78:79] op_sel_hi:[1,0,1]
	v_pk_fma_f32 v[44:45], v[44:45], 0.5, v[76:77] op_sel_hi:[1,0,1]
	v_lshl_add_u64 v[84:85], v[84:85], 0, v[176:177]
	global_store_dwordx4 v[98:99], v[44:47], off nt
	v_cvt_pk_f16_f32 v76, v44, v45
	v_readlane_b32 s2, v253, 24
	v_mul_f32_e32 v45, v45, v45
	v_lshlrev_b64 v[78:79], 1, v[84:85]
	v_readlane_b32 s3, v253, 25
	v_fmac_f32_e32 v45, v44, v44
	v_mul_f32_e32 v44, v47, v47
	v_cvt_pk_f16_f32 v77, v46, v47
	v_lshl_add_u64 v[84:85], s[2:3], 0, v[78:79]
	v_fmac_f32_e32 v44, v46, v46
	s_waitcnt vmcnt(15)
	v_pk_fma_f32 v[42:43], v[42:43], 0.5, v[74:75] op_sel_hi:[1,0,1]
	v_pk_fma_f32 v[40:41], v[40:41], 0.5, v[72:73] op_sel_hi:[1,0,1]
	global_store_dwordx2 v[84:85], v[76:77], off
	v_add_f32_e32 v76, v45, v44
	global_store_dwordx4 v[98:99], v[40:43], off offset:64 nt
	v_cvt_pk_f16_f32 v44, v40, v41
	v_or_b32_e32 v46, 32, v78
	v_mul_f32_e32 v41, v41, v41
	v_fmac_f32_e32 v41, v40, v40
	v_mul_f32_e32 v40, v43, v43
	v_mov_b32_e32 v47, v79
	v_fmac_f32_e32 v40, v42, v42
	v_cvt_pk_f16_f32 v45, v42, v43
	v_lshl_add_u64 v[46:47], s[2:3], 0, v[46:47]
	v_add_f32_e32 v40, v41, v40
	s_waitcnt vmcnt(16)
	v_pk_fma_f32 v[38:39], v[38:39], 0.5, v[70:71] op_sel_hi:[1,0,1]
	v_pk_fma_f32 v[36:37], v[36:37], 0.5, v[68:69] op_sel_hi:[1,0,1]
	global_store_dwordx2 v[46:47], v[44:45], off
	v_add_f32_e32 v44, v76, v40
	global_store_dwordx4 v[98:99], v[36:39], off offset:512 nt
	v_cvt_pk_f16_f32 v40, v36, v37
	s_waitcnt vmcnt(17)
	v_pk_fma_f32 v[34:35], v[34:35], 0.5, v[66:67] op_sel_hi:[1,0,1]
	v_mul_f32_e32 v37, v37, v37
	v_fmac_f32_e32 v37, v36, v36
	v_mul_f32_e32 v36, v39, v39
	v_fmac_f32_e32 v36, v38, v38
	v_pk_fma_f32 v[32:33], v[32:33], 0.5, v[64:65] op_sel_hi:[1,0,1]
	v_cvt_pk_f16_f32 v41, v38, v39
	v_add_f32_e32 v36, v37, v36
	v_mul_f32_e32 v37, v33, v33
	v_mul_f32_e32 v38, v35, v35
	v_fmac_f32_e32 v37, v32, v32
	v_fmac_f32_e32 v38, v34, v34
	v_add_f32_e32 v36, v44, v36
	v_add_f32_e32 v37, v37, v38
	v_add_f32_e32 v38, v36, v37
	ds_bpermute_b32 v39, v163, v38
	v_or_b32_e32 v42, 0x100, v78
	v_mov_b32_e32 v43, v79
	v_lshl_add_u64 v[36:37], s[2:3], 0, v[42:43]
	global_store_dwordx2 v[36:37], v[40:41], off
	global_store_dwordx4 v[98:99], v[32:35], off offset:576 nt
	v_cvt_pk_f16_f32 v36, v32, v33
	v_or_b32_e32 v78, 0x120, v78
	s_waitcnt lgkmcnt(0)
	v_add_f32_e32 v32, v38, v39
	ds_bpermute_b32 v33, v162, v32
	v_cvt_pk_f16_f32 v37, v34, v35
	v_lshl_add_u64 v[34:35], s[2:3], 0, v[78:79]
	global_store_dwordx2 v[34:35], v[36:37], off
	s_and_saveexec_b64 s[2:3], s[6:7]
	s_cbranch_execz .LBB0_760
	s_waitcnt lgkmcnt(0)
	v_add_f32_e32 v34, v32, v33
	v_lshlrev_b64 v[32:33], 6, v[96:97]
	v_lshl_add_u64 v[32:33], s[46:47], 0, v[32:33]
	v_lshl_add_u64 v[32:33], s[18:19], 2, v[32:33]
	s_lshl_b32 s92, s38, 2
	v_lshl_add_u64 v[32:33], v[32:33], 0, s[92:93]
	global_store_dword v[32:33], v34, off
;     __device__ __forceinline__ void operator()(const Acc& acc, const Unit& u, int wr, int wc, int fr, int fq) const {
;     ...
;         for (int i = 0; i < 8; ++i) {
;             const int ai = i >> 2, m = i & 3;
;             const int row = row0 + ai * HALF + m * 16; const size_t off = (size_t)row * D + col0; float sq = 0.f;
;             if (i + 1 < 8) { const size_t offn = (size_t)(row0 + ((i + 1) >> 2) * HALF + ((i + 1) & 3) * 16) * D + col0;
; #pragma unroll
;                 for (int k = 0; k < 4; ++k) rn[k] = *(const f32x4*)(res + offn + (k >> 1) * HALF + (k & 1) * 16); }
; #pragma unroll
;             for (int bj = 0; bj < 2; ++bj)
; #pragma unroll
;                 for (int n = 0; n < 2; ++n) { const size_t o = off + bj * HALF + n * 16; const f32x4 v = rc[bj * 2 + n] + acc[ai][bj][m][n] * alpha;
;                     *(f32x4*)(out + o) = v; u32x2 w; w.x = pk2h(v.x, v.y); w.y = pk2h(v.z, v.w); *(u32x2*)(o16 + o) = w; sq += (v.x * v.x + v.y * v.y) + (v.z * v.z + v.w * v.w); }
;             sq += __shfl_xor(sq, 16); sq += __shfl_xor(sq, 32);
;             if (fq == 0) ss[(size_t)row * 16 + u.pn * 4 + wc] = sq;
; #pragma unroll
;             for (int k = 0; k < 4; ++k) rc[k] = rn[k];
;         }
.LBB0_760:
	s_or_b64 exec, exec, s[2:3]
	v_or_b32_e32 v64, 48, v112
	v_ashrrev_i32_e32 v65, 31, v64
	s_waitcnt lgkmcnt(0)
	v_lshlrev_b64 v[32:33], 12, v[64:65]
	v_lshl_add_u64 v[66:67], v[178:179], 0, v[32:33]
	global_load_dwordx4 v[44:47], v[66:67], off
	global_load_dwordx4 v[40:43], v[66:67], off offset:64
	global_load_dwordx4 v[36:39], v[66:67], off offset:512
	global_load_dwordx4 v[32:35], v[66:67], off offset:576
	v_lshlrev_b64 v[68:69], 10, v[80:81]
	s_waitcnt vmcnt(15)
	v_pk_fma_f32 v[30:31], v[30:31], 0.5, v[62:63] op_sel_hi:[1,0,1]
	v_pk_fma_f32 v[28:29], v[28:29], 0.5, v[60:61] op_sel_hi:[1,0,1]
	v_lshl_add_u64 v[68:69], v[68:69], 0, v[176:177]
	global_store_dwordx4 v[82:83], v[28:31], off nt
	v_cvt_pk_f16_f32 v60, v28, v29
	v_readlane_b32 s2, v253, 24
	v_mul_f32_e32 v29, v29, v29
	v_lshlrev_b64 v[62:63], 1, v[68:69]
	v_readlane_b32 s3, v253, 25
	v_fmac_f32_e32 v29, v28, v28
	v_mul_f32_e32 v28, v31, v31
	v_cvt_pk_f16_f32 v61, v30, v31
	v_lshl_add_u64 v[68:69], s[2:3], 0, v[62:63]
	v_fmac_f32_e32 v28, v30, v30
	s_waitcnt vmcnt(15)
	v_pk_fma_f32 v[26:27], v[26:27], 0.5, v[58:59] op_sel_hi:[1,0,1]
	v_pk_fma_f32 v[24:25], v[24:25], 0.5, v[56:57] op_sel_hi:[1,0,1]
	global_store_dwordx2 v[68:69], v[60:61], off
	v_add_f32_e32 v60, v29, v28
	global_store_dwordx4 v[82:83], v[24:27], off offset:64 nt
	v_cvt_pk_f16_f32 v28, v24, v25
	v_or_b32_e32 v30, 32, v62
	v_mul_f32_e32 v25, v25, v25
	v_fmac_f32_e32 v25, v24, v24
	v_mul_f32_e32 v24, v27, v27
	v_mov_b32_e32 v31, v63
	v_fmac_f32_e32 v24, v26, v26
	v_cvt_pk_f16_f32 v29, v26, v27
	v_lshl_add_u64 v[30:31], s[2:3], 0, v[30:31]
	v_add_f32_e32 v24, v25, v24
	s_waitcnt vmcnt(16)
	v_pk_fma_f32 v[22:23], v[22:23], 0.5, v[54:55] op_sel_hi:[1,0,1]
	v_pk_fma_f32 v[20:21], v[20:21], 0.5, v[52:53] op_sel_hi:[1,0,1]
	global_store_dwordx2 v[30:31], v[28:29], off
	v_add_f32_e32 v28, v60, v24
	global_store_dwordx4 v[82:83], v[20:23], off offset:512 nt
	v_cvt_pk_f16_f32 v24, v20, v21
	s_waitcnt vmcnt(17)
	v_pk_fma_f32 v[18:19], v[18:19], 0.5, v[50:51] op_sel_hi:[1,0,1]
	v_mul_f32_e32 v21, v21, v21
	v_fmac_f32_e32 v21, v20, v20
	v_mul_f32_e32 v20, v23, v23
	v_fmac_f32_e32 v20, v22, v22
	v_pk_fma_f32 v[16:17], v[16:17], 0.5, v[48:49] op_sel_hi:[1,0,1]
	v_cvt_pk_f16_f32 v25, v22, v23
	v_add_f32_e32 v20, v21, v20
	v_mul_f32_e32 v21, v17, v17
	v_mul_f32_e32 v22, v19, v19
	v_fmac_f32_e32 v21, v16, v16
	v_fmac_f32_e32 v22, v18, v18
	v_add_f32_e32 v20, v28, v20
	v_add_f32_e32 v21, v21, v22
	v_add_f32_e32 v22, v20, v21
	ds_bpermute_b32 v23, v163, v22
	v_or_b32_e32 v26, 0x100, v62
	v_mov_b32_e32 v27, v63
	v_lshl_add_u64 v[20:21], s[2:3], 0, v[26:27]
	global_store_dwordx2 v[20:21], v[24:25], off
	global_store_dwordx4 v[82:83], v[16:19], off offset:576 nt
	v_cvt_pk_f16_f32 v20, v16, v17
	v_or_b32_e32 v62, 0x120, v62
	s_waitcnt lgkmcnt(0)
	v_add_f32_e32 v16, v22, v23
	ds_bpermute_b32 v17, v162, v16
	v_cvt_pk_f16_f32 v21, v18, v19
	v_lshl_add_u64 v[18:19], s[2:3], 0, v[62:63]
	global_store_dwordx2 v[18:19], v[20:21], off
	s_and_saveexec_b64 s[2:3], s[6:7]
	s_cbranch_execz .LBB0_762
	s_waitcnt lgkmcnt(0)
	v_add_f32_e32 v18, v16, v17
	v_lshlrev_b64 v[16:17], 6, v[80:81]
	v_lshl_add_u64 v[16:17], s[46:47], 0, v[16:17]
	v_lshl_add_u64 v[16:17], s[18:19], 2, v[16:17]
	s_lshl_b32 s92, s38, 2
	v_lshl_add_u64 v[16:17], v[16:17], 0, s[92:93]
	global_store_dword v[16:17], v18, off
.LBB0_762:
	s_or_b64 exec, exec, s[2:3]
	s_waitcnt lgkmcnt(0)
	v_lshlrev_b64 v[16:17], 10, v[64:65]
	s_waitcnt vmcnt(11)
	v_pk_fma_f32 v[14:15], v[14:15], 0.5, v[46:47] op_sel_hi:[1,0,1]
	v_pk_fma_f32 v[12:13], v[12:13], 0.5, v[44:45] op_sel_hi:[1,0,1]
	v_lshl_add_u64 v[16:17], v[16:17], 0, v[176:177]
	global_store_dwordx4 v[66:67], v[12:15], off nt
	v_cvt_pk_f16_f32 v18, v12, v13
	v_readlane_b32 s2, v253, 24
	v_mul_f32_e32 v13, v13, v13
	v_lshlrev_b64 v[16:17], 1, v[16:17]
	v_readlane_b32 s3, v253, 25
	v_fmac_f32_e32 v13, v12, v12
	v_mul_f32_e32 v12, v15, v15
	v_cvt_pk_f16_f32 v19, v14, v15
	v_lshl_add_u64 v[20:21], s[2:3], 0, v[16:17]
	v_fmac_f32_e32 v12, v14, v14
	s_waitcnt vmcnt(11)
	v_pk_fma_f32 v[10:11], v[10:11], 0.5, v[42:43] op_sel_hi:[1,0,1]
	v_pk_fma_f32 v[8:9], v[8:9], 0.5, v[40:41] op_sel_hi:[1,0,1]
	global_store_dwordx2 v[20:21], v[18:19], off
	v_add_f32_e32 v18, v13, v12
	global_store_dwordx4 v[66:67], v[8:11], off offset:64 nt
	v_cvt_pk_f16_f32 v12, v8, v9
	v_or_b32_e32 v14, 32, v16
	v_mul_f32_e32 v9, v9, v9
	v_fmac_f32_e32 v9, v8, v8
	v_mul_f32_e32 v8, v11, v11
	v_mov_b32_e32 v15, v17
	v_fmac_f32_e32 v8, v10, v10
	v_cvt_pk_f16_f32 v13, v10, v11
	v_lshl_add_u64 v[14:15], s[2:3], 0, v[14:15]
	v_add_f32_e32 v8, v9, v8
	s_waitcnt vmcnt(12)
	v_pk_fma_f32 v[6:7], v[6:7], 0.5, v[38:39] op_sel_hi:[1,0,1]
	v_pk_fma_f32 v[4:5], v[4:5], 0.5, v[36:37] op_sel_hi:[1,0,1]
	global_store_dwordx2 v[14:15], v[12:13], off
	v_add_f32_e32 v12, v18, v8
	global_store_dwordx4 v[66:67], v[4:7], off offset:512 nt
	v_cvt_pk_f16_f32 v8, v4, v5
	s_waitcnt vmcnt(13)
	v_pk_fma_f32 v[2:3], v[2:3], 0.5, v[34:35] op_sel_hi:[1,0,1]
	v_mul_f32_e32 v5, v5, v5
	v_fmac_f32_e32 v5, v4, v4
	v_mul_f32_e32 v4, v7, v7
	v_fmac_f32_e32 v4, v6, v6
	v_pk_fma_f32 v[0:1], v[0:1], 0.5, v[32:33] op_sel_hi:[1,0,1]
	v_cvt_pk_f16_f32 v9, v6, v7
	v_add_f32_e32 v4, v5, v4
	v_mul_f32_e32 v5, v1, v1
	v_mul_f32_e32 v6, v3, v3
	v_fmac_f32_e32 v5, v0, v0
	v_fmac_f32_e32 v6, v2, v2
	v_add_f32_e32 v4, v12, v4
	v_add_f32_e32 v5, v5, v6
	v_add_f32_e32 v6, v4, v5
	ds_bpermute_b32 v7, v163, v6
	v_or_b32_e32 v10, 0x100, v16
	v_mov_b32_e32 v11, v17
	v_lshl_add_u64 v[4:5], s[2:3], 0, v[10:11]
	global_store_dwordx2 v[4:5], v[8:9], off
	global_store_dwordx4 v[66:67], v[0:3], off offset:576 nt
	v_cvt_pk_f16_f32 v4, v0, v1
	v_or_b32_e32 v16, 0x120, v16
	s_waitcnt lgkmcnt(0)
	v_add_f32_e32 v0, v6, v7
	ds_bpermute_b32 v1, v162, v0
	v_cvt_pk_f16_f32 v5, v2, v3
	v_lshl_add_u64 v[2:3], s[2:3], 0, v[16:17]
	global_store_dwordx2 v[2:3], v[4:5], off
	s_and_saveexec_b64 s[2:3], s[6:7]
	s_cbranch_execz .LBB0_764
	s_waitcnt lgkmcnt(0)
	v_add_f32_e32 v2, v0, v1
	v_lshlrev_b64 v[0:1], 6, v[64:65]
	v_lshl_add_u64 v[0:1], s[46:47], 0, v[0:1]
	v_lshl_add_u64 v[0:1], s[18:19], 2, v[0:1]
	s_lshl_b32 s92, s38, 2
	v_lshl_add_u64 v[0:1], v[0:1], 0, s[92:93]
	global_store_dword v[0:1], v2, off

;     __device__ __forceinline__ void operator()(const Acc& acc, const Unit& u, int wr, int wc, int fr, int fq) const {
;         const int row0 = u.pm * BM + wr * 64 + fr, col0 = u.pn * BM + wc * 32 + 4 * fq;
;         const float* res = (u.pm * BM < MP) ? res_p : res_s;
;         f32x4 rc[4], rn[4];
; #pragma unroll
;         for (int k = 0; k < 4; ++k) rc[k] = *(const f32x4*)(res + (size_t)row0 * D + col0 + (k >> 1) * HALF + (k & 1) * 16);
; #pragma unroll
;         for (int i = 0; i < 8; ++i) {
;             const int ai = i >> 2, m = i & 3;
;             const int row = row0 + ai * HALF + m * 16; const size_t off = (size_t)row * D + col0; float sq = 0.f;
;             if (i + 1 < 8) { const size_t offn = (size_t)(row0 + ((i + 1) >> 2) * HALF + ((i + 1) & 3) * 16) * D + col0;
; #pragma unroll
;                 for (int k = 0; k < 4; ++k) rn[k] = *(const f32x4*)(res + offn + (k >> 1) * HALF + (k & 1) * 16); }
; #pragma unroll
;             for (int bj = 0; bj < 2; ++bj)
; #pragma unroll
;                 for (int n = 0; n < 2; ++n) { const size_t o = off + bj * HALF + n * 16; const f32x4 v = rc[bj * 2 + n] + acc[ai][bj][m][n] * alpha;
;                     *(f32x4*)(out + o) = v; u32x2 w; w.x = pk2h(v.x, v.y); w.y = pk2h(v.z, v.w); *(u32x2*)(o16 + o) = w; sq += (v.x * v.x + v.y * v.y) + (v.z * v.z + v.w * v.w); }
;             sq += __shfl_xor(sq, 16); sq += __shfl_xor(sq, 32);
;             if (fq == 0) ss[(size_t)row * 16 + u.pn * 4 + wc] = sq;
.LBB0_797:
	v_lshl_add_u32 v180, s43, 8, v188
	v_lshl_or_b32 v176, s42, 8, v190
	v_ashrrev_i32_e32 v181, 31, v180
	v_readlane_b32 s52, v248, 48
	v_lshlrev_b64 v[128:129], 12, v[180:181]
	v_readlane_b32 s66, v248, 62
	v_readlane_b32 s67, v248, 63
	v_ashrrev_i32_e32 v177, 31, v176
	v_lshlrev_b64 v[130:131], 2, v[176:177]
	v_lshl_add_u64 v[128:129], s[66:67], 0, v[128:129]
	v_lshl_add_u64 v[186:187], v[128:129], 0, v[130:131]
	global_load_dwordx4 v[154:157], v[186:187], off
	global_load_dwordx4 v[164:167], v[186:187], off offset:64
	global_load_dwordx4 v[148:151], v[186:187], off offset:512
	global_load_dwordx4 v[144:147], v[186:187], off offset:576
	v_and_b32_e32 v129, 64, v203
	v_xor_b32_e32 v128, 16, v203
	v_add_u32_e32 v129, 64, v129
	v_cmp_lt_i32_e32 vcc, v128, v129
	v_or_b32_e32 v182, 16, v180
	v_ashrrev_i32_e32 v183, 31, v182
	v_cndmask_b32_e32 v128, v203, v128, vcc
	v_lshlrev_b32_e32 v163, 2, v128
	v_xor_b32_e32 v128, 32, v203
	v_cmp_lt_i32_e32 vcc, v128, v129
	v_lshl_add_u64 v[178:179], s[66:67], 0, v[130:131]
	v_readlane_b32 s48, v254, 12
	v_cndmask_b32_e32 v128, v203, v128, vcc
	v_lshlrev_b32_e32 v162, 2, v128
	v_lshlrev_b64 v[128:129], 10, v[180:181]
	v_lshl_add_u64 v[192:193], v[128:129], 0, v[176:177]
	v_lshlrev_b64 v[128:129], 12, v[182:183]
	v_lshl_add_u64 v[184:185], v[178:179], 0, v[128:129]
	global_load_dwordx4 v[140:143], v[184:185], off
	global_load_dwordx4 v[136:139], v[184:185], off offset:64
	global_load_dwordx4 v[132:135], v[184:185], off offset:512
	global_load_dwordx4 v[128:131], v[184:185], off offset:576
	v_readlane_b32 s49, v254, 13
	s_lshl_b32 s22, s42, 2
	s_ashr_i32 s23, s22, 31
	v_readlane_b32 s53, v248, 49
	v_readlane_b32 s54, v248, 50
	v_readlane_b32 s55, v248, 51
	v_readlane_b32 s56, v248, 52
	v_readlane_b32 s57, v248, 53
	v_readlane_b32 s58, v248, 54
	v_readlane_b32 s59, v248, 55
	v_readlane_b32 s60, v248, 56
	v_readlane_b32 s61, v248, 57
	v_readlane_b32 s62, v248, 58
	v_readlane_b32 s63, v248, 59
	v_readlane_b32 s64, v248, 60
	v_readlane_b32 s65, v248, 61
	s_waitcnt vmcnt(0)
	v_pk_add_f32 v[126:127], v[126:127], v[156:157]
	v_pk_add_f32 v[124:125], v[124:125], v[154:155]
	global_store_dwordx4 v[186:187], v[124:127], off nt
	v_cvt_pk_f16_f32 v154, v124, v125
	v_lshlrev_b64 v[156:157], 1, v[192:193]
	v_mul_f32_e32 v125, v125, v125
	v_fmac_f32_e32 v125, v124, v124
	v_mul_f32_e32 v124, v127, v127
	v_cvt_pk_f16_f32 v155, v126, v127
	v_lshl_add_u64 v[192:193], s[48:49], 0, v[156:157]
	v_fmac_f32_e32 v124, v126, v126
	v_pk_add_f32 v[122:123], v[122:123], v[166:167]
	v_pk_add_f32 v[120:121], v[120:121], v[164:165]
	global_store_dwordx2 v[192:193], v[154:155], off
	v_add_f32_e32 v154, v125, v124
	global_store_dwordx4 v[186:187], v[120:123], off offset:64 nt
	v_cvt_pk_f16_f32 v124, v120, v121
	v_or_b32_e32 v126, 32, v156
	v_mul_f32_e32 v121, v121, v121
	v_fmac_f32_e32 v121, v120, v120
	v_mul_f32_e32 v120, v123, v123
	v_mov_b32_e32 v127, v157
	v_fmac_f32_e32 v120, v122, v122
	v_cvt_pk_f16_f32 v125, v122, v123
	v_lshl_add_u64 v[126:127], s[48:49], 0, v[126:127]
	v_add_f32_e32 v120, v121, v120
	v_pk_add_f32 v[118:119], v[118:119], v[150:151]
	v_pk_add_f32 v[116:117], v[116:117], v[148:149]
	global_store_dwordx2 v[126:127], v[124:125], off
	v_add_f32_e32 v124, v154, v120
	global_store_dwordx4 v[186:187], v[116:119], off offset:512 nt
	v_cvt_pk_f16_f32 v120, v116, v117
	v_or_b32_e32 v122, 0x100, v156
	v_mul_f32_e32 v117, v117, v117
	v_fmac_f32_e32 v117, v116, v116
	v_mul_f32_e32 v116, v119, v119
	v_mov_b32_e32 v123, v157
	v_fmac_f32_e32 v116, v118, v118
	v_cvt_pk_f16_f32 v121, v118, v119
	v_lshl_add_u64 v[122:123], s[48:49], 0, v[122:123]
	v_add_f32_e32 v116, v117, v116
	v_pk_add_f32 v[114:115], v[114:115], v[146:147]
	v_pk_add_f32 v[112:113], v[112:113], v[144:145]
	global_store_dwordx2 v[122:123], v[120:121], off
	v_add_f32_e32 v120, v124, v116
	global_store_dwordx4 v[186:187], v[112:115], off offset:576 nt
	v_cvt_pk_f16_f32 v116, v112, v113
	v_or_b32_e32 v156, 0x120, v156
	v_mul_f32_e32 v113, v113, v113
	v_fmac_f32_e32 v113, v112, v112
	v_mul_f32_e32 v112, v115, v115
	v_fmac_f32_e32 v112, v114, v114
	v_add_f32_e32 v112, v113, v112
	v_add_f32_e32 v112, v120, v112
	ds_bpermute_b32 v113, v163, v112
	v_cvt_pk_f16_f32 v117, v114, v115
	v_lshl_add_u64 v[118:119], s[48:49], 0, v[156:157]
	global_store_dwordx2 v[118:119], v[116:117], off
	s_waitcnt lgkmcnt(0)
	v_add_f32_e32 v112, v112, v113
	ds_bpermute_b32 v113, v162, v112
	s_and_saveexec_b64 s[2:3], s[6:7]
	v_readlane_b32 s46, v254, 16
	v_readlane_b32 s47, v254, 17
	s_cbranch_execz .LBB0_799
	s_waitcnt lgkmcnt(0)
	v_add_f32_e32 v114, v112, v113
	v_lshlrev_b64 v[112:113], 6, v[180:181]
	v_lshl_add_u64 v[112:113], s[46:47], 0, v[112:113]
	v_lshl_add_u64 v[112:113], s[22:23], 2, v[112:113]
	s_lshl_b32 s92, s40, 2
	v_lshl_add_u64 v[112:113], v[112:113], 0, s[92:93]
	global_store_dword v[112:113], v114, off
;     __device__ __forceinline__ void operator()(const Acc& acc, const Unit& u, int wr, int wc, int fr, int fq) const {
;     ...
;         for (int i = 0; i < 8; ++i) {
;             const int ai = i >> 2, m = i & 3;
;             const int row = row0 + ai * HALF + m * 16; const size_t off = (size_t)row * D + col0; float sq = 0.f;
;             if (i + 1 < 8) { const size_t offn = (size_t)(row0 + ((i + 1) >> 2) * HALF + ((i + 1) & 3) * 16) * D + col0;
; #pragma unroll
;                 for (int k = 0; k < 4; ++k) rn[k] = *(const f32x4*)(res + offn + (k >> 1) * HALF + (k & 1) * 16); }
; #pragma unroll
;             for (int bj = 0; bj < 2; ++bj)
; #pragma unroll
;                 for (int n = 0; n < 2; ++n) { const size_t o = off + bj * HALF + n * 16; const f32x4 v = rc[bj * 2 + n] + acc[ai][bj][m][n] * alpha;
;                     *(f32x4*)(out + o) = v; u32x2 w; w.x = pk2h(v.x, v.y); w.y = pk2h(v.z, v.w); *(u32x2*)(o16 + o) = w; sq += (v.x * v.x + v.y * v.y) + (v.z * v.z + v.w * v.w); }
;             sq += __shfl_xor(sq, 16); sq += __shfl_xor(sq, 32);
;             if (fq == 0) ss[(size_t)row * 16 + u.pn * 4 + wc] = sq;
.LBB0_799:
	s_or_b64 exec, exec, s[2:3]
	v_or_b32_e32 v144, 32, v180
	v_ashrrev_i32_e32 v145, 31, v144
	s_waitcnt lgkmcnt(0)
	v_lshlrev_b64 v[112:113], 12, v[144:145]
	v_lshl_add_u64 v[146:147], v[178:179], 0, v[112:113]
	global_load_dwordx4 v[124:127], v[146:147], off
	global_load_dwordx4 v[120:123], v[146:147], off offset:64
	global_load_dwordx4 v[116:119], v[146:147], off offset:512
	global_load_dwordx4 v[112:115], v[146:147], off offset:576
	v_lshlrev_b64 v[148:149], 10, v[182:183]
	v_pk_add_f32 v[110:111], v[110:111], v[142:143]
	v_pk_add_f32 v[108:109], v[108:109], v[140:141]
	v_lshl_add_u64 v[148:149], v[148:149], 0, v[176:177]
	global_store_dwordx4 v[184:185], v[108:111], off nt
	v_cvt_pk_f16_f32 v140, v108, v109
	v_lshlrev_b64 v[142:143], 1, v[148:149]
	v_mul_f32_e32 v109, v109, v109
	v_fmac_f32_e32 v109, v108, v108
	v_mul_f32_e32 v108, v111, v111
	v_cvt_pk_f16_f32 v141, v110, v111
	v_lshl_add_u64 v[148:149], s[48:49], 0, v[142:143]
	v_fmac_f32_e32 v108, v110, v110
	v_pk_add_f32 v[106:107], v[106:107], v[138:139]
	v_pk_add_f32 v[104:105], v[104:105], v[136:137]
	global_store_dwordx2 v[148:149], v[140:141], off
	v_add_f32_e32 v140, v109, v108
	global_store_dwordx4 v[184:185], v[104:107], off offset:64 nt
	v_cvt_pk_f16_f32 v108, v104, v105
	v_or_b32_e32 v110, 32, v142
	v_mul_f32_e32 v105, v105, v105
	v_fmac_f32_e32 v105, v104, v104
	v_mul_f32_e32 v104, v107, v107
	v_mov_b32_e32 v111, v143
	v_fmac_f32_e32 v104, v106, v106
	v_cvt_pk_f16_f32 v109, v106, v107
	v_lshl_add_u64 v[110:111], s[48:49], 0, v[110:111]
	v_add_f32_e32 v104, v105, v104
	v_pk_add_f32 v[102:103], v[102:103], v[134:135]
	v_pk_add_f32 v[100:101], v[100:101], v[132:133]
	global_store_dwordx2 v[110:111], v[108:109], off
	v_add_f32_e32 v108, v140, v104
	global_store_dwordx4 v[184:185], v[100:103], off offset:512 nt
	v_cvt_pk_f16_f32 v104, v100, v101
	v_pk_add_f32 v[98:99], v[98:99], v[130:131]
	v_mul_f32_e32 v101, v101, v101
	v_fmac_f32_e32 v101, v100, v100
	v_mul_f32_e32 v100, v103, v103
	v_fmac_f32_e32 v100, v102, v102
	v_pk_add_f32 v[96:97], v[96:97], v[128:129]
	v_cvt_pk_f16_f32 v105, v102, v103
	v_add_f32_e32 v100, v101, v100
	v_mul_f32_e32 v101, v97, v97
	v_mul_f32_e32 v102, v99, v99
	v_fmac_f32_e32 v101, v96, v96
	v_fmac_f32_e32 v102, v98, v98
	v_add_f32_e32 v100, v108, v100
	v_add_f32_e32 v101, v101, v102
	v_add_f32_e32 v102, v100, v101
	ds_bpermute_b32 v103, v163, v102
	v_or_b32_e32 v106, 0x100, v142
	v_mov_b32_e32 v107, v143
	v_lshl_add_u64 v[100:101], s[48:49], 0, v[106:107]
	global_store_dwordx2 v[100:101], v[104:105], off
	global_store_dwordx4 v[184:185], v[96:99], off offset:576 nt
	v_cvt_pk_f16_f32 v100, v96, v97
	v_or_b32_e32 v142, 0x120, v142
	s_waitcnt lgkmcnt(0)
	v_add_f32_e32 v96, v102, v103
	ds_bpermute_b32 v97, v162, v96
	v_cvt_pk_f16_f32 v101, v98, v99
	v_lshl_add_u64 v[98:99], s[48:49], 0, v[142:143]
	global_store_dwordx2 v[98:99], v[100:101], off
	s_and_saveexec_b64 s[2:3], s[6:7]
	s_cbranch_execz .LBB0_801
	s_waitcnt lgkmcnt(0)
	v_add_f32_e32 v98, v96, v97
	v_lshlrev_b64 v[96:97], 6, v[182:183]
	v_lshl_add_u64 v[96:97], s[46:47], 0, v[96:97]
	v_lshl_add_u64 v[96:97], s[22:23], 2, v[96:97]
	s_lshl_b32 s92, s40, 2
	v_lshl_add_u64 v[96:97], v[96:97], 0, s[92:93]
	global_store_dword v[96:97], v98, off
.LBB0_801:
	s_or_b64 exec, exec, s[2:3]
	v_or_b32_e32 v128, 48, v180
	v_ashrrev_i32_e32 v129, 31, v128
	s_waitcnt lgkmcnt(0)
	v_lshlrev_b64 v[96:97], 12, v[128:129]
	v_lshl_add_u64 v[130:131], v[178:179], 0, v[96:97]
	global_load_dwordx4 v[108:111], v[130:131], off
	global_load_dwordx4 v[104:107], v[130:131], off offset:64
	global_load_dwordx4 v[100:103], v[130:131], off offset:512
	global_load_dwordx4 v[96:99], v[130:131], off offset:576
	v_lshlrev_b64 v[132:133], 10, v[144:145]
	s_waitcnt vmcnt(15)
	v_pk_add_f32 v[94:95], v[94:95], v[126:127]
	v_pk_add_f32 v[92:93], v[92:93], v[124:125]
	v_lshl_add_u64 v[132:133], v[132:133], 0, v[176:177]
	global_store_dwordx4 v[146:147], v[92:95], off nt
	v_cvt_pk_f16_f32 v124, v92, v93
	v_lshlrev_b64 v[126:127], 1, v[132:133]
	v_mul_f32_e32 v93, v93, v93
	v_fmac_f32_e32 v93, v92, v92
	v_mul_f32_e32 v92, v95, v95
	v_cvt_pk_f16_f32 v125, v94, v95
	v_lshl_add_u64 v[132:133], s[48:49], 0, v[126:127]
	v_fmac_f32_e32 v92, v94, v94
	s_waitcnt vmcnt(15)
	v_pk_add_f32 v[90:91], v[90:91], v[122:123]
	v_pk_add_f32 v[88:89], v[88:89], v[120:121]
	global_store_dwordx2 v[132:133], v[124:125], off
	v_add_f32_e32 v124, v93, v92
	global_store_dwordx4 v[146:147], v[88:91], off offset:64 nt
	v_cvt_pk_f16_f32 v92, v88, v89
	v_or_b32_e32 v94, 32, v126
	v_mul_f32_e32 v89, v89, v89
	v_fmac_f32_e32 v89, v88, v88
	v_mul_f32_e32 v88, v91, v91
	v_mov_b32_e32 v95, v127
	v_fmac_f32_e32 v88, v90, v90
	v_cvt_pk_f16_f32 v93, v90, v91
	v_lshl_add_u64 v[94:95], s[48:49], 0, v[94:95]
	v_add_f32_e32 v88, v89, v88
	s_waitcnt vmcnt(16)
	v_pk_add_f32 v[86:87], v[86:87], v[118:119]
	v_pk_add_f32 v[84:85], v[84:85], v[116:117]
	global_store_dwordx2 v[94:95], v[92:93], off
	v_add_f32_e32 v92, v124, v88
	global_store_dwordx4 v[146:147], v[84:87], off offset:512 nt
	v_cvt_pk_f16_f32 v88, v84, v85
	s_waitcnt vmcnt(17)
	v_pk_add_f32 v[82:83], v[82:83], v[114:115]
	v_mul_f32_e32 v85, v85, v85
	v_fmac_f32_e32 v85, v84, v84
	v_mul_f32_e32 v84, v87, v87
	v_fmac_f32_e32 v84, v86, v86
	v_pk_add_f32 v[80:81], v[80:81], v[112:113]
	v_cvt_pk_f16_f32 v89, v86, v87
	v_add_f32_e32 v84, v85, v84
	v_mul_f32_e32 v85, v81, v81
	v_mul_f32_e32 v86, v83, v83
	v_fmac_f32_e32 v85, v80, v80
	v_fmac_f32_e32 v86, v82, v82
	v_add_f32_e32 v84, v92, v84
	v_add_f32_e32 v85, v85, v86
	v_add_f32_e32 v86, v84, v85
	ds_bpermute_b32 v87, v163, v86
	v_or_b32_e32 v90, 0x100, v126
	v_mov_b32_e32 v91, v127
	v_lshl_add_u64 v[84:85], s[48:49], 0, v[90:91]
	global_store_dwordx2 v[84:85], v[88:89], off
	global_store_dwordx4 v[146:147], v[80:83], off offset:576 nt
	v_cvt_pk_f16_f32 v84, v80, v81
	v_or_b32_e32 v126, 0x120, v126
	s_waitcnt lgkmcnt(0)
	v_add_f32_e32 v80, v86, v87
	ds_bpermute_b32 v81, v162, v80
	v_cvt_pk_f16_f32 v85, v82, v83
	v_lshl_add_u64 v[82:83], s[48:49], 0, v[126:127]
	global_store_dwordx2 v[82:83], v[84:85], off
	s_mov_b64 s[2:3], exec
	v_mov_b64_e32 v[154:155], v[158:159]
	s_and_b64 s[24:25], s[2:3], s[6:7]
	v_mov_b64_e32 v[156:157], v[160:161]
	s_mov_b64 exec, s[24:25]
	s_cbranch_execz .LBB0_803
	s_waitcnt lgkmcnt(0)
	v_add_f32_e32 v82, v80, v81
	v_lshlrev_b64 v[80:81], 6, v[144:145]
	v_lshl_add_u64 v[80:81], s[46:47], 0, v[80:81]
	v_lshl_add_u64 v[80:81], s[22:23], 2, v[80:81]
	s_lshl_b32 s92, s40, 2
	v_lshl_add_u64 v[80:81], v[80:81], 0, s[92:93]
	global_store_dword v[80:81], v82, off
;     __device__ __forceinline__ void operator()(const Acc& acc, const Unit& u, int wr, int wc, int fr, int fq) const {
;     ...
;         for (int i = 0; i < 8; ++i) {
;             const int ai = i >> 2, m = i & 3;
;             const int row = row0 + ai * HALF + m * 16; const size_t off = (size_t)row * D + col0; float sq = 0.f;
;             if (i + 1 < 8) { const size_t offn = (size_t)(row0 + ((i + 1) >> 2) * HALF + ((i + 1) & 3) * 16) * D + col0;
; #pragma unroll
;                 for (int k = 0; k < 4; ++k) rn[k] = *(const f32x4*)(res + offn + (k >> 1) * HALF + (k & 1) * 16); }
; #pragma unroll
;             for (int bj = 0; bj < 2; ++bj)
; #pragma unroll
;                 for (int n = 0; n < 2; ++n) { const size_t o = off + bj * HALF + n * 16; const f32x4 v = rc[bj * 2 + n] + acc[ai][bj][m][n] * alpha;
;                     *(f32x4*)(out + o) = v; u32x2 w; w.x = pk2h(v.x, v.y); w.y = pk2h(v.z, v.w); *(u32x2*)(o16 + o) = w; sq += (v.x * v.x + v.y * v.y) + (v.z * v.z + v.w * v.w); }
;             sq += __shfl_xor(sq, 16); sq += __shfl_xor(sq, 32);
;             if (fq == 0) ss[(size_t)row * 16 + u.pn * 4 + wc] = sq;
.LBB0_803:
	s_or_b64 exec, exec, s[2:3]
	v_add_u32_e32 v112, 0x80, v180
	v_ashrrev_i32_e32 v113, 31, v112
	s_waitcnt lgkmcnt(0)
	v_lshlrev_b64 v[80:81], 12, v[112:113]
	v_lshl_add_u64 v[114:115], v[178:179], 0, v[80:81]
	global_load_dwordx4 v[92:95], v[114:115], off
	global_load_dwordx4 v[88:91], v[114:115], off offset:64
	global_load_dwordx4 v[84:87], v[114:115], off offset:512
	global_load_dwordx4 v[80:83], v[114:115], off offset:576
	v_lshlrev_b64 v[116:117], 10, v[128:129]
	s_waitcnt vmcnt(15)
	v_pk_add_f32 v[78:79], v[78:79], v[110:111]
	v_pk_add_f32 v[76:77], v[76:77], v[108:109]
	v_lshl_add_u64 v[116:117], v[116:117], 0, v[176:177]
	global_store_dwordx4 v[130:131], v[76:79], off nt
	v_cvt_pk_f16_f32 v108, v76, v77
	v_lshlrev_b64 v[110:111], 1, v[116:117]
	v_mul_f32_e32 v77, v77, v77
	v_fmac_f32_e32 v77, v76, v76
	v_mul_f32_e32 v76, v79, v79
	v_cvt_pk_f16_f32 v109, v78, v79
	v_lshl_add_u64 v[116:117], s[48:49], 0, v[110:111]
	v_fmac_f32_e32 v76, v78, v78
	s_waitcnt vmcnt(15)
	v_pk_add_f32 v[74:75], v[74:75], v[106:107]
	v_pk_add_f32 v[72:73], v[72:73], v[104:105]
	global_store_dwordx2 v[116:117], v[108:109], off
	v_add_f32_e32 v108, v77, v76
	global_store_dwordx4 v[130:131], v[72:75], off offset:64 nt
	v_cvt_pk_f16_f32 v76, v72, v73
	v_or_b32_e32 v78, 32, v110
	v_mul_f32_e32 v73, v73, v73
	v_fmac_f32_e32 v73, v72, v72
	v_mul_f32_e32 v72, v75, v75
	v_mov_b32_e32 v79, v111
	v_fmac_f32_e32 v72, v74, v74
	v_cvt_pk_f16_f32 v77, v74, v75
	v_lshl_add_u64 v[78:79], s[48:49], 0, v[78:79]
	v_add_f32_e32 v72, v73, v72
	s_waitcnt vmcnt(16)
	v_pk_add_f32 v[70:71], v[70:71], v[102:103]
	v_pk_add_f32 v[68:69], v[68:69], v[100:101]
	global_store_dwordx2 v[78:79], v[76:77], off
	v_add_f32_e32 v76, v108, v72
	global_store_dwordx4 v[130:131], v[68:71], off offset:512 nt
	v_cvt_pk_f16_f32 v72, v68, v69
	s_waitcnt vmcnt(17)
	v_pk_add_f32 v[66:67], v[66:67], v[98:99]
	v_mul_f32_e32 v69, v69, v69
	v_fmac_f32_e32 v69, v68, v68
	v_mul_f32_e32 v68, v71, v71
	v_fmac_f32_e32 v68, v70, v70
	v_pk_add_f32 v[64:65], v[64:65], v[96:97]
	v_cvt_pk_f16_f32 v73, v70, v71
	v_add_f32_e32 v68, v69, v68
	v_mul_f32_e32 v69, v65, v65
	v_mul_f32_e32 v70, v67, v67
	v_fmac_f32_e32 v69, v64, v64
	v_fmac_f32_e32 v70, v66, v66
	v_add_f32_e32 v68, v76, v68
	v_add_f32_e32 v69, v69, v70
	v_add_f32_e32 v70, v68, v69
	ds_bpermute_b32 v71, v163, v70
	v_or_b32_e32 v74, 0x100, v110
	v_mov_b32_e32 v75, v111
	v_lshl_add_u64 v[68:69], s[48:49], 0, v[74:75]
	global_store_dwordx2 v[68:69], v[72:73], off
	global_store_dwordx4 v[130:131], v[64:67], off offset:576 nt
	v_cvt_pk_f16_f32 v68, v64, v65
	v_or_b32_e32 v110, 0x120, v110
	s_waitcnt lgkmcnt(0)
	v_add_f32_e32 v64, v70, v71
	ds_bpermute_b32 v65, v162, v64
	v_cvt_pk_f16_f32 v69, v66, v67
	v_lshl_add_u64 v[66:67], s[48:49], 0, v[110:111]
	global_store_dwordx2 v[66:67], v[68:69], off
	s_and_saveexec_b64 s[2:3], s[6:7]
	s_cbranch_execz .LBB0_805
	s_waitcnt lgkmcnt(0)
	v_add_f32_e32 v66, v64, v65
	v_lshlrev_b64 v[64:65], 6, v[128:129]
	v_lshl_add_u64 v[64:65], s[46:47], 0, v[64:65]
	v_lshl_add_u64 v[64:65], s[22:23], 2, v[64:65]
	s_lshl_b32 s92, s40, 2
	v_lshl_add_u64 v[64:65], v[64:65], 0, s[92:93]
	global_store_dword v[64:65], v66, off
.LBB0_805:
	s_or_b64 exec, exec, s[2:3]
	v_or_b32_e32 v96, 16, v112
	v_ashrrev_i32_e32 v97, 31, v96
	s_waitcnt lgkmcnt(0)
	v_lshlrev_b64 v[64:65], 12, v[96:97]
	v_lshl_add_u64 v[98:99], v[178:179], 0, v[64:65]
	global_load_dwordx4 v[76:79], v[98:99], off
	global_load_dwordx4 v[72:75], v[98:99], off offset:64
	global_load_dwordx4 v[68:71], v[98:99], off offset:512
	global_load_dwordx4 v[64:67], v[98:99], off offset:576
	v_lshlrev_b64 v[100:101], 10, v[112:113]
	s_waitcnt vmcnt(15)
	v_pk_add_f32 v[62:63], v[62:63], v[94:95]
	v_pk_add_f32 v[60:61], v[60:61], v[92:93]
	v_lshl_add_u64 v[100:101], v[100:101], 0, v[176:177]
	global_store_dwordx4 v[114:115], v[60:63], off nt
	v_cvt_pk_f16_f32 v92, v60, v61
	v_lshlrev_b64 v[94:95], 1, v[100:101]
	v_mul_f32_e32 v61, v61, v61
	v_fmac_f32_e32 v61, v60, v60
	v_mul_f32_e32 v60, v63, v63
	v_cvt_pk_f16_f32 v93, v62, v63
	v_lshl_add_u64 v[100:101], s[48:49], 0, v[94:95]
	v_fmac_f32_e32 v60, v62, v62
	s_waitcnt vmcnt(15)
	v_pk_add_f32 v[58:59], v[58:59], v[90:91]
	v_pk_add_f32 v[56:57], v[56:57], v[88:89]
	global_store_dwordx2 v[100:101], v[92:93], off
	v_add_f32_e32 v92, v61, v60
	global_store_dwordx4 v[114:115], v[56:59], off offset:64 nt
	v_cvt_pk_f16_f32 v60, v56, v57
	v_or_b32_e32 v62, 32, v94
	v_mul_f32_e32 v57, v57, v57
	v_fmac_f32_e32 v57, v56, v56
	v_mul_f32_e32 v56, v59, v59
	v_mov_b32_e32 v63, v95
	v_fmac_f32_e32 v56, v58, v58
	v_cvt_pk_f16_f32 v61, v58, v59
	v_lshl_add_u64 v[62:63], s[48:49], 0, v[62:63]
	v_add_f32_e32 v56, v57, v56
	s_waitcnt vmcnt(16)
	v_pk_add_f32 v[54:55], v[54:55], v[86:87]
	v_pk_add_f32 v[52:53], v[52:53], v[84:85]
	global_store_dwordx2 v[62:63], v[60:61], off
	v_add_f32_e32 v60, v92, v56
	global_store_dwordx4 v[114:115], v[52:55], off offset:512 nt
	v_cvt_pk_f16_f32 v56, v52, v53
	s_waitcnt vmcnt(17)
	v_pk_add_f32 v[50:51], v[50:51], v[82:83]
	v_mul_f32_e32 v53, v53, v53
	v_fmac_f32_e32 v53, v52, v52
	v_mul_f32_e32 v52, v55, v55
	v_fmac_f32_e32 v52, v54, v54
	v_pk_add_f32 v[48:49], v[48:49], v[80:81]
	v_cvt_pk_f16_f32 v57, v54, v55
	v_add_f32_e32 v52, v53, v52
	v_mul_f32_e32 v53, v49, v49
	v_mul_f32_e32 v54, v51, v51
	v_fmac_f32_e32 v53, v48, v48
	v_fmac_f32_e32 v54, v50, v50
	v_add_f32_e32 v52, v60, v52
	v_add_f32_e32 v53, v53, v54
	v_add_f32_e32 v54, v52, v53
	ds_bpermute_b32 v55, v163, v54
	v_or_b32_e32 v58, 0x100, v94
	v_mov_b32_e32 v59, v95
	v_lshl_add_u64 v[52:53], s[48:49], 0, v[58:59]
	global_store_dwordx2 v[52:53], v[56:57], off
	global_store_dwordx4 v[114:115], v[48:51], off offset:576 nt
	v_cvt_pk_f16_f32 v52, v48, v49
	v_or_b32_e32 v94, 0x120, v94
	s_waitcnt lgkmcnt(0)
	v_add_f32_e32 v48, v54, v55
	ds_bpermute_b32 v49, v162, v48
	v_cvt_pk_f16_f32 v53, v50, v51
	v_lshl_add_u64 v[50:51], s[48:49], 0, v[94:95]
	global_store_dwordx2 v[50:51], v[52:53], off
	s_and_saveexec_b64 s[2:3], s[6:7]
	s_cbranch_execz .LBB0_807
	s_waitcnt lgkmcnt(0)
	v_add_f32_e32 v50, v48, v49
	v_lshlrev_b64 v[48:49], 6, v[112:113]
	v_lshl_add_u64 v[48:49], s[46:47], 0, v[48:49]
	v_lshl_add_u64 v[48:49], s[22:23], 2, v[48:49]
	s_lshl_b32 s92, s40, 2
	v_lshl_add_u64 v[48:49], v[48:49], 0, s[92:93]
	global_store_dword v[48:49], v50, off
;     __device__ __forceinline__ void operator()(const Acc& acc, const Unit& u, int wr, int wc, int fr, int fq) const {
;     ...
;         for (int i = 0; i < 8; ++i) {
;             const int ai = i >> 2, m = i & 3;
;             const int row = row0 + ai * HALF + m * 16; const size_t off = (size_t)row * D + col0; float sq = 0.f;
;             if (i + 1 < 8) { const size_t offn = (size_t)(row0 + ((i + 1) >> 2) * HALF + ((i + 1) & 3) * 16) * D + col0;
; #pragma unroll
;                 for (int k = 0; k < 4; ++k) rn[k] = *(const f32x4*)(res + offn + (k >> 1) * HALF + (k & 1) * 16); }
; #pragma unroll
;             for (int bj = 0; bj < 2; ++bj)
; #pragma unroll
;                 for (int n = 0; n < 2; ++n) { const size_t o = off + bj * HALF + n * 16; const f32x4 v = rc[bj * 2 + n] + acc[ai][bj][m][n] * alpha;
;                     *(f32x4*)(out + o) = v; u32x2 w; w.x = pk2h(v.x, v.y); w.y = pk2h(v.z, v.w); *(u32x2*)(o16 + o) = w; sq += (v.x * v.x + v.y * v.y) + (v.z * v.z + v.w * v.w); }
;             sq += __shfl_xor(sq, 16); sq += __shfl_xor(sq, 32);
;             if (fq == 0) ss[(size_t)row * 16 + u.pn * 4 + wc] = sq;
.LBB0_807:
	s_or_b64 exec, exec, s[2:3]
	v_or_b32_e32 v80, 32, v112
	v_ashrrev_i32_e32 v81, 31, v80
	s_waitcnt lgkmcnt(0)
	v_lshlrev_b64 v[48:49], 12, v[80:81]
	v_lshl_add_u64 v[82:83], v[178:179], 0, v[48:49]
	global_load_dwordx4 v[60:63], v[82:83], off
	global_load_dwordx4 v[56:59], v[82:83], off offset:64
	global_load_dwordx4 v[52:55], v[82:83], off offset:512
	global_load_dwordx4 v[48:51], v[82:83], off offset:576
	v_lshlrev_b64 v[84:85], 10, v[96:97]
	s_waitcnt vmcnt(15)
	v_pk_add_f32 v[46:47], v[46:47], v[78:79]
	v_pk_add_f32 v[44:45], v[44:45], v[76:77]
	v_lshl_add_u64 v[84:85], v[84:85], 0, v[176:177]
	global_store_dwordx4 v[98:99], v[44:47], off nt
	v_cvt_pk_f16_f32 v76, v44, v45
	v_lshlrev_b64 v[78:79], 1, v[84:85]
	v_mul_f32_e32 v45, v45, v45
	v_fmac_f32_e32 v45, v44, v44
	v_mul_f32_e32 v44, v47, v47
	v_cvt_pk_f16_f32 v77, v46, v47
	v_lshl_add_u64 v[84:85], s[48:49], 0, v[78:79]
	v_fmac_f32_e32 v44, v46, v46
	s_waitcnt vmcnt(15)
	v_pk_add_f32 v[42:43], v[42:43], v[74:75]
	v_pk_add_f32 v[40:41], v[40:41], v[72:73]
	global_store_dwordx2 v[84:85], v[76:77], off
	v_add_f32_e32 v76, v45, v44
	global_store_dwordx4 v[98:99], v[40:43], off offset:64 nt
	v_cvt_pk_f16_f32 v44, v40, v41
	v_or_b32_e32 v46, 32, v78
	v_mul_f32_e32 v41, v41, v41
	v_fmac_f32_e32 v41, v40, v40
	v_mul_f32_e32 v40, v43, v43
	v_mov_b32_e32 v47, v79
	v_fmac_f32_e32 v40, v42, v42
	v_cvt_pk_f16_f32 v45, v42, v43
	v_lshl_add_u64 v[46:47], s[48:49], 0, v[46:47]
	v_add_f32_e32 v40, v41, v40
	s_waitcnt vmcnt(16)
	v_pk_add_f32 v[38:39], v[38:39], v[70:71]
	v_pk_add_f32 v[36:37], v[36:37], v[68:69]
	global_store_dwordx2 v[46:47], v[44:45], off
	v_add_f32_e32 v44, v76, v40
	global_store_dwordx4 v[98:99], v[36:39], off offset:512 nt
	v_cvt_pk_f16_f32 v40, v36, v37
	s_waitcnt vmcnt(17)
	v_pk_add_f32 v[34:35], v[34:35], v[66:67]
	v_mul_f32_e32 v37, v37, v37
	v_fmac_f32_e32 v37, v36, v36
	v_mul_f32_e32 v36, v39, v39
	v_fmac_f32_e32 v36, v38, v38
	v_pk_add_f32 v[32:33], v[32:33], v[64:65]
	v_cvt_pk_f16_f32 v41, v38, v39
	v_add_f32_e32 v36, v37, v36
	v_mul_f32_e32 v37, v33, v33
	v_mul_f32_e32 v38, v35, v35
	v_fmac_f32_e32 v37, v32, v32
	v_fmac_f32_e32 v38, v34, v34
	v_add_f32_e32 v36, v44, v36
	v_add_f32_e32 v37, v37, v38
	v_add_f32_e32 v38, v36, v37
	ds_bpermute_b32 v39, v163, v38
	v_or_b32_e32 v42, 0x100, v78
	v_mov_b32_e32 v43, v79
	v_lshl_add_u64 v[36:37], s[48:49], 0, v[42:43]
	global_store_dwordx2 v[36:37], v[40:41], off
	global_store_dwordx4 v[98:99], v[32:35], off offset:576 nt
	v_cvt_pk_f16_f32 v36, v32, v33
	v_or_b32_e32 v78, 0x120, v78
	s_waitcnt lgkmcnt(0)
	v_add_f32_e32 v32, v38, v39
	ds_bpermute_b32 v33, v162, v32
	v_cvt_pk_f16_f32 v37, v34, v35
	v_lshl_add_u64 v[34:35], s[48:49], 0, v[78:79]
	global_store_dwordx2 v[34:35], v[36:37], off
	s_and_saveexec_b64 s[2:3], s[6:7]
	s_cbranch_execz .LBB0_809
	s_waitcnt lgkmcnt(0)
	v_add_f32_e32 v34, v32, v33
	v_lshlrev_b64 v[32:33], 6, v[96:97]
	v_lshl_add_u64 v[32:33], s[46:47], 0, v[32:33]
	v_lshl_add_u64 v[32:33], s[22:23], 2, v[32:33]
	s_lshl_b32 s92, s40, 2
	v_lshl_add_u64 v[32:33], v[32:33], 0, s[92:93]
	global_store_dword v[32:33], v34, off
;     __device__ __forceinline__ void operator()(const Acc& acc, const Unit& u, int wr, int wc, int fr, int fq) const {
;     ...
;         for (int i = 0; i < 8; ++i) {
;             const int ai = i >> 2, m = i & 3;
;             const int row = row0 + ai * HALF + m * 16; const size_t off = (size_t)row * D + col0; float sq = 0.f;
;             if (i + 1 < 8) { const size_t offn = (size_t)(row0 + ((i + 1) >> 2) * HALF + ((i + 1) & 3) * 16) * D + col0;
; #pragma unroll
;                 for (int k = 0; k < 4; ++k) rn[k] = *(const f32x4*)(res + offn + (k >> 1) * HALF + (k & 1) * 16); }
; #pragma unroll
;             for (int bj = 0; bj < 2; ++bj)
; #pragma unroll
;                 for (int n = 0; n < 2; ++n) { const size_t o = off + bj * HALF + n * 16; const f32x4 v = rc[bj * 2 + n] + acc[ai][bj][m][n] * alpha;
;                     *(f32x4*)(out + o) = v; u32x2 w; w.x = pk2h(v.x, v.y); w.y = pk2h(v.z, v.w); *(u32x2*)(o16 + o) = w; sq += (v.x * v.x + v.y * v.y) + (v.z * v.z + v.w * v.w); }
;             sq += __shfl_xor(sq, 16); sq += __shfl_xor(sq, 32);
;             if (fq == 0) ss[(size_t)row * 16 + u.pn * 4 + wc] = sq;
; #pragma unroll
;             for (int k = 0; k < 4; ++k) rc[k] = rn[k];
;         }
.LBB0_809:
	s_or_b64 exec, exec, s[2:3]
	v_or_b32_e32 v64, 48, v112
	v_ashrrev_i32_e32 v65, 31, v64
	s_waitcnt lgkmcnt(0)
	v_lshlrev_b64 v[32:33], 12, v[64:65]
	v_lshl_add_u64 v[66:67], v[178:179], 0, v[32:33]
	global_load_dwordx4 v[44:47], v[66:67], off
	global_load_dwordx4 v[40:43], v[66:67], off offset:64
	global_load_dwordx4 v[36:39], v[66:67], off offset:512
	global_load_dwordx4 v[32:35], v[66:67], off offset:576
	v_lshlrev_b64 v[68:69], 10, v[80:81]
	s_waitcnt vmcnt(15)
	v_pk_add_f32 v[30:31], v[30:31], v[62:63]
	v_pk_add_f32 v[28:29], v[28:29], v[60:61]
	v_lshl_add_u64 v[68:69], v[68:69], 0, v[176:177]
	global_store_dwordx4 v[82:83], v[28:31], off nt
	v_cvt_pk_f16_f32 v60, v28, v29
	v_lshlrev_b64 v[62:63], 1, v[68:69]
	v_mul_f32_e32 v29, v29, v29
	v_fmac_f32_e32 v29, v28, v28
	v_mul_f32_e32 v28, v31, v31
	v_cvt_pk_f16_f32 v61, v30, v31
	v_lshl_add_u64 v[68:69], s[48:49], 0, v[62:63]
	v_fmac_f32_e32 v28, v30, v30
	s_waitcnt vmcnt(15)
	v_pk_add_f32 v[26:27], v[26:27], v[58:59]
	v_pk_add_f32 v[24:25], v[24:25], v[56:57]
	global_store_dwordx2 v[68:69], v[60:61], off
	v_add_f32_e32 v60, v29, v28
	global_store_dwordx4 v[82:83], v[24:27], off offset:64 nt
	v_cvt_pk_f16_f32 v28, v24, v25
	v_or_b32_e32 v30, 32, v62
	v_mul_f32_e32 v25, v25, v25
	v_fmac_f32_e32 v25, v24, v24
	v_mul_f32_e32 v24, v27, v27
	v_mov_b32_e32 v31, v63
	v_fmac_f32_e32 v24, v26, v26
	v_cvt_pk_f16_f32 v29, v26, v27
	v_lshl_add_u64 v[30:31], s[48:49], 0, v[30:31]
	v_add_f32_e32 v24, v25, v24
	s_waitcnt vmcnt(16)
	v_pk_add_f32 v[22:23], v[22:23], v[54:55]
	v_pk_add_f32 v[20:21], v[20:21], v[52:53]
	global_store_dwordx2 v[30:31], v[28:29], off
	v_add_f32_e32 v28, v60, v24
	global_store_dwordx4 v[82:83], v[20:23], off offset:512 nt
	v_cvt_pk_f16_f32 v24, v20, v21
	s_waitcnt vmcnt(17)
	v_pk_add_f32 v[18:19], v[18:19], v[50:51]
	v_mul_f32_e32 v21, v21, v21
	v_fmac_f32_e32 v21, v20, v20
	v_mul_f32_e32 v20, v23, v23
	v_fmac_f32_e32 v20, v22, v22
	v_pk_add_f32 v[16:17], v[16:17], v[48:49]
	v_cvt_pk_f16_f32 v25, v22, v23
	v_add_f32_e32 v20, v21, v20
	v_mul_f32_e32 v21, v17, v17
	v_mul_f32_e32 v22, v19, v19
	v_fmac_f32_e32 v21, v16, v16
	v_fmac_f32_e32 v22, v18, v18
	v_add_f32_e32 v20, v28, v20
	v_add_f32_e32 v21, v21, v22
	v_add_f32_e32 v22, v20, v21
	ds_bpermute_b32 v23, v163, v22
	v_or_b32_e32 v26, 0x100, v62
	v_mov_b32_e32 v27, v63
	v_lshl_add_u64 v[20:21], s[48:49], 0, v[26:27]
	global_store_dwordx2 v[20:21], v[24:25], off
	global_store_dwordx4 v[82:83], v[16:19], off offset:576 nt
	v_cvt_pk_f16_f32 v20, v16, v17
	v_or_b32_e32 v62, 0x120, v62
	s_waitcnt lgkmcnt(0)
	v_add_f32_e32 v16, v22, v23
	ds_bpermute_b32 v17, v162, v16
	v_cvt_pk_f16_f32 v21, v18, v19
	v_lshl_add_u64 v[18:19], s[48:49], 0, v[62:63]
	global_store_dwordx2 v[18:19], v[20:21], off
	s_and_saveexec_b64 s[2:3], s[6:7]
	s_cbranch_execz .LBB0_811
	s_waitcnt lgkmcnt(0)
	v_add_f32_e32 v18, v16, v17
	v_lshlrev_b64 v[16:17], 6, v[80:81]
	v_lshl_add_u64 v[16:17], s[46:47], 0, v[16:17]
	v_lshl_add_u64 v[16:17], s[22:23], 2, v[16:17]
	s_lshl_b32 s92, s40, 2
	v_lshl_add_u64 v[16:17], v[16:17], 0, s[92:93]
	global_store_dword v[16:17], v18, off
.LBB0_811:
	s_or_b64 exec, exec, s[2:3]
	s_waitcnt lgkmcnt(0)
	v_lshlrev_b64 v[16:17], 10, v[64:65]
	s_waitcnt vmcnt(11)
	v_pk_add_f32 v[14:15], v[14:15], v[46:47]
	v_pk_add_f32 v[12:13], v[12:13], v[44:45]
	v_lshl_add_u64 v[16:17], v[16:17], 0, v[176:177]
	global_store_dwordx4 v[66:67], v[12:15], off nt
	v_cvt_pk_f16_f32 v18, v12, v13
	v_lshlrev_b64 v[16:17], 1, v[16:17]
	v_mul_f32_e32 v13, v13, v13
	v_fmac_f32_e32 v13, v12, v12
	v_mul_f32_e32 v12, v15, v15
	v_cvt_pk_f16_f32 v19, v14, v15
	v_lshl_add_u64 v[20:21], s[48:49], 0, v[16:17]
	v_fmac_f32_e32 v12, v14, v14
	s_waitcnt vmcnt(11)
	v_pk_add_f32 v[10:11], v[10:11], v[42:43]
	v_pk_add_f32 v[8:9], v[8:9], v[40:41]
	global_store_dwordx2 v[20:21], v[18:19], off
	v_add_f32_e32 v18, v13, v12
	global_store_dwordx4 v[66:67], v[8:11], off offset:64 nt
	v_cvt_pk_f16_f32 v12, v8, v9
	v_or_b32_e32 v14, 32, v16
	v_mul_f32_e32 v9, v9, v9
	v_fmac_f32_e32 v9, v8, v8
	v_mul_f32_e32 v8, v11, v11
	v_mov_b32_e32 v15, v17
	v_fmac_f32_e32 v8, v10, v10
	v_cvt_pk_f16_f32 v13, v10, v11
	v_lshl_add_u64 v[14:15], s[48:49], 0, v[14:15]
	v_add_f32_e32 v8, v9, v8
	s_waitcnt vmcnt(12)
	v_pk_add_f32 v[6:7], v[6:7], v[38:39]
	v_pk_add_f32 v[4:5], v[4:5], v[36:37]
	global_store_dwordx2 v[14:15], v[12:13], off
	v_add_f32_e32 v12, v18, v8
	global_store_dwordx4 v[66:67], v[4:7], off offset:512 nt
	v_cvt_pk_f16_f32 v8, v4, v5
	s_waitcnt vmcnt(13)
	v_pk_add_f32 v[2:3], v[2:3], v[34:35]
	v_mul_f32_e32 v5, v5, v5
	v_fmac_f32_e32 v5, v4, v4
	v_mul_f32_e32 v4, v7, v7
	v_fmac_f32_e32 v4, v6, v6
	v_pk_add_f32 v[0:1], v[0:1], v[32:33]
	v_cvt_pk_f16_f32 v9, v6, v7
	v_add_f32_e32 v4, v5, v4
	v_mul_f32_e32 v5, v1, v1
	v_mul_f32_e32 v6, v3, v3
	v_fmac_f32_e32 v5, v0, v0
	v_fmac_f32_e32 v6, v2, v2
	v_add_f32_e32 v4, v12, v4
	v_add_f32_e32 v5, v5, v6
	v_add_f32_e32 v6, v4, v5
	ds_bpermute_b32 v7, v163, v6
	v_or_b32_e32 v10, 0x100, v16
	v_mov_b32_e32 v11, v17
	v_lshl_add_u64 v[4:5], s[48:49], 0, v[10:11]
	global_store_dwordx2 v[4:5], v[8:9], off
	global_store_dwordx4 v[66:67], v[0:3], off offset:576 nt
	v_cvt_pk_f16_f32 v4, v0, v1
	v_or_b32_e32 v16, 0x120, v16
	s_waitcnt lgkmcnt(0)
	v_add_f32_e32 v0, v6, v7
	ds_bpermute_b32 v1, v162, v0
	v_cvt_pk_f16_f32 v5, v2, v3
	v_lshl_add_u64 v[2:3], s[48:49], 0, v[16:17]
	global_store_dwordx2 v[2:3], v[4:5], off
	s_and_saveexec_b64 s[2:3], s[6:7]
	s_cbranch_execz .LBB0_813
	s_waitcnt lgkmcnt(0)
	v_add_f32_e32 v2, v0, v1
	v_lshlrev_b64 v[0:1], 6, v[64:65]
	v_lshl_add_u64 v[0:1], s[46:47], 0, v[0:1]
	v_lshl_add_u64 v[0:1], s[22:23], 2, v[0:1]
	s_lshl_b32 s92, s40, 2
	v_lshl_add_u64 v[0:1], v[0:1], 0, s[92:93]
	global_store_dword v[0:1], v2, off

; __device__ __forceinline__ float sigmoidf_(float x) { return __builtin_amdgcn_rcpf(1.0f + __expf(-x)); }
; __device__ __forceinline__ void rows_rstd8(const float* ss, int row0, int fq, float (&rs)[2][4]) {
;     ...
;         for (int m = 0; m < 4; ++m) q[ai][m] = *(const f32x4*)(ss + (size_t)(row0 + ai * 128 + m * 16) * 16 + 4 * fq);
; #pragma unroll
;     for (int ai = 0; ai < 2; ++ai)
; #pragma unroll
;         for (int m = 0; m < 4; ++m) { float t = (q[ai][m].x + q[ai][m].y) + (q[ai][m].z + q[ai][m].w); t += __shfl_xor(t, 16); t += __shfl_xor(t, 32); rs[ai][m] = __builtin_amdgcn_rsqf(t * (1.0f / 1024.0f) + 1e-6f); }
;     __device__ __forceinline__ void operator()(const Acc& acc, const Unit& u, int wr, int wc, int fr, int fq) const {
;     ...
;         float rs8[2][4]; rows_rstd8(ssr, row0, fq, rs8);
; #pragma unroll
;         for (int ai = 0; ai < 2; ++ai)
; #pragma unroll
;             for (int m = 0; m < 4; ++m) {
;                 const int row = row0 + ai * HALF + m * 16; const size_t off = (size_t)row * D + col0; float sq = 0.f; const float rs = rs8[ai][m];
; #pragma unroll
;                 for (int bj = 0; bj < 2; ++bj)
; #pragma unroll
;                     for (int n = 0; n < 2; ++n) { const size_t o = off + bj * HALF + n * 16; const f32x4 r = *(const f32x4*)(out + o); const h16x4 p = *(const h16x4*)(pu + o);
;                         const f32x4 a = acc[ai][bj][m][n] * rs; f32x4 v;
;                         v.x = r.x + sigmoidf_(a.x) * (float)p.x; v.y = r.y + sigmoidf_(a.y) * (float)p.y; v.z = r.z + sigmoidf_(a.z) * (float)p.z; v.w = r.w + sigmoidf_(a.w) * (float)p.w;
.LBB0_885:
	v_lshl_add_u32 v188, s41, 8, v187
	v_ashrrev_i32_e32 v189, 31, v188
	v_lshlrev_b64 v[184:185], 6, v[188:189]
	v_lshl_add_u64 v[136:137], v[130:131], 0, v[184:185]
	global_load_dwordx4 v[154:157], v[136:137], off
	v_or_b32_e32 v182, 16, v188
	v_ashrrev_i32_e32 v183, 31, v182
	v_lshlrev_b64 v[180:181], 6, v[182:183]
	v_lshl_add_u64 v[136:137], v[130:131], 0, v[180:181]
	global_load_dwordx4 v[162:165], v[136:137], off
	v_or_b32_e32 v178, 32, v188
	v_ashrrev_i32_e32 v179, 31, v178
	v_lshlrev_b64 v[176:177], 6, v[178:179]
	v_lshl_add_u64 v[136:137], v[130:131], 0, v[176:177]
	global_load_dwordx4 v[190:193], v[136:137], off
	v_or_b32_e32 v174, 48, v188
	v_ashrrev_i32_e32 v175, 31, v174
	v_lshlrev_b64 v[172:173], 6, v[174:175]
	v_lshl_add_u64 v[136:137], v[130:131], 0, v[172:173]
	global_load_dwordx4 v[194:197], v[136:137], off
	v_add_u32_e32 v170, 0x80, v188
	v_ashrrev_i32_e32 v171, 31, v170
	v_lshlrev_b64 v[150:151], 6, v[170:171]
	v_lshl_add_u64 v[136:137], v[130:131], 0, v[150:151]
	global_load_dwordx4 v[216:219], v[136:137], off
	v_add_u32_e32 v148, 0x90, v188
	v_ashrrev_i32_e32 v149, 31, v148
	v_lshlrev_b64 v[146:147], 6, v[148:149]
	v_lshl_add_u64 v[136:137], v[130:131], 0, v[146:147]
	global_load_dwordx4 v[228:231], v[136:137], off
	v_add_u32_e32 v144, 0xa0, v188
	v_ashrrev_i32_e32 v145, 31, v144
	v_lshlrev_b64 v[142:143], 6, v[144:145]
	v_lshl_add_u64 v[136:137], v[130:131], 0, v[142:143]
	global_load_dwordx4 v[232:235], v[136:137], off
	v_add_u32_e32 v140, 0xb0, v188
	v_ashrrev_i32_e32 v141, 31, v140
	v_lshlrev_b64 v[136:137], 6, v[140:141]
	v_lshl_add_u64 v[166:167], v[130:131], 0, v[136:137]
	global_load_dwordx4 v[236:239], v[166:167], off
	v_and_b32_e32 v166, 64, v203
	v_xor_b32_e32 v139, 16, v203
	v_add_u32_e32 v166, 64, v166
	v_cmp_lt_i32_e32 vcc, v139, v166
	v_lshl_or_b32 v138, s40, 8, v211
	v_readlane_b32 s52, v248, 48
	v_cndmask_b32_e32 v139, v203, v139, vcc
	v_lshlrev_b32_e32 v214, 2, v139
	v_xor_b32_e32 v139, 32, v203
	v_cmp_lt_i32_e32 vcc, v139, v166
	v_readlane_b32 s42, v254, 18
	v_readlane_b32 s66, v248, 62
	v_cndmask_b32_e32 v139, v203, v139, vcc
	v_lshlrev_b32_e32 v213, 2, v139
	v_readlane_b32 s67, v248, 63
	v_readlane_b32 s43, v254, 19
	v_readlane_b32 s24, v253, 0
	v_readlane_b32 s25, v253, 1
	s_lshl_b32 s22, s40, 2
	s_ashr_i32 s23, s22, 31
	v_readlane_b32 s53, v248, 49
	v_readlane_b32 s54, v248, 50
	v_readlane_b32 s55, v248, 51
	v_readlane_b32 s56, v248, 52
	v_readlane_b32 s57, v248, 53
	v_readlane_b32 s58, v248, 54
	v_readlane_b32 s59, v248, 55
	v_readlane_b32 s60, v248, 56
	v_readlane_b32 s61, v248, 57
	v_readlane_b32 s62, v248, 58
	v_readlane_b32 s63, v248, 59
	v_readlane_b32 s64, v248, 60
	v_readlane_b32 s65, v248, 61
	s_waitcnt vmcnt(0)
	v_mov_b32_e32 v166, v155
	v_mov_b32_e32 v167, v156
	v_mov_b32_e32 v155, v157
	v_pk_add_f32 v[154:155], v[166:167], v[154:155]
	s_nop 0
	v_add_f32_e32 v139, v154, v155
	ds_bpermute_b32 v154, v214, v139
	s_waitcnt lgkmcnt(0)
	v_add_f32_e32 v139, v139, v154
	ds_bpermute_b32 v154, v213, v139
	s_waitcnt lgkmcnt(0)
	v_add_f32_e32 v139, v139, v154
	v_fmamk_f32 v139, v139, 0x3a800000, v201
	v_rsq_f32_e32 v186, v139
	v_add_f32_e32 v139, v162, v163
	v_add_f32_e32 v154, v164, v165
	v_add_f32_e32 v139, v139, v154
	ds_bpermute_b32 v154, v214, v139
	v_pk_mul_f32 v[124:125], v[124:125], v[186:187] op_sel_hi:[1,0]
	v_pk_mul_f32 v[126:127], v[126:127], v[186:187] op_sel_hi:[1,0]
	v_mul_f32_e32 v124, 0xbfb8aa3b, v124
	v_mul_f32_e32 v125, 0xbfb8aa3b, v125
	s_waitcnt lgkmcnt(0)
	v_add_f32_e32 v162, v139, v154
	v_add_f32_e32 v139, v190, v191
	v_add_f32_e32 v154, v192, v193
	v_add_f32_e32 v139, v139, v154
	ds_bpermute_b32 v154, v214, v139
	v_exp_f32_e32 v124, v124
	v_exp_f32_e32 v125, v125
	v_mul_f32_e32 v126, 0xbfb8aa3b, v126
	v_mul_f32_e32 v127, 0xbfb8aa3b, v127
	s_waitcnt lgkmcnt(0)
	v_add_f32_e32 v225, v139, v154
	v_add_f32_e32 v139, v194, v195
	v_add_f32_e32 v154, v196, v197
	v_add_f32_e32 v139, v139, v154
	ds_bpermute_b32 v154, v214, v139
	v_add_f32_e32 v124, 1.0, v124
	v_add_f32_e32 v125, 1.0, v125
	v_exp_f32_e32 v126, v126
	v_exp_f32_e32 v127, v127
	s_waitcnt lgkmcnt(0)
	v_add_f32_e32 v223, v139, v154
	v_add_f32_e32 v139, v216, v217
	v_add_f32_e32 v154, v218, v219
	v_add_f32_e32 v139, v139, v154
	ds_bpermute_b32 v154, v214, v139
	v_rcp_f32_e32 v124, v124
	v_rcp_f32_e32 v125, v125
	v_add_f32_e32 v126, 1.0, v126
	v_add_f32_e32 v127, 1.0, v127
	s_waitcnt lgkmcnt(0)
	v_add_f32_e32 v221, v139, v154
	v_add_f32_e32 v139, v228, v229
	v_add_f32_e32 v154, v230, v231
	v_add_f32_e32 v139, v139, v154
	ds_bpermute_b32 v154, v214, v139
	v_rcp_f32_e32 v126, v126
	v_rcp_f32_e32 v127, v127
	v_pk_mul_f32 v[120:121], v[120:121], v[186:187] op_sel_hi:[1,0]
	v_pk_mul_f32 v[122:123], v[122:123], v[186:187] op_sel_hi:[1,0]
	s_waitcnt lgkmcnt(0)
	v_add_f32_e32 v219, v139, v154
	v_add_f32_e32 v139, v232, v233
	v_add_f32_e32 v154, v234, v235
	v_add_f32_e32 v139, v139, v154
	ds_bpermute_b32 v154, v214, v139
	v_mul_f32_e32 v120, 0xbfb8aa3b, v120
	v_mul_f32_e32 v121, 0xbfb8aa3b, v121
	v_exp_f32_e32 v120, v120
	v_exp_f32_e32 v121, v121
	s_waitcnt lgkmcnt(0)
	v_add_f32_e32 v217, v139, v154
	v_add_f32_e32 v139, v236, v237
	v_add_f32_e32 v154, v238, v239
	v_add_f32_e32 v139, v139, v154
	ds_bpermute_b32 v154, v214, v139
	v_mul_f32_e32 v122, 0xbfb8aa3b, v122
	v_mul_f32_e32 v123, 0xbfb8aa3b, v123
	v_add_f32_e32 v120, 1.0, v120
	v_add_f32_e32 v121, 1.0, v121
	s_waitcnt lgkmcnt(0)
; __device__ __forceinline__ float sigmoidf_(float x) { return __builtin_amdgcn_rcpf(1.0f + __expf(-x)); }
;     __device__ __forceinline__ void operator()(const Acc& acc, const Unit& u, int wr, int wc, int fr, int fq) const {
;     ...
;                 const int row = row0 + ai * HALF + m * 16; const size_t off = (size_t)row * D + col0; float sq = 0.f; const float rs = rs8[ai][m];
; #pragma unroll
;                 for (int bj = 0; bj < 2; ++bj)
; #pragma unroll
;                     for (int n = 0; n < 2; ++n) { const size_t o = off + bj * HALF + n * 16; const f32x4 r = *(const f32x4*)(out + o); const h16x4 p = *(const h16x4*)(pu + o);
;                         const f32x4 a = acc[ai][bj][m][n] * rs; f32x4 v;
;                         v.x = r.x + sigmoidf_(a.x) * (float)p.x; v.y = r.y + sigmoidf_(a.y) * (float)p.y; v.z = r.z + sigmoidf_(a.z) * (float)p.z; v.w = r.w + sigmoidf_(a.w) * (float)p.w;
;                         *(f32x4*)(out + o) = v; u32x2 w; w.x = pk2h(v.x, v.y); w.y = pk2h(v.z, v.w); *(u32x2*)(o16 + o) = w; sq += (v.x * v.x + v.y * v.y) + (v.z * v.z + v.w * v.w); }
;                 sq += __shfl_xor(sq, 16); sq += __shfl_xor(sq, 32);
;                 if (fq == 0) ssw[(size_t)row * 16 + u.pn * 4 + wc] = sq;
	v_add_f32_e32 v215, v139, v154
	v_ashrrev_i32_e32 v139, 31, v138
	v_lshlrev_b64 v[154:155], 10, v[188:189]
	v_lshl_add_u64 v[164:165], v[154:155], 0, v[138:139]
	v_lshlrev_b64 v[194:195], 1, v[164:165]
	v_lshl_add_u64 v[192:193], v[164:165], 2, s[66:67]
	v_lshl_add_u64 v[164:165], s[42:43], 0, v[194:195]
	global_load_dwordx2 v[164:165], v[164:165], off
	v_exp_f32_e32 v122, v122
	global_load_dwordx4 v[154:157], v[192:193], off
	v_exp_f32_e32 v123, v123
	v_rcp_f32_e32 v120, v120
	v_rcp_f32_e32 v121, v121
	v_add_f32_e32 v122, 1.0, v122
	v_add_f32_e32 v123, 1.0, v123
	v_rcp_f32_e32 v122, v122
	v_rcp_f32_e32 v123, v123
	v_or_b32_e32 v196, 0x100, v194
	v_mov_b32_e32 v197, v195
	v_pk_mul_f32 v[116:117], v[116:117], v[186:187] op_sel_hi:[1,0]
	v_pk_mul_f32 v[118:119], v[118:119], v[186:187] op_sel_hi:[1,0]
	v_mul_f32_e32 v116, 0xbfb8aa3b, v116
	v_mul_f32_e32 v117, 0xbfb8aa3b, v117
	v_exp_f32_e32 v116, v116
	v_exp_f32_e32 v117, v117
	v_mul_f32_e32 v118, 0xbfb8aa3b, v118
	v_mul_f32_e32 v119, 0xbfb8aa3b, v119
	v_add_f32_e32 v116, 1.0, v116
	v_add_f32_e32 v117, 1.0, v117
	v_exp_f32_e32 v118, v118
	v_exp_f32_e32 v119, v119
	v_rcp_f32_e32 v116, v116
	v_rcp_f32_e32 v117, v117
	v_add_f32_e32 v118, 1.0, v118
	v_add_f32_e32 v119, 1.0, v119
	v_rcp_f32_e32 v118, v118
	v_rcp_f32_e32 v119, v119
	v_pk_mul_f32 v[112:113], v[112:113], v[186:187] op_sel_hi:[1,0]
	v_pk_mul_f32 v[114:115], v[114:115], v[186:187] op_sel_hi:[1,0]
	v_mul_f32_e32 v112, 0xbfb8aa3b, v112
	v_mul_f32_e32 v113, 0xbfb8aa3b, v113
	v_exp_f32_e32 v112, v112
	v_exp_f32_e32 v113, v113
	v_mul_f32_e32 v114, 0xbfb8aa3b, v114
	v_mul_f32_e32 v115, 0xbfb8aa3b, v115
	v_add_f32_e32 v112, 1.0, v112
	v_add_f32_e32 v113, 1.0, v113
	v_exp_f32_e32 v114, v114
	v_exp_f32_e32 v115, v115
	v_rcp_f32_e32 v112, v112
	v_rcp_f32_e32 v113, v113
	v_add_f32_e32 v114, 1.0, v114
	v_add_f32_e32 v115, 1.0, v115
	v_rcp_f32_e32 v114, v114
	v_rcp_f32_e32 v115, v115
	ds_bpermute_b32 v163, v213, v162
	ds_bpermute_b32 v226, v213, v225
	ds_bpermute_b32 v224, v213, v223
	ds_bpermute_b32 v222, v213, v221
	ds_bpermute_b32 v220, v213, v219
	ds_bpermute_b32 v218, v213, v217
	ds_bpermute_b32 v216, v213, v215
	s_waitcnt vmcnt(1)
	v_cvt_f32_f16_e32 v166, v164
	v_cvt_f32_f16_sdwa v167, v164 dst_sel:DWORD dst_unused:UNUSED_PAD src0_sel:WORD_1
	s_waitcnt vmcnt(0)
	v_pk_fma_f32 v[124:125], v[124:125], v[166:167], v[154:155]
	v_cvt_f32_f16_e32 v154, v165
	v_cvt_f32_f16_sdwa v155, v165 dst_sel:DWORD dst_unused:UNUSED_PAD src0_sel:WORD_1
	v_pk_mul_f32 v[188:189], v[124:125], v[124:125]
	v_pk_fma_f32 v[126:127], v[126:127], v[154:155], v[156:157]
	v_cvt_pk_f16_f32 v154, v124, v125
	v_cvt_pk_f16_f32 v155, v126, v127
	v_lshl_add_u64 v[156:157], s[24:25], 0, v[194:195]
	global_store_dwordx4 v[192:193], v[124:127], off nt
	global_store_dwordx2 v[156:157], v[154:155], off
	v_or_b32_e32 v154, 32, v194
	v_mov_b32_e32 v155, v195
	v_lshl_add_u64 v[156:157], s[42:43], 0, v[154:155]
	global_load_dwordx2 v[156:157], v[156:157], off
	v_pk_mul_f32 v[190:191], v[126:127], v[126:127]
	global_load_dwordx4 v[124:127], v[192:193], off offset:64
	v_or_b32_e32 v194, 0x120, v194
	s_waitcnt vmcnt(1)
	v_cvt_f32_f16_e32 v164, v156
	v_cvt_f32_f16_sdwa v165, v156 dst_sel:DWORD dst_unused:UNUSED_PAD src0_sel:WORD_1
	s_waitcnt vmcnt(0)
	v_pk_fma_f32 v[120:121], v[120:121], v[164:165], v[124:125]
	v_cvt_f32_f16_e32 v124, v157
	v_cvt_f32_f16_sdwa v125, v157 dst_sel:DWORD dst_unused:UNUSED_PAD src0_sel:WORD_1
	v_pk_fma_f32 v[122:123], v[122:123], v[124:125], v[126:127]
	global_store_dwordx4 v[192:193], v[120:123], off offset:64 nt
	v_lshl_add_u64 v[126:127], s[24:25], 0, v[154:155]
	v_lshl_add_u64 v[154:155], s[42:43], 0, v[196:197]
	global_load_dwordx2 v[154:155], v[154:155], off
	v_cvt_pk_f16_f32 v124, v120, v121
	v_cvt_pk_f16_f32 v125, v122, v123
	global_store_dwordx2 v[126:127], v[124:125], off
	v_pk_mul_f32 v[124:125], v[120:121], v[120:121]
	v_pk_mul_f32 v[126:127], v[122:123], v[122:123]
	global_load_dwordx4 v[120:123], v[192:193], off offset:512
	s_waitcnt vmcnt(2)
	v_cvt_f32_f16_e32 v156, v154
	v_cvt_f32_f16_sdwa v157, v154 dst_sel:DWORD dst_unused:UNUSED_PAD src0_sel:WORD_1
	s_waitcnt vmcnt(0)
	v_pk_fma_f32 v[116:117], v[116:117], v[156:157], v[120:121]
	v_cvt_f32_f16_e32 v120, v155
	v_cvt_f32_f16_sdwa v121, v155 dst_sel:DWORD dst_unused:UNUSED_PAD src0_sel:WORD_1
	v_lshl_add_u64 v[154:155], s[42:43], 0, v[194:195]
	v_pk_fma_f32 v[118:119], v[118:119], v[120:121], v[122:123]
	global_store_dwordx4 v[192:193], v[116:119], off offset:512 nt
	v_lshl_add_u64 v[122:123], s[24:25], 0, v[196:197]
	global_load_dwordx2 v[196:197], v[154:155], off
	v_cvt_pk_f16_f32 v120, v116, v117
	v_cvt_pk_f16_f32 v121, v118, v119
	global_store_dwordx2 v[122:123], v[120:121], off
	v_pk_mul_f32 v[120:121], v[116:117], v[116:117]
	v_pk_mul_f32 v[122:123], v[118:119], v[118:119]
	global_load_dwordx4 v[116:119], v[192:193], off offset:576
	s_waitcnt vmcnt(2)
	v_cvt_f32_f16_e32 v154, v196
	v_cvt_f32_f16_sdwa v155, v196 dst_sel:DWORD dst_unused:UNUSED_PAD src0_sel:WORD_1
	s_waitcnt vmcnt(0)
	v_pk_fma_f32 v[112:113], v[112:113], v[154:155], v[116:117]
	v_cvt_f32_f16_e32 v116, v197
	v_cvt_f32_f16_sdwa v117, v197 dst_sel:DWORD dst_unused:UNUSED_PAD src0_sel:WORD_1
	v_pk_fma_f32 v[114:115], v[114:115], v[116:117], v[118:119]
	v_cvt_pk_f16_f32 v116, v112, v113
	v_cvt_pk_f16_f32 v117, v114, v115
	v_lshl_add_u64 v[118:119], s[24:25], 0, v[194:195]
	global_store_dwordx4 v[192:193], v[112:115], off offset:576 nt
	global_store_dwordx2 v[118:119], v[116:117], off
	v_add_f32_e32 v116, v190, v191
	v_add_f32_e32 v117, v188, v189
	v_add_f32_e32 v116, v117, v116
	v_add_f32_e32 v117, v126, v127
	v_add_f32_e32 v118, v124, v125
	v_add_f32_e32 v117, v118, v117
	v_pk_mul_f32 v[112:113], v[112:113], v[112:113]
	v_pk_mul_f32 v[114:115], v[114:115], v[114:115]
	v_add_f32_e32 v116, v116, v117
	v_add_f32_e32 v117, v122, v123
	v_add_f32_e32 v118, v120, v121
	v_add_f32_e32 v117, v118, v117
	v_add_f32_e32 v114, v114, v115
	v_add_f32_e32 v112, v112, v113
	v_add_f32_e32 v116, v116, v117
	v_add_f32_e32 v112, v112, v114
	v_add_f32_e32 v112, v116, v112
	ds_bpermute_b32 v113, v214, v112
	s_waitcnt lgkmcnt(0)
	v_add_f32_e32 v112, v112, v113
	ds_bpermute_b32 v113, v213, v112
	s_and_saveexec_b64 s[2:3], s[10:11]
	s_cbranch_execz .LBB0_887
	s_waitcnt lgkmcnt(0)
	v_add_f32_e32 v114, v112, v113
	v_lshl_add_u64 v[112:113], s[70:71], 0, v[184:185]
	v_lshl_add_u64 v[112:113], s[22:23], 2, v[112:113]
	s_lshl_b32 s92, s38, 2
	v_lshl_add_u64 v[112:113], v[112:113], 0, s[92:93]
	global_store_dword v[112:113], v114, off
; __device__ __forceinline__ float sigmoidf_(float x) { return __builtin_amdgcn_rcpf(1.0f + __expf(-x)); }
;     __device__ __forceinline__ void operator()(const Acc& acc, const Unit& u, int wr, int wc, int fr, int fq) const {
;     ...
;                 const int row = row0 + ai * HALF + m * 16; const size_t off = (size_t)row * D + col0; float sq = 0.f; const float rs = rs8[ai][m];
; #pragma unroll
;                 for (int bj = 0; bj < 2; ++bj)
; #pragma unroll
;                     for (int n = 0; n < 2; ++n) { const size_t o = off + bj * HALF + n * 16; const f32x4 r = *(const f32x4*)(out + o); const h16x4 p = *(const h16x4*)(pu + o);
;                         const f32x4 a = acc[ai][bj][m][n] * rs; f32x4 v;
;                         v.x = r.x + sigmoidf_(a.x) * (float)p.x; v.y = r.y + sigmoidf_(a.y) * (float)p.y; v.z = r.z + sigmoidf_(a.z) * (float)p.z; v.w = r.w + sigmoidf_(a.w) * (float)p.w;
;                         *(f32x4*)(out + o) = v; u32x2 w; w.x = pk2h(v.x, v.y); w.y = pk2h(v.z, v.w); *(u32x2*)(o16 + o) = w; sq += (v.x * v.x + v.y * v.y) + (v.z * v.z + v.w * v.w); }
;                 sq += __shfl_xor(sq, 16); sq += __shfl_xor(sq, 32);
;                 if (fq == 0) ssw[(size_t)row * 16 + u.pn * 4 + wc] = sq;
.LBB0_887:
	s_or_b64 exec, exec, s[2:3]
	v_add_f32_e32 v112, v162, v163
	v_fmamk_f32 v112, v112, 0x3a800000, v201
	v_rsq_f32_e32 v120, v112
	s_waitcnt lgkmcnt(0)
	v_lshlrev_b64 v[112:113], 10, v[182:183]
	v_readlane_b32 s52, v248, 48
	v_lshl_add_u64 v[118:119], v[112:113], 0, v[138:139]
	v_readlane_b32 s66, v248, 62
	v_readlane_b32 s67, v248, 63
	v_pk_mul_f32 v[108:109], v[108:109], v[120:121] op_sel_hi:[1,0]
	v_pk_mul_f32 v[110:111], v[110:111], v[120:121] op_sel_hi:[1,0]
	v_lshl_add_u64 v[116:117], v[118:119], 2, s[66:67]
	v_lshlrev_b64 v[118:119], 1, v[118:119]
	v_lshl_add_u64 v[122:123], s[42:43], 0, v[118:119]
	global_load_dwordx2 v[122:123], v[122:123], off
	v_mul_f32_e32 v108, 0xbfb8aa3b, v108
	global_load_dwordx4 v[112:115], v[116:117], off
	v_mul_f32_e32 v109, 0xbfb8aa3b, v109
	v_exp_f32_e32 v108, v108
	v_exp_f32_e32 v109, v109
	v_mul_f32_e32 v110, 0xbfb8aa3b, v110
	v_mul_f32_e32 v111, 0xbfb8aa3b, v111
	v_add_f32_e32 v108, 1.0, v108
	v_add_f32_e32 v109, 1.0, v109
	v_exp_f32_e32 v110, v110
	v_exp_f32_e32 v111, v111
	v_rcp_f32_e32 v108, v108
	v_rcp_f32_e32 v109, v109
	v_add_f32_e32 v110, 1.0, v110
	v_add_f32_e32 v111, 1.0, v111
	v_rcp_f32_e32 v110, v110
	v_rcp_f32_e32 v111, v111
	v_pk_mul_f32 v[104:105], v[104:105], v[120:121] op_sel_hi:[1,0]
	v_pk_mul_f32 v[106:107], v[106:107], v[120:121] op_sel_hi:[1,0]
	v_mul_f32_e32 v104, 0xbfb8aa3b, v104
	v_mul_f32_e32 v105, 0xbfb8aa3b, v105
	v_exp_f32_e32 v104, v104
	v_exp_f32_e32 v105, v105
	v_mul_f32_e32 v106, 0xbfb8aa3b, v106
	v_mul_f32_e32 v107, 0xbfb8aa3b, v107
	v_add_f32_e32 v104, 1.0, v104
	v_add_f32_e32 v105, 1.0, v105
	v_exp_f32_e32 v106, v106
	v_exp_f32_e32 v107, v107
	v_rcp_f32_e32 v104, v104
	v_rcp_f32_e32 v105, v105
	v_add_f32_e32 v106, 1.0, v106
	v_add_f32_e32 v107, 1.0, v107
	v_rcp_f32_e32 v106, v106
	v_rcp_f32_e32 v107, v107
	v_pk_mul_f32 v[100:101], v[100:101], v[120:121] op_sel_hi:[1,0]
	v_pk_mul_f32 v[102:103], v[102:103], v[120:121] op_sel_hi:[1,0]
	v_mul_f32_e32 v100, 0xbfb8aa3b, v100
	v_mul_f32_e32 v101, 0xbfb8aa3b, v101
	v_exp_f32_e32 v100, v100
	v_exp_f32_e32 v101, v101
	v_mul_f32_e32 v102, 0xbfb8aa3b, v102
	v_mul_f32_e32 v103, 0xbfb8aa3b, v103
	v_add_f32_e32 v100, 1.0, v100
	v_add_f32_e32 v101, 1.0, v101
	v_exp_f32_e32 v102, v102
	v_exp_f32_e32 v103, v103
	v_rcp_f32_e32 v100, v100
	v_rcp_f32_e32 v101, v101
	v_add_f32_e32 v102, 1.0, v102
	v_add_f32_e32 v103, 1.0, v103
	v_rcp_f32_e32 v102, v102
	v_rcp_f32_e32 v103, v103
	v_pk_mul_f32 v[96:97], v[96:97], v[120:121] op_sel_hi:[1,0]
	v_pk_mul_f32 v[98:99], v[98:99], v[120:121] op_sel_hi:[1,0]
	v_mul_f32_e32 v96, 0xbfb8aa3b, v96
	v_mul_f32_e32 v97, 0xbfb8aa3b, v97
	v_exp_f32_e32 v96, v96
	v_exp_f32_e32 v97, v97
	v_mul_f32_e32 v98, 0xbfb8aa3b, v98
	v_mul_f32_e32 v99, 0xbfb8aa3b, v99
	v_add_f32_e32 v96, 1.0, v96
	v_add_f32_e32 v97, 1.0, v97
	v_exp_f32_e32 v98, v98
	v_exp_f32_e32 v99, v99
	v_rcp_f32_e32 v96, v96
	v_rcp_f32_e32 v97, v97
	v_add_f32_e32 v98, 1.0, v98
	v_add_f32_e32 v99, 1.0, v99
	v_rcp_f32_e32 v98, v98
	v_rcp_f32_e32 v99, v99
	v_readlane_b32 s53, v248, 49
	v_readlane_b32 s54, v248, 50
	v_readlane_b32 s55, v248, 51
	v_readlane_b32 s56, v248, 52
	v_readlane_b32 s57, v248, 53
	v_readlane_b32 s58, v248, 54
	v_readlane_b32 s59, v248, 55
	v_readlane_b32 s60, v248, 56
	s_waitcnt vmcnt(1)
	v_cvt_f32_f16_e32 v124, v122
	v_cvt_f32_f16_sdwa v125, v122 dst_sel:DWORD dst_unused:UNUSED_PAD src0_sel:WORD_1
	v_or_b32_e32 v122, 32, v118
	v_readlane_b32 s61, v248, 57
	v_readlane_b32 s62, v248, 58
	s_waitcnt vmcnt(0)
	v_pk_fma_f32 v[108:109], v[108:109], v[124:125], v[112:113]
	v_cvt_f32_f16_e32 v112, v123
	v_cvt_f32_f16_sdwa v113, v123 dst_sel:DWORD dst_unused:UNUSED_PAD src0_sel:WORD_1
	v_mov_b32_e32 v123, v119
	v_lshl_add_u64 v[124:125], s[42:43], 0, v[122:123]
	v_readlane_b32 s63, v248, 59
	v_pk_fma_f32 v[110:111], v[110:111], v[112:113], v[114:115]
	global_store_dwordx4 v[116:117], v[108:111], off nt
	global_load_dwordx2 v[124:125], v[124:125], off
	v_cvt_pk_f16_f32 v112, v108, v109
	v_cvt_pk_f16_f32 v113, v110, v111
	v_lshl_add_u64 v[114:115], s[24:25], 0, v[118:119]
	global_store_dwordx2 v[114:115], v[112:113], off
	v_pk_mul_f32 v[112:113], v[108:109], v[108:109]
	v_pk_mul_f32 v[114:115], v[110:111], v[110:111]
	global_load_dwordx4 v[108:111], v[116:117], off offset:64
	v_readlane_b32 s64, v248, 60
	v_readlane_b32 s65, v248, 61
	s_waitcnt vmcnt(2)
	v_cvt_f32_f16_e32 v126, v124
	v_cvt_f32_f16_sdwa v127, v124 dst_sel:DWORD dst_unused:UNUSED_PAD src0_sel:WORD_1
	s_waitcnt vmcnt(0)
	v_pk_fma_f32 v[104:105], v[104:105], v[126:127], v[108:109]
	v_cvt_f32_f16_e32 v108, v125
	v_cvt_f32_f16_sdwa v109, v125 dst_sel:DWORD dst_unused:UNUSED_PAD src0_sel:WORD_1
	v_pk_fma_f32 v[106:107], v[106:107], v[108:109], v[110:111]
	v_lshl_add_u64 v[110:111], s[24:25], 0, v[122:123]
	v_or_b32_e32 v122, 0x100, v118
	global_store_dwordx4 v[116:117], v[104:107], off offset:64 nt
	v_lshl_add_u64 v[124:125], s[42:43], 0, v[122:123]
	global_load_dwordx2 v[124:125], v[124:125], off
	v_cvt_pk_f16_f32 v108, v104, v105
	v_cvt_pk_f16_f32 v109, v106, v107
	global_store_dwordx2 v[110:111], v[108:109], off
	v_pk_mul_f32 v[108:109], v[104:105], v[104:105]
	v_pk_mul_f32 v[110:111], v[106:107], v[106:107]
	global_load_dwordx4 v[104:107], v[116:117], off offset:512
	v_or_b32_e32 v118, 0x120, v118
	s_waitcnt vmcnt(2)
	v_cvt_f32_f16_e32 v126, v124
	v_cvt_f32_f16_sdwa v127, v124 dst_sel:DWORD dst_unused:UNUSED_PAD src0_sel:WORD_1
	s_waitcnt vmcnt(0)
; __device__ __forceinline__ float sigmoidf_(float x) { return __builtin_amdgcn_rcpf(1.0f + __expf(-x)); }
;     __device__ __forceinline__ void operator()(const Acc& acc, const Unit& u, int wr, int wc, int fr, int fq) const {
;     ...
;                 const int row = row0 + ai * HALF + m * 16; const size_t off = (size_t)row * D + col0; float sq = 0.f; const float rs = rs8[ai][m];
; #pragma unroll
;                 for (int bj = 0; bj < 2; ++bj)
; #pragma unroll
;                     for (int n = 0; n < 2; ++n) { const size_t o = off + bj * HALF + n * 16; const f32x4 r = *(const f32x4*)(out + o); const h16x4 p = *(const h16x4*)(pu + o);
;                         const f32x4 a = acc[ai][bj][m][n] * rs; f32x4 v;
;                         v.x = r.x + sigmoidf_(a.x) * (float)p.x; v.y = r.y + sigmoidf_(a.y) * (float)p.y; v.z = r.z + sigmoidf_(a.z) * (float)p.z; v.w = r.w + sigmoidf_(a.w) * (float)p.w;
;                         *(f32x4*)(out + o) = v; u32x2 w; w.x = pk2h(v.x, v.y); w.y = pk2h(v.z, v.w); *(u32x2*)(o16 + o) = w; sq += (v.x * v.x + v.y * v.y) + (v.z * v.z + v.w * v.w); }
;                 sq += __shfl_xor(sq, 16); sq += __shfl_xor(sq, 32);
;                 if (fq == 0) ssw[(size_t)row * 16 + u.pn * 4 + wc] = sq;
	v_pk_fma_f32 v[100:101], v[100:101], v[126:127], v[104:105]
	v_cvt_f32_f16_e32 v104, v125
	v_cvt_f32_f16_sdwa v105, v125 dst_sel:DWORD dst_unused:UNUSED_PAD src0_sel:WORD_1
	v_pk_fma_f32 v[102:103], v[102:103], v[104:105], v[106:107]
	global_store_dwordx4 v[116:117], v[100:103], off offset:512 nt
	v_lshl_add_u64 v[106:107], s[24:25], 0, v[122:123]
	v_lshl_add_u64 v[122:123], s[42:43], 0, v[118:119]
	global_load_dwordx2 v[122:123], v[122:123], off
	v_cvt_pk_f16_f32 v104, v100, v101
	v_cvt_pk_f16_f32 v105, v102, v103
	global_store_dwordx2 v[106:107], v[104:105], off
	global_load_dwordx4 v[104:107], v[116:117], off offset:576
	v_pk_mul_f32 v[100:101], v[100:101], v[100:101]
	v_pk_mul_f32 v[102:103], v[102:103], v[102:103]
	v_add_f32_e32 v100, v100, v101
	v_add_f32_e32 v102, v102, v103
	v_add_f32_e32 v100, v100, v102
	s_waitcnt vmcnt(2)
	v_cvt_f32_f16_e32 v120, v122
	v_cvt_f32_f16_sdwa v121, v122 dst_sel:DWORD dst_unused:UNUSED_PAD src0_sel:WORD_1
	s_waitcnt vmcnt(0)
	v_pk_fma_f32 v[96:97], v[96:97], v[120:121], v[104:105]
	v_cvt_f32_f16_e32 v104, v123
	v_cvt_f32_f16_sdwa v105, v123 dst_sel:DWORD dst_unused:UNUSED_PAD src0_sel:WORD_1
	v_pk_fma_f32 v[98:99], v[98:99], v[104:105], v[106:107]
	v_cvt_pk_f16_f32 v104, v96, v97
	v_cvt_pk_f16_f32 v105, v98, v99
	v_lshl_add_u64 v[106:107], s[24:25], 0, v[118:119]
	global_store_dwordx4 v[116:117], v[96:99], off offset:576 nt
	global_store_dwordx2 v[106:107], v[104:105], off
	v_add_f32_e32 v104, v114, v115
	v_add_f32_e32 v105, v112, v113
	v_add_f32_e32 v104, v105, v104
	v_add_f32_e32 v105, v110, v111
	v_add_f32_e32 v106, v108, v109
	v_pk_mul_f32 v[96:97], v[96:97], v[96:97]
	v_pk_mul_f32 v[98:99], v[98:99], v[98:99]
	v_add_f32_e32 v105, v106, v105
	v_add_f32_e32 v104, v104, v105
	v_add_f32_e32 v98, v98, v99
	v_add_f32_e32 v96, v96, v97
	v_add_f32_e32 v100, v104, v100
	v_add_f32_e32 v96, v96, v98
	v_add_f32_e32 v96, v100, v96
	ds_bpermute_b32 v97, v214, v96
	s_waitcnt lgkmcnt(0)
	v_add_f32_e32 v96, v96, v97
	ds_bpermute_b32 v97, v213, v96
	s_and_saveexec_b64 s[2:3], s[10:11]
	s_cbranch_execz .LBB0_889
	s_waitcnt lgkmcnt(0)
	v_add_f32_e32 v98, v96, v97
	v_lshl_add_u64 v[96:97], s[70:71], 0, v[180:181]
	v_lshl_add_u64 v[96:97], s[22:23], 2, v[96:97]
	s_lshl_b32 s92, s38, 2
	v_lshl_add_u64 v[96:97], v[96:97], 0, s[92:93]
	global_store_dword v[96:97], v98, off
.LBB0_889:
	s_or_b64 exec, exec, s[2:3]
	v_add_f32_e32 v96, v225, v226
	v_fmamk_f32 v96, v96, 0x3a800000, v201
	v_rsq_f32_e32 v104, v96
	s_waitcnt lgkmcnt(0)
	v_lshlrev_b64 v[96:97], 10, v[178:179]
	v_readlane_b32 s52, v248, 48
	v_lshl_add_u64 v[102:103], v[96:97], 0, v[138:139]
	v_readlane_b32 s66, v248, 62
	v_readlane_b32 s67, v248, 63
	v_pk_mul_f32 v[92:93], v[92:93], v[104:105] op_sel_hi:[1,0]
	v_pk_mul_f32 v[94:95], v[94:95], v[104:105] op_sel_hi:[1,0]
	v_lshl_add_u64 v[100:101], v[102:103], 2, s[66:67]
	v_lshlrev_b64 v[102:103], 1, v[102:103]
	v_lshl_add_u64 v[106:107], s[42:43], 0, v[102:103]
	global_load_dwordx2 v[106:107], v[106:107], off
	v_mul_f32_e32 v92, 0xbfb8aa3b, v92
	global_load_dwordx4 v[96:99], v[100:101], off
	v_mul_f32_e32 v93, 0xbfb8aa3b, v93
	v_exp_f32_e32 v92, v92
	v_exp_f32_e32 v93, v93
	v_mul_f32_e32 v94, 0xbfb8aa3b, v94
	v_mul_f32_e32 v95, 0xbfb8aa3b, v95
	v_add_f32_e32 v92, 1.0, v92
	v_add_f32_e32 v93, 1.0, v93
	v_exp_f32_e32 v94, v94
	v_exp_f32_e32 v95, v95
	v_rcp_f32_e32 v92, v92
	v_rcp_f32_e32 v93, v93
	v_add_f32_e32 v94, 1.0, v94
	v_add_f32_e32 v95, 1.0, v95
	v_rcp_f32_e32 v94, v94
	v_rcp_f32_e32 v95, v95
	v_pk_mul_f32 v[88:89], v[88:89], v[104:105] op_sel_hi:[1,0]
	v_pk_mul_f32 v[90:91], v[90:91], v[104:105] op_sel_hi:[1,0]
	v_mul_f32_e32 v88, 0xbfb8aa3b, v88
	v_mul_f32_e32 v89, 0xbfb8aa3b, v89
	v_exp_f32_e32 v88, v88
	v_exp_f32_e32 v89, v89
	v_mul_f32_e32 v90, 0xbfb8aa3b, v90
	v_mul_f32_e32 v91, 0xbfb8aa3b, v91
	v_add_f32_e32 v88, 1.0, v88
	v_add_f32_e32 v89, 1.0, v89
	v_exp_f32_e32 v90, v90
	v_exp_f32_e32 v91, v91
	v_rcp_f32_e32 v88, v88
	v_rcp_f32_e32 v89, v89
	v_add_f32_e32 v90, 1.0, v90
	v_add_f32_e32 v91, 1.0, v91
	v_rcp_f32_e32 v90, v90
	v_rcp_f32_e32 v91, v91
	v_pk_mul_f32 v[84:85], v[84:85], v[104:105] op_sel_hi:[1,0]
	v_pk_mul_f32 v[86:87], v[86:87], v[104:105] op_sel_hi:[1,0]
	v_mul_f32_e32 v84, 0xbfb8aa3b, v84
	v_mul_f32_e32 v85, 0xbfb8aa3b, v85
	v_exp_f32_e32 v84, v84
	v_exp_f32_e32 v85, v85
	v_mul_f32_e32 v86, 0xbfb8aa3b, v86
	v_mul_f32_e32 v87, 0xbfb8aa3b, v87
	v_add_f32_e32 v84, 1.0, v84
	v_add_f32_e32 v85, 1.0, v85
	v_exp_f32_e32 v86, v86
	v_exp_f32_e32 v87, v87
	v_rcp_f32_e32 v84, v84
	v_rcp_f32_e32 v85, v85
	v_add_f32_e32 v86, 1.0, v86
	v_add_f32_e32 v87, 1.0, v87
	v_rcp_f32_e32 v86, v86
	v_rcp_f32_e32 v87, v87
	v_pk_mul_f32 v[80:81], v[80:81], v[104:105] op_sel_hi:[1,0]
	v_pk_mul_f32 v[82:83], v[82:83], v[104:105] op_sel_hi:[1,0]
	v_mul_f32_e32 v80, 0xbfb8aa3b, v80
	v_mul_f32_e32 v81, 0xbfb8aa3b, v81
	v_exp_f32_e32 v80, v80
	v_exp_f32_e32 v81, v81
	v_mul_f32_e32 v82, 0xbfb8aa3b, v82
	v_mul_f32_e32 v83, 0xbfb8aa3b, v83
	v_add_f32_e32 v80, 1.0, v80
	v_add_f32_e32 v81, 1.0, v81
	v_exp_f32_e32 v82, v82
	v_exp_f32_e32 v83, v83
	v_rcp_f32_e32 v80, v80
	v_rcp_f32_e32 v81, v81
	v_add_f32_e32 v82, 1.0, v82
	v_add_f32_e32 v83, 1.0, v83
	v_rcp_f32_e32 v82, v82
	v_rcp_f32_e32 v83, v83
	v_readlane_b32 s53, v248, 49
	v_readlane_b32 s54, v248, 50
	v_readlane_b32 s55, v248, 51
	v_readlane_b32 s56, v248, 52
	v_readlane_b32 s57, v248, 53
	v_readlane_b32 s58, v248, 54
	v_readlane_b32 s59, v248, 55
	v_readlane_b32 s60, v248, 56
	s_waitcnt vmcnt(1)
	v_cvt_f32_f16_e32 v108, v106
	v_cvt_f32_f16_sdwa v109, v106 dst_sel:DWORD dst_unused:UNUSED_PAD src0_sel:WORD_1
	v_or_b32_e32 v106, 32, v102
	v_readlane_b32 s61, v248, 57
	v_readlane_b32 s62, v248, 58
	s_waitcnt vmcnt(0)
; __device__ __forceinline__ float sigmoidf_(float x) { return __builtin_amdgcn_rcpf(1.0f + __expf(-x)); }
;     __device__ __forceinline__ void operator()(const Acc& acc, const Unit& u, int wr, int wc, int fr, int fq) const {
;     ...
;                 const int row = row0 + ai * HALF + m * 16; const size_t off = (size_t)row * D + col0; float sq = 0.f; const float rs = rs8[ai][m];
; #pragma unroll
;                 for (int bj = 0; bj < 2; ++bj)
; #pragma unroll
;                     for (int n = 0; n < 2; ++n) { const size_t o = off + bj * HALF + n * 16; const f32x4 r = *(const f32x4*)(out + o); const h16x4 p = *(const h16x4*)(pu + o);
;                         const f32x4 a = acc[ai][bj][m][n] * rs; f32x4 v;
;                         v.x = r.x + sigmoidf_(a.x) * (float)p.x; v.y = r.y + sigmoidf_(a.y) * (float)p.y; v.z = r.z + sigmoidf_(a.z) * (float)p.z; v.w = r.w + sigmoidf_(a.w) * (float)p.w;
;                         *(f32x4*)(out + o) = v; u32x2 w; w.x = pk2h(v.x, v.y); w.y = pk2h(v.z, v.w); *(u32x2*)(o16 + o) = w; sq += (v.x * v.x + v.y * v.y) + (v.z * v.z + v.w * v.w); }
;                 sq += __shfl_xor(sq, 16); sq += __shfl_xor(sq, 32);
;                 if (fq == 0) ssw[(size_t)row * 16 + u.pn * 4 + wc] = sq;
	v_pk_fma_f32 v[92:93], v[92:93], v[108:109], v[96:97]
	v_cvt_f32_f16_e32 v96, v107
	v_cvt_f32_f16_sdwa v97, v107 dst_sel:DWORD dst_unused:UNUSED_PAD src0_sel:WORD_1
	v_mov_b32_e32 v107, v103
	v_lshl_add_u64 v[108:109], s[42:43], 0, v[106:107]
	v_readlane_b32 s63, v248, 59
	v_pk_fma_f32 v[94:95], v[94:95], v[96:97], v[98:99]
	global_store_dwordx4 v[100:101], v[92:95], off nt
	global_load_dwordx2 v[108:109], v[108:109], off
	v_cvt_pk_f16_f32 v96, v92, v93
	v_cvt_pk_f16_f32 v97, v94, v95
	v_lshl_add_u64 v[98:99], s[24:25], 0, v[102:103]
	global_store_dwordx2 v[98:99], v[96:97], off
	v_pk_mul_f32 v[96:97], v[92:93], v[92:93]
	v_pk_mul_f32 v[98:99], v[94:95], v[94:95]
	global_load_dwordx4 v[92:95], v[100:101], off offset:64
	v_readlane_b32 s64, v248, 60
	v_readlane_b32 s65, v248, 61
	s_waitcnt vmcnt(2)
	v_cvt_f32_f16_e32 v110, v108
	v_cvt_f32_f16_sdwa v111, v108 dst_sel:DWORD dst_unused:UNUSED_PAD src0_sel:WORD_1
	s_waitcnt vmcnt(0)
	v_pk_fma_f32 v[88:89], v[88:89], v[110:111], v[92:93]
	v_cvt_f32_f16_e32 v92, v109
	v_cvt_f32_f16_sdwa v93, v109 dst_sel:DWORD dst_unused:UNUSED_PAD src0_sel:WORD_1
	v_pk_fma_f32 v[90:91], v[90:91], v[92:93], v[94:95]
	v_lshl_add_u64 v[94:95], s[24:25], 0, v[106:107]
	v_or_b32_e32 v106, 0x100, v102
	global_store_dwordx4 v[100:101], v[88:91], off offset:64 nt
	v_lshl_add_u64 v[108:109], s[42:43], 0, v[106:107]
	global_load_dwordx2 v[108:109], v[108:109], off
	v_cvt_pk_f16_f32 v92, v88, v89
	v_cvt_pk_f16_f32 v93, v90, v91
	global_store_dwordx2 v[94:95], v[92:93], off
	v_pk_mul_f32 v[92:93], v[88:89], v[88:89]
	v_pk_mul_f32 v[94:95], v[90:91], v[90:91]
	global_load_dwordx4 v[88:91], v[100:101], off offset:512
	v_or_b32_e32 v102, 0x120, v102
	s_waitcnt vmcnt(2)
	v_cvt_f32_f16_e32 v110, v108
	v_cvt_f32_f16_sdwa v111, v108 dst_sel:DWORD dst_unused:UNUSED_PAD src0_sel:WORD_1
	s_waitcnt vmcnt(0)
	v_pk_fma_f32 v[84:85], v[84:85], v[110:111], v[88:89]
	v_cvt_f32_f16_e32 v88, v109
	v_cvt_f32_f16_sdwa v89, v109 dst_sel:DWORD dst_unused:UNUSED_PAD src0_sel:WORD_1
	v_pk_fma_f32 v[86:87], v[86:87], v[88:89], v[90:91]
	global_store_dwordx4 v[100:101], v[84:87], off offset:512 nt
	v_lshl_add_u64 v[90:91], s[24:25], 0, v[106:107]
	v_lshl_add_u64 v[106:107], s[42:43], 0, v[102:103]
	global_load_dwordx2 v[106:107], v[106:107], off
	v_cvt_pk_f16_f32 v88, v84, v85
	v_cvt_pk_f16_f32 v89, v86, v87
	global_store_dwordx2 v[90:91], v[88:89], off
	global_load_dwordx4 v[88:91], v[100:101], off offset:576
	v_pk_mul_f32 v[84:85], v[84:85], v[84:85]
	v_pk_mul_f32 v[86:87], v[86:87], v[86:87]
	v_add_f32_e32 v84, v84, v85
	v_add_f32_e32 v86, v86, v87
	v_add_f32_e32 v84, v84, v86
	s_waitcnt vmcnt(2)
	v_cvt_f32_f16_e32 v104, v106
	v_cvt_f32_f16_sdwa v105, v106 dst_sel:DWORD dst_unused:UNUSED_PAD src0_sel:WORD_1
	s_waitcnt vmcnt(0)
	v_pk_fma_f32 v[80:81], v[80:81], v[104:105], v[88:89]
	v_cvt_f32_f16_e32 v88, v107
	v_cvt_f32_f16_sdwa v89, v107 dst_sel:DWORD dst_unused:UNUSED_PAD src0_sel:WORD_1
	v_pk_fma_f32 v[82:83], v[82:83], v[88:89], v[90:91]
	v_cvt_pk_f16_f32 v88, v80, v81
	v_cvt_pk_f16_f32 v89, v82, v83
	v_lshl_add_u64 v[90:91], s[24:25], 0, v[102:103]
	global_store_dwordx4 v[100:101], v[80:83], off offset:576 nt
	global_store_dwordx2 v[90:91], v[88:89], off
	v_add_f32_e32 v88, v98, v99
	v_add_f32_e32 v89, v96, v97
	v_add_f32_e32 v88, v89, v88
	v_add_f32_e32 v89, v94, v95
	v_add_f32_e32 v90, v92, v93
	v_pk_mul_f32 v[80:81], v[80:81], v[80:81]
	v_pk_mul_f32 v[82:83], v[82:83], v[82:83]
	v_add_f32_e32 v89, v90, v89
	v_add_f32_e32 v88, v88, v89
	v_add_f32_e32 v82, v82, v83
	v_add_f32_e32 v80, v80, v81
	v_add_f32_e32 v84, v88, v84
	v_add_f32_e32 v80, v80, v82
	v_add_f32_e32 v80, v84, v80
	ds_bpermute_b32 v81, v214, v80
	s_waitcnt lgkmcnt(0)
	v_add_f32_e32 v80, v80, v81
	ds_bpermute_b32 v81, v213, v80
	s_mov_b64 s[2:3], exec
	v_readlane_b32 s46, v254, 16
	v_mov_b64_e32 v[154:155], v[158:159]
	s_and_b64 s[4:5], s[2:3], s[10:11]
	v_readlane_b32 s47, v254, 17
	v_mov_b64_e32 v[156:157], v[160:161]
	s_mov_b64 exec, s[4:5]
	s_cbranch_execz .LBB0_891
	s_waitcnt lgkmcnt(0)
	v_add_f32_e32 v82, v80, v81
	v_lshl_add_u64 v[80:81], s[70:71], 0, v[176:177]
	v_lshl_add_u64 v[80:81], s[22:23], 2, v[80:81]
	s_lshl_b32 s92, s38, 2
	v_lshl_add_u64 v[80:81], v[80:81], 0, s[92:93]
	global_store_dword v[80:81], v82, off
; __device__ __forceinline__ float sigmoidf_(float x) { return __builtin_amdgcn_rcpf(1.0f + __expf(-x)); }
;     __device__ __forceinline__ void operator()(const Acc& acc, const Unit& u, int wr, int wc, int fr, int fq) const {
;     ...
;                 const int row = row0 + ai * HALF + m * 16; const size_t off = (size_t)row * D + col0; float sq = 0.f; const float rs = rs8[ai][m];
; #pragma unroll
;                 for (int bj = 0; bj < 2; ++bj)
; #pragma unroll
;                     for (int n = 0; n < 2; ++n) { const size_t o = off + bj * HALF + n * 16; const f32x4 r = *(const f32x4*)(out + o); const h16x4 p = *(const h16x4*)(pu + o);
;                         const f32x4 a = acc[ai][bj][m][n] * rs; f32x4 v;
;                         v.x = r.x + sigmoidf_(a.x) * (float)p.x; v.y = r.y + sigmoidf_(a.y) * (float)p.y; v.z = r.z + sigmoidf_(a.z) * (float)p.z; v.w = r.w + sigmoidf_(a.w) * (float)p.w;
;                         *(f32x4*)(out + o) = v; u32x2 w; w.x = pk2h(v.x, v.y); w.y = pk2h(v.z, v.w); *(u32x2*)(o16 + o) = w; sq += (v.x * v.x + v.y * v.y) + (v.z * v.z + v.w * v.w); }
;                 sq += __shfl_xor(sq, 16); sq += __shfl_xor(sq, 32);
;                 if (fq == 0) ssw[(size_t)row * 16 + u.pn * 4 + wc] = sq;
.LBB0_891:
	s_or_b64 exec, exec, s[2:3]
	v_add_f32_e32 v80, v223, v224
	v_fmamk_f32 v80, v80, 0x3a800000, v201
	v_rsq_f32_e32 v88, v80
	s_waitcnt lgkmcnt(0)
	v_lshlrev_b64 v[80:81], 10, v[174:175]
	v_readlane_b32 s52, v248, 48
	v_lshl_add_u64 v[86:87], v[80:81], 0, v[138:139]
	v_readlane_b32 s66, v248, 62
	v_readlane_b32 s67, v248, 63
	v_pk_mul_f32 v[76:77], v[76:77], v[88:89] op_sel_hi:[1,0]
	v_pk_mul_f32 v[78:79], v[78:79], v[88:89] op_sel_hi:[1,0]
	v_lshl_add_u64 v[84:85], v[86:87], 2, s[66:67]
	v_lshlrev_b64 v[86:87], 1, v[86:87]
	v_lshl_add_u64 v[90:91], s[42:43], 0, v[86:87]
	global_load_dwordx2 v[90:91], v[90:91], off
	v_mul_f32_e32 v76, 0xbfb8aa3b, v76
	global_load_dwordx4 v[80:83], v[84:85], off
	v_mul_f32_e32 v77, 0xbfb8aa3b, v77
	v_exp_f32_e32 v76, v76
	v_exp_f32_e32 v77, v77
	v_mul_f32_e32 v78, 0xbfb8aa3b, v78
	v_mul_f32_e32 v79, 0xbfb8aa3b, v79
	v_add_f32_e32 v76, 1.0, v76
	v_add_f32_e32 v77, 1.0, v77
	v_exp_f32_e32 v78, v78
	v_exp_f32_e32 v79, v79
	v_rcp_f32_e32 v76, v76
	v_rcp_f32_e32 v77, v77
	v_add_f32_e32 v78, 1.0, v78
	v_add_f32_e32 v79, 1.0, v79
	v_rcp_f32_e32 v78, v78
	v_rcp_f32_e32 v79, v79
	v_pk_mul_f32 v[72:73], v[72:73], v[88:89] op_sel_hi:[1,0]
	v_pk_mul_f32 v[74:75], v[74:75], v[88:89] op_sel_hi:[1,0]
	v_mul_f32_e32 v72, 0xbfb8aa3b, v72
	v_mul_f32_e32 v73, 0xbfb8aa3b, v73
	v_exp_f32_e32 v72, v72
	v_exp_f32_e32 v73, v73
	v_mul_f32_e32 v74, 0xbfb8aa3b, v74
	v_mul_f32_e32 v75, 0xbfb8aa3b, v75
	v_add_f32_e32 v72, 1.0, v72
	v_add_f32_e32 v73, 1.0, v73
	v_exp_f32_e32 v74, v74
	v_exp_f32_e32 v75, v75
	v_rcp_f32_e32 v72, v72
	v_rcp_f32_e32 v73, v73
	v_add_f32_e32 v74, 1.0, v74
	v_add_f32_e32 v75, 1.0, v75
	v_rcp_f32_e32 v74, v74
	v_rcp_f32_e32 v75, v75
	v_pk_mul_f32 v[68:69], v[68:69], v[88:89] op_sel_hi:[1,0]
	v_pk_mul_f32 v[70:71], v[70:71], v[88:89] op_sel_hi:[1,0]
	v_mul_f32_e32 v68, 0xbfb8aa3b, v68
	v_mul_f32_e32 v69, 0xbfb8aa3b, v69
	v_exp_f32_e32 v68, v68
	v_exp_f32_e32 v69, v69
	v_mul_f32_e32 v70, 0xbfb8aa3b, v70
	v_mul_f32_e32 v71, 0xbfb8aa3b, v71
	v_add_f32_e32 v68, 1.0, v68
	v_add_f32_e32 v69, 1.0, v69
	v_exp_f32_e32 v70, v70
	v_exp_f32_e32 v71, v71
	v_rcp_f32_e32 v68, v68
	v_rcp_f32_e32 v69, v69
	v_add_f32_e32 v70, 1.0, v70
	v_add_f32_e32 v71, 1.0, v71
	v_rcp_f32_e32 v70, v70
	v_rcp_f32_e32 v71, v71
	v_pk_mul_f32 v[64:65], v[64:65], v[88:89] op_sel_hi:[1,0]
	v_pk_mul_f32 v[66:67], v[66:67], v[88:89] op_sel_hi:[1,0]
	v_mul_f32_e32 v64, 0xbfb8aa3b, v64
	v_mul_f32_e32 v65, 0xbfb8aa3b, v65
	v_exp_f32_e32 v64, v64
	v_exp_f32_e32 v65, v65
	v_mul_f32_e32 v66, 0xbfb8aa3b, v66
	v_mul_f32_e32 v67, 0xbfb8aa3b, v67
	v_add_f32_e32 v64, 1.0, v64
	v_add_f32_e32 v65, 1.0, v65
	v_exp_f32_e32 v66, v66
	v_exp_f32_e32 v67, v67
	v_rcp_f32_e32 v64, v64
	v_rcp_f32_e32 v65, v65
	v_add_f32_e32 v66, 1.0, v66
	v_add_f32_e32 v67, 1.0, v67
	v_rcp_f32_e32 v66, v66
	v_rcp_f32_e32 v67, v67
	v_readlane_b32 s53, v248, 49
	v_readlane_b32 s54, v248, 50
	v_readlane_b32 s55, v248, 51
	v_readlane_b32 s56, v248, 52
	v_readlane_b32 s57, v248, 53
	v_readlane_b32 s58, v248, 54
	v_readlane_b32 s59, v248, 55
	v_readlane_b32 s60, v248, 56
	s_waitcnt vmcnt(1)
	v_cvt_f32_f16_e32 v92, v90
	v_cvt_f32_f16_sdwa v93, v90 dst_sel:DWORD dst_unused:UNUSED_PAD src0_sel:WORD_1
	v_or_b32_e32 v90, 32, v86
	v_readlane_b32 s61, v248, 57
	v_readlane_b32 s62, v248, 58
	s_waitcnt vmcnt(0)
	v_pk_fma_f32 v[76:77], v[76:77], v[92:93], v[80:81]
	v_cvt_f32_f16_e32 v80, v91
	v_cvt_f32_f16_sdwa v81, v91 dst_sel:DWORD dst_unused:UNUSED_PAD src0_sel:WORD_1
	v_mov_b32_e32 v91, v87
	v_lshl_add_u64 v[92:93], s[42:43], 0, v[90:91]
	v_readlane_b32 s63, v248, 59
	v_pk_fma_f32 v[78:79], v[78:79], v[80:81], v[82:83]
	global_store_dwordx4 v[84:85], v[76:79], off nt
	global_load_dwordx2 v[92:93], v[92:93], off
	v_cvt_pk_f16_f32 v80, v76, v77
	v_cvt_pk_f16_f32 v81, v78, v79
	v_lshl_add_u64 v[82:83], s[24:25], 0, v[86:87]
	global_store_dwordx2 v[82:83], v[80:81], off
	v_pk_mul_f32 v[80:81], v[76:77], v[76:77]
	v_pk_mul_f32 v[82:83], v[78:79], v[78:79]
	global_load_dwordx4 v[76:79], v[84:85], off offset:64
	v_readlane_b32 s64, v248, 60
	v_readlane_b32 s65, v248, 61
	s_waitcnt vmcnt(2)
	v_cvt_f32_f16_e32 v94, v92
	v_cvt_f32_f16_sdwa v95, v92 dst_sel:DWORD dst_unused:UNUSED_PAD src0_sel:WORD_1
	s_waitcnt vmcnt(0)
	v_pk_fma_f32 v[72:73], v[72:73], v[94:95], v[76:77]
	v_cvt_f32_f16_e32 v76, v93
	v_cvt_f32_f16_sdwa v77, v93 dst_sel:DWORD dst_unused:UNUSED_PAD src0_sel:WORD_1
	v_pk_fma_f32 v[74:75], v[74:75], v[76:77], v[78:79]
	v_lshl_add_u64 v[78:79], s[24:25], 0, v[90:91]
	v_or_b32_e32 v90, 0x100, v86
	global_store_dwordx4 v[84:85], v[72:75], off offset:64 nt
	v_lshl_add_u64 v[92:93], s[42:43], 0, v[90:91]
	global_load_dwordx2 v[92:93], v[92:93], off
	v_cvt_pk_f16_f32 v76, v72, v73
	v_cvt_pk_f16_f32 v77, v74, v75
	global_store_dwordx2 v[78:79], v[76:77], off
	v_pk_mul_f32 v[76:77], v[72:73], v[72:73]
	v_pk_mul_f32 v[78:79], v[74:75], v[74:75]
	global_load_dwordx4 v[72:75], v[84:85], off offset:512
	v_or_b32_e32 v86, 0x120, v86
	s_waitcnt vmcnt(2)
	v_cvt_f32_f16_e32 v94, v92
	v_cvt_f32_f16_sdwa v95, v92 dst_sel:DWORD dst_unused:UNUSED_PAD src0_sel:WORD_1
	s_waitcnt vmcnt(0)
	v_pk_fma_f32 v[68:69], v[68:69], v[94:95], v[72:73]
	v_cvt_f32_f16_e32 v72, v93
	v_cvt_f32_f16_sdwa v73, v93 dst_sel:DWORD dst_unused:UNUSED_PAD src0_sel:WORD_1
	v_pk_fma_f32 v[70:71], v[70:71], v[72:73], v[74:75]
	global_store_dwordx4 v[84:85], v[68:71], off offset:512 nt
	v_lshl_add_u64 v[74:75], s[24:25], 0, v[90:91]
	v_lshl_add_u64 v[90:91], s[42:43], 0, v[86:87]
	global_load_dwordx2 v[90:91], v[90:91], off
	v_cvt_pk_f16_f32 v72, v68, v69
	v_cvt_pk_f16_f32 v73, v70, v71
	global_store_dwordx2 v[74:75], v[72:73], off
	global_load_dwordx4 v[72:75], v[84:85], off offset:576
	v_pk_mul_f32 v[68:69], v[68:69], v[68:69]
	v_pk_mul_f32 v[70:71], v[70:71], v[70:71]
	v_add_f32_e32 v68, v68, v69
	v_add_f32_e32 v70, v70, v71
	v_add_f32_e32 v68, v68, v70
	s_waitcnt vmcnt(2)
; __device__ __forceinline__ float sigmoidf_(float x) { return __builtin_amdgcn_rcpf(1.0f + __expf(-x)); }
;     __device__ __forceinline__ void operator()(const Acc& acc, const Unit& u, int wr, int wc, int fr, int fq) const {
;     ...
;                 const int row = row0 + ai * HALF + m * 16; const size_t off = (size_t)row * D + col0; float sq = 0.f; const float rs = rs8[ai][m];
; #pragma unroll
;                 for (int bj = 0; bj < 2; ++bj)
; #pragma unroll
;                     for (int n = 0; n < 2; ++n) { const size_t o = off + bj * HALF + n * 16; const f32x4 r = *(const f32x4*)(out + o); const h16x4 p = *(const h16x4*)(pu + o);
;                         const f32x4 a = acc[ai][bj][m][n] * rs; f32x4 v;
;                         v.x = r.x + sigmoidf_(a.x) * (float)p.x; v.y = r.y + sigmoidf_(a.y) * (float)p.y; v.z = r.z + sigmoidf_(a.z) * (float)p.z; v.w = r.w + sigmoidf_(a.w) * (float)p.w;
;                         *(f32x4*)(out + o) = v; u32x2 w; w.x = pk2h(v.x, v.y); w.y = pk2h(v.z, v.w); *(u32x2*)(o16 + o) = w; sq += (v.x * v.x + v.y * v.y) + (v.z * v.z + v.w * v.w); }
;                 sq += __shfl_xor(sq, 16); sq += __shfl_xor(sq, 32);
;                 if (fq == 0) ssw[(size_t)row * 16 + u.pn * 4 + wc] = sq;
	v_cvt_f32_f16_e32 v88, v90
	v_cvt_f32_f16_sdwa v89, v90 dst_sel:DWORD dst_unused:UNUSED_PAD src0_sel:WORD_1
	s_waitcnt vmcnt(0)
	v_pk_fma_f32 v[64:65], v[64:65], v[88:89], v[72:73]
	v_cvt_f32_f16_e32 v72, v91
	v_cvt_f32_f16_sdwa v73, v91 dst_sel:DWORD dst_unused:UNUSED_PAD src0_sel:WORD_1
	v_pk_fma_f32 v[66:67], v[66:67], v[72:73], v[74:75]
	v_cvt_pk_f16_f32 v72, v64, v65
	v_cvt_pk_f16_f32 v73, v66, v67
	v_lshl_add_u64 v[74:75], s[24:25], 0, v[86:87]
	global_store_dwordx4 v[84:85], v[64:67], off offset:576 nt
	global_store_dwordx2 v[74:75], v[72:73], off
	v_add_f32_e32 v72, v82, v83
	v_add_f32_e32 v73, v80, v81
	v_add_f32_e32 v72, v73, v72
	v_add_f32_e32 v73, v78, v79
	v_add_f32_e32 v74, v76, v77
	v_pk_mul_f32 v[64:65], v[64:65], v[64:65]
	v_pk_mul_f32 v[66:67], v[66:67], v[66:67]
	v_add_f32_e32 v73, v74, v73
	v_add_f32_e32 v72, v72, v73
	v_add_f32_e32 v66, v66, v67
	v_add_f32_e32 v64, v64, v65
	v_add_f32_e32 v68, v72, v68
	v_add_f32_e32 v64, v64, v66
	v_add_f32_e32 v64, v68, v64
	ds_bpermute_b32 v65, v214, v64
	s_waitcnt lgkmcnt(0)
	v_add_f32_e32 v64, v64, v65
	ds_bpermute_b32 v65, v213, v64
	s_and_saveexec_b64 s[2:3], s[10:11]
	s_cbranch_execz .LBB0_893
	s_waitcnt lgkmcnt(0)
	v_add_f32_e32 v66, v64, v65
	v_lshl_add_u64 v[64:65], s[70:71], 0, v[172:173]
	v_lshl_add_u64 v[64:65], s[22:23], 2, v[64:65]
	s_lshl_b32 s92, s38, 2
	v_lshl_add_u64 v[64:65], v[64:65], 0, s[92:93]
	global_store_dword v[64:65], v66, off
.LBB0_893:
	s_or_b64 exec, exec, s[2:3]
	v_add_f32_e32 v64, v221, v222
	v_fmamk_f32 v64, v64, 0x3a800000, v201
	v_rsq_f32_e32 v72, v64
	s_waitcnt lgkmcnt(0)
	v_lshlrev_b64 v[64:65], 10, v[170:171]
	v_readlane_b32 s52, v248, 48
	v_lshl_add_u64 v[70:71], v[64:65], 0, v[138:139]
	v_readlane_b32 s66, v248, 62
	v_readlane_b32 s67, v248, 63
	v_pk_mul_f32 v[60:61], v[60:61], v[72:73] op_sel_hi:[1,0]
	v_pk_mul_f32 v[62:63], v[62:63], v[72:73] op_sel_hi:[1,0]
	v_lshl_add_u64 v[68:69], v[70:71], 2, s[66:67]
	v_lshlrev_b64 v[70:71], 1, v[70:71]
	v_lshl_add_u64 v[74:75], s[42:43], 0, v[70:71]
	global_load_dwordx2 v[74:75], v[74:75], off
	v_mul_f32_e32 v60, 0xbfb8aa3b, v60
	global_load_dwordx4 v[64:67], v[68:69], off
	v_mul_f32_e32 v61, 0xbfb8aa3b, v61
	v_exp_f32_e32 v60, v60
	v_exp_f32_e32 v61, v61
	v_mul_f32_e32 v62, 0xbfb8aa3b, v62
	v_mul_f32_e32 v63, 0xbfb8aa3b, v63
	v_add_f32_e32 v60, 1.0, v60
	v_add_f32_e32 v61, 1.0, v61
	v_exp_f32_e32 v62, v62
	v_exp_f32_e32 v63, v63
	v_rcp_f32_e32 v60, v60
	v_rcp_f32_e32 v61, v61
	v_add_f32_e32 v62, 1.0, v62
	v_add_f32_e32 v63, 1.0, v63
	v_rcp_f32_e32 v62, v62
	v_rcp_f32_e32 v63, v63
	v_pk_mul_f32 v[56:57], v[56:57], v[72:73] op_sel_hi:[1,0]
	v_pk_mul_f32 v[58:59], v[58:59], v[72:73] op_sel_hi:[1,0]
	v_mul_f32_e32 v56, 0xbfb8aa3b, v56
	v_mul_f32_e32 v57, 0xbfb8aa3b, v57
	v_exp_f32_e32 v56, v56
	v_exp_f32_e32 v57, v57
	v_mul_f32_e32 v58, 0xbfb8aa3b, v58
	v_mul_f32_e32 v59, 0xbfb8aa3b, v59
	v_add_f32_e32 v56, 1.0, v56
	v_add_f32_e32 v57, 1.0, v57
	v_exp_f32_e32 v58, v58
	v_exp_f32_e32 v59, v59
	v_rcp_f32_e32 v56, v56
	v_rcp_f32_e32 v57, v57
	v_add_f32_e32 v58, 1.0, v58
	v_add_f32_e32 v59, 1.0, v59
	v_rcp_f32_e32 v58, v58
	v_rcp_f32_e32 v59, v59
	v_pk_mul_f32 v[52:53], v[52:53], v[72:73] op_sel_hi:[1,0]
	v_pk_mul_f32 v[54:55], v[54:55], v[72:73] op_sel_hi:[1,0]
	v_mul_f32_e32 v52, 0xbfb8aa3b, v52
	v_mul_f32_e32 v53, 0xbfb8aa3b, v53
	v_exp_f32_e32 v52, v52
	v_exp_f32_e32 v53, v53
	v_mul_f32_e32 v54, 0xbfb8aa3b, v54
	v_mul_f32_e32 v55, 0xbfb8aa3b, v55
	v_add_f32_e32 v52, 1.0, v52
	v_add_f32_e32 v53, 1.0, v53
	v_exp_f32_e32 v54, v54
	v_exp_f32_e32 v55, v55
	v_rcp_f32_e32 v52, v52
	v_rcp_f32_e32 v53, v53
	v_add_f32_e32 v54, 1.0, v54
	v_add_f32_e32 v55, 1.0, v55
	v_rcp_f32_e32 v54, v54
	v_rcp_f32_e32 v55, v55
	v_pk_mul_f32 v[48:49], v[48:49], v[72:73] op_sel_hi:[1,0]
	v_pk_mul_f32 v[50:51], v[50:51], v[72:73] op_sel_hi:[1,0]
	v_mul_f32_e32 v48, 0xbfb8aa3b, v48
	v_mul_f32_e32 v49, 0xbfb8aa3b, v49
	v_exp_f32_e32 v48, v48
	v_exp_f32_e32 v49, v49
	v_mul_f32_e32 v50, 0xbfb8aa3b, v50
	v_mul_f32_e32 v51, 0xbfb8aa3b, v51
	v_add_f32_e32 v48, 1.0, v48
	v_add_f32_e32 v49, 1.0, v49
	v_exp_f32_e32 v50, v50
	v_exp_f32_e32 v51, v51
	v_rcp_f32_e32 v48, v48
	v_rcp_f32_e32 v49, v49
	v_add_f32_e32 v50, 1.0, v50
	v_add_f32_e32 v51, 1.0, v51
	v_rcp_f32_e32 v50, v50
	v_rcp_f32_e32 v51, v51
	v_readlane_b32 s53, v248, 49
	v_readlane_b32 s54, v248, 50
	v_readlane_b32 s55, v248, 51
	v_readlane_b32 s56, v248, 52
	v_readlane_b32 s57, v248, 53
	v_readlane_b32 s58, v248, 54
	v_readlane_b32 s59, v248, 55
	v_readlane_b32 s60, v248, 56
	s_waitcnt vmcnt(1)
	v_cvt_f32_f16_e32 v76, v74
	v_cvt_f32_f16_sdwa v77, v74 dst_sel:DWORD dst_unused:UNUSED_PAD src0_sel:WORD_1
	v_or_b32_e32 v74, 32, v70
	v_readlane_b32 s61, v248, 57
	v_readlane_b32 s62, v248, 58
	s_waitcnt vmcnt(0)
	v_pk_fma_f32 v[60:61], v[60:61], v[76:77], v[64:65]
	v_cvt_f32_f16_e32 v64, v75
	v_cvt_f32_f16_sdwa v65, v75 dst_sel:DWORD dst_unused:UNUSED_PAD src0_sel:WORD_1
	v_mov_b32_e32 v75, v71
	v_lshl_add_u64 v[76:77], s[42:43], 0, v[74:75]
	v_readlane_b32 s63, v248, 59
	v_pk_fma_f32 v[62:63], v[62:63], v[64:65], v[66:67]
	global_store_dwordx4 v[68:69], v[60:63], off nt
	global_load_dwordx2 v[76:77], v[76:77], off
	v_cvt_pk_f16_f32 v64, v60, v61
	v_cvt_pk_f16_f32 v65, v62, v63
	v_lshl_add_u64 v[66:67], s[24:25], 0, v[70:71]
	global_store_dwordx2 v[66:67], v[64:65], off
	v_pk_mul_f32 v[64:65], v[60:61], v[60:61]
	v_pk_mul_f32 v[66:67], v[62:63], v[62:63]
	global_load_dwordx4 v[60:63], v[68:69], off offset:64
	v_readlane_b32 s64, v248, 60
	v_readlane_b32 s65, v248, 61
	s_waitcnt vmcnt(2)
	v_cvt_f32_f16_e32 v78, v76
	v_cvt_f32_f16_sdwa v79, v76 dst_sel:DWORD dst_unused:UNUSED_PAD src0_sel:WORD_1
	s_waitcnt vmcnt(0)
; __device__ __forceinline__ float sigmoidf_(float x) { return __builtin_amdgcn_rcpf(1.0f + __expf(-x)); }
;     __device__ __forceinline__ void operator()(const Acc& acc, const Unit& u, int wr, int wc, int fr, int fq) const {
;     ...
;                 const int row = row0 + ai * HALF + m * 16; const size_t off = (size_t)row * D + col0; float sq = 0.f; const float rs = rs8[ai][m];
; #pragma unroll
;                 for (int bj = 0; bj < 2; ++bj)
; #pragma unroll
;                     for (int n = 0; n < 2; ++n) { const size_t o = off + bj * HALF + n * 16; const f32x4 r = *(const f32x4*)(out + o); const h16x4 p = *(const h16x4*)(pu + o);
;                         const f32x4 a = acc[ai][bj][m][n] * rs; f32x4 v;
;                         v.x = r.x + sigmoidf_(a.x) * (float)p.x; v.y = r.y + sigmoidf_(a.y) * (float)p.y; v.z = r.z + sigmoidf_(a.z) * (float)p.z; v.w = r.w + sigmoidf_(a.w) * (float)p.w;
;                         *(f32x4*)(out + o) = v; u32x2 w; w.x = pk2h(v.x, v.y); w.y = pk2h(v.z, v.w); *(u32x2*)(o16 + o) = w; sq += (v.x * v.x + v.y * v.y) + (v.z * v.z + v.w * v.w); }
;                 sq += __shfl_xor(sq, 16); sq += __shfl_xor(sq, 32);
;                 if (fq == 0) ssw[(size_t)row * 16 + u.pn * 4 + wc] = sq;
	v_pk_fma_f32 v[56:57], v[56:57], v[78:79], v[60:61]
	v_cvt_f32_f16_e32 v60, v77
	v_cvt_f32_f16_sdwa v61, v77 dst_sel:DWORD dst_unused:UNUSED_PAD src0_sel:WORD_1
	v_pk_fma_f32 v[58:59], v[58:59], v[60:61], v[62:63]
	v_lshl_add_u64 v[62:63], s[24:25], 0, v[74:75]
	v_or_b32_e32 v74, 0x100, v70
	global_store_dwordx4 v[68:69], v[56:59], off offset:64 nt
	v_lshl_add_u64 v[76:77], s[42:43], 0, v[74:75]
	global_load_dwordx2 v[76:77], v[76:77], off
	v_cvt_pk_f16_f32 v60, v56, v57
	v_cvt_pk_f16_f32 v61, v58, v59
	global_store_dwordx2 v[62:63], v[60:61], off
	v_pk_mul_f32 v[60:61], v[56:57], v[56:57]
	v_pk_mul_f32 v[62:63], v[58:59], v[58:59]
	global_load_dwordx4 v[56:59], v[68:69], off offset:512
	v_or_b32_e32 v70, 0x120, v70
	s_waitcnt vmcnt(2)
	v_cvt_f32_f16_e32 v78, v76
	v_cvt_f32_f16_sdwa v79, v76 dst_sel:DWORD dst_unused:UNUSED_PAD src0_sel:WORD_1
	s_waitcnt vmcnt(0)
	v_pk_fma_f32 v[52:53], v[52:53], v[78:79], v[56:57]
	v_cvt_f32_f16_e32 v56, v77
	v_cvt_f32_f16_sdwa v57, v77 dst_sel:DWORD dst_unused:UNUSED_PAD src0_sel:WORD_1
	v_pk_fma_f32 v[54:55], v[54:55], v[56:57], v[58:59]
	global_store_dwordx4 v[68:69], v[52:55], off offset:512 nt
	v_lshl_add_u64 v[58:59], s[24:25], 0, v[74:75]
	v_lshl_add_u64 v[74:75], s[42:43], 0, v[70:71]
	global_load_dwordx2 v[74:75], v[74:75], off
	v_cvt_pk_f16_f32 v56, v52, v53
	v_cvt_pk_f16_f32 v57, v54, v55
	global_store_dwordx2 v[58:59], v[56:57], off
	global_load_dwordx4 v[56:59], v[68:69], off offset:576
	v_pk_mul_f32 v[52:53], v[52:53], v[52:53]
	v_pk_mul_f32 v[54:55], v[54:55], v[54:55]
	v_add_f32_e32 v52, v52, v53
	v_add_f32_e32 v54, v54, v55
	v_add_f32_e32 v52, v52, v54
	s_waitcnt vmcnt(2)
	v_cvt_f32_f16_e32 v72, v74
	v_cvt_f32_f16_sdwa v73, v74 dst_sel:DWORD dst_unused:UNUSED_PAD src0_sel:WORD_1
	s_waitcnt vmcnt(0)
	v_pk_fma_f32 v[48:49], v[48:49], v[72:73], v[56:57]
	v_cvt_f32_f16_e32 v56, v75
	v_cvt_f32_f16_sdwa v57, v75 dst_sel:DWORD dst_unused:UNUSED_PAD src0_sel:WORD_1
	v_pk_fma_f32 v[50:51], v[50:51], v[56:57], v[58:59]
	v_cvt_pk_f16_f32 v56, v48, v49
	v_cvt_pk_f16_f32 v57, v50, v51
	v_lshl_add_u64 v[58:59], s[24:25], 0, v[70:71]
	global_store_dwordx4 v[68:69], v[48:51], off offset:576 nt
	global_store_dwordx2 v[58:59], v[56:57], off
	v_add_f32_e32 v56, v66, v67
	v_add_f32_e32 v57, v64, v65
	v_add_f32_e32 v56, v57, v56
	v_add_f32_e32 v57, v62, v63
	v_add_f32_e32 v58, v60, v61
	v_pk_mul_f32 v[48:49], v[48:49], v[48:49]
	v_pk_mul_f32 v[50:51], v[50:51], v[50:51]
	v_add_f32_e32 v57, v58, v57
	v_add_f32_e32 v56, v56, v57
	v_add_f32_e32 v50, v50, v51
	v_add_f32_e32 v48, v48, v49
	v_add_f32_e32 v52, v56, v52
	v_add_f32_e32 v48, v48, v50
	v_add_f32_e32 v48, v52, v48
	ds_bpermute_b32 v49, v214, v48
	s_waitcnt lgkmcnt(0)
	v_add_f32_e32 v48, v48, v49
	ds_bpermute_b32 v49, v213, v48
	s_and_saveexec_b64 s[2:3], s[10:11]
	s_cbranch_execz .LBB0_895
	s_waitcnt lgkmcnt(0)
	v_add_f32_e32 v50, v48, v49
	v_lshl_add_u64 v[48:49], s[70:71], 0, v[150:151]
	v_lshl_add_u64 v[48:49], s[22:23], 2, v[48:49]
	s_lshl_b32 s92, s38, 2
	v_lshl_add_u64 v[48:49], v[48:49], 0, s[92:93]
	global_store_dword v[48:49], v50, off
.LBB0_895:
	s_or_b64 exec, exec, s[2:3]
	v_add_f32_e32 v48, v219, v220
	v_fmamk_f32 v48, v48, 0x3a800000, v201
	v_rsq_f32_e32 v56, v48
	s_waitcnt lgkmcnt(0)
	v_lshlrev_b64 v[48:49], 10, v[148:149]
	v_readlane_b32 s52, v248, 48
	v_lshl_add_u64 v[54:55], v[48:49], 0, v[138:139]
	v_readlane_b32 s66, v248, 62
	v_readlane_b32 s67, v248, 63
	v_pk_mul_f32 v[44:45], v[44:45], v[56:57] op_sel_hi:[1,0]
	v_pk_mul_f32 v[46:47], v[46:47], v[56:57] op_sel_hi:[1,0]
	v_lshl_add_u64 v[52:53], v[54:55], 2, s[66:67]
	v_lshlrev_b64 v[54:55], 1, v[54:55]
	v_lshl_add_u64 v[58:59], s[42:43], 0, v[54:55]
	global_load_dwordx2 v[58:59], v[58:59], off
	v_mul_f32_e32 v44, 0xbfb8aa3b, v44
	global_load_dwordx4 v[48:51], v[52:53], off
	v_mul_f32_e32 v45, 0xbfb8aa3b, v45
	v_exp_f32_e32 v44, v44
	v_exp_f32_e32 v45, v45
	v_mul_f32_e32 v46, 0xbfb8aa3b, v46
	v_mul_f32_e32 v47, 0xbfb8aa3b, v47
	v_add_f32_e32 v44, 1.0, v44
	v_add_f32_e32 v45, 1.0, v45
	v_exp_f32_e32 v46, v46
	v_exp_f32_e32 v47, v47
	v_rcp_f32_e32 v44, v44
	v_rcp_f32_e32 v45, v45
	v_add_f32_e32 v46, 1.0, v46
	v_add_f32_e32 v47, 1.0, v47
	v_rcp_f32_e32 v46, v46
	v_rcp_f32_e32 v47, v47
	v_pk_mul_f32 v[40:41], v[40:41], v[56:57] op_sel_hi:[1,0]
	v_pk_mul_f32 v[42:43], v[42:43], v[56:57] op_sel_hi:[1,0]
	v_mul_f32_e32 v40, 0xbfb8aa3b, v40
	v_mul_f32_e32 v41, 0xbfb8aa3b, v41
	v_exp_f32_e32 v40, v40
	v_exp_f32_e32 v41, v41
	v_mul_f32_e32 v42, 0xbfb8aa3b, v42
	v_mul_f32_e32 v43, 0xbfb8aa3b, v43
	v_add_f32_e32 v40, 1.0, v40
	v_add_f32_e32 v41, 1.0, v41
	v_exp_f32_e32 v42, v42
	v_exp_f32_e32 v43, v43
	v_rcp_f32_e32 v40, v40
	v_rcp_f32_e32 v41, v41
	v_add_f32_e32 v42, 1.0, v42
	v_add_f32_e32 v43, 1.0, v43
	v_rcp_f32_e32 v42, v42
	v_rcp_f32_e32 v43, v43
	v_pk_mul_f32 v[36:37], v[36:37], v[56:57] op_sel_hi:[1,0]
	v_pk_mul_f32 v[38:39], v[38:39], v[56:57] op_sel_hi:[1,0]
	v_mul_f32_e32 v36, 0xbfb8aa3b, v36
	v_mul_f32_e32 v37, 0xbfb8aa3b, v37
	v_exp_f32_e32 v36, v36
	v_exp_f32_e32 v37, v37
	v_mul_f32_e32 v38, 0xbfb8aa3b, v38
	v_mul_f32_e32 v39, 0xbfb8aa3b, v39
	v_add_f32_e32 v36, 1.0, v36
	v_add_f32_e32 v37, 1.0, v37
	v_exp_f32_e32 v38, v38
	v_exp_f32_e32 v39, v39
	v_rcp_f32_e32 v36, v36
	v_rcp_f32_e32 v37, v37
	v_add_f32_e32 v38, 1.0, v38
	v_add_f32_e32 v39, 1.0, v39
	v_rcp_f32_e32 v38, v38
	v_rcp_f32_e32 v39, v39
	v_pk_mul_f32 v[32:33], v[32:33], v[56:57] op_sel_hi:[1,0]
	v_pk_mul_f32 v[34:35], v[34:35], v[56:57] op_sel_hi:[1,0]
	v_mul_f32_e32 v32, 0xbfb8aa3b, v32
	v_mul_f32_e32 v33, 0xbfb8aa3b, v33
	v_exp_f32_e32 v32, v32
	v_exp_f32_e32 v33, v33
	v_mul_f32_e32 v34, 0xbfb8aa3b, v34
	v_mul_f32_e32 v35, 0xbfb8aa3b, v35
	v_add_f32_e32 v32, 1.0, v32
	v_add_f32_e32 v33, 1.0, v33
	v_exp_f32_e32 v34, v34
	v_exp_f32_e32 v35, v35
	v_rcp_f32_e32 v32, v32
	v_rcp_f32_e32 v33, v33
	v_add_f32_e32 v34, 1.0, v34
	v_add_f32_e32 v35, 1.0, v35
	v_rcp_f32_e32 v34, v34
	v_rcp_f32_e32 v35, v35
	v_readlane_b32 s53, v248, 49
	v_readlane_b32 s54, v248, 50
	v_readlane_b32 s55, v248, 51
	v_readlane_b32 s56, v248, 52
	v_readlane_b32 s57, v248, 53
	v_readlane_b32 s58, v248, 54
	v_readlane_b32 s59, v248, 55
	v_readlane_b32 s60, v248, 56
	s_waitcnt vmcnt(1)
; __device__ __forceinline__ float sigmoidf_(float x) { return __builtin_amdgcn_rcpf(1.0f + __expf(-x)); }
;     __device__ __forceinline__ void operator()(const Acc& acc, const Unit& u, int wr, int wc, int fr, int fq) const {
;     ...
;                 const int row = row0 + ai * HALF + m * 16; const size_t off = (size_t)row * D + col0; float sq = 0.f; const float rs = rs8[ai][m];
; #pragma unroll
;                 for (int bj = 0; bj < 2; ++bj)
; #pragma unroll
;                     for (int n = 0; n < 2; ++n) { const size_t o = off + bj * HALF + n * 16; const f32x4 r = *(const f32x4*)(out + o); const h16x4 p = *(const h16x4*)(pu + o);
;                         const f32x4 a = acc[ai][bj][m][n] * rs; f32x4 v;
;                         v.x = r.x + sigmoidf_(a.x) * (float)p.x; v.y = r.y + sigmoidf_(a.y) * (float)p.y; v.z = r.z + sigmoidf_(a.z) * (float)p.z; v.w = r.w + sigmoidf_(a.w) * (float)p.w;
;                         *(f32x4*)(out + o) = v; u32x2 w; w.x = pk2h(v.x, v.y); w.y = pk2h(v.z, v.w); *(u32x2*)(o16 + o) = w; sq += (v.x * v.x + v.y * v.y) + (v.z * v.z + v.w * v.w); }
;                 sq += __shfl_xor(sq, 16); sq += __shfl_xor(sq, 32);
;                 if (fq == 0) ssw[(size_t)row * 16 + u.pn * 4 + wc] = sq;
	v_cvt_f32_f16_e32 v60, v58
	v_cvt_f32_f16_sdwa v61, v58 dst_sel:DWORD dst_unused:UNUSED_PAD src0_sel:WORD_1
	v_or_b32_e32 v58, 32, v54
	v_readlane_b32 s61, v248, 57
	v_readlane_b32 s62, v248, 58
	s_waitcnt vmcnt(0)
	v_pk_fma_f32 v[44:45], v[44:45], v[60:61], v[48:49]
	v_cvt_f32_f16_e32 v48, v59
	v_cvt_f32_f16_sdwa v49, v59 dst_sel:DWORD dst_unused:UNUSED_PAD src0_sel:WORD_1
	v_mov_b32_e32 v59, v55
	v_lshl_add_u64 v[60:61], s[42:43], 0, v[58:59]
	v_readlane_b32 s63, v248, 59
	v_pk_fma_f32 v[46:47], v[46:47], v[48:49], v[50:51]
	global_store_dwordx4 v[52:53], v[44:47], off nt
	global_load_dwordx2 v[60:61], v[60:61], off
	v_cvt_pk_f16_f32 v48, v44, v45
	v_cvt_pk_f16_f32 v49, v46, v47
	v_lshl_add_u64 v[50:51], s[24:25], 0, v[54:55]
	global_store_dwordx2 v[50:51], v[48:49], off
	v_pk_mul_f32 v[48:49], v[44:45], v[44:45]
	v_pk_mul_f32 v[50:51], v[46:47], v[46:47]
	global_load_dwordx4 v[44:47], v[52:53], off offset:64
	v_readlane_b32 s64, v248, 60
	v_readlane_b32 s65, v248, 61
	s_waitcnt vmcnt(2)
	v_cvt_f32_f16_e32 v62, v60
	v_cvt_f32_f16_sdwa v63, v60 dst_sel:DWORD dst_unused:UNUSED_PAD src0_sel:WORD_1
	s_waitcnt vmcnt(0)
	v_pk_fma_f32 v[40:41], v[40:41], v[62:63], v[44:45]
	v_cvt_f32_f16_e32 v44, v61
	v_cvt_f32_f16_sdwa v45, v61 dst_sel:DWORD dst_unused:UNUSED_PAD src0_sel:WORD_1
	v_pk_fma_f32 v[42:43], v[42:43], v[44:45], v[46:47]
	v_lshl_add_u64 v[46:47], s[24:25], 0, v[58:59]
	v_or_b32_e32 v58, 0x100, v54
	global_store_dwordx4 v[52:53], v[40:43], off offset:64 nt
	v_lshl_add_u64 v[60:61], s[42:43], 0, v[58:59]
	global_load_dwordx2 v[60:61], v[60:61], off
	v_cvt_pk_f16_f32 v44, v40, v41
	v_cvt_pk_f16_f32 v45, v42, v43
	global_store_dwordx2 v[46:47], v[44:45], off
	v_pk_mul_f32 v[44:45], v[40:41], v[40:41]
	v_pk_mul_f32 v[46:47], v[42:43], v[42:43]
	global_load_dwordx4 v[40:43], v[52:53], off offset:512
	v_or_b32_e32 v54, 0x120, v54
	s_waitcnt vmcnt(2)
	v_cvt_f32_f16_e32 v62, v60
	v_cvt_f32_f16_sdwa v63, v60 dst_sel:DWORD dst_unused:UNUSED_PAD src0_sel:WORD_1
	s_waitcnt vmcnt(0)
	v_pk_fma_f32 v[36:37], v[36:37], v[62:63], v[40:41]
	v_cvt_f32_f16_e32 v40, v61
	v_cvt_f32_f16_sdwa v41, v61 dst_sel:DWORD dst_unused:UNUSED_PAD src0_sel:WORD_1
	v_pk_fma_f32 v[38:39], v[38:39], v[40:41], v[42:43]
	global_store_dwordx4 v[52:53], v[36:39], off offset:512 nt
	v_lshl_add_u64 v[42:43], s[24:25], 0, v[58:59]
	v_lshl_add_u64 v[58:59], s[42:43], 0, v[54:55]
	global_load_dwordx2 v[58:59], v[58:59], off
	v_cvt_pk_f16_f32 v40, v36, v37
	v_cvt_pk_f16_f32 v41, v38, v39
	global_store_dwordx2 v[42:43], v[40:41], off
	global_load_dwordx4 v[40:43], v[52:53], off offset:576
	v_pk_mul_f32 v[36:37], v[36:37], v[36:37]
	v_pk_mul_f32 v[38:39], v[38:39], v[38:39]
	v_add_f32_e32 v36, v36, v37
	v_add_f32_e32 v38, v38, v39
	v_add_f32_e32 v36, v36, v38
	s_waitcnt vmcnt(2)
	v_cvt_f32_f16_e32 v56, v58
	v_cvt_f32_f16_sdwa v57, v58 dst_sel:DWORD dst_unused:UNUSED_PAD src0_sel:WORD_1
	s_waitcnt vmcnt(0)
	v_pk_fma_f32 v[32:33], v[32:33], v[56:57], v[40:41]
	v_cvt_f32_f16_e32 v40, v59
	v_cvt_f32_f16_sdwa v41, v59 dst_sel:DWORD dst_unused:UNUSED_PAD src0_sel:WORD_1
	v_pk_fma_f32 v[34:35], v[34:35], v[40:41], v[42:43]
	v_cvt_pk_f16_f32 v40, v32, v33
	v_cvt_pk_f16_f32 v41, v34, v35
	v_lshl_add_u64 v[42:43], s[24:25], 0, v[54:55]
	global_store_dwordx4 v[52:53], v[32:35], off offset:576 nt
	global_store_dwordx2 v[42:43], v[40:41], off
	v_add_f32_e32 v40, v50, v51
	v_add_f32_e32 v41, v48, v49
	v_add_f32_e32 v40, v41, v40
	v_add_f32_e32 v41, v46, v47
	v_add_f32_e32 v42, v44, v45
	v_pk_mul_f32 v[32:33], v[32:33], v[32:33]
	v_pk_mul_f32 v[34:35], v[34:35], v[34:35]
	v_add_f32_e32 v41, v42, v41
	v_add_f32_e32 v40, v40, v41
	v_add_f32_e32 v34, v34, v35
	v_add_f32_e32 v32, v32, v33
	v_add_f32_e32 v36, v40, v36
	v_add_f32_e32 v32, v32, v34
	v_add_f32_e32 v32, v36, v32
	ds_bpermute_b32 v33, v214, v32
	s_waitcnt lgkmcnt(0)
	v_add_f32_e32 v32, v32, v33
	ds_bpermute_b32 v33, v213, v32
	s_and_saveexec_b64 s[2:3], s[10:11]
	s_cbranch_execz .LBB0_897
	s_waitcnt lgkmcnt(0)
	v_add_f32_e32 v34, v32, v33
	v_lshl_add_u64 v[32:33], s[70:71], 0, v[146:147]
	v_lshl_add_u64 v[32:33], s[22:23], 2, v[32:33]
	s_lshl_b32 s92, s38, 2
	v_lshl_add_u64 v[32:33], v[32:33], 0, s[92:93]
	global_store_dword v[32:33], v34, off
.LBB0_897:
	s_or_b64 exec, exec, s[2:3]
	v_add_f32_e32 v32, v217, v218
	v_fmamk_f32 v32, v32, 0x3a800000, v201
	v_rsq_f32_e32 v40, v32
	s_waitcnt lgkmcnt(0)
; __device__ __forceinline__ float sigmoidf_(float x) { return __builtin_amdgcn_rcpf(1.0f + __expf(-x)); }
;     __device__ __forceinline__ void operator()(const Acc& acc, const Unit& u, int wr, int wc, int fr, int fq) const {
;     ...
;                 const int row = row0 + ai * HALF + m * 16; const size_t off = (size_t)row * D + col0; float sq = 0.f; const float rs = rs8[ai][m];
; #pragma unroll
;                 for (int bj = 0; bj < 2; ++bj)
; #pragma unroll
;                     for (int n = 0; n < 2; ++n) { const size_t o = off + bj * HALF + n * 16; const f32x4 r = *(const f32x4*)(out + o); const h16x4 p = *(const h16x4*)(pu + o);
;                         const f32x4 a = acc[ai][bj][m][n] * rs; f32x4 v;
;                         v.x = r.x + sigmoidf_(a.x) * (float)p.x; v.y = r.y + sigmoidf_(a.y) * (float)p.y; v.z = r.z + sigmoidf_(a.z) * (float)p.z; v.w = r.w + sigmoidf_(a.w) * (float)p.w;
;                         *(f32x4*)(out + o) = v; u32x2 w; w.x = pk2h(v.x, v.y); w.y = pk2h(v.z, v.w); *(u32x2*)(o16 + o) = w; sq += (v.x * v.x + v.y * v.y) + (v.z * v.z + v.w * v.w); }
;                 sq += __shfl_xor(sq, 16); sq += __shfl_xor(sq, 32);
;                 if (fq == 0) ssw[(size_t)row * 16 + u.pn * 4 + wc] = sq;
	v_lshlrev_b64 v[32:33], 10, v[144:145]
	v_readlane_b32 s52, v248, 48
	v_lshl_add_u64 v[38:39], v[32:33], 0, v[138:139]
	v_readlane_b32 s66, v248, 62
	v_readlane_b32 s67, v248, 63
	v_pk_mul_f32 v[28:29], v[28:29], v[40:41] op_sel_hi:[1,0]
	v_pk_mul_f32 v[30:31], v[30:31], v[40:41] op_sel_hi:[1,0]
	v_lshl_add_u64 v[36:37], v[38:39], 2, s[66:67]
	v_lshlrev_b64 v[38:39], 1, v[38:39]
	v_lshl_add_u64 v[42:43], s[42:43], 0, v[38:39]
	global_load_dwordx2 v[42:43], v[42:43], off
	v_mul_f32_e32 v28, 0xbfb8aa3b, v28
	global_load_dwordx4 v[32:35], v[36:37], off
	v_mul_f32_e32 v29, 0xbfb8aa3b, v29
	v_exp_f32_e32 v28, v28
	v_exp_f32_e32 v29, v29
	v_mul_f32_e32 v30, 0xbfb8aa3b, v30
	v_mul_f32_e32 v31, 0xbfb8aa3b, v31
	v_add_f32_e32 v28, 1.0, v28
	v_add_f32_e32 v29, 1.0, v29
	v_exp_f32_e32 v30, v30
	v_exp_f32_e32 v31, v31
	v_rcp_f32_e32 v28, v28
	v_rcp_f32_e32 v29, v29
	v_add_f32_e32 v30, 1.0, v30
	v_add_f32_e32 v31, 1.0, v31
	v_rcp_f32_e32 v30, v30
	v_rcp_f32_e32 v31, v31
	v_pk_mul_f32 v[24:25], v[24:25], v[40:41] op_sel_hi:[1,0]
	v_pk_mul_f32 v[26:27], v[26:27], v[40:41] op_sel_hi:[1,0]
	v_mul_f32_e32 v24, 0xbfb8aa3b, v24
	v_mul_f32_e32 v25, 0xbfb8aa3b, v25
	v_exp_f32_e32 v24, v24
	v_exp_f32_e32 v25, v25
	v_mul_f32_e32 v26, 0xbfb8aa3b, v26
	v_mul_f32_e32 v27, 0xbfb8aa3b, v27
	v_add_f32_e32 v24, 1.0, v24
	v_add_f32_e32 v25, 1.0, v25
	v_exp_f32_e32 v26, v26
	v_exp_f32_e32 v27, v27
	v_rcp_f32_e32 v24, v24
	v_rcp_f32_e32 v25, v25
	v_add_f32_e32 v26, 1.0, v26
	v_add_f32_e32 v27, 1.0, v27
	v_rcp_f32_e32 v26, v26
	v_rcp_f32_e32 v27, v27
	v_pk_mul_f32 v[20:21], v[20:21], v[40:41] op_sel_hi:[1,0]
	v_pk_mul_f32 v[22:23], v[22:23], v[40:41] op_sel_hi:[1,0]
	v_mul_f32_e32 v20, 0xbfb8aa3b, v20
	v_mul_f32_e32 v21, 0xbfb8aa3b, v21
	v_exp_f32_e32 v20, v20
	v_exp_f32_e32 v21, v21
	v_mul_f32_e32 v22, 0xbfb8aa3b, v22
	v_mul_f32_e32 v23, 0xbfb8aa3b, v23
	v_add_f32_e32 v20, 1.0, v20
	v_add_f32_e32 v21, 1.0, v21
	v_exp_f32_e32 v22, v22
	v_exp_f32_e32 v23, v23
	v_rcp_f32_e32 v20, v20
	v_rcp_f32_e32 v21, v21
	v_add_f32_e32 v22, 1.0, v22
	v_add_f32_e32 v23, 1.0, v23
	v_rcp_f32_e32 v22, v22
	v_rcp_f32_e32 v23, v23
	v_pk_mul_f32 v[16:17], v[16:17], v[40:41] op_sel_hi:[1,0]
	v_pk_mul_f32 v[18:19], v[18:19], v[40:41] op_sel_hi:[1,0]
	v_mul_f32_e32 v16, 0xbfb8aa3b, v16
	v_mul_f32_e32 v17, 0xbfb8aa3b, v17
	v_exp_f32_e32 v16, v16
	v_exp_f32_e32 v17, v17
	v_mul_f32_e32 v18, 0xbfb8aa3b, v18
	v_mul_f32_e32 v19, 0xbfb8aa3b, v19
	v_add_f32_e32 v16, 1.0, v16
	v_add_f32_e32 v17, 1.0, v17
	v_exp_f32_e32 v18, v18
	v_exp_f32_e32 v19, v19
	v_rcp_f32_e32 v16, v16
	v_rcp_f32_e32 v17, v17
	v_add_f32_e32 v18, 1.0, v18
	v_add_f32_e32 v19, 1.0, v19
	v_rcp_f32_e32 v18, v18
	v_rcp_f32_e32 v19, v19
	v_readlane_b32 s53, v248, 49
	v_readlane_b32 s54, v248, 50
	v_readlane_b32 s55, v248, 51
	v_readlane_b32 s56, v248, 52
	v_readlane_b32 s57, v248, 53
	v_readlane_b32 s58, v248, 54
	v_readlane_b32 s59, v248, 55
	v_readlane_b32 s60, v248, 56
	s_waitcnt vmcnt(1)
	v_cvt_f32_f16_e32 v44, v42
	v_cvt_f32_f16_sdwa v45, v42 dst_sel:DWORD dst_unused:UNUSED_PAD src0_sel:WORD_1
	v_or_b32_e32 v42, 32, v38
	v_readlane_b32 s61, v248, 57
	v_readlane_b32 s62, v248, 58
	s_waitcnt vmcnt(0)
	v_pk_fma_f32 v[28:29], v[28:29], v[44:45], v[32:33]
	v_cvt_f32_f16_e32 v32, v43
	v_cvt_f32_f16_sdwa v33, v43 dst_sel:DWORD dst_unused:UNUSED_PAD src0_sel:WORD_1
	v_mov_b32_e32 v43, v39
	v_lshl_add_u64 v[44:45], s[42:43], 0, v[42:43]
	v_readlane_b32 s63, v248, 59
	v_pk_fma_f32 v[30:31], v[30:31], v[32:33], v[34:35]
	global_store_dwordx4 v[36:37], v[28:31], off nt
	global_load_dwordx2 v[44:45], v[44:45], off
	v_cvt_pk_f16_f32 v32, v28, v29
	v_cvt_pk_f16_f32 v33, v30, v31
	v_lshl_add_u64 v[34:35], s[24:25], 0, v[38:39]
	global_store_dwordx2 v[34:35], v[32:33], off
	v_pk_mul_f32 v[32:33], v[28:29], v[28:29]
	v_pk_mul_f32 v[34:35], v[30:31], v[30:31]
	global_load_dwordx4 v[28:31], v[36:37], off offset:64
	v_readlane_b32 s64, v248, 60
	v_readlane_b32 s65, v248, 61
	s_waitcnt vmcnt(2)
	v_cvt_f32_f16_e32 v46, v44
	v_cvt_f32_f16_sdwa v47, v44 dst_sel:DWORD dst_unused:UNUSED_PAD src0_sel:WORD_1
	s_waitcnt vmcnt(0)
	v_pk_fma_f32 v[24:25], v[24:25], v[46:47], v[28:29]
	v_cvt_f32_f16_e32 v28, v45
	v_cvt_f32_f16_sdwa v29, v45 dst_sel:DWORD dst_unused:UNUSED_PAD src0_sel:WORD_1
	v_pk_fma_f32 v[26:27], v[26:27], v[28:29], v[30:31]
	v_lshl_add_u64 v[30:31], s[24:25], 0, v[42:43]
	v_or_b32_e32 v42, 0x100, v38
	global_store_dwordx4 v[36:37], v[24:27], off offset:64 nt
	v_lshl_add_u64 v[44:45], s[42:43], 0, v[42:43]
	global_load_dwordx2 v[44:45], v[44:45], off
	v_cvt_pk_f16_f32 v28, v24, v25
	v_cvt_pk_f16_f32 v29, v26, v27
	global_store_dwordx2 v[30:31], v[28:29], off
	v_pk_mul_f32 v[28:29], v[24:25], v[24:25]
	v_pk_mul_f32 v[30:31], v[26:27], v[26:27]
	global_load_dwordx4 v[24:27], v[36:37], off offset:512
	v_or_b32_e32 v38, 0x120, v38
	s_waitcnt vmcnt(2)
	v_cvt_f32_f16_e32 v46, v44
	v_cvt_f32_f16_sdwa v47, v44 dst_sel:DWORD dst_unused:UNUSED_PAD src0_sel:WORD_1
	s_waitcnt vmcnt(0)
	v_pk_fma_f32 v[20:21], v[20:21], v[46:47], v[24:25]
	v_cvt_f32_f16_e32 v24, v45
	v_cvt_f32_f16_sdwa v25, v45 dst_sel:DWORD dst_unused:UNUSED_PAD src0_sel:WORD_1
	v_pk_fma_f32 v[22:23], v[22:23], v[24:25], v[26:27]
	global_store_dwordx4 v[36:37], v[20:23], off offset:512 nt
	v_lshl_add_u64 v[26:27], s[24:25], 0, v[42:43]
	v_lshl_add_u64 v[42:43], s[42:43], 0, v[38:39]
	global_load_dwordx2 v[42:43], v[42:43], off
	v_cvt_pk_f16_f32 v24, v20, v21
	v_cvt_pk_f16_f32 v25, v22, v23
	global_store_dwordx2 v[26:27], v[24:25], off
	global_load_dwordx4 v[24:27], v[36:37], off offset:576
	v_pk_mul_f32 v[20:21], v[20:21], v[20:21]
	v_pk_mul_f32 v[22:23], v[22:23], v[22:23]
	v_add_f32_e32 v20, v20, v21
	v_add_f32_e32 v22, v22, v23
	v_add_f32_e32 v20, v20, v22
	s_waitcnt vmcnt(2)
	v_cvt_f32_f16_e32 v40, v42
	v_cvt_f32_f16_sdwa v41, v42 dst_sel:DWORD dst_unused:UNUSED_PAD src0_sel:WORD_1
	s_waitcnt vmcnt(0)
	v_pk_fma_f32 v[16:17], v[16:17], v[40:41], v[24:25]
	v_cvt_f32_f16_e32 v24, v43
	v_cvt_f32_f16_sdwa v25, v43 dst_sel:DWORD dst_unused:UNUSED_PAD src0_sel:WORD_1
	v_pk_fma_f32 v[18:19], v[18:19], v[24:25], v[26:27]
	v_cvt_pk_f16_f32 v24, v16, v17
	v_cvt_pk_f16_f32 v25, v18, v19
	v_lshl_add_u64 v[26:27], s[24:25], 0, v[38:39]
	global_store_dwordx4 v[36:37], v[16:19], off offset:576 nt
	global_store_dwordx2 v[26:27], v[24:25], off
	v_add_f32_e32 v24, v34, v35
	v_add_f32_e32 v25, v32, v33
	v_add_f32_e32 v24, v25, v24
	v_add_f32_e32 v25, v30, v31
	v_add_f32_e32 v26, v28, v29
	v_pk_mul_f32 v[16:17], v[16:17], v[16:17]
	v_pk_mul_f32 v[18:19], v[18:19], v[18:19]
	v_add_f32_e32 v25, v26, v25
	v_add_f32_e32 v24, v24, v25
	v_add_f32_e32 v18, v18, v19
	v_add_f32_e32 v16, v16, v17
	v_add_f32_e32 v20, v24, v20
	v_add_f32_e32 v16, v16, v18
	v_add_f32_e32 v16, v20, v16
	ds_bpermute_b32 v17, v214, v16
	s_waitcnt lgkmcnt(0)
	v_add_f32_e32 v16, v16, v17
	ds_bpermute_b32 v17, v213, v16
	s_and_saveexec_b64 s[2:3], s[10:11]
	s_cbranch_execz .LBB0_899
; __device__ __forceinline__ float sigmoidf_(float x) { return __builtin_amdgcn_rcpf(1.0f + __expf(-x)); }
;     __device__ __forceinline__ void operator()(const Acc& acc, const Unit& u, int wr, int wc, int fr, int fq) const {
;     ...
;                 const int row = row0 + ai * HALF + m * 16; const size_t off = (size_t)row * D + col0; float sq = 0.f; const float rs = rs8[ai][m];
; #pragma unroll
;                 for (int bj = 0; bj < 2; ++bj)
; #pragma unroll
;                     for (int n = 0; n < 2; ++n) { const size_t o = off + bj * HALF + n * 16; const f32x4 r = *(const f32x4*)(out + o); const h16x4 p = *(const h16x4*)(pu + o);
;                         const f32x4 a = acc[ai][bj][m][n] * rs; f32x4 v;
;                         v.x = r.x + sigmoidf_(a.x) * (float)p.x; v.y = r.y + sigmoidf_(a.y) * (float)p.y; v.z = r.z + sigmoidf_(a.z) * (float)p.z; v.w = r.w + sigmoidf_(a.w) * (float)p.w;
;                         *(f32x4*)(out + o) = v; u32x2 w; w.x = pk2h(v.x, v.y); w.y = pk2h(v.z, v.w); *(u32x2*)(o16 + o) = w; sq += (v.x * v.x + v.y * v.y) + (v.z * v.z + v.w * v.w); }
;                 sq += __shfl_xor(sq, 16); sq += __shfl_xor(sq, 32);
;                 if (fq == 0) ssw[(size_t)row * 16 + u.pn * 4 + wc] = sq;
	s_waitcnt lgkmcnt(0)
	v_add_f32_e32 v18, v16, v17
	v_lshl_add_u64 v[16:17], s[70:71], 0, v[142:143]
	v_lshl_add_u64 v[16:17], s[22:23], 2, v[16:17]
	s_lshl_b32 s92, s38, 2
	v_lshl_add_u64 v[16:17], v[16:17], 0, s[92:93]
	global_store_dword v[16:17], v18, off
.LBB0_899:
	s_or_b64 exec, exec, s[2:3]
	v_add_f32_e32 v16, v215, v216
	v_fmamk_f32 v16, v16, 0x3a800000, v201
	v_rsq_f32_e32 v24, v16
	s_waitcnt lgkmcnt(0)
	v_lshlrev_b64 v[16:17], 10, v[140:141]
	v_readlane_b32 s52, v248, 48
	v_lshl_add_u64 v[22:23], v[16:17], 0, v[138:139]
	v_readlane_b32 s66, v248, 62
	v_readlane_b32 s67, v248, 63
	v_pk_mul_f32 v[12:13], v[12:13], v[24:25] op_sel_hi:[1,0]
	v_pk_mul_f32 v[14:15], v[14:15], v[24:25] op_sel_hi:[1,0]
	v_lshl_add_u64 v[20:21], v[22:23], 2, s[66:67]
	v_lshlrev_b64 v[22:23], 1, v[22:23]
	v_lshl_add_u64 v[26:27], s[42:43], 0, v[22:23]
	global_load_dwordx2 v[26:27], v[26:27], off
	v_mul_f32_e32 v12, 0xbfb8aa3b, v12
	global_load_dwordx4 v[16:19], v[20:21], off
	v_mul_f32_e32 v13, 0xbfb8aa3b, v13
	v_exp_f32_e32 v12, v12
	v_exp_f32_e32 v13, v13
	v_mul_f32_e32 v14, 0xbfb8aa3b, v14
	v_mul_f32_e32 v15, 0xbfb8aa3b, v15
	v_add_f32_e32 v12, 1.0, v12
	v_add_f32_e32 v13, 1.0, v13
	v_exp_f32_e32 v14, v14
	v_exp_f32_e32 v15, v15
	v_rcp_f32_e32 v12, v12
	v_rcp_f32_e32 v13, v13
	v_add_f32_e32 v14, 1.0, v14
	v_add_f32_e32 v15, 1.0, v15
	v_rcp_f32_e32 v14, v14
	v_rcp_f32_e32 v15, v15
	v_pk_mul_f32 v[8:9], v[8:9], v[24:25] op_sel_hi:[1,0]
	v_pk_mul_f32 v[10:11], v[10:11], v[24:25] op_sel_hi:[1,0]
	v_mul_f32_e32 v8, 0xbfb8aa3b, v8
	v_mul_f32_e32 v9, 0xbfb8aa3b, v9
	v_exp_f32_e32 v8, v8
	v_exp_f32_e32 v9, v9
	v_mul_f32_e32 v10, 0xbfb8aa3b, v10
	v_mul_f32_e32 v11, 0xbfb8aa3b, v11
	v_add_f32_e32 v8, 1.0, v8
	v_add_f32_e32 v9, 1.0, v9
	v_exp_f32_e32 v10, v10
	v_exp_f32_e32 v11, v11
	v_rcp_f32_e32 v8, v8
	v_rcp_f32_e32 v9, v9
	v_add_f32_e32 v10, 1.0, v10
	v_add_f32_e32 v11, 1.0, v11
	v_rcp_f32_e32 v10, v10
	v_rcp_f32_e32 v11, v11
	v_pk_mul_f32 v[4:5], v[4:5], v[24:25] op_sel_hi:[1,0]
	v_pk_mul_f32 v[6:7], v[6:7], v[24:25] op_sel_hi:[1,0]
	v_mul_f32_e32 v4, 0xbfb8aa3b, v4
	v_mul_f32_e32 v5, 0xbfb8aa3b, v5
	v_exp_f32_e32 v4, v4
	v_exp_f32_e32 v5, v5
	v_mul_f32_e32 v6, 0xbfb8aa3b, v6
	v_mul_f32_e32 v7, 0xbfb8aa3b, v7
	v_add_f32_e32 v4, 1.0, v4
	v_add_f32_e32 v5, 1.0, v5
	v_exp_f32_e32 v6, v6
	v_exp_f32_e32 v7, v7
	v_rcp_f32_e32 v4, v4
	v_rcp_f32_e32 v5, v5
	v_add_f32_e32 v6, 1.0, v6
	v_add_f32_e32 v7, 1.0, v7
	v_rcp_f32_e32 v6, v6
	v_rcp_f32_e32 v7, v7
	v_pk_mul_f32 v[0:1], v[0:1], v[24:25] op_sel_hi:[1,0]
	v_pk_mul_f32 v[2:3], v[2:3], v[24:25] op_sel_hi:[1,0]
	v_mul_f32_e32 v0, 0xbfb8aa3b, v0
	v_mul_f32_e32 v1, 0xbfb8aa3b, v1
	v_exp_f32_e32 v0, v0
	v_exp_f32_e32 v1, v1
	v_mul_f32_e32 v2, 0xbfb8aa3b, v2
	v_mul_f32_e32 v3, 0xbfb8aa3b, v3
	v_add_f32_e32 v0, 1.0, v0
	v_add_f32_e32 v1, 1.0, v1
	v_exp_f32_e32 v2, v2
	v_exp_f32_e32 v3, v3
	v_rcp_f32_e32 v0, v0
	v_rcp_f32_e32 v1, v1
	v_add_f32_e32 v2, 1.0, v2
	v_add_f32_e32 v3, 1.0, v3
	v_rcp_f32_e32 v2, v2
	v_rcp_f32_e32 v3, v3
	v_readlane_b32 s53, v248, 49
	v_readlane_b32 s54, v248, 50
	v_readlane_b32 s55, v248, 51
	v_readlane_b32 s56, v248, 52
	v_readlane_b32 s57, v248, 53
	v_readlane_b32 s58, v248, 54
	v_readlane_b32 s59, v248, 55
	v_readlane_b32 s60, v248, 56
	s_waitcnt vmcnt(1)
	v_cvt_f32_f16_e32 v28, v26
	v_cvt_f32_f16_sdwa v29, v26 dst_sel:DWORD dst_unused:UNUSED_PAD src0_sel:WORD_1
	v_or_b32_e32 v26, 32, v22
	v_readlane_b32 s61, v248, 57
	v_readlane_b32 s62, v248, 58
	s_waitcnt vmcnt(0)
; __device__ __forceinline__ float sigmoidf_(float x) { return __builtin_amdgcn_rcpf(1.0f + __expf(-x)); }
;     __device__ __forceinline__ void operator()(const Acc& acc, const Unit& u, int wr, int wc, int fr, int fq) const {
;     ...
;                 const int row = row0 + ai * HALF + m * 16; const size_t off = (size_t)row * D + col0; float sq = 0.f; const float rs = rs8[ai][m];
; #pragma unroll
;                 for (int bj = 0; bj < 2; ++bj)
; #pragma unroll
;                     for (int n = 0; n < 2; ++n) { const size_t o = off + bj * HALF + n * 16; const f32x4 r = *(const f32x4*)(out + o); const h16x4 p = *(const h16x4*)(pu + o);
;                         const f32x4 a = acc[ai][bj][m][n] * rs; f32x4 v;
;                         v.x = r.x + sigmoidf_(a.x) * (float)p.x; v.y = r.y + sigmoidf_(a.y) * (float)p.y; v.z = r.z + sigmoidf_(a.z) * (float)p.z; v.w = r.w + sigmoidf_(a.w) * (float)p.w;
;                         *(f32x4*)(out + o) = v; u32x2 w; w.x = pk2h(v.x, v.y); w.y = pk2h(v.z, v.w); *(u32x2*)(o16 + o) = w; sq += (v.x * v.x + v.y * v.y) + (v.z * v.z + v.w * v.w); }
;                 sq += __shfl_xor(sq, 16); sq += __shfl_xor(sq, 32);
;                 if (fq == 0) ssw[(size_t)row * 16 + u.pn * 4 + wc] = sq;
	v_pk_fma_f32 v[12:13], v[12:13], v[28:29], v[16:17]
	v_cvt_f32_f16_e32 v16, v27
	v_cvt_f32_f16_sdwa v17, v27 dst_sel:DWORD dst_unused:UNUSED_PAD src0_sel:WORD_1
	v_mov_b32_e32 v27, v23
	v_lshl_add_u64 v[28:29], s[42:43], 0, v[26:27]
	v_readlane_b32 s63, v248, 59
	v_pk_fma_f32 v[14:15], v[14:15], v[16:17], v[18:19]
	global_store_dwordx4 v[20:21], v[12:15], off nt
	global_load_dwordx2 v[28:29], v[28:29], off
	v_cvt_pk_f16_f32 v16, v12, v13
	v_cvt_pk_f16_f32 v17, v14, v15
	v_lshl_add_u64 v[18:19], s[24:25], 0, v[22:23]
	global_store_dwordx2 v[18:19], v[16:17], off
	v_pk_mul_f32 v[16:17], v[12:13], v[12:13]
	v_pk_mul_f32 v[18:19], v[14:15], v[14:15]
	global_load_dwordx4 v[12:15], v[20:21], off offset:64
	v_readlane_b32 s64, v248, 60
	v_readlane_b32 s65, v248, 61
	s_waitcnt vmcnt(2)
	v_cvt_f32_f16_e32 v30, v28
	v_cvt_f32_f16_sdwa v31, v28 dst_sel:DWORD dst_unused:UNUSED_PAD src0_sel:WORD_1
	s_waitcnt vmcnt(0)
	v_pk_fma_f32 v[8:9], v[8:9], v[30:31], v[12:13]
	v_cvt_f32_f16_e32 v12, v29
	v_cvt_f32_f16_sdwa v13, v29 dst_sel:DWORD dst_unused:UNUSED_PAD src0_sel:WORD_1
	v_pk_fma_f32 v[10:11], v[10:11], v[12:13], v[14:15]
	v_lshl_add_u64 v[14:15], s[24:25], 0, v[26:27]
	v_or_b32_e32 v26, 0x100, v22
	global_store_dwordx4 v[20:21], v[8:11], off offset:64 nt
	v_lshl_add_u64 v[28:29], s[42:43], 0, v[26:27]
	global_load_dwordx2 v[28:29], v[28:29], off
	v_cvt_pk_f16_f32 v12, v8, v9
	v_cvt_pk_f16_f32 v13, v10, v11
	global_store_dwordx2 v[14:15], v[12:13], off
	v_pk_mul_f32 v[12:13], v[8:9], v[8:9]
	v_pk_mul_f32 v[14:15], v[10:11], v[10:11]
	global_load_dwordx4 v[8:11], v[20:21], off offset:512
	v_or_b32_e32 v22, 0x120, v22
	s_waitcnt vmcnt(2)
	v_cvt_f32_f16_e32 v30, v28
	v_cvt_f32_f16_sdwa v31, v28 dst_sel:DWORD dst_unused:UNUSED_PAD src0_sel:WORD_1
	s_waitcnt vmcnt(0)
	v_pk_fma_f32 v[4:5], v[4:5], v[30:31], v[8:9]
	v_cvt_f32_f16_e32 v8, v29
	v_cvt_f32_f16_sdwa v9, v29 dst_sel:DWORD dst_unused:UNUSED_PAD src0_sel:WORD_1
	v_pk_fma_f32 v[6:7], v[6:7], v[8:9], v[10:11]
	global_store_dwordx4 v[20:21], v[4:7], off offset:512 nt
	v_lshl_add_u64 v[10:11], s[24:25], 0, v[26:27]
	v_lshl_add_u64 v[26:27], s[42:43], 0, v[22:23]
	global_load_dwordx2 v[26:27], v[26:27], off
	v_cvt_pk_f16_f32 v8, v4, v5
	v_cvt_pk_f16_f32 v9, v6, v7
	global_store_dwordx2 v[10:11], v[8:9], off
	global_load_dwordx4 v[8:11], v[20:21], off offset:576
	v_pk_mul_f32 v[4:5], v[4:5], v[4:5]
	v_pk_mul_f32 v[6:7], v[6:7], v[6:7]
	v_add_f32_e32 v4, v4, v5
	v_add_f32_e32 v6, v6, v7
	v_add_f32_e32 v4, v4, v6
	s_waitcnt vmcnt(2)
	v_cvt_f32_f16_e32 v24, v26
	v_cvt_f32_f16_sdwa v25, v26 dst_sel:DWORD dst_unused:UNUSED_PAD src0_sel:WORD_1
	s_waitcnt vmcnt(0)
	v_pk_fma_f32 v[0:1], v[0:1], v[24:25], v[8:9]
	v_cvt_f32_f16_e32 v8, v27
	v_cvt_f32_f16_sdwa v9, v27 dst_sel:DWORD dst_unused:UNUSED_PAD src0_sel:WORD_1
	v_pk_fma_f32 v[2:3], v[2:3], v[8:9], v[10:11]
	v_cvt_pk_f16_f32 v8, v0, v1
	v_cvt_pk_f16_f32 v9, v2, v3
	v_lshl_add_u64 v[10:11], s[24:25], 0, v[22:23]
	global_store_dwordx4 v[20:21], v[0:3], off offset:576 nt
	global_store_dwordx2 v[10:11], v[8:9], off
	v_add_f32_e32 v8, v18, v19
	v_add_f32_e32 v9, v16, v17
	v_add_f32_e32 v8, v9, v8
	v_add_f32_e32 v9, v14, v15
	v_add_f32_e32 v10, v12, v13
	v_pk_mul_f32 v[0:1], v[0:1], v[0:1]
	v_pk_mul_f32 v[2:3], v[2:3], v[2:3]
	v_add_f32_e32 v9, v10, v9
	v_add_f32_e32 v8, v8, v9
	v_add_f32_e32 v2, v2, v3
	v_add_f32_e32 v0, v0, v1
	v_add_f32_e32 v4, v8, v4
	v_add_f32_e32 v0, v0, v2
	v_add_f32_e32 v0, v4, v0
	ds_bpermute_b32 v1, v214, v0
	s_waitcnt lgkmcnt(0)
	v_add_f32_e32 v0, v0, v1
	ds_bpermute_b32 v1, v213, v0
	s_and_saveexec_b64 s[2:3], s[10:11]
	s_cbranch_execz .LBB0_901
	s_waitcnt lgkmcnt(0)
	v_add_f32_e32 v2, v0, v1
	v_lshl_add_u64 v[0:1], s[70:71], 0, v[136:137]
	v_lshl_add_u64 v[0:1], s[22:23], 2, v[0:1]
	s_lshl_b32 s92, s38, 2
	v_lshl_add_u64 v[0:1], v[0:1], 0, s[92:93]
	global_store_dword v[0:1], v2, off

;     __device__ __forceinline__ void operator()(const Acc& acc, const Unit& u, int wr, int wc, int fr, int fq) const {
;         const int row0 = u.pm * BM + wr * 64 + fr, col0 = u.pn * BM + wc * 32 + 4 * fq;
;         const float* res = (u.pm * BM < MP) ? res_p : res_s;
;         f32x4 rc[4], rn[4];
; #pragma unroll
;         for (int k = 0; k < 4; ++k) rc[k] = *(const f32x4*)(res + (size_t)row0 * D + col0 + (k >> 1) * HALF + (k & 1) * 16);
; #pragma unroll
;         for (int i = 0; i < 8; ++i) {
;             const int ai = i >> 2, m = i & 3;
;             const int row = row0 + ai * HALF + m * 16; const size_t off = (size_t)row * D + col0; float sq = 0.f;
;             if (i + 1 < 8) { const size_t offn = (size_t)(row0 + ((i + 1) >> 2) * HALF + ((i + 1) & 3) * 16) * D + col0;
; #pragma unroll
;                 for (int k = 0; k < 4; ++k) rn[k] = *(const f32x4*)(res + offn + (k >> 1) * HALF + (k & 1) * 16); }
; #pragma unroll
;             for (int bj = 0; bj < 2; ++bj)
; #pragma unroll
;                 for (int n = 0; n < 2; ++n) { const size_t o = off + bj * HALF + n * 16; const f32x4 v = rc[bj * 2 + n] + acc[ai][bj][m][n] * alpha;
;                     *(f32x4*)(out + o) = v; u32x2 w; w.x = pk2h(v.x, v.y); w.y = pk2h(v.z, v.w); *(u32x2*)(o16 + o) = w; sq += (v.x * v.x + v.y * v.y) + (v.z * v.z + v.w * v.w); }
;             sq += __shfl_xor(sq, 16); sq += __shfl_xor(sq, 32);
;             if (fq == 0) ss[(size_t)row * 16 + u.pn * 4 + wc] = sq;
.LBB0_935:
	v_lshl_add_u32 v180, s41, 8, v188
	v_lshl_or_b32 v176, s40, 8, v190
	v_ashrrev_i32_e32 v181, 31, v180
	v_readlane_b32 s52, v248, 48
	v_lshlrev_b64 v[128:129], 12, v[180:181]
	v_readlane_b32 s66, v248, 62
	v_readlane_b32 s67, v248, 63
	v_ashrrev_i32_e32 v177, 31, v176
	v_lshlrev_b64 v[130:131], 2, v[176:177]
	v_lshl_add_u64 v[128:129], s[66:67], 0, v[128:129]
	v_lshl_add_u64 v[186:187], v[128:129], 0, v[130:131]
	global_load_dwordx4 v[154:157], v[186:187], off
	global_load_dwordx4 v[164:167], v[186:187], off offset:64
	global_load_dwordx4 v[148:151], v[186:187], off offset:512
	global_load_dwordx4 v[144:147], v[186:187], off offset:576
	v_and_b32_e32 v129, 64, v203
	v_xor_b32_e32 v128, 16, v203
	v_add_u32_e32 v129, 64, v129
	v_cmp_lt_i32_e32 vcc, v128, v129
	v_or_b32_e32 v182, 16, v180
	v_ashrrev_i32_e32 v183, 31, v182
	v_cndmask_b32_e32 v128, v203, v128, vcc
	v_lshlrev_b32_e32 v163, 2, v128
	v_xor_b32_e32 v128, 32, v203
	v_cmp_lt_i32_e32 vcc, v128, v129
	v_lshl_add_u64 v[178:179], s[66:67], 0, v[130:131]
	s_lshl_b32 s16, s40, 2
	v_cndmask_b32_e32 v128, v203, v128, vcc
	v_lshlrev_b32_e32 v162, 2, v128
	v_lshlrev_b64 v[128:129], 10, v[180:181]
	v_lshl_add_u64 v[192:193], v[128:129], 0, v[176:177]
	v_lshlrev_b64 v[128:129], 12, v[182:183]
	v_lshl_add_u64 v[184:185], v[178:179], 0, v[128:129]
	global_load_dwordx4 v[140:143], v[184:185], off
	global_load_dwordx4 v[136:139], v[184:185], off offset:64
	global_load_dwordx4 v[132:135], v[184:185], off offset:512
	global_load_dwordx4 v[128:131], v[184:185], off offset:576
	s_ashr_i32 s17, s16, 31
	v_readlane_b32 s53, v248, 49
	v_readlane_b32 s54, v248, 50
	v_readlane_b32 s55, v248, 51
	v_readlane_b32 s56, v248, 52
	v_readlane_b32 s57, v248, 53
	v_readlane_b32 s58, v248, 54
	v_readlane_b32 s59, v248, 55
	v_readlane_b32 s60, v248, 56
	v_readlane_b32 s61, v248, 57
	v_readlane_b32 s62, v248, 58
	v_readlane_b32 s63, v248, 59
	v_readlane_b32 s64, v248, 60
	v_readlane_b32 s65, v248, 61
	s_waitcnt vmcnt(0)
	v_pk_fma_f32 v[126:127], v[126:127], 0.5, v[156:157] op_sel_hi:[1,0,1]
	v_pk_fma_f32 v[124:125], v[124:125], 0.5, v[154:155] op_sel_hi:[1,0,1]
	global_store_dwordx4 v[186:187], v[124:127], off nt
	v_cvt_pk_f16_f32 v154, v124, v125
	v_lshlrev_b64 v[156:157], 1, v[192:193]
	v_mul_f32_e32 v125, v125, v125
	v_fmac_f32_e32 v125, v124, v124
	v_mul_f32_e32 v124, v127, v127
	v_cvt_pk_f16_f32 v155, v126, v127
	v_lshl_add_u64 v[192:193], s[48:49], 0, v[156:157]
	v_fmac_f32_e32 v124, v126, v126
	v_pk_fma_f32 v[122:123], v[122:123], 0.5, v[166:167] op_sel_hi:[1,0,1]
	v_pk_fma_f32 v[120:121], v[120:121], 0.5, v[164:165] op_sel_hi:[1,0,1]
	global_store_dwordx2 v[192:193], v[154:155], off
	v_add_f32_e32 v154, v125, v124
	global_store_dwordx4 v[186:187], v[120:123], off offset:64 nt
	v_cvt_pk_f16_f32 v124, v120, v121
	v_or_b32_e32 v126, 32, v156
	v_mul_f32_e32 v121, v121, v121
	v_fmac_f32_e32 v121, v120, v120
	v_mul_f32_e32 v120, v123, v123
	v_mov_b32_e32 v127, v157
	v_fmac_f32_e32 v120, v122, v122
	v_cvt_pk_f16_f32 v125, v122, v123
	v_lshl_add_u64 v[126:127], s[48:49], 0, v[126:127]
	v_add_f32_e32 v120, v121, v120
	v_pk_fma_f32 v[118:119], v[118:119], 0.5, v[150:151] op_sel_hi:[1,0,1]
	v_pk_fma_f32 v[116:117], v[116:117], 0.5, v[148:149] op_sel_hi:[1,0,1]
	global_store_dwordx2 v[126:127], v[124:125], off
	v_add_f32_e32 v124, v154, v120
	global_store_dwordx4 v[186:187], v[116:119], off offset:512 nt
	v_cvt_pk_f16_f32 v120, v116, v117
	v_or_b32_e32 v122, 0x100, v156
	v_mul_f32_e32 v117, v117, v117
	v_fmac_f32_e32 v117, v116, v116
	v_mul_f32_e32 v116, v119, v119
	v_mov_b32_e32 v123, v157
	v_fmac_f32_e32 v116, v118, v118
	v_cvt_pk_f16_f32 v121, v118, v119
	v_lshl_add_u64 v[122:123], s[48:49], 0, v[122:123]
	v_add_f32_e32 v116, v117, v116
	v_pk_fma_f32 v[114:115], v[114:115], 0.5, v[146:147] op_sel_hi:[1,0,1]
	v_pk_fma_f32 v[112:113], v[112:113], 0.5, v[144:145] op_sel_hi:[1,0,1]
	global_store_dwordx2 v[122:123], v[120:121], off
	v_add_f32_e32 v120, v124, v116
	global_store_dwordx4 v[186:187], v[112:115], off offset:576 nt
	v_cvt_pk_f16_f32 v116, v112, v113
	v_or_b32_e32 v156, 0x120, v156
	v_mul_f32_e32 v113, v113, v113
	v_fmac_f32_e32 v113, v112, v112
	v_mul_f32_e32 v112, v115, v115
	v_fmac_f32_e32 v112, v114, v114
	v_add_f32_e32 v112, v113, v112
	v_add_f32_e32 v112, v120, v112
	ds_bpermute_b32 v113, v163, v112
	v_cvt_pk_f16_f32 v117, v114, v115
	v_lshl_add_u64 v[118:119], s[48:49], 0, v[156:157]
	global_store_dwordx2 v[118:119], v[116:117], off
	s_waitcnt lgkmcnt(0)
	v_add_f32_e32 v112, v112, v113
	ds_bpermute_b32 v113, v162, v112
	s_and_saveexec_b64 s[2:3], s[6:7]
	v_readlane_b32 s42, v254, 18
	v_readlane_b32 s43, v254, 19
	s_cbranch_execz .LBB0_937
	s_waitcnt lgkmcnt(0)
	v_add_f32_e32 v114, v112, v113
	v_lshlrev_b64 v[112:113], 6, v[180:181]
	v_lshl_add_u64 v[112:113], s[46:47], 0, v[112:113]
	v_lshl_add_u64 v[112:113], s[16:17], 2, v[112:113]
	s_lshl_b32 s92, s36, 2
	v_lshl_add_u64 v[112:113], v[112:113], 0, s[92:93]
	global_store_dword v[112:113], v114, off
;     __device__ __forceinline__ void operator()(const Acc& acc, const Unit& u, int wr, int wc, int fr, int fq) const {
;     ...
;         for (int i = 0; i < 8; ++i) {
;             const int ai = i >> 2, m = i & 3;
;             const int row = row0 + ai * HALF + m * 16; const size_t off = (size_t)row * D + col0; float sq = 0.f;
;             if (i + 1 < 8) { const size_t offn = (size_t)(row0 + ((i + 1) >> 2) * HALF + ((i + 1) & 3) * 16) * D + col0;
; #pragma unroll
;                 for (int k = 0; k < 4; ++k) rn[k] = *(const f32x4*)(res + offn + (k >> 1) * HALF + (k & 1) * 16); }
; #pragma unroll
;             for (int bj = 0; bj < 2; ++bj)
; #pragma unroll
;                 for (int n = 0; n < 2; ++n) { const size_t o = off + bj * HALF + n * 16; const f32x4 v = rc[bj * 2 + n] + acc[ai][bj][m][n] * alpha;
;                     *(f32x4*)(out + o) = v; u32x2 w; w.x = pk2h(v.x, v.y); w.y = pk2h(v.z, v.w); *(u32x2*)(o16 + o) = w; sq += (v.x * v.x + v.y * v.y) + (v.z * v.z + v.w * v.w); }
;             sq += __shfl_xor(sq, 16); sq += __shfl_xor(sq, 32);
;             if (fq == 0) ss[(size_t)row * 16 + u.pn * 4 + wc] = sq;
; #pragma unroll
;             for (int k = 0; k < 4; ++k) rc[k] = rn[k];
.LBB0_937:
	s_or_b64 exec, exec, s[2:3]
	v_or_b32_e32 v144, 32, v180
	v_ashrrev_i32_e32 v145, 31, v144
	s_waitcnt lgkmcnt(0)
	v_lshlrev_b64 v[112:113], 12, v[144:145]
	v_lshl_add_u64 v[146:147], v[178:179], 0, v[112:113]
	global_load_dwordx4 v[124:127], v[146:147], off
	global_load_dwordx4 v[120:123], v[146:147], off offset:64
	global_load_dwordx4 v[116:119], v[146:147], off offset:512
	global_load_dwordx4 v[112:115], v[146:147], off offset:576
	v_lshlrev_b64 v[148:149], 10, v[182:183]
	v_pk_fma_f32 v[110:111], v[110:111], 0.5, v[142:143] op_sel_hi:[1,0,1]
	v_pk_fma_f32 v[108:109], v[108:109], 0.5, v[140:141] op_sel_hi:[1,0,1]
	v_lshl_add_u64 v[148:149], v[148:149], 0, v[176:177]
	global_store_dwordx4 v[184:185], v[108:111], off nt
	v_cvt_pk_f16_f32 v140, v108, v109
	v_lshlrev_b64 v[142:143], 1, v[148:149]
	v_mul_f32_e32 v109, v109, v109
	v_fmac_f32_e32 v109, v108, v108
	v_mul_f32_e32 v108, v111, v111
	v_cvt_pk_f16_f32 v141, v110, v111
	v_lshl_add_u64 v[148:149], s[48:49], 0, v[142:143]
	v_fmac_f32_e32 v108, v110, v110
	v_pk_fma_f32 v[106:107], v[106:107], 0.5, v[138:139] op_sel_hi:[1,0,1]
	v_pk_fma_f32 v[104:105], v[104:105], 0.5, v[136:137] op_sel_hi:[1,0,1]
	global_store_dwordx2 v[148:149], v[140:141], off
	v_add_f32_e32 v140, v109, v108
	global_store_dwordx4 v[184:185], v[104:107], off offset:64 nt
	v_cvt_pk_f16_f32 v108, v104, v105
	v_or_b32_e32 v110, 32, v142
	v_mul_f32_e32 v105, v105, v105
	v_fmac_f32_e32 v105, v104, v104
	v_mul_f32_e32 v104, v107, v107
	v_mov_b32_e32 v111, v143
	v_fmac_f32_e32 v104, v106, v106
	v_cvt_pk_f16_f32 v109, v106, v107
	v_lshl_add_u64 v[110:111], s[48:49], 0, v[110:111]
	v_add_f32_e32 v104, v105, v104
	v_pk_fma_f32 v[102:103], v[102:103], 0.5, v[134:135] op_sel_hi:[1,0,1]
	v_pk_fma_f32 v[100:101], v[100:101], 0.5, v[132:133] op_sel_hi:[1,0,1]
	global_store_dwordx2 v[110:111], v[108:109], off
	v_add_f32_e32 v108, v140, v104
	global_store_dwordx4 v[184:185], v[100:103], off offset:512 nt
	v_cvt_pk_f16_f32 v104, v100, v101
	v_pk_fma_f32 v[98:99], v[98:99], 0.5, v[130:131] op_sel_hi:[1,0,1]
	v_mul_f32_e32 v101, v101, v101
	v_fmac_f32_e32 v101, v100, v100
	v_mul_f32_e32 v100, v103, v103
	v_fmac_f32_e32 v100, v102, v102
	v_pk_fma_f32 v[96:97], v[96:97], 0.5, v[128:129] op_sel_hi:[1,0,1]
	v_cvt_pk_f16_f32 v105, v102, v103
	v_add_f32_e32 v100, v101, v100
	v_mul_f32_e32 v101, v97, v97
	v_mul_f32_e32 v102, v99, v99
	v_fmac_f32_e32 v101, v96, v96
	v_fmac_f32_e32 v102, v98, v98
	v_add_f32_e32 v100, v108, v100
	v_add_f32_e32 v101, v101, v102
	v_add_f32_e32 v102, v100, v101
	ds_bpermute_b32 v103, v163, v102
	v_or_b32_e32 v106, 0x100, v142
	v_mov_b32_e32 v107, v143
	v_lshl_add_u64 v[100:101], s[48:49], 0, v[106:107]
	global_store_dwordx2 v[100:101], v[104:105], off
	global_store_dwordx4 v[184:185], v[96:99], off offset:576 nt
	v_cvt_pk_f16_f32 v100, v96, v97
	v_or_b32_e32 v142, 0x120, v142
	s_waitcnt lgkmcnt(0)
	v_add_f32_e32 v96, v102, v103
	ds_bpermute_b32 v97, v162, v96
	v_cvt_pk_f16_f32 v101, v98, v99
	v_lshl_add_u64 v[98:99], s[48:49], 0, v[142:143]
	global_store_dwordx2 v[98:99], v[100:101], off
	s_and_saveexec_b64 s[2:3], s[6:7]
	s_cbranch_execz .LBB0_939
	s_waitcnt lgkmcnt(0)
	v_add_f32_e32 v98, v96, v97
	v_lshlrev_b64 v[96:97], 6, v[182:183]
	v_lshl_add_u64 v[96:97], s[46:47], 0, v[96:97]
	v_lshl_add_u64 v[96:97], s[16:17], 2, v[96:97]
	s_lshl_b32 s92, s36, 2
	v_lshl_add_u64 v[96:97], v[96:97], 0, s[92:93]
	global_store_dword v[96:97], v98, off
.LBB0_939:
	s_or_b64 exec, exec, s[2:3]
	v_or_b32_e32 v128, 48, v180
	v_ashrrev_i32_e32 v129, 31, v128
	s_waitcnt lgkmcnt(0)
	v_lshlrev_b64 v[96:97], 12, v[128:129]
	v_lshl_add_u64 v[130:131], v[178:179], 0, v[96:97]
	global_load_dwordx4 v[108:111], v[130:131], off
	global_load_dwordx4 v[104:107], v[130:131], off offset:64
	global_load_dwordx4 v[100:103], v[130:131], off offset:512
	global_load_dwordx4 v[96:99], v[130:131], off offset:576
	v_lshlrev_b64 v[132:133], 10, v[144:145]
	s_waitcnt vmcnt(15)
	v_pk_fma_f32 v[94:95], v[94:95], 0.5, v[126:127] op_sel_hi:[1,0,1]
	v_pk_fma_f32 v[92:93], v[92:93], 0.5, v[124:125] op_sel_hi:[1,0,1]
	v_lshl_add_u64 v[132:133], v[132:133], 0, v[176:177]
	global_store_dwordx4 v[146:147], v[92:95], off nt
	v_cvt_pk_f16_f32 v124, v92, v93
	v_lshlrev_b64 v[126:127], 1, v[132:133]
	v_mul_f32_e32 v93, v93, v93
	v_fmac_f32_e32 v93, v92, v92
	v_mul_f32_e32 v92, v95, v95
	v_cvt_pk_f16_f32 v125, v94, v95
	v_lshl_add_u64 v[132:133], s[48:49], 0, v[126:127]
	v_fmac_f32_e32 v92, v94, v94
	s_waitcnt vmcnt(15)
	v_pk_fma_f32 v[90:91], v[90:91], 0.5, v[122:123] op_sel_hi:[1,0,1]
	v_pk_fma_f32 v[88:89], v[88:89], 0.5, v[120:121] op_sel_hi:[1,0,1]
	global_store_dwordx2 v[132:133], v[124:125], off
	v_add_f32_e32 v124, v93, v92
	global_store_dwordx4 v[146:147], v[88:91], off offset:64 nt
	v_cvt_pk_f16_f32 v92, v88, v89
	v_or_b32_e32 v94, 32, v126
	v_mul_f32_e32 v89, v89, v89
	v_fmac_f32_e32 v89, v88, v88
	v_mul_f32_e32 v88, v91, v91
	v_mov_b32_e32 v95, v127
	v_fmac_f32_e32 v88, v90, v90
	v_cvt_pk_f16_f32 v93, v90, v91
	v_lshl_add_u64 v[94:95], s[48:49], 0, v[94:95]
	v_add_f32_e32 v88, v89, v88
	s_waitcnt vmcnt(16)
	v_pk_fma_f32 v[86:87], v[86:87], 0.5, v[118:119] op_sel_hi:[1,0,1]
	v_pk_fma_f32 v[84:85], v[84:85], 0.5, v[116:117] op_sel_hi:[1,0,1]
	global_store_dwordx2 v[94:95], v[92:93], off
	v_add_f32_e32 v92, v124, v88
	global_store_dwordx4 v[146:147], v[84:87], off offset:512 nt
	v_cvt_pk_f16_f32 v88, v84, v85
	s_waitcnt vmcnt(17)
	v_pk_fma_f32 v[82:83], v[82:83], 0.5, v[114:115] op_sel_hi:[1,0,1]
	v_mul_f32_e32 v85, v85, v85
	v_fmac_f32_e32 v85, v84, v84
	v_mul_f32_e32 v84, v87, v87
	v_fmac_f32_e32 v84, v86, v86
	v_pk_fma_f32 v[80:81], v[80:81], 0.5, v[112:113] op_sel_hi:[1,0,1]
	v_cvt_pk_f16_f32 v89, v86, v87
	v_add_f32_e32 v84, v85, v84
	v_mul_f32_e32 v85, v81, v81
	v_mul_f32_e32 v86, v83, v83
	v_fmac_f32_e32 v85, v80, v80
	v_fmac_f32_e32 v86, v82, v82
	v_add_f32_e32 v84, v92, v84
	v_add_f32_e32 v85, v85, v86
	v_add_f32_e32 v86, v84, v85
	ds_bpermute_b32 v87, v163, v86
	v_or_b32_e32 v90, 0x100, v126
	v_mov_b32_e32 v91, v127
	v_lshl_add_u64 v[84:85], s[48:49], 0, v[90:91]
	global_store_dwordx2 v[84:85], v[88:89], off
	global_store_dwordx4 v[146:147], v[80:83], off offset:576 nt
	v_cvt_pk_f16_f32 v84, v80, v81
	v_or_b32_e32 v126, 0x120, v126
	s_waitcnt lgkmcnt(0)
	v_add_f32_e32 v80, v86, v87
	ds_bpermute_b32 v81, v162, v80
	v_cvt_pk_f16_f32 v85, v82, v83
	v_lshl_add_u64 v[82:83], s[48:49], 0, v[126:127]
	global_store_dwordx2 v[82:83], v[84:85], off
	s_mov_b64 s[2:3], exec
	v_mov_b64_e32 v[154:155], v[158:159]
	s_and_b64 s[18:19], s[2:3], s[6:7]
	v_mov_b64_e32 v[156:157], v[160:161]
	s_mov_b64 exec, s[18:19]
	s_cbranch_execz .LBB0_941
	s_waitcnt lgkmcnt(0)
	v_add_f32_e32 v82, v80, v81
	v_lshlrev_b64 v[80:81], 6, v[144:145]
	v_lshl_add_u64 v[80:81], s[46:47], 0, v[80:81]
	v_lshl_add_u64 v[80:81], s[16:17], 2, v[80:81]
	s_lshl_b32 s92, s36, 2
	v_lshl_add_u64 v[80:81], v[80:81], 0, s[92:93]
	global_store_dword v[80:81], v82, off
;     __device__ __forceinline__ void operator()(const Acc& acc, const Unit& u, int wr, int wc, int fr, int fq) const {
;     ...
;         for (int i = 0; i < 8; ++i) {
;             const int ai = i >> 2, m = i & 3;
;             const int row = row0 + ai * HALF + m * 16; const size_t off = (size_t)row * D + col0; float sq = 0.f;
;             if (i + 1 < 8) { const size_t offn = (size_t)(row0 + ((i + 1) >> 2) * HALF + ((i + 1) & 3) * 16) * D + col0;
; #pragma unroll
;                 for (int k = 0; k < 4; ++k) rn[k] = *(const f32x4*)(res + offn + (k >> 1) * HALF + (k & 1) * 16); }
; #pragma unroll
;             for (int bj = 0; bj < 2; ++bj)
; #pragma unroll
;                 for (int n = 0; n < 2; ++n) { const size_t o = off + bj * HALF + n * 16; const f32x4 v = rc[bj * 2 + n] + acc[ai][bj][m][n] * alpha;
;                     *(f32x4*)(out + o) = v; u32x2 w; w.x = pk2h(v.x, v.y); w.y = pk2h(v.z, v.w); *(u32x2*)(o16 + o) = w; sq += (v.x * v.x + v.y * v.y) + (v.z * v.z + v.w * v.w); }
;             sq += __shfl_xor(sq, 16); sq += __shfl_xor(sq, 32);
;             if (fq == 0) ss[(size_t)row * 16 + u.pn * 4 + wc] = sq;
; #pragma unroll
;             for (int k = 0; k < 4; ++k) rc[k] = rn[k];
.LBB0_941:
	s_or_b64 exec, exec, s[2:3]
	v_add_u32_e32 v112, 0x80, v180
	v_ashrrev_i32_e32 v113, 31, v112
	s_waitcnt lgkmcnt(0)
	v_lshlrev_b64 v[80:81], 12, v[112:113]
	v_lshl_add_u64 v[114:115], v[178:179], 0, v[80:81]
	global_load_dwordx4 v[92:95], v[114:115], off
	global_load_dwordx4 v[88:91], v[114:115], off offset:64
	global_load_dwordx4 v[84:87], v[114:115], off offset:512
	global_load_dwordx4 v[80:83], v[114:115], off offset:576
	v_lshlrev_b64 v[116:117], 10, v[128:129]
	s_waitcnt vmcnt(15)
	v_pk_fma_f32 v[78:79], v[78:79], 0.5, v[110:111] op_sel_hi:[1,0,1]
	v_pk_fma_f32 v[76:77], v[76:77], 0.5, v[108:109] op_sel_hi:[1,0,1]
	v_lshl_add_u64 v[116:117], v[116:117], 0, v[176:177]
	global_store_dwordx4 v[130:131], v[76:79], off nt
	v_cvt_pk_f16_f32 v108, v76, v77
	v_lshlrev_b64 v[110:111], 1, v[116:117]
	v_mul_f32_e32 v77, v77, v77
	v_fmac_f32_e32 v77, v76, v76
	v_mul_f32_e32 v76, v79, v79
	v_cvt_pk_f16_f32 v109, v78, v79
	v_lshl_add_u64 v[116:117], s[48:49], 0, v[110:111]
	v_fmac_f32_e32 v76, v78, v78
	s_waitcnt vmcnt(15)
	v_pk_fma_f32 v[74:75], v[74:75], 0.5, v[106:107] op_sel_hi:[1,0,1]
	v_pk_fma_f32 v[72:73], v[72:73], 0.5, v[104:105] op_sel_hi:[1,0,1]
	global_store_dwordx2 v[116:117], v[108:109], off
	v_add_f32_e32 v108, v77, v76
	global_store_dwordx4 v[130:131], v[72:75], off offset:64 nt
	v_cvt_pk_f16_f32 v76, v72, v73
	v_or_b32_e32 v78, 32, v110
	v_mul_f32_e32 v73, v73, v73
	v_fmac_f32_e32 v73, v72, v72
	v_mul_f32_e32 v72, v75, v75
	v_mov_b32_e32 v79, v111
	v_fmac_f32_e32 v72, v74, v74
	v_cvt_pk_f16_f32 v77, v74, v75
	v_lshl_add_u64 v[78:79], s[48:49], 0, v[78:79]
	v_add_f32_e32 v72, v73, v72
	s_waitcnt vmcnt(16)
	v_pk_fma_f32 v[70:71], v[70:71], 0.5, v[102:103] op_sel_hi:[1,0,1]
	v_pk_fma_f32 v[68:69], v[68:69], 0.5, v[100:101] op_sel_hi:[1,0,1]
	global_store_dwordx2 v[78:79], v[76:77], off
	v_add_f32_e32 v76, v108, v72
	global_store_dwordx4 v[130:131], v[68:71], off offset:512 nt
	v_cvt_pk_f16_f32 v72, v68, v69
	s_waitcnt vmcnt(17)
	v_pk_fma_f32 v[66:67], v[66:67], 0.5, v[98:99] op_sel_hi:[1,0,1]
	v_mul_f32_e32 v69, v69, v69
	v_fmac_f32_e32 v69, v68, v68
	v_mul_f32_e32 v68, v71, v71
	v_fmac_f32_e32 v68, v70, v70
	v_pk_fma_f32 v[64:65], v[64:65], 0.5, v[96:97] op_sel_hi:[1,0,1]
	v_cvt_pk_f16_f32 v73, v70, v71
	v_add_f32_e32 v68, v69, v68
	v_mul_f32_e32 v69, v65, v65
	v_mul_f32_e32 v70, v67, v67
	v_fmac_f32_e32 v69, v64, v64
	v_fmac_f32_e32 v70, v66, v66
	v_add_f32_e32 v68, v76, v68
	v_add_f32_e32 v69, v69, v70
	v_add_f32_e32 v70, v68, v69
	ds_bpermute_b32 v71, v163, v70
	v_or_b32_e32 v74, 0x100, v110
	v_mov_b32_e32 v75, v111
	v_lshl_add_u64 v[68:69], s[48:49], 0, v[74:75]
	global_store_dwordx2 v[68:69], v[72:73], off
	global_store_dwordx4 v[130:131], v[64:67], off offset:576 nt
	v_cvt_pk_f16_f32 v68, v64, v65
	v_or_b32_e32 v110, 0x120, v110
	s_waitcnt lgkmcnt(0)
	v_add_f32_e32 v64, v70, v71
	ds_bpermute_b32 v65, v162, v64
	v_cvt_pk_f16_f32 v69, v66, v67
	v_lshl_add_u64 v[66:67], s[48:49], 0, v[110:111]
	global_store_dwordx2 v[66:67], v[68:69], off
	s_and_saveexec_b64 s[2:3], s[6:7]
	s_cbranch_execz .LBB0_943
	s_waitcnt lgkmcnt(0)
	v_add_f32_e32 v66, v64, v65
	v_lshlrev_b64 v[64:65], 6, v[128:129]
	v_lshl_add_u64 v[64:65], s[46:47], 0, v[64:65]
	v_lshl_add_u64 v[64:65], s[16:17], 2, v[64:65]
	s_lshl_b32 s92, s36, 2
	v_lshl_add_u64 v[64:65], v[64:65], 0, s[92:93]
	global_store_dword v[64:65], v66, off
.LBB0_943:
	s_or_b64 exec, exec, s[2:3]
	v_or_b32_e32 v96, 16, v112
	v_ashrrev_i32_e32 v97, 31, v96
	s_waitcnt lgkmcnt(0)
	v_lshlrev_b64 v[64:65], 12, v[96:97]
	v_lshl_add_u64 v[98:99], v[178:179], 0, v[64:65]
	global_load_dwordx4 v[76:79], v[98:99], off
	global_load_dwordx4 v[72:75], v[98:99], off offset:64
	global_load_dwordx4 v[68:71], v[98:99], off offset:512
	global_load_dwordx4 v[64:67], v[98:99], off offset:576
	v_lshlrev_b64 v[100:101], 10, v[112:113]
	s_waitcnt vmcnt(15)
	v_pk_fma_f32 v[62:63], v[62:63], 0.5, v[94:95] op_sel_hi:[1,0,1]
	v_pk_fma_f32 v[60:61], v[60:61], 0.5, v[92:93] op_sel_hi:[1,0,1]
	v_lshl_add_u64 v[100:101], v[100:101], 0, v[176:177]
	global_store_dwordx4 v[114:115], v[60:63], off nt
	v_cvt_pk_f16_f32 v92, v60, v61
	v_lshlrev_b64 v[94:95], 1, v[100:101]
	v_mul_f32_e32 v61, v61, v61
	v_fmac_f32_e32 v61, v60, v60
	v_mul_f32_e32 v60, v63, v63
	v_cvt_pk_f16_f32 v93, v62, v63
	v_lshl_add_u64 v[100:101], s[48:49], 0, v[94:95]
	v_fmac_f32_e32 v60, v62, v62
	s_waitcnt vmcnt(15)
	v_pk_fma_f32 v[58:59], v[58:59], 0.5, v[90:91] op_sel_hi:[1,0,1]
	v_pk_fma_f32 v[56:57], v[56:57], 0.5, v[88:89] op_sel_hi:[1,0,1]
	global_store_dwordx2 v[100:101], v[92:93], off
	v_add_f32_e32 v92, v61, v60
	global_store_dwordx4 v[114:115], v[56:59], off offset:64 nt
	v_cvt_pk_f16_f32 v60, v56, v57
	v_or_b32_e32 v62, 32, v94
	v_mul_f32_e32 v57, v57, v57
	v_fmac_f32_e32 v57, v56, v56
	v_mul_f32_e32 v56, v59, v59
	v_mov_b32_e32 v63, v95
	v_fmac_f32_e32 v56, v58, v58
	v_cvt_pk_f16_f32 v61, v58, v59
	v_lshl_add_u64 v[62:63], s[48:49], 0, v[62:63]
	v_add_f32_e32 v56, v57, v56
	s_waitcnt vmcnt(16)
	v_pk_fma_f32 v[54:55], v[54:55], 0.5, v[86:87] op_sel_hi:[1,0,1]
	v_pk_fma_f32 v[52:53], v[52:53], 0.5, v[84:85] op_sel_hi:[1,0,1]
	global_store_dwordx2 v[62:63], v[60:61], off
	v_add_f32_e32 v60, v92, v56
	global_store_dwordx4 v[114:115], v[52:55], off offset:512 nt
	v_cvt_pk_f16_f32 v56, v52, v53
	s_waitcnt vmcnt(17)
	v_pk_fma_f32 v[50:51], v[50:51], 0.5, v[82:83] op_sel_hi:[1,0,1]
	v_mul_f32_e32 v53, v53, v53
	v_fmac_f32_e32 v53, v52, v52
	v_mul_f32_e32 v52, v55, v55
	v_fmac_f32_e32 v52, v54, v54
	v_pk_fma_f32 v[48:49], v[48:49], 0.5, v[80:81] op_sel_hi:[1,0,1]
	v_cvt_pk_f16_f32 v57, v54, v55
	v_add_f32_e32 v52, v53, v52
	v_mul_f32_e32 v53, v49, v49
	v_mul_f32_e32 v54, v51, v51
	v_fmac_f32_e32 v53, v48, v48
	v_fmac_f32_e32 v54, v50, v50
	v_add_f32_e32 v52, v60, v52
	v_add_f32_e32 v53, v53, v54
	v_add_f32_e32 v54, v52, v53
	ds_bpermute_b32 v55, v163, v54
	v_or_b32_e32 v58, 0x100, v94
	v_mov_b32_e32 v59, v95
	v_lshl_add_u64 v[52:53], s[48:49], 0, v[58:59]
	global_store_dwordx2 v[52:53], v[56:57], off
	global_store_dwordx4 v[114:115], v[48:51], off offset:576 nt
	v_cvt_pk_f16_f32 v52, v48, v49
	v_or_b32_e32 v94, 0x120, v94
	s_waitcnt lgkmcnt(0)
	v_add_f32_e32 v48, v54, v55
	ds_bpermute_b32 v49, v162, v48
	v_cvt_pk_f16_f32 v53, v50, v51
	v_lshl_add_u64 v[50:51], s[48:49], 0, v[94:95]
	global_store_dwordx2 v[50:51], v[52:53], off
	s_and_saveexec_b64 s[2:3], s[6:7]
	s_cbranch_execz .LBB0_945
	s_waitcnt lgkmcnt(0)
	v_add_f32_e32 v50, v48, v49
	v_lshlrev_b64 v[48:49], 6, v[112:113]
	v_lshl_add_u64 v[48:49], s[46:47], 0, v[48:49]
	v_lshl_add_u64 v[48:49], s[16:17], 2, v[48:49]
	s_lshl_b32 s92, s36, 2
	v_lshl_add_u64 v[48:49], v[48:49], 0, s[92:93]
	global_store_dword v[48:49], v50, off
;     __device__ __forceinline__ void operator()(const Acc& acc, const Unit& u, int wr, int wc, int fr, int fq) const {
;     ...
;         for (int i = 0; i < 8; ++i) {
;             const int ai = i >> 2, m = i & 3;
;             const int row = row0 + ai * HALF + m * 16; const size_t off = (size_t)row * D + col0; float sq = 0.f;
;             if (i + 1 < 8) { const size_t offn = (size_t)(row0 + ((i + 1) >> 2) * HALF + ((i + 1) & 3) * 16) * D + col0;
; #pragma unroll
;                 for (int k = 0; k < 4; ++k) rn[k] = *(const f32x4*)(res + offn + (k >> 1) * HALF + (k & 1) * 16); }
; #pragma unroll
;             for (int bj = 0; bj < 2; ++bj)
; #pragma unroll
;                 for (int n = 0; n < 2; ++n) { const size_t o = off + bj * HALF + n * 16; const f32x4 v = rc[bj * 2 + n] + acc[ai][bj][m][n] * alpha;
;                     *(f32x4*)(out + o) = v; u32x2 w; w.x = pk2h(v.x, v.y); w.y = pk2h(v.z, v.w); *(u32x2*)(o16 + o) = w; sq += (v.x * v.x + v.y * v.y) + (v.z * v.z + v.w * v.w); }
;             sq += __shfl_xor(sq, 16); sq += __shfl_xor(sq, 32);
;             if (fq == 0) ss[(size_t)row * 16 + u.pn * 4 + wc] = sq;
; #pragma unroll
;             for (int k = 0; k < 4; ++k) rc[k] = rn[k];
.LBB0_945:
	s_or_b64 exec, exec, s[2:3]
	v_or_b32_e32 v80, 32, v112
	v_ashrrev_i32_e32 v81, 31, v80
	s_waitcnt lgkmcnt(0)
	v_lshlrev_b64 v[48:49], 12, v[80:81]
	v_lshl_add_u64 v[82:83], v[178:179], 0, v[48:49]
	global_load_dwordx4 v[60:63], v[82:83], off
	global_load_dwordx4 v[56:59], v[82:83], off offset:64
	global_load_dwordx4 v[52:55], v[82:83], off offset:512
	global_load_dwordx4 v[48:51], v[82:83], off offset:576
	v_lshlrev_b64 v[84:85], 10, v[96:97]
	s_waitcnt vmcnt(15)
	v_pk_fma_f32 v[46:47], v[46:47], 0.5, v[78:79] op_sel_hi:[1,0,1]
	v_pk_fma_f32 v[44:45], v[44:45], 0.5, v[76:77] op_sel_hi:[1,0,1]
	v_lshl_add_u64 v[84:85], v[84:85], 0, v[176:177]
	global_store_dwordx4 v[98:99], v[44:47], off nt
	v_cvt_pk_f16_f32 v76, v44, v45
	v_lshlrev_b64 v[78:79], 1, v[84:85]
	v_mul_f32_e32 v45, v45, v45
	v_fmac_f32_e32 v45, v44, v44
	v_mul_f32_e32 v44, v47, v47
	v_cvt_pk_f16_f32 v77, v46, v47
	v_lshl_add_u64 v[84:85], s[48:49], 0, v[78:79]
	v_fmac_f32_e32 v44, v46, v46
	s_waitcnt vmcnt(15)
	v_pk_fma_f32 v[42:43], v[42:43], 0.5, v[74:75] op_sel_hi:[1,0,1]
	v_pk_fma_f32 v[40:41], v[40:41], 0.5, v[72:73] op_sel_hi:[1,0,1]
	global_store_dwordx2 v[84:85], v[76:77], off
	v_add_f32_e32 v76, v45, v44
	global_store_dwordx4 v[98:99], v[40:43], off offset:64 nt
	v_cvt_pk_f16_f32 v44, v40, v41
	v_or_b32_e32 v46, 32, v78
	v_mul_f32_e32 v41, v41, v41
	v_fmac_f32_e32 v41, v40, v40
	v_mul_f32_e32 v40, v43, v43
	v_mov_b32_e32 v47, v79
	v_fmac_f32_e32 v40, v42, v42
	v_cvt_pk_f16_f32 v45, v42, v43
	v_lshl_add_u64 v[46:47], s[48:49], 0, v[46:47]
	v_add_f32_e32 v40, v41, v40
	s_waitcnt vmcnt(16)
	v_pk_fma_f32 v[38:39], v[38:39], 0.5, v[70:71] op_sel_hi:[1,0,1]
	v_pk_fma_f32 v[36:37], v[36:37], 0.5, v[68:69] op_sel_hi:[1,0,1]
	global_store_dwordx2 v[46:47], v[44:45], off
	v_add_f32_e32 v44, v76, v40
	global_store_dwordx4 v[98:99], v[36:39], off offset:512 nt
	v_cvt_pk_f16_f32 v40, v36, v37
	s_waitcnt vmcnt(17)
	v_pk_fma_f32 v[34:35], v[34:35], 0.5, v[66:67] op_sel_hi:[1,0,1]
	v_mul_f32_e32 v37, v37, v37
	v_fmac_f32_e32 v37, v36, v36
	v_mul_f32_e32 v36, v39, v39
	v_fmac_f32_e32 v36, v38, v38
	v_pk_fma_f32 v[32:33], v[32:33], 0.5, v[64:65] op_sel_hi:[1,0,1]
	v_cvt_pk_f16_f32 v41, v38, v39
	v_add_f32_e32 v36, v37, v36
	v_mul_f32_e32 v37, v33, v33
	v_mul_f32_e32 v38, v35, v35
	v_fmac_f32_e32 v37, v32, v32
	v_fmac_f32_e32 v38, v34, v34
	v_add_f32_e32 v36, v44, v36
	v_add_f32_e32 v37, v37, v38
	v_add_f32_e32 v38, v36, v37
	ds_bpermute_b32 v39, v163, v38
	v_or_b32_e32 v42, 0x100, v78
	v_mov_b32_e32 v43, v79
	v_lshl_add_u64 v[36:37], s[48:49], 0, v[42:43]
	global_store_dwordx2 v[36:37], v[40:41], off
	global_store_dwordx4 v[98:99], v[32:35], off offset:576 nt
	v_cvt_pk_f16_f32 v36, v32, v33
	v_or_b32_e32 v78, 0x120, v78
	s_waitcnt lgkmcnt(0)
	v_add_f32_e32 v32, v38, v39
	ds_bpermute_b32 v33, v162, v32
	v_cvt_pk_f16_f32 v37, v34, v35
	v_lshl_add_u64 v[34:35], s[48:49], 0, v[78:79]
	global_store_dwordx2 v[34:35], v[36:37], off
	s_and_saveexec_b64 s[2:3], s[6:7]
	s_cbranch_execz .LBB0_947
	s_waitcnt lgkmcnt(0)
	v_add_f32_e32 v34, v32, v33
	v_lshlrev_b64 v[32:33], 6, v[96:97]
	v_lshl_add_u64 v[32:33], s[46:47], 0, v[32:33]
	v_lshl_add_u64 v[32:33], s[16:17], 2, v[32:33]
	s_lshl_b32 s92, s36, 2
	v_lshl_add_u64 v[32:33], v[32:33], 0, s[92:93]
	global_store_dword v[32:33], v34, off
;     __device__ __forceinline__ void operator()(const Acc& acc, const Unit& u, int wr, int wc, int fr, int fq) const {
;     ...
;         for (int i = 0; i < 8; ++i) {
;             const int ai = i >> 2, m = i & 3;
;             const int row = row0 + ai * HALF + m * 16; const size_t off = (size_t)row * D + col0; float sq = 0.f;
;             if (i + 1 < 8) { const size_t offn = (size_t)(row0 + ((i + 1) >> 2) * HALF + ((i + 1) & 3) * 16) * D + col0;
; #pragma unroll
;                 for (int k = 0; k < 4; ++k) rn[k] = *(const f32x4*)(res + offn + (k >> 1) * HALF + (k & 1) * 16); }
; #pragma unroll
;             for (int bj = 0; bj < 2; ++bj)
; #pragma unroll
;                 for (int n = 0; n < 2; ++n) { const size_t o = off + bj * HALF + n * 16; const f32x4 v = rc[bj * 2 + n] + acc[ai][bj][m][n] * alpha;
;                     *(f32x4*)(out + o) = v; u32x2 w; w.x = pk2h(v.x, v.y); w.y = pk2h(v.z, v.w); *(u32x2*)(o16 + o) = w; sq += (v.x * v.x + v.y * v.y) + (v.z * v.z + v.w * v.w); }
;             sq += __shfl_xor(sq, 16); sq += __shfl_xor(sq, 32);
;             if (fq == 0) ss[(size_t)row * 16 + u.pn * 4 + wc] = sq;
; #pragma unroll
;             for (int k = 0; k < 4; ++k) rc[k] = rn[k];
.LBB0_947:
	s_or_b64 exec, exec, s[2:3]
	v_or_b32_e32 v64, 48, v112
	v_ashrrev_i32_e32 v65, 31, v64
	s_waitcnt lgkmcnt(0)
	v_lshlrev_b64 v[32:33], 12, v[64:65]
	v_lshl_add_u64 v[66:67], v[178:179], 0, v[32:33]
	global_load_dwordx4 v[44:47], v[66:67], off
	global_load_dwordx4 v[40:43], v[66:67], off offset:64
	global_load_dwordx4 v[36:39], v[66:67], off offset:512
	global_load_dwordx4 v[32:35], v[66:67], off offset:576
	v_lshlrev_b64 v[68:69], 10, v[80:81]
	s_waitcnt vmcnt(15)
	v_pk_fma_f32 v[30:31], v[30:31], 0.5, v[62:63] op_sel_hi:[1,0,1]
	v_pk_fma_f32 v[28:29], v[28:29], 0.5, v[60:61] op_sel_hi:[1,0,1]
	v_lshl_add_u64 v[68:69], v[68:69], 0, v[176:177]
	global_store_dwordx4 v[82:83], v[28:31], off nt
	v_cvt_pk_f16_f32 v60, v28, v29
	v_lshlrev_b64 v[62:63], 1, v[68:69]
	v_mul_f32_e32 v29, v29, v29
	v_fmac_f32_e32 v29, v28, v28
	v_mul_f32_e32 v28, v31, v31
	v_cvt_pk_f16_f32 v61, v30, v31
	v_lshl_add_u64 v[68:69], s[48:49], 0, v[62:63]
	v_fmac_f32_e32 v28, v30, v30
	s_waitcnt vmcnt(15)
	v_pk_fma_f32 v[26:27], v[26:27], 0.5, v[58:59] op_sel_hi:[1,0,1]
	v_pk_fma_f32 v[24:25], v[24:25], 0.5, v[56:57] op_sel_hi:[1,0,1]
	global_store_dwordx2 v[68:69], v[60:61], off
	v_add_f32_e32 v60, v29, v28
	global_store_dwordx4 v[82:83], v[24:27], off offset:64 nt
	v_cvt_pk_f16_f32 v28, v24, v25
	v_or_b32_e32 v30, 32, v62
	v_mul_f32_e32 v25, v25, v25
	v_fmac_f32_e32 v25, v24, v24
	v_mul_f32_e32 v24, v27, v27
	v_mov_b32_e32 v31, v63
	v_fmac_f32_e32 v24, v26, v26
	v_cvt_pk_f16_f32 v29, v26, v27
	v_lshl_add_u64 v[30:31], s[48:49], 0, v[30:31]
	v_add_f32_e32 v24, v25, v24
	s_waitcnt vmcnt(16)
	v_pk_fma_f32 v[22:23], v[22:23], 0.5, v[54:55] op_sel_hi:[1,0,1]
	v_pk_fma_f32 v[20:21], v[20:21], 0.5, v[52:53] op_sel_hi:[1,0,1]
	global_store_dwordx2 v[30:31], v[28:29], off
	v_add_f32_e32 v28, v60, v24
	global_store_dwordx4 v[82:83], v[20:23], off offset:512 nt
	v_cvt_pk_f16_f32 v24, v20, v21
	s_waitcnt vmcnt(17)
	v_pk_fma_f32 v[18:19], v[18:19], 0.5, v[50:51] op_sel_hi:[1,0,1]
	v_mul_f32_e32 v21, v21, v21
	v_fmac_f32_e32 v21, v20, v20
	v_mul_f32_e32 v20, v23, v23
	v_fmac_f32_e32 v20, v22, v22
	v_pk_fma_f32 v[16:17], v[16:17], 0.5, v[48:49] op_sel_hi:[1,0,1]
	v_cvt_pk_f16_f32 v25, v22, v23
	v_add_f32_e32 v20, v21, v20
	v_mul_f32_e32 v21, v17, v17
	v_mul_f32_e32 v22, v19, v19
	v_fmac_f32_e32 v21, v16, v16
	v_fmac_f32_e32 v22, v18, v18
	v_add_f32_e32 v20, v28, v20
	v_add_f32_e32 v21, v21, v22
	v_add_f32_e32 v22, v20, v21
	ds_bpermute_b32 v23, v163, v22
	v_or_b32_e32 v26, 0x100, v62
	v_mov_b32_e32 v27, v63
	v_lshl_add_u64 v[20:21], s[48:49], 0, v[26:27]
	global_store_dwordx2 v[20:21], v[24:25], off
	global_store_dwordx4 v[82:83], v[16:19], off offset:576 nt
	v_cvt_pk_f16_f32 v20, v16, v17
	v_or_b32_e32 v62, 0x120, v62
	s_waitcnt lgkmcnt(0)
	v_add_f32_e32 v16, v22, v23
	ds_bpermute_b32 v17, v162, v16
	v_cvt_pk_f16_f32 v21, v18, v19
	v_lshl_add_u64 v[18:19], s[48:49], 0, v[62:63]
	global_store_dwordx2 v[18:19], v[20:21], off
	s_and_saveexec_b64 s[2:3], s[6:7]
	s_cbranch_execz .LBB0_949
	s_waitcnt lgkmcnt(0)
	v_add_f32_e32 v18, v16, v17
	v_lshlrev_b64 v[16:17], 6, v[80:81]
	v_lshl_add_u64 v[16:17], s[46:47], 0, v[16:17]
	v_lshl_add_u64 v[16:17], s[16:17], 2, v[16:17]
	s_lshl_b32 s92, s36, 2
	v_lshl_add_u64 v[16:17], v[16:17], 0, s[92:93]
	global_store_dword v[16:17], v18, off
.LBB0_949:
	s_or_b64 exec, exec, s[2:3]
	s_waitcnt lgkmcnt(0)
	v_lshlrev_b64 v[16:17], 10, v[64:65]
	s_waitcnt vmcnt(11)
	v_pk_fma_f32 v[14:15], v[14:15], 0.5, v[46:47] op_sel_hi:[1,0,1]
	v_pk_fma_f32 v[12:13], v[12:13], 0.5, v[44:45] op_sel_hi:[1,0,1]
	v_lshl_add_u64 v[16:17], v[16:17], 0, v[176:177]
	global_store_dwordx4 v[66:67], v[12:15], off nt
	v_cvt_pk_f16_f32 v18, v12, v13
	v_lshlrev_b64 v[16:17], 1, v[16:17]
	v_mul_f32_e32 v13, v13, v13
	v_fmac_f32_e32 v13, v12, v12
	v_mul_f32_e32 v12, v15, v15
	v_cvt_pk_f16_f32 v19, v14, v15
	v_lshl_add_u64 v[20:21], s[48:49], 0, v[16:17]
	v_fmac_f32_e32 v12, v14, v14
	s_waitcnt vmcnt(11)
	v_pk_fma_f32 v[10:11], v[10:11], 0.5, v[42:43] op_sel_hi:[1,0,1]
	v_pk_fma_f32 v[8:9], v[8:9], 0.5, v[40:41] op_sel_hi:[1,0,1]
	global_store_dwordx2 v[20:21], v[18:19], off
	v_add_f32_e32 v18, v13, v12
	global_store_dwordx4 v[66:67], v[8:11], off offset:64 nt
	v_cvt_pk_f16_f32 v12, v8, v9
	v_or_b32_e32 v14, 32, v16
	v_mul_f32_e32 v9, v9, v9
	v_fmac_f32_e32 v9, v8, v8
	v_mul_f32_e32 v8, v11, v11
	v_mov_b32_e32 v15, v17
	v_fmac_f32_e32 v8, v10, v10
	v_cvt_pk_f16_f32 v13, v10, v11
	v_lshl_add_u64 v[14:15], s[48:49], 0, v[14:15]
	v_add_f32_e32 v8, v9, v8
	s_waitcnt vmcnt(12)
	v_pk_fma_f32 v[6:7], v[6:7], 0.5, v[38:39] op_sel_hi:[1,0,1]
	v_pk_fma_f32 v[4:5], v[4:5], 0.5, v[36:37] op_sel_hi:[1,0,1]
	global_store_dwordx2 v[14:15], v[12:13], off
	v_add_f32_e32 v12, v18, v8
	global_store_dwordx4 v[66:67], v[4:7], off offset:512 nt
	v_cvt_pk_f16_f32 v8, v4, v5
	s_waitcnt vmcnt(13)
	v_pk_fma_f32 v[2:3], v[2:3], 0.5, v[34:35] op_sel_hi:[1,0,1]
	v_mul_f32_e32 v5, v5, v5
	v_fmac_f32_e32 v5, v4, v4
	v_mul_f32_e32 v4, v7, v7
	v_fmac_f32_e32 v4, v6, v6
	v_pk_fma_f32 v[0:1], v[0:1], 0.5, v[32:33] op_sel_hi:[1,0,1]
	v_cvt_pk_f16_f32 v9, v6, v7
	v_add_f32_e32 v4, v5, v4
	v_mul_f32_e32 v5, v1, v1
	v_mul_f32_e32 v6, v3, v3
	v_fmac_f32_e32 v5, v0, v0
	v_fmac_f32_e32 v6, v2, v2
	v_add_f32_e32 v4, v12, v4
	v_add_f32_e32 v5, v5, v6
	v_add_f32_e32 v6, v4, v5
	ds_bpermute_b32 v7, v163, v6
	v_or_b32_e32 v10, 0x100, v16
	v_mov_b32_e32 v11, v17
	v_lshl_add_u64 v[4:5], s[48:49], 0, v[10:11]
	global_store_dwordx2 v[4:5], v[8:9], off
	global_store_dwordx4 v[66:67], v[0:3], off offset:576 nt
	v_cvt_pk_f16_f32 v4, v0, v1
	v_or_b32_e32 v16, 0x120, v16
	s_waitcnt lgkmcnt(0)
	v_add_f32_e32 v0, v6, v7
	ds_bpermute_b32 v1, v162, v0
	v_cvt_pk_f16_f32 v5, v2, v3
	v_lshl_add_u64 v[2:3], s[48:49], 0, v[16:17]
	global_store_dwordx2 v[2:3], v[4:5], off
	s_and_saveexec_b64 s[2:3], s[6:7]
	s_cbranch_execz .LBB0_951
	s_waitcnt lgkmcnt(0)
	v_add_f32_e32 v2, v0, v1
	v_lshlrev_b64 v[0:1], 6, v[64:65]
	v_lshl_add_u64 v[0:1], s[46:47], 0, v[0:1]
	v_lshl_add_u64 v[0:1], s[16:17], 2, v[0:1]
	s_lshl_b32 s92, s36, 2
	v_lshl_add_u64 v[0:1], v[0:1], 0, s[92:93]
	global_store_dword v[0:1], v2, off

; __device__ __forceinline__ float sigmoidf_(float x) { return __builtin_amdgcn_rcpf(1.0f + __expf(-x)); }
; __device__ __forceinline__ void rows_rstd8(const float* ss, int row0, int fq, float (&rs)[2][4]) {
;     f32x4 q[2][4];
; #pragma unroll
;     for (int ai = 0; ai < 2; ++ai)
; #pragma unroll
;         for (int m = 0; m < 4; ++m) q[ai][m] = *(const f32x4*)(ss + (size_t)(row0 + ai * 128 + m * 16) * 16 + 4 * fq);
; #pragma unroll
;     for (int ai = 0; ai < 2; ++ai)
; #pragma unroll
;         for (int m = 0; m < 4; ++m) { float t = (q[ai][m].x + q[ai][m].y) + (q[ai][m].z + q[ai][m].w); t += __shfl_xor(t, 16); t += __shfl_xor(t, 32); rs[ai][m] = __builtin_amdgcn_rsqf(t * (1.0f / 1024.0f) + 1e-6f); }
; }
;     __device__ __forceinline__ void operator()(const Acc& acc, const Unit& u, int wr, int wc, int fr, int fq) const {
;         const int row0 = u.pm * BM + wr * 64 + fr, col0 = u.pn * BM + wc * 32 + 4 * fq;
;         float rs8[2][4]; rows_rstd8(ssr, row0, fq, rs8);
; #pragma unroll
;         for (int ai = 0; ai < 2; ++ai)
; #pragma unroll
;             for (int m = 0; m < 4; ++m) {
;                 const int row = row0 + ai * HALF + m * 16; const size_t off = (size_t)row * D + col0; float sq = 0.f; const float rs = rs8[ai][m];
; #pragma unroll
;                 for (int bj = 0; bj < 2; ++bj)
; #pragma unroll
;                     for (int n = 0; n < 2; ++n) { const size_t o = off + bj * HALF + n * 16; const f32x4 r = *(const f32x4*)(out + o); const h16x4 p = *(const h16x4*)(pu + o);
;                         const f32x4 a = acc[ai][bj][m][n] * rs; f32x4 v;
;                         v.x = r.x + sigmoidf_(a.x) * (float)p.x; v.y = r.y + sigmoidf_(a.y) * (float)p.y; v.z = r.z + sigmoidf_(a.z) * (float)p.z; v.w = r.w + sigmoidf_(a.w) * (float)p.w;
.LBB0_1020:
	v_lshl_add_u32 v188, s41, 8, v187
	v_ashrrev_i32_e32 v189, 31, v188
	v_lshlrev_b64 v[184:185], 6, v[188:189]
	v_lshl_add_u64 v[136:137], v[130:131], 0, v[184:185]
	global_load_dwordx4 v[154:157], v[136:137], off
	v_or_b32_e32 v182, 16, v188
	v_ashrrev_i32_e32 v183, 31, v182
	v_lshlrev_b64 v[180:181], 6, v[182:183]
	v_lshl_add_u64 v[136:137], v[130:131], 0, v[180:181]
	global_load_dwordx4 v[162:165], v[136:137], off
	v_or_b32_e32 v178, 32, v188
	v_ashrrev_i32_e32 v179, 31, v178
	v_lshlrev_b64 v[176:177], 6, v[178:179]
	v_lshl_add_u64 v[136:137], v[130:131], 0, v[176:177]
	global_load_dwordx4 v[190:193], v[136:137], off
	v_or_b32_e32 v174, 48, v188
	v_ashrrev_i32_e32 v175, 31, v174
	v_lshlrev_b64 v[172:173], 6, v[174:175]
	v_lshl_add_u64 v[136:137], v[130:131], 0, v[172:173]
	global_load_dwordx4 v[194:197], v[136:137], off
	v_add_u32_e32 v170, 0x80, v188
	v_ashrrev_i32_e32 v171, 31, v170
	v_lshlrev_b64 v[150:151], 6, v[170:171]
	v_lshl_add_u64 v[136:137], v[130:131], 0, v[150:151]
	global_load_dwordx4 v[216:219], v[136:137], off
	v_add_u32_e32 v148, 0x90, v188
	v_ashrrev_i32_e32 v149, 31, v148
	v_lshlrev_b64 v[146:147], 6, v[148:149]
	v_lshl_add_u64 v[136:137], v[130:131], 0, v[146:147]
	global_load_dwordx4 v[228:231], v[136:137], off
	v_add_u32_e32 v144, 0xa0, v188
	v_ashrrev_i32_e32 v145, 31, v144
	v_lshlrev_b64 v[142:143], 6, v[144:145]
	v_lshl_add_u64 v[136:137], v[130:131], 0, v[142:143]
	global_load_dwordx4 v[232:235], v[136:137], off
	v_add_u32_e32 v140, 0xb0, v188
	v_ashrrev_i32_e32 v141, 31, v140
	v_lshlrev_b64 v[136:137], 6, v[140:141]
	v_lshl_add_u64 v[166:167], v[130:131], 0, v[136:137]
	global_load_dwordx4 v[236:239], v[166:167], off
	v_and_b32_e32 v166, 64, v203
	v_xor_b32_e32 v139, 16, v203
	v_add_u32_e32 v166, 64, v166
	v_cmp_lt_i32_e32 vcc, v139, v166
	v_lshl_or_b32 v138, s40, 8, v211
	s_lshl_b32 s22, s40, 2
	v_cndmask_b32_e32 v139, v203, v139, vcc
	v_lshlrev_b32_e32 v214, 2, v139
	v_xor_b32_e32 v139, 32, v203
	v_cmp_lt_i32_e32 vcc, v139, v166
	v_readlane_b32 s52, v248, 48
	v_readlane_b32 s40, v252, 16
	v_cndmask_b32_e32 v139, v203, v139, vcc
	v_lshlrev_b32_e32 v213, 2, v139
	v_readlane_b32 s66, v248, 62
	v_readlane_b32 s67, v248, 63
	v_readlane_b32 s41, v252, 17
	v_readlane_b32 s24, v254, 14
	v_readlane_b32 s25, v254, 15
	s_ashr_i32 s23, s22, 31
	v_readlane_b32 s53, v248, 49
	v_readlane_b32 s54, v248, 50
	v_readlane_b32 s55, v248, 51
	v_readlane_b32 s56, v248, 52
	v_readlane_b32 s57, v248, 53
	v_readlane_b32 s58, v248, 54
	v_readlane_b32 s59, v248, 55
	v_readlane_b32 s60, v248, 56
	v_readlane_b32 s61, v248, 57
	v_readlane_b32 s62, v248, 58
	v_readlane_b32 s63, v248, 59
	v_readlane_b32 s64, v248, 60
	v_readlane_b32 s65, v248, 61
	s_waitcnt vmcnt(0)
	v_mov_b32_e32 v166, v155
	v_mov_b32_e32 v167, v156
	v_mov_b32_e32 v155, v157
	v_pk_add_f32 v[154:155], v[166:167], v[154:155]
	s_nop 0
	v_add_f32_e32 v139, v154, v155
	ds_bpermute_b32 v154, v214, v139
	s_waitcnt lgkmcnt(0)
	v_add_f32_e32 v139, v139, v154
	ds_bpermute_b32 v154, v213, v139
	s_waitcnt lgkmcnt(0)
	v_add_f32_e32 v139, v139, v154
	v_fmamk_f32 v139, v139, 0x3a800000, v201
	v_rsq_f32_e32 v186, v139
	v_add_f32_e32 v139, v162, v163
	v_add_f32_e32 v154, v164, v165
	v_add_f32_e32 v139, v139, v154
	ds_bpermute_b32 v154, v214, v139
	v_pk_mul_f32 v[124:125], v[124:125], v[186:187] op_sel_hi:[1,0]
	v_pk_mul_f32 v[126:127], v[126:127], v[186:187] op_sel_hi:[1,0]
	v_mul_f32_e32 v124, 0xbfb8aa3b, v124
	v_mul_f32_e32 v125, 0xbfb8aa3b, v125
	s_waitcnt lgkmcnt(0)
	v_add_f32_e32 v162, v139, v154
	v_add_f32_e32 v139, v190, v191
	v_add_f32_e32 v154, v192, v193
	v_add_f32_e32 v139, v139, v154
	ds_bpermute_b32 v154, v214, v139
	v_exp_f32_e32 v124, v124
	v_exp_f32_e32 v125, v125
	v_mul_f32_e32 v126, 0xbfb8aa3b, v126
	v_mul_f32_e32 v127, 0xbfb8aa3b, v127
	s_waitcnt lgkmcnt(0)
	v_add_f32_e32 v225, v139, v154
	v_add_f32_e32 v139, v194, v195
	v_add_f32_e32 v154, v196, v197
	v_add_f32_e32 v139, v139, v154
	ds_bpermute_b32 v154, v214, v139
	v_add_f32_e32 v124, 1.0, v124
	v_add_f32_e32 v125, 1.0, v125
	v_exp_f32_e32 v126, v126
	v_exp_f32_e32 v127, v127
	s_waitcnt lgkmcnt(0)
	v_add_f32_e32 v223, v139, v154
	v_add_f32_e32 v139, v216, v217
	v_add_f32_e32 v154, v218, v219
	v_add_f32_e32 v139, v139, v154
	ds_bpermute_b32 v154, v214, v139
	v_rcp_f32_e32 v124, v124
	v_rcp_f32_e32 v125, v125
	v_add_f32_e32 v126, 1.0, v126
	v_add_f32_e32 v127, 1.0, v127
	s_waitcnt lgkmcnt(0)
	v_add_f32_e32 v221, v139, v154
	v_add_f32_e32 v139, v228, v229
	v_add_f32_e32 v154, v230, v231
	v_add_f32_e32 v139, v139, v154
	ds_bpermute_b32 v154, v214, v139
	v_rcp_f32_e32 v126, v126
	v_rcp_f32_e32 v127, v127
	v_pk_mul_f32 v[120:121], v[120:121], v[186:187] op_sel_hi:[1,0]
	v_pk_mul_f32 v[122:123], v[122:123], v[186:187] op_sel_hi:[1,0]
	s_waitcnt lgkmcnt(0)
	v_add_f32_e32 v219, v139, v154
	v_add_f32_e32 v139, v232, v233
	v_add_f32_e32 v154, v234, v235
	v_add_f32_e32 v139, v139, v154
	ds_bpermute_b32 v154, v214, v139
	v_mul_f32_e32 v120, 0xbfb8aa3b, v120
	v_mul_f32_e32 v121, 0xbfb8aa3b, v121
	v_exp_f32_e32 v120, v120
	v_exp_f32_e32 v121, v121
	s_waitcnt lgkmcnt(0)
	v_add_f32_e32 v217, v139, v154
	v_add_f32_e32 v139, v236, v237
	v_add_f32_e32 v154, v238, v239
	v_add_f32_e32 v139, v139, v154
	ds_bpermute_b32 v154, v214, v139
	v_mul_f32_e32 v122, 0xbfb8aa3b, v122
	v_mul_f32_e32 v123, 0xbfb8aa3b, v123
	v_add_f32_e32 v120, 1.0, v120
	v_add_f32_e32 v121, 1.0, v121
	s_waitcnt lgkmcnt(0)
; __device__ __forceinline__ float sigmoidf_(float x) { return __builtin_amdgcn_rcpf(1.0f + __expf(-x)); }
;     __device__ __forceinline__ void operator()(const Acc& acc, const Unit& u, int wr, int wc, int fr, int fq) const {
;     ...
;                 const int row = row0 + ai * HALF + m * 16; const size_t off = (size_t)row * D + col0; float sq = 0.f; const float rs = rs8[ai][m];
; #pragma unroll
;                 for (int bj = 0; bj < 2; ++bj)
; #pragma unroll
;                     for (int n = 0; n < 2; ++n) { const size_t o = off + bj * HALF + n * 16; const f32x4 r = *(const f32x4*)(out + o); const h16x4 p = *(const h16x4*)(pu + o);
;                         const f32x4 a = acc[ai][bj][m][n] * rs; f32x4 v;
;                         v.x = r.x + sigmoidf_(a.x) * (float)p.x; v.y = r.y + sigmoidf_(a.y) * (float)p.y; v.z = r.z + sigmoidf_(a.z) * (float)p.z; v.w = r.w + sigmoidf_(a.w) * (float)p.w;
;                         *(f32x4*)(out + o) = v; u32x2 w; w.x = pk2h(v.x, v.y); w.y = pk2h(v.z, v.w); *(u32x2*)(o16 + o) = w; sq += (v.x * v.x + v.y * v.y) + (v.z * v.z + v.w * v.w); }
;                 sq += __shfl_xor(sq, 16); sq += __shfl_xor(sq, 32);
;                 if (fq == 0) ssw[(size_t)row * 16 + u.pn * 4 + wc] = sq;
	v_add_f32_e32 v215, v139, v154
	v_ashrrev_i32_e32 v139, 31, v138
	v_lshlrev_b64 v[154:155], 10, v[188:189]
	v_lshl_add_u64 v[164:165], v[154:155], 0, v[138:139]
	v_lshlrev_b64 v[194:195], 1, v[164:165]
	v_lshl_add_u64 v[192:193], v[164:165], 2, s[66:67]
	v_lshl_add_u64 v[164:165], s[40:41], 0, v[194:195]
	global_load_dwordx2 v[164:165], v[164:165], off
	v_exp_f32_e32 v122, v122
	global_load_dwordx4 v[154:157], v[192:193], off
	v_exp_f32_e32 v123, v123
	v_rcp_f32_e32 v120, v120
	v_rcp_f32_e32 v121, v121
	v_add_f32_e32 v122, 1.0, v122
	v_add_f32_e32 v123, 1.0, v123
	v_rcp_f32_e32 v122, v122
	v_rcp_f32_e32 v123, v123
	v_or_b32_e32 v196, 0x100, v194
	v_mov_b32_e32 v197, v195
	v_pk_mul_f32 v[116:117], v[116:117], v[186:187] op_sel_hi:[1,0]
	v_pk_mul_f32 v[118:119], v[118:119], v[186:187] op_sel_hi:[1,0]
	v_mul_f32_e32 v116, 0xbfb8aa3b, v116
	v_mul_f32_e32 v117, 0xbfb8aa3b, v117
	v_exp_f32_e32 v116, v116
	v_exp_f32_e32 v117, v117
	v_mul_f32_e32 v118, 0xbfb8aa3b, v118
	v_mul_f32_e32 v119, 0xbfb8aa3b, v119
	v_add_f32_e32 v116, 1.0, v116
	v_add_f32_e32 v117, 1.0, v117
	v_exp_f32_e32 v118, v118
	v_exp_f32_e32 v119, v119
	v_rcp_f32_e32 v116, v116
	v_rcp_f32_e32 v117, v117
	v_add_f32_e32 v118, 1.0, v118
	v_add_f32_e32 v119, 1.0, v119
	v_rcp_f32_e32 v118, v118
	v_rcp_f32_e32 v119, v119
	v_pk_mul_f32 v[112:113], v[112:113], v[186:187] op_sel_hi:[1,0]
	v_pk_mul_f32 v[114:115], v[114:115], v[186:187] op_sel_hi:[1,0]
	v_mul_f32_e32 v112, 0xbfb8aa3b, v112
	v_mul_f32_e32 v113, 0xbfb8aa3b, v113
	v_exp_f32_e32 v112, v112
	v_exp_f32_e32 v113, v113
	v_mul_f32_e32 v114, 0xbfb8aa3b, v114
	v_mul_f32_e32 v115, 0xbfb8aa3b, v115
	v_add_f32_e32 v112, 1.0, v112
	v_add_f32_e32 v113, 1.0, v113
	v_exp_f32_e32 v114, v114
	v_exp_f32_e32 v115, v115
	v_rcp_f32_e32 v112, v112
	v_rcp_f32_e32 v113, v113
	v_add_f32_e32 v114, 1.0, v114
	v_add_f32_e32 v115, 1.0, v115
	v_rcp_f32_e32 v114, v114
	v_rcp_f32_e32 v115, v115
	ds_bpermute_b32 v163, v213, v162
	ds_bpermute_b32 v226, v213, v225
	ds_bpermute_b32 v224, v213, v223
	ds_bpermute_b32 v222, v213, v221
	ds_bpermute_b32 v220, v213, v219
	ds_bpermute_b32 v218, v213, v217
	ds_bpermute_b32 v216, v213, v215
	s_waitcnt vmcnt(1)
	v_cvt_f32_f16_e32 v166, v164
	v_cvt_f32_f16_sdwa v167, v164 dst_sel:DWORD dst_unused:UNUSED_PAD src0_sel:WORD_1
	s_waitcnt vmcnt(0)
	v_pk_fma_f32 v[124:125], v[124:125], v[166:167], v[154:155]
	v_cvt_f32_f16_e32 v154, v165
	v_cvt_f32_f16_sdwa v155, v165 dst_sel:DWORD dst_unused:UNUSED_PAD src0_sel:WORD_1
	v_pk_mul_f32 v[188:189], v[124:125], v[124:125]
	v_pk_fma_f32 v[126:127], v[126:127], v[154:155], v[156:157]
	v_cvt_pk_f16_f32 v154, v124, v125
	v_cvt_pk_f16_f32 v155, v126, v127
	v_lshl_add_u64 v[156:157], s[24:25], 0, v[194:195]
	global_store_dwordx4 v[192:193], v[124:127], off nt
	global_store_dwordx2 v[156:157], v[154:155], off
	v_or_b32_e32 v154, 32, v194
	v_mov_b32_e32 v155, v195
	v_lshl_add_u64 v[156:157], s[40:41], 0, v[154:155]
	global_load_dwordx2 v[156:157], v[156:157], off
	v_pk_mul_f32 v[190:191], v[126:127], v[126:127]
	global_load_dwordx4 v[124:127], v[192:193], off offset:64
	v_or_b32_e32 v194, 0x120, v194
	s_waitcnt vmcnt(1)
	v_cvt_f32_f16_e32 v164, v156
	v_cvt_f32_f16_sdwa v165, v156 dst_sel:DWORD dst_unused:UNUSED_PAD src0_sel:WORD_1
	s_waitcnt vmcnt(0)
	v_pk_fma_f32 v[120:121], v[120:121], v[164:165], v[124:125]
	v_cvt_f32_f16_e32 v124, v157
	v_cvt_f32_f16_sdwa v125, v157 dst_sel:DWORD dst_unused:UNUSED_PAD src0_sel:WORD_1
	v_pk_fma_f32 v[122:123], v[122:123], v[124:125], v[126:127]
	global_store_dwordx4 v[192:193], v[120:123], off offset:64 nt
	v_lshl_add_u64 v[126:127], s[24:25], 0, v[154:155]
	v_lshl_add_u64 v[154:155], s[40:41], 0, v[196:197]
	global_load_dwordx2 v[154:155], v[154:155], off
	v_cvt_pk_f16_f32 v124, v120, v121
	v_cvt_pk_f16_f32 v125, v122, v123
	global_store_dwordx2 v[126:127], v[124:125], off
	v_pk_mul_f32 v[124:125], v[120:121], v[120:121]
	v_pk_mul_f32 v[126:127], v[122:123], v[122:123]
	global_load_dwordx4 v[120:123], v[192:193], off offset:512
	s_waitcnt vmcnt(2)
	v_cvt_f32_f16_e32 v156, v154
	v_cvt_f32_f16_sdwa v157, v154 dst_sel:DWORD dst_unused:UNUSED_PAD src0_sel:WORD_1
	s_waitcnt vmcnt(0)
	v_pk_fma_f32 v[116:117], v[116:117], v[156:157], v[120:121]
	v_cvt_f32_f16_e32 v120, v155
	v_cvt_f32_f16_sdwa v121, v155 dst_sel:DWORD dst_unused:UNUSED_PAD src0_sel:WORD_1
	v_lshl_add_u64 v[154:155], s[40:41], 0, v[194:195]
	v_pk_fma_f32 v[118:119], v[118:119], v[120:121], v[122:123]
	global_store_dwordx4 v[192:193], v[116:119], off offset:512 nt
	v_lshl_add_u64 v[122:123], s[24:25], 0, v[196:197]
	global_load_dwordx2 v[196:197], v[154:155], off
	v_cvt_pk_f16_f32 v120, v116, v117
	v_cvt_pk_f16_f32 v121, v118, v119
	global_store_dwordx2 v[122:123], v[120:121], off
	v_pk_mul_f32 v[120:121], v[116:117], v[116:117]
	v_pk_mul_f32 v[122:123], v[118:119], v[118:119]
	global_load_dwordx4 v[116:119], v[192:193], off offset:576
	s_waitcnt vmcnt(2)
	v_cvt_f32_f16_e32 v154, v196
	v_cvt_f32_f16_sdwa v155, v196 dst_sel:DWORD dst_unused:UNUSED_PAD src0_sel:WORD_1
	s_waitcnt vmcnt(0)
	v_pk_fma_f32 v[112:113], v[112:113], v[154:155], v[116:117]
	v_cvt_f32_f16_e32 v116, v197
	v_cvt_f32_f16_sdwa v117, v197 dst_sel:DWORD dst_unused:UNUSED_PAD src0_sel:WORD_1
	v_pk_fma_f32 v[114:115], v[114:115], v[116:117], v[118:119]
	v_cvt_pk_f16_f32 v116, v112, v113
	v_cvt_pk_f16_f32 v117, v114, v115
	v_lshl_add_u64 v[118:119], s[24:25], 0, v[194:195]
	global_store_dwordx4 v[192:193], v[112:115], off offset:576 nt
	global_store_dwordx2 v[118:119], v[116:117], off
	v_add_f32_e32 v116, v190, v191
	v_add_f32_e32 v117, v188, v189
	v_add_f32_e32 v116, v117, v116
	v_add_f32_e32 v117, v126, v127
	v_add_f32_e32 v118, v124, v125
	v_add_f32_e32 v117, v118, v117
	v_pk_mul_f32 v[112:113], v[112:113], v[112:113]
	v_pk_mul_f32 v[114:115], v[114:115], v[114:115]
	v_add_f32_e32 v116, v116, v117
	v_add_f32_e32 v117, v122, v123
	v_add_f32_e32 v118, v120, v121
	v_add_f32_e32 v117, v118, v117
	v_add_f32_e32 v114, v114, v115
	v_add_f32_e32 v112, v112, v113
	v_add_f32_e32 v116, v116, v117
	v_add_f32_e32 v112, v112, v114
	v_add_f32_e32 v112, v116, v112
	ds_bpermute_b32 v113, v214, v112
	s_waitcnt lgkmcnt(0)
	v_add_f32_e32 v112, v112, v113
	ds_bpermute_b32 v113, v213, v112
	s_and_saveexec_b64 s[2:3], s[8:9]
	v_readlane_b32 s42, v254, 18
	v_readlane_b32 s43, v254, 19
	s_cbranch_execz .LBB0_1022
	s_waitcnt lgkmcnt(0)
	v_add_f32_e32 v114, v112, v113
	v_lshl_add_u64 v[112:113], s[70:71], 0, v[184:185]
	v_lshl_add_u64 v[112:113], s[22:23], 2, v[112:113]
	s_lshl_b32 s92, s38, 2
	v_lshl_add_u64 v[112:113], v[112:113], 0, s[92:93]
	global_store_dword v[112:113], v114, off
; __device__ __forceinline__ float sigmoidf_(float x) { return __builtin_amdgcn_rcpf(1.0f + __expf(-x)); }
;     __device__ __forceinline__ void operator()(const Acc& acc, const Unit& u, int wr, int wc, int fr, int fq) const {
;     ...
;                 const int row = row0 + ai * HALF + m * 16; const size_t off = (size_t)row * D + col0; float sq = 0.f; const float rs = rs8[ai][m];
; #pragma unroll
;                 for (int bj = 0; bj < 2; ++bj)
; #pragma unroll
;                     for (int n = 0; n < 2; ++n) { const size_t o = off + bj * HALF + n * 16; const f32x4 r = *(const f32x4*)(out + o); const h16x4 p = *(const h16x4*)(pu + o);
;                         const f32x4 a = acc[ai][bj][m][n] * rs; f32x4 v;
;                         v.x = r.x + sigmoidf_(a.x) * (float)p.x; v.y = r.y + sigmoidf_(a.y) * (float)p.y; v.z = r.z + sigmoidf_(a.z) * (float)p.z; v.w = r.w + sigmoidf_(a.w) * (float)p.w;
;                         *(f32x4*)(out + o) = v; u32x2 w; w.x = pk2h(v.x, v.y); w.y = pk2h(v.z, v.w); *(u32x2*)(o16 + o) = w; sq += (v.x * v.x + v.y * v.y) + (v.z * v.z + v.w * v.w); }
;                 sq += __shfl_xor(sq, 16); sq += __shfl_xor(sq, 32);
;                 if (fq == 0) ssw[(size_t)row * 16 + u.pn * 4 + wc] = sq;
.LBB0_1022:
	s_or_b64 exec, exec, s[2:3]
	v_add_f32_e32 v112, v162, v163
	v_fmamk_f32 v112, v112, 0x3a800000, v201
	v_rsq_f32_e32 v120, v112
	s_waitcnt lgkmcnt(0)
	v_lshlrev_b64 v[112:113], 10, v[182:183]
	v_readlane_b32 s52, v248, 48
	v_lshl_add_u64 v[118:119], v[112:113], 0, v[138:139]
	v_readlane_b32 s66, v248, 62
	v_readlane_b32 s67, v248, 63
	v_pk_mul_f32 v[108:109], v[108:109], v[120:121] op_sel_hi:[1,0]
	v_pk_mul_f32 v[110:111], v[110:111], v[120:121] op_sel_hi:[1,0]
	v_lshl_add_u64 v[116:117], v[118:119], 2, s[66:67]
	v_lshlrev_b64 v[118:119], 1, v[118:119]
	v_lshl_add_u64 v[122:123], s[40:41], 0, v[118:119]
	global_load_dwordx2 v[122:123], v[122:123], off
	v_mul_f32_e32 v108, 0xbfb8aa3b, v108
	global_load_dwordx4 v[112:115], v[116:117], off
	v_mul_f32_e32 v109, 0xbfb8aa3b, v109
	v_exp_f32_e32 v108, v108
	v_exp_f32_e32 v109, v109
	v_mul_f32_e32 v110, 0xbfb8aa3b, v110
	v_mul_f32_e32 v111, 0xbfb8aa3b, v111
	v_add_f32_e32 v108, 1.0, v108
	v_add_f32_e32 v109, 1.0, v109
	v_exp_f32_e32 v110, v110
	v_exp_f32_e32 v111, v111
	v_rcp_f32_e32 v108, v108
	v_rcp_f32_e32 v109, v109
	v_add_f32_e32 v110, 1.0, v110
	v_add_f32_e32 v111, 1.0, v111
	v_rcp_f32_e32 v110, v110
	v_rcp_f32_e32 v111, v111
	v_pk_mul_f32 v[104:105], v[104:105], v[120:121] op_sel_hi:[1,0]
	v_pk_mul_f32 v[106:107], v[106:107], v[120:121] op_sel_hi:[1,0]
	v_mul_f32_e32 v104, 0xbfb8aa3b, v104
	v_mul_f32_e32 v105, 0xbfb8aa3b, v105
	v_exp_f32_e32 v104, v104
	v_exp_f32_e32 v105, v105
	v_mul_f32_e32 v106, 0xbfb8aa3b, v106
	v_mul_f32_e32 v107, 0xbfb8aa3b, v107
	v_add_f32_e32 v104, 1.0, v104
	v_add_f32_e32 v105, 1.0, v105
	v_exp_f32_e32 v106, v106
	v_exp_f32_e32 v107, v107
	v_rcp_f32_e32 v104, v104
	v_rcp_f32_e32 v105, v105
	v_add_f32_e32 v106, 1.0, v106
	v_add_f32_e32 v107, 1.0, v107
	v_rcp_f32_e32 v106, v106
	v_rcp_f32_e32 v107, v107
	v_pk_mul_f32 v[100:101], v[100:101], v[120:121] op_sel_hi:[1,0]
	v_pk_mul_f32 v[102:103], v[102:103], v[120:121] op_sel_hi:[1,0]
	v_mul_f32_e32 v100, 0xbfb8aa3b, v100
	v_mul_f32_e32 v101, 0xbfb8aa3b, v101
	v_exp_f32_e32 v100, v100
	v_exp_f32_e32 v101, v101
	v_mul_f32_e32 v102, 0xbfb8aa3b, v102
	v_mul_f32_e32 v103, 0xbfb8aa3b, v103
	v_add_f32_e32 v100, 1.0, v100
	v_add_f32_e32 v101, 1.0, v101
	v_exp_f32_e32 v102, v102
	v_exp_f32_e32 v103, v103
	v_rcp_f32_e32 v100, v100
	v_rcp_f32_e32 v101, v101
	v_add_f32_e32 v102, 1.0, v102
	v_add_f32_e32 v103, 1.0, v103
	v_rcp_f32_e32 v102, v102
	v_rcp_f32_e32 v103, v103
	v_pk_mul_f32 v[96:97], v[96:97], v[120:121] op_sel_hi:[1,0]
	v_pk_mul_f32 v[98:99], v[98:99], v[120:121] op_sel_hi:[1,0]
	v_mul_f32_e32 v96, 0xbfb8aa3b, v96
	v_mul_f32_e32 v97, 0xbfb8aa3b, v97
	v_exp_f32_e32 v96, v96
	v_exp_f32_e32 v97, v97
	v_mul_f32_e32 v98, 0xbfb8aa3b, v98
	v_mul_f32_e32 v99, 0xbfb8aa3b, v99
	v_add_f32_e32 v96, 1.0, v96
	v_add_f32_e32 v97, 1.0, v97
	v_exp_f32_e32 v98, v98
	v_exp_f32_e32 v99, v99
	v_rcp_f32_e32 v96, v96
	v_rcp_f32_e32 v97, v97
	v_add_f32_e32 v98, 1.0, v98
	v_add_f32_e32 v99, 1.0, v99
	v_rcp_f32_e32 v98, v98
	v_rcp_f32_e32 v99, v99
	v_readlane_b32 s53, v248, 49
	v_readlane_b32 s54, v248, 50
	v_readlane_b32 s55, v248, 51
	v_readlane_b32 s56, v248, 52
	v_readlane_b32 s57, v248, 53
	v_readlane_b32 s58, v248, 54
	v_readlane_b32 s59, v248, 55
	v_readlane_b32 s60, v248, 56
	s_waitcnt vmcnt(1)
	v_cvt_f32_f16_e32 v124, v122
	v_cvt_f32_f16_sdwa v125, v122 dst_sel:DWORD dst_unused:UNUSED_PAD src0_sel:WORD_1
	v_or_b32_e32 v122, 32, v118
	v_readlane_b32 s61, v248, 57
	v_readlane_b32 s62, v248, 58
	s_waitcnt vmcnt(0)
	v_pk_fma_f32 v[108:109], v[108:109], v[124:125], v[112:113]
	v_cvt_f32_f16_e32 v112, v123
	v_cvt_f32_f16_sdwa v113, v123 dst_sel:DWORD dst_unused:UNUSED_PAD src0_sel:WORD_1
	v_mov_b32_e32 v123, v119
	v_lshl_add_u64 v[124:125], s[40:41], 0, v[122:123]
	v_readlane_b32 s63, v248, 59
	v_pk_fma_f32 v[110:111], v[110:111], v[112:113], v[114:115]
	global_store_dwordx4 v[116:117], v[108:111], off nt
	global_load_dwordx2 v[124:125], v[124:125], off
	v_cvt_pk_f16_f32 v112, v108, v109
	v_cvt_pk_f16_f32 v113, v110, v111
	v_lshl_add_u64 v[114:115], s[24:25], 0, v[118:119]
	global_store_dwordx2 v[114:115], v[112:113], off
	v_pk_mul_f32 v[112:113], v[108:109], v[108:109]
	v_pk_mul_f32 v[114:115], v[110:111], v[110:111]
	global_load_dwordx4 v[108:111], v[116:117], off offset:64
	v_readlane_b32 s64, v248, 60
	v_readlane_b32 s65, v248, 61
	s_waitcnt vmcnt(2)
	v_cvt_f32_f16_e32 v126, v124
	v_cvt_f32_f16_sdwa v127, v124 dst_sel:DWORD dst_unused:UNUSED_PAD src0_sel:WORD_1
	s_waitcnt vmcnt(0)
	v_pk_fma_f32 v[104:105], v[104:105], v[126:127], v[108:109]
	v_cvt_f32_f16_e32 v108, v125
	v_cvt_f32_f16_sdwa v109, v125 dst_sel:DWORD dst_unused:UNUSED_PAD src0_sel:WORD_1
	v_pk_fma_f32 v[106:107], v[106:107], v[108:109], v[110:111]
	v_lshl_add_u64 v[110:111], s[24:25], 0, v[122:123]
	v_or_b32_e32 v122, 0x100, v118
	global_store_dwordx4 v[116:117], v[104:107], off offset:64 nt
	v_lshl_add_u64 v[124:125], s[40:41], 0, v[122:123]
	global_load_dwordx2 v[124:125], v[124:125], off
	v_cvt_pk_f16_f32 v108, v104, v105
	v_cvt_pk_f16_f32 v109, v106, v107
	global_store_dwordx2 v[110:111], v[108:109], off
	v_pk_mul_f32 v[108:109], v[104:105], v[104:105]
	v_pk_mul_f32 v[110:111], v[106:107], v[106:107]
	global_load_dwordx4 v[104:107], v[116:117], off offset:512
	v_or_b32_e32 v118, 0x120, v118
	s_waitcnt vmcnt(2)
	v_cvt_f32_f16_e32 v126, v124
	v_cvt_f32_f16_sdwa v127, v124 dst_sel:DWORD dst_unused:UNUSED_PAD src0_sel:WORD_1
	s_waitcnt vmcnt(0)
; __device__ __forceinline__ float sigmoidf_(float x) { return __builtin_amdgcn_rcpf(1.0f + __expf(-x)); }
;     __device__ __forceinline__ void operator()(const Acc& acc, const Unit& u, int wr, int wc, int fr, int fq) const {
;     ...
;                 const int row = row0 + ai * HALF + m * 16; const size_t off = (size_t)row * D + col0; float sq = 0.f; const float rs = rs8[ai][m];
; #pragma unroll
;                 for (int bj = 0; bj < 2; ++bj)
; #pragma unroll
;                     for (int n = 0; n < 2; ++n) { const size_t o = off + bj * HALF + n * 16; const f32x4 r = *(const f32x4*)(out + o); const h16x4 p = *(const h16x4*)(pu + o);
;                         const f32x4 a = acc[ai][bj][m][n] * rs; f32x4 v;
;                         v.x = r.x + sigmoidf_(a.x) * (float)p.x; v.y = r.y + sigmoidf_(a.y) * (float)p.y; v.z = r.z + sigmoidf_(a.z) * (float)p.z; v.w = r.w + sigmoidf_(a.w) * (float)p.w;
;                         *(f32x4*)(out + o) = v; u32x2 w; w.x = pk2h(v.x, v.y); w.y = pk2h(v.z, v.w); *(u32x2*)(o16 + o) = w; sq += (v.x * v.x + v.y * v.y) + (v.z * v.z + v.w * v.w); }
;                 sq += __shfl_xor(sq, 16); sq += __shfl_xor(sq, 32);
;                 if (fq == 0) ssw[(size_t)row * 16 + u.pn * 4 + wc] = sq;
;                 asm volatile("" ::: "memory");
;             }
	v_pk_fma_f32 v[100:101], v[100:101], v[126:127], v[104:105]
	v_cvt_f32_f16_e32 v104, v125
	v_cvt_f32_f16_sdwa v105, v125 dst_sel:DWORD dst_unused:UNUSED_PAD src0_sel:WORD_1
	v_pk_fma_f32 v[102:103], v[102:103], v[104:105], v[106:107]
	global_store_dwordx4 v[116:117], v[100:103], off offset:512 nt
	v_lshl_add_u64 v[106:107], s[24:25], 0, v[122:123]
	v_lshl_add_u64 v[122:123], s[40:41], 0, v[118:119]
	global_load_dwordx2 v[122:123], v[122:123], off
	v_cvt_pk_f16_f32 v104, v100, v101
	v_cvt_pk_f16_f32 v105, v102, v103
	global_store_dwordx2 v[106:107], v[104:105], off
	global_load_dwordx4 v[104:107], v[116:117], off offset:576
	v_pk_mul_f32 v[100:101], v[100:101], v[100:101]
	v_pk_mul_f32 v[102:103], v[102:103], v[102:103]
	v_add_f32_e32 v100, v100, v101
	v_add_f32_e32 v102, v102, v103
	v_add_f32_e32 v100, v100, v102
	s_waitcnt vmcnt(2)
	v_cvt_f32_f16_e32 v120, v122
	v_cvt_f32_f16_sdwa v121, v122 dst_sel:DWORD dst_unused:UNUSED_PAD src0_sel:WORD_1
	s_waitcnt vmcnt(0)
	v_pk_fma_f32 v[96:97], v[96:97], v[120:121], v[104:105]
	v_cvt_f32_f16_e32 v104, v123
	v_cvt_f32_f16_sdwa v105, v123 dst_sel:DWORD dst_unused:UNUSED_PAD src0_sel:WORD_1
	v_pk_fma_f32 v[98:99], v[98:99], v[104:105], v[106:107]
	v_cvt_pk_f16_f32 v104, v96, v97
	v_cvt_pk_f16_f32 v105, v98, v99
	v_lshl_add_u64 v[106:107], s[24:25], 0, v[118:119]
	global_store_dwordx4 v[116:117], v[96:99], off offset:576 nt
	global_store_dwordx2 v[106:107], v[104:105], off
	v_add_f32_e32 v104, v114, v115
	v_add_f32_e32 v105, v112, v113
	v_add_f32_e32 v104, v105, v104
	v_add_f32_e32 v105, v110, v111
	v_add_f32_e32 v106, v108, v109
	v_pk_mul_f32 v[96:97], v[96:97], v[96:97]
	v_pk_mul_f32 v[98:99], v[98:99], v[98:99]
	v_add_f32_e32 v105, v106, v105
	v_add_f32_e32 v104, v104, v105
	v_add_f32_e32 v98, v98, v99
	v_add_f32_e32 v96, v96, v97
	v_add_f32_e32 v100, v104, v100
	v_add_f32_e32 v96, v96, v98
	v_add_f32_e32 v96, v100, v96
	ds_bpermute_b32 v97, v214, v96
	s_waitcnt lgkmcnt(0)
	v_add_f32_e32 v96, v96, v97
	ds_bpermute_b32 v97, v213, v96
	s_and_saveexec_b64 s[2:3], s[8:9]
	s_cbranch_execz .LBB0_1024
	s_waitcnt lgkmcnt(0)
	v_add_f32_e32 v98, v96, v97
	v_lshl_add_u64 v[96:97], s[70:71], 0, v[180:181]
	v_lshl_add_u64 v[96:97], s[22:23], 2, v[96:97]
	s_lshl_b32 s92, s38, 2
	v_lshl_add_u64 v[96:97], v[96:97], 0, s[92:93]
	global_store_dword v[96:97], v98, off
.LBB0_1024:
	s_or_b64 exec, exec, s[2:3]
	v_add_f32_e32 v96, v225, v226
	v_fmamk_f32 v96, v96, 0x3a800000, v201
	v_rsq_f32_e32 v104, v96
	s_waitcnt lgkmcnt(0)
	v_lshlrev_b64 v[96:97], 10, v[178:179]
	v_readlane_b32 s52, v248, 48
	v_lshl_add_u64 v[102:103], v[96:97], 0, v[138:139]
	v_readlane_b32 s66, v248, 62
	v_readlane_b32 s67, v248, 63
	v_pk_mul_f32 v[92:93], v[92:93], v[104:105] op_sel_hi:[1,0]
	v_pk_mul_f32 v[94:95], v[94:95], v[104:105] op_sel_hi:[1,0]
	v_lshl_add_u64 v[100:101], v[102:103], 2, s[66:67]
	v_lshlrev_b64 v[102:103], 1, v[102:103]
	v_lshl_add_u64 v[106:107], s[40:41], 0, v[102:103]
	global_load_dwordx2 v[106:107], v[106:107], off
	v_mul_f32_e32 v92, 0xbfb8aa3b, v92
	global_load_dwordx4 v[96:99], v[100:101], off
	v_mul_f32_e32 v93, 0xbfb8aa3b, v93
	v_exp_f32_e32 v92, v92
	v_exp_f32_e32 v93, v93
	v_mul_f32_e32 v94, 0xbfb8aa3b, v94
	v_mul_f32_e32 v95, 0xbfb8aa3b, v95
	v_add_f32_e32 v92, 1.0, v92
	v_add_f32_e32 v93, 1.0, v93
	v_exp_f32_e32 v94, v94
	v_exp_f32_e32 v95, v95
	v_rcp_f32_e32 v92, v92
	v_rcp_f32_e32 v93, v93
	v_add_f32_e32 v94, 1.0, v94
	v_add_f32_e32 v95, 1.0, v95
	v_rcp_f32_e32 v94, v94
	v_rcp_f32_e32 v95, v95
	v_pk_mul_f32 v[88:89], v[88:89], v[104:105] op_sel_hi:[1,0]
	v_pk_mul_f32 v[90:91], v[90:91], v[104:105] op_sel_hi:[1,0]
	v_mul_f32_e32 v88, 0xbfb8aa3b, v88
	v_mul_f32_e32 v89, 0xbfb8aa3b, v89
	v_exp_f32_e32 v88, v88
	v_exp_f32_e32 v89, v89
	v_mul_f32_e32 v90, 0xbfb8aa3b, v90
	v_mul_f32_e32 v91, 0xbfb8aa3b, v91
	v_add_f32_e32 v88, 1.0, v88
	v_add_f32_e32 v89, 1.0, v89
	v_exp_f32_e32 v90, v90
	v_exp_f32_e32 v91, v91
	v_rcp_f32_e32 v88, v88
	v_rcp_f32_e32 v89, v89
	v_add_f32_e32 v90, 1.0, v90
	v_add_f32_e32 v91, 1.0, v91
	v_rcp_f32_e32 v90, v90
	v_rcp_f32_e32 v91, v91
	v_pk_mul_f32 v[84:85], v[84:85], v[104:105] op_sel_hi:[1,0]
	v_pk_mul_f32 v[86:87], v[86:87], v[104:105] op_sel_hi:[1,0]
	v_mul_f32_e32 v84, 0xbfb8aa3b, v84
	v_mul_f32_e32 v85, 0xbfb8aa3b, v85
	v_exp_f32_e32 v84, v84
	v_exp_f32_e32 v85, v85
	v_mul_f32_e32 v86, 0xbfb8aa3b, v86
	v_mul_f32_e32 v87, 0xbfb8aa3b, v87
	v_add_f32_e32 v84, 1.0, v84
	v_add_f32_e32 v85, 1.0, v85
	v_exp_f32_e32 v86, v86
	v_exp_f32_e32 v87, v87
	v_rcp_f32_e32 v84, v84
	v_rcp_f32_e32 v85, v85
	v_add_f32_e32 v86, 1.0, v86
	v_add_f32_e32 v87, 1.0, v87
	v_rcp_f32_e32 v86, v86
	v_rcp_f32_e32 v87, v87
	v_pk_mul_f32 v[80:81], v[80:81], v[104:105] op_sel_hi:[1,0]
	v_pk_mul_f32 v[82:83], v[82:83], v[104:105] op_sel_hi:[1,0]
	v_mul_f32_e32 v80, 0xbfb8aa3b, v80
	v_mul_f32_e32 v81, 0xbfb8aa3b, v81
	v_exp_f32_e32 v80, v80
	v_exp_f32_e32 v81, v81
	v_mul_f32_e32 v82, 0xbfb8aa3b, v82
	v_mul_f32_e32 v83, 0xbfb8aa3b, v83
	v_add_f32_e32 v80, 1.0, v80
	v_add_f32_e32 v81, 1.0, v81
	v_exp_f32_e32 v82, v82
	v_exp_f32_e32 v83, v83
	v_rcp_f32_e32 v80, v80
	v_rcp_f32_e32 v81, v81
	v_add_f32_e32 v82, 1.0, v82
	v_add_f32_e32 v83, 1.0, v83
	v_rcp_f32_e32 v82, v82
	v_rcp_f32_e32 v83, v83
	v_readlane_b32 s53, v248, 49
	v_readlane_b32 s54, v248, 50
	v_readlane_b32 s55, v248, 51
	v_readlane_b32 s56, v248, 52
	v_readlane_b32 s57, v248, 53
	v_readlane_b32 s58, v248, 54
	v_readlane_b32 s59, v248, 55
	v_readlane_b32 s60, v248, 56
	s_waitcnt vmcnt(1)
	v_cvt_f32_f16_e32 v108, v106
	v_cvt_f32_f16_sdwa v109, v106 dst_sel:DWORD dst_unused:UNUSED_PAD src0_sel:WORD_1
	v_or_b32_e32 v106, 32, v102
	v_readlane_b32 s61, v248, 57
	v_readlane_b32 s62, v248, 58
	s_waitcnt vmcnt(0)
; __device__ __forceinline__ float sigmoidf_(float x) { return __builtin_amdgcn_rcpf(1.0f + __expf(-x)); }
;     __device__ __forceinline__ void operator()(const Acc& acc, const Unit& u, int wr, int wc, int fr, int fq) const {
;     ...
;                 const int row = row0 + ai * HALF + m * 16; const size_t off = (size_t)row * D + col0; float sq = 0.f; const float rs = rs8[ai][m];
; #pragma unroll
;                 for (int bj = 0; bj < 2; ++bj)
; #pragma unroll
;                     for (int n = 0; n < 2; ++n) { const size_t o = off + bj * HALF + n * 16; const f32x4 r = *(const f32x4*)(out + o); const h16x4 p = *(const h16x4*)(pu + o);
;                         const f32x4 a = acc[ai][bj][m][n] * rs; f32x4 v;
;                         v.x = r.x + sigmoidf_(a.x) * (float)p.x; v.y = r.y + sigmoidf_(a.y) * (float)p.y; v.z = r.z + sigmoidf_(a.z) * (float)p.z; v.w = r.w + sigmoidf_(a.w) * (float)p.w;
;                         *(f32x4*)(out + o) = v; u32x2 w; w.x = pk2h(v.x, v.y); w.y = pk2h(v.z, v.w); *(u32x2*)(o16 + o) = w; sq += (v.x * v.x + v.y * v.y) + (v.z * v.z + v.w * v.w); }
;                 sq += __shfl_xor(sq, 16); sq += __shfl_xor(sq, 32);
;                 if (fq == 0) ssw[(size_t)row * 16 + u.pn * 4 + wc] = sq;
;                 asm volatile("" ::: "memory");
;             }
	v_pk_fma_f32 v[92:93], v[92:93], v[108:109], v[96:97]
	v_cvt_f32_f16_e32 v96, v107
	v_cvt_f32_f16_sdwa v97, v107 dst_sel:DWORD dst_unused:UNUSED_PAD src0_sel:WORD_1
	v_mov_b32_e32 v107, v103
	v_lshl_add_u64 v[108:109], s[40:41], 0, v[106:107]
	v_readlane_b32 s63, v248, 59
	v_pk_fma_f32 v[94:95], v[94:95], v[96:97], v[98:99]
	global_store_dwordx4 v[100:101], v[92:95], off nt
	global_load_dwordx2 v[108:109], v[108:109], off
	v_cvt_pk_f16_f32 v96, v92, v93
	v_cvt_pk_f16_f32 v97, v94, v95
	v_lshl_add_u64 v[98:99], s[24:25], 0, v[102:103]
	global_store_dwordx2 v[98:99], v[96:97], off
	v_pk_mul_f32 v[96:97], v[92:93], v[92:93]
	v_pk_mul_f32 v[98:99], v[94:95], v[94:95]
	global_load_dwordx4 v[92:95], v[100:101], off offset:64
	v_readlane_b32 s64, v248, 60
	v_readlane_b32 s65, v248, 61
	s_waitcnt vmcnt(2)
	v_cvt_f32_f16_e32 v110, v108
	v_cvt_f32_f16_sdwa v111, v108 dst_sel:DWORD dst_unused:UNUSED_PAD src0_sel:WORD_1
	s_waitcnt vmcnt(0)
	v_pk_fma_f32 v[88:89], v[88:89], v[110:111], v[92:93]
	v_cvt_f32_f16_e32 v92, v109
	v_cvt_f32_f16_sdwa v93, v109 dst_sel:DWORD dst_unused:UNUSED_PAD src0_sel:WORD_1
	v_pk_fma_f32 v[90:91], v[90:91], v[92:93], v[94:95]
	v_lshl_add_u64 v[94:95], s[24:25], 0, v[106:107]
	v_or_b32_e32 v106, 0x100, v102
	global_store_dwordx4 v[100:101], v[88:91], off offset:64 nt
	v_lshl_add_u64 v[108:109], s[40:41], 0, v[106:107]
	global_load_dwordx2 v[108:109], v[108:109], off
	v_cvt_pk_f16_f32 v92, v88, v89
	v_cvt_pk_f16_f32 v93, v90, v91
	global_store_dwordx2 v[94:95], v[92:93], off
	v_pk_mul_f32 v[92:93], v[88:89], v[88:89]
	v_pk_mul_f32 v[94:95], v[90:91], v[90:91]
	global_load_dwordx4 v[88:91], v[100:101], off offset:512
	v_or_b32_e32 v102, 0x120, v102
	s_waitcnt vmcnt(2)
	v_cvt_f32_f16_e32 v110, v108
	v_cvt_f32_f16_sdwa v111, v108 dst_sel:DWORD dst_unused:UNUSED_PAD src0_sel:WORD_1
	s_waitcnt vmcnt(0)
	v_pk_fma_f32 v[84:85], v[84:85], v[110:111], v[88:89]
	v_cvt_f32_f16_e32 v88, v109
	v_cvt_f32_f16_sdwa v89, v109 dst_sel:DWORD dst_unused:UNUSED_PAD src0_sel:WORD_1
	v_pk_fma_f32 v[86:87], v[86:87], v[88:89], v[90:91]
	global_store_dwordx4 v[100:101], v[84:87], off offset:512 nt
	v_lshl_add_u64 v[90:91], s[24:25], 0, v[106:107]
	v_lshl_add_u64 v[106:107], s[40:41], 0, v[102:103]
	global_load_dwordx2 v[106:107], v[106:107], off
	v_cvt_pk_f16_f32 v88, v84, v85
	v_cvt_pk_f16_f32 v89, v86, v87
	global_store_dwordx2 v[90:91], v[88:89], off
	global_load_dwordx4 v[88:91], v[100:101], off offset:576
	v_pk_mul_f32 v[84:85], v[84:85], v[84:85]
	v_pk_mul_f32 v[86:87], v[86:87], v[86:87]
	v_add_f32_e32 v84, v84, v85
	v_add_f32_e32 v86, v86, v87
	v_add_f32_e32 v84, v84, v86
	s_waitcnt vmcnt(2)
	v_cvt_f32_f16_e32 v104, v106
	v_cvt_f32_f16_sdwa v105, v106 dst_sel:DWORD dst_unused:UNUSED_PAD src0_sel:WORD_1
	s_waitcnt vmcnt(0)
	v_pk_fma_f32 v[80:81], v[80:81], v[104:105], v[88:89]
	v_cvt_f32_f16_e32 v88, v107
	v_cvt_f32_f16_sdwa v89, v107 dst_sel:DWORD dst_unused:UNUSED_PAD src0_sel:WORD_1
	v_pk_fma_f32 v[82:83], v[82:83], v[88:89], v[90:91]
	v_cvt_pk_f16_f32 v88, v80, v81
	v_cvt_pk_f16_f32 v89, v82, v83
	v_lshl_add_u64 v[90:91], s[24:25], 0, v[102:103]
	global_store_dwordx4 v[100:101], v[80:83], off offset:576 nt
	global_store_dwordx2 v[90:91], v[88:89], off
	v_add_f32_e32 v88, v98, v99
	v_add_f32_e32 v89, v96, v97
	v_add_f32_e32 v88, v89, v88
	v_add_f32_e32 v89, v94, v95
	v_add_f32_e32 v90, v92, v93
	v_pk_mul_f32 v[80:81], v[80:81], v[80:81]
	v_pk_mul_f32 v[82:83], v[82:83], v[82:83]
	v_add_f32_e32 v89, v90, v89
	v_add_f32_e32 v88, v88, v89
	v_add_f32_e32 v82, v82, v83
	v_add_f32_e32 v80, v80, v81
	v_add_f32_e32 v84, v88, v84
	v_add_f32_e32 v80, v80, v82
	v_add_f32_e32 v80, v84, v80
	ds_bpermute_b32 v81, v214, v80
	s_waitcnt lgkmcnt(0)
	v_add_f32_e32 v80, v80, v81
	ds_bpermute_b32 v81, v213, v80
	s_mov_b64 s[2:3], exec
	v_readlane_b32 s46, v254, 16
	v_mov_b64_e32 v[154:155], v[158:159]
	s_and_b64 s[4:5], s[2:3], s[8:9]
	v_readlane_b32 s47, v254, 17
	v_mov_b64_e32 v[156:157], v[160:161]
	s_mov_b64 exec, s[4:5]
	s_cbranch_execz .LBB0_1026
	s_waitcnt lgkmcnt(0)
	v_add_f32_e32 v82, v80, v81
	v_lshl_add_u64 v[80:81], s[70:71], 0, v[176:177]
	v_lshl_add_u64 v[80:81], s[22:23], 2, v[80:81]
	s_lshl_b32 s92, s38, 2
	v_lshl_add_u64 v[80:81], v[80:81], 0, s[92:93]
	global_store_dword v[80:81], v82, off
; __device__ __forceinline__ float sigmoidf_(float x) { return __builtin_amdgcn_rcpf(1.0f + __expf(-x)); }
;     __device__ __forceinline__ void operator()(const Acc& acc, const Unit& u, int wr, int wc, int fr, int fq) const {
;     ...
;                 const int row = row0 + ai * HALF + m * 16; const size_t off = (size_t)row * D + col0; float sq = 0.f; const float rs = rs8[ai][m];
; #pragma unroll
;                 for (int bj = 0; bj < 2; ++bj)
; #pragma unroll
;                     for (int n = 0; n < 2; ++n) { const size_t o = off + bj * HALF + n * 16; const f32x4 r = *(const f32x4*)(out + o); const h16x4 p = *(const h16x4*)(pu + o);
;                         const f32x4 a = acc[ai][bj][m][n] * rs; f32x4 v;
;                         v.x = r.x + sigmoidf_(a.x) * (float)p.x; v.y = r.y + sigmoidf_(a.y) * (float)p.y; v.z = r.z + sigmoidf_(a.z) * (float)p.z; v.w = r.w + sigmoidf_(a.w) * (float)p.w;
;                         *(f32x4*)(out + o) = v; u32x2 w; w.x = pk2h(v.x, v.y); w.y = pk2h(v.z, v.w); *(u32x2*)(o16 + o) = w; sq += (v.x * v.x + v.y * v.y) + (v.z * v.z + v.w * v.w); }
;                 sq += __shfl_xor(sq, 16); sq += __shfl_xor(sq, 32);
;                 if (fq == 0) ssw[(size_t)row * 16 + u.pn * 4 + wc] = sq;
.LBB0_1026:
	s_or_b64 exec, exec, s[2:3]
	v_add_f32_e32 v80, v223, v224
	v_fmamk_f32 v80, v80, 0x3a800000, v201
	v_rsq_f32_e32 v88, v80
	s_waitcnt lgkmcnt(0)
	v_lshlrev_b64 v[80:81], 10, v[174:175]
	v_readlane_b32 s52, v248, 48
	v_lshl_add_u64 v[86:87], v[80:81], 0, v[138:139]
	v_readlane_b32 s66, v248, 62
	v_readlane_b32 s67, v248, 63
	v_pk_mul_f32 v[76:77], v[76:77], v[88:89] op_sel_hi:[1,0]
	v_pk_mul_f32 v[78:79], v[78:79], v[88:89] op_sel_hi:[1,0]
	v_lshl_add_u64 v[84:85], v[86:87], 2, s[66:67]
	v_lshlrev_b64 v[86:87], 1, v[86:87]
	v_lshl_add_u64 v[90:91], s[40:41], 0, v[86:87]
	global_load_dwordx2 v[90:91], v[90:91], off
	v_mul_f32_e32 v76, 0xbfb8aa3b, v76
	global_load_dwordx4 v[80:83], v[84:85], off
	v_mul_f32_e32 v77, 0xbfb8aa3b, v77
	v_exp_f32_e32 v76, v76
	v_exp_f32_e32 v77, v77
	v_mul_f32_e32 v78, 0xbfb8aa3b, v78
	v_mul_f32_e32 v79, 0xbfb8aa3b, v79
	v_add_f32_e32 v76, 1.0, v76
	v_add_f32_e32 v77, 1.0, v77
	v_exp_f32_e32 v78, v78
	v_exp_f32_e32 v79, v79
	v_rcp_f32_e32 v76, v76
	v_rcp_f32_e32 v77, v77
	v_add_f32_e32 v78, 1.0, v78
	v_add_f32_e32 v79, 1.0, v79
	v_rcp_f32_e32 v78, v78
	v_rcp_f32_e32 v79, v79
	v_pk_mul_f32 v[72:73], v[72:73], v[88:89] op_sel_hi:[1,0]
	v_pk_mul_f32 v[74:75], v[74:75], v[88:89] op_sel_hi:[1,0]
	v_mul_f32_e32 v72, 0xbfb8aa3b, v72
	v_mul_f32_e32 v73, 0xbfb8aa3b, v73
	v_exp_f32_e32 v72, v72
	v_exp_f32_e32 v73, v73
	v_mul_f32_e32 v74, 0xbfb8aa3b, v74
	v_mul_f32_e32 v75, 0xbfb8aa3b, v75
	v_add_f32_e32 v72, 1.0, v72
	v_add_f32_e32 v73, 1.0, v73
	v_exp_f32_e32 v74, v74
	v_exp_f32_e32 v75, v75
	v_rcp_f32_e32 v72, v72
	v_rcp_f32_e32 v73, v73
	v_add_f32_e32 v74, 1.0, v74
	v_add_f32_e32 v75, 1.0, v75
	v_rcp_f32_e32 v74, v74
	v_rcp_f32_e32 v75, v75
	v_pk_mul_f32 v[68:69], v[68:69], v[88:89] op_sel_hi:[1,0]
	v_pk_mul_f32 v[70:71], v[70:71], v[88:89] op_sel_hi:[1,0]
	v_mul_f32_e32 v68, 0xbfb8aa3b, v68
	v_mul_f32_e32 v69, 0xbfb8aa3b, v69
	v_exp_f32_e32 v68, v68
	v_exp_f32_e32 v69, v69
	v_mul_f32_e32 v70, 0xbfb8aa3b, v70
	v_mul_f32_e32 v71, 0xbfb8aa3b, v71
	v_add_f32_e32 v68, 1.0, v68
	v_add_f32_e32 v69, 1.0, v69
	v_exp_f32_e32 v70, v70
	v_exp_f32_e32 v71, v71
	v_rcp_f32_e32 v68, v68
	v_rcp_f32_e32 v69, v69
	v_add_f32_e32 v70, 1.0, v70
	v_add_f32_e32 v71, 1.0, v71
	v_rcp_f32_e32 v70, v70
	v_rcp_f32_e32 v71, v71
	v_pk_mul_f32 v[64:65], v[64:65], v[88:89] op_sel_hi:[1,0]
	v_pk_mul_f32 v[66:67], v[66:67], v[88:89] op_sel_hi:[1,0]
	v_mul_f32_e32 v64, 0xbfb8aa3b, v64
	v_mul_f32_e32 v65, 0xbfb8aa3b, v65
	v_exp_f32_e32 v64, v64
	v_exp_f32_e32 v65, v65
	v_mul_f32_e32 v66, 0xbfb8aa3b, v66
	v_mul_f32_e32 v67, 0xbfb8aa3b, v67
	v_add_f32_e32 v64, 1.0, v64
	v_add_f32_e32 v65, 1.0, v65
	v_exp_f32_e32 v66, v66
	v_exp_f32_e32 v67, v67
	v_rcp_f32_e32 v64, v64
	v_rcp_f32_e32 v65, v65
	v_add_f32_e32 v66, 1.0, v66
	v_add_f32_e32 v67, 1.0, v67
	v_rcp_f32_e32 v66, v66
	v_rcp_f32_e32 v67, v67
	v_readlane_b32 s53, v248, 49
	v_readlane_b32 s54, v248, 50
	v_readlane_b32 s55, v248, 51
	v_readlane_b32 s56, v248, 52
	v_readlane_b32 s57, v248, 53
	v_readlane_b32 s58, v248, 54
	v_readlane_b32 s59, v248, 55
	v_readlane_b32 s60, v248, 56
	s_waitcnt vmcnt(1)
	v_cvt_f32_f16_e32 v92, v90
	v_cvt_f32_f16_sdwa v93, v90 dst_sel:DWORD dst_unused:UNUSED_PAD src0_sel:WORD_1
	v_or_b32_e32 v90, 32, v86
	v_readlane_b32 s61, v248, 57
	v_readlane_b32 s62, v248, 58
	s_waitcnt vmcnt(0)
	v_pk_fma_f32 v[76:77], v[76:77], v[92:93], v[80:81]
	v_cvt_f32_f16_e32 v80, v91
	v_cvt_f32_f16_sdwa v81, v91 dst_sel:DWORD dst_unused:UNUSED_PAD src0_sel:WORD_1
	v_mov_b32_e32 v91, v87
	v_lshl_add_u64 v[92:93], s[40:41], 0, v[90:91]
	v_readlane_b32 s63, v248, 59
	v_pk_fma_f32 v[78:79], v[78:79], v[80:81], v[82:83]
	global_store_dwordx4 v[84:85], v[76:79], off nt
	global_load_dwordx2 v[92:93], v[92:93], off
	v_cvt_pk_f16_f32 v80, v76, v77
	v_cvt_pk_f16_f32 v81, v78, v79
	v_lshl_add_u64 v[82:83], s[24:25], 0, v[86:87]
	global_store_dwordx2 v[82:83], v[80:81], off
	v_pk_mul_f32 v[80:81], v[76:77], v[76:77]
	v_pk_mul_f32 v[82:83], v[78:79], v[78:79]
	global_load_dwordx4 v[76:79], v[84:85], off offset:64
	v_readlane_b32 s64, v248, 60
	v_readlane_b32 s65, v248, 61
	s_waitcnt vmcnt(2)
	v_cvt_f32_f16_e32 v94, v92
	v_cvt_f32_f16_sdwa v95, v92 dst_sel:DWORD dst_unused:UNUSED_PAD src0_sel:WORD_1
	s_waitcnt vmcnt(0)
	v_pk_fma_f32 v[72:73], v[72:73], v[94:95], v[76:77]
	v_cvt_f32_f16_e32 v76, v93
	v_cvt_f32_f16_sdwa v77, v93 dst_sel:DWORD dst_unused:UNUSED_PAD src0_sel:WORD_1
	v_pk_fma_f32 v[74:75], v[74:75], v[76:77], v[78:79]
	v_lshl_add_u64 v[78:79], s[24:25], 0, v[90:91]
	v_or_b32_e32 v90, 0x100, v86
	global_store_dwordx4 v[84:85], v[72:75], off offset:64 nt
	v_lshl_add_u64 v[92:93], s[40:41], 0, v[90:91]
	global_load_dwordx2 v[92:93], v[92:93], off
	v_cvt_pk_f16_f32 v76, v72, v73
	v_cvt_pk_f16_f32 v77, v74, v75
	global_store_dwordx2 v[78:79], v[76:77], off
	v_pk_mul_f32 v[76:77], v[72:73], v[72:73]
	v_pk_mul_f32 v[78:79], v[74:75], v[74:75]
	global_load_dwordx4 v[72:75], v[84:85], off offset:512
	v_or_b32_e32 v86, 0x120, v86
	s_waitcnt vmcnt(2)
	v_cvt_f32_f16_e32 v94, v92
	v_cvt_f32_f16_sdwa v95, v92 dst_sel:DWORD dst_unused:UNUSED_PAD src0_sel:WORD_1
	s_waitcnt vmcnt(0)
	v_pk_fma_f32 v[68:69], v[68:69], v[94:95], v[72:73]
	v_cvt_f32_f16_e32 v72, v93
	v_cvt_f32_f16_sdwa v73, v93 dst_sel:DWORD dst_unused:UNUSED_PAD src0_sel:WORD_1
	v_pk_fma_f32 v[70:71], v[70:71], v[72:73], v[74:75]
	global_store_dwordx4 v[84:85], v[68:71], off offset:512 nt
	v_lshl_add_u64 v[74:75], s[24:25], 0, v[90:91]
	v_lshl_add_u64 v[90:91], s[40:41], 0, v[86:87]
	global_load_dwordx2 v[90:91], v[90:91], off
	v_cvt_pk_f16_f32 v72, v68, v69
	v_cvt_pk_f16_f32 v73, v70, v71
	global_store_dwordx2 v[74:75], v[72:73], off
	global_load_dwordx4 v[72:75], v[84:85], off offset:576
	v_pk_mul_f32 v[68:69], v[68:69], v[68:69]
	v_pk_mul_f32 v[70:71], v[70:71], v[70:71]
	v_add_f32_e32 v68, v68, v69
	v_add_f32_e32 v70, v70, v71
	v_add_f32_e32 v68, v68, v70
	s_waitcnt vmcnt(2)
; __device__ __forceinline__ float sigmoidf_(float x) { return __builtin_amdgcn_rcpf(1.0f + __expf(-x)); }
;     __device__ __forceinline__ void operator()(const Acc& acc, const Unit& u, int wr, int wc, int fr, int fq) const {
;     ...
;                 const int row = row0 + ai * HALF + m * 16; const size_t off = (size_t)row * D + col0; float sq = 0.f; const float rs = rs8[ai][m];
; #pragma unroll
;                 for (int bj = 0; bj < 2; ++bj)
; #pragma unroll
;                     for (int n = 0; n < 2; ++n) { const size_t o = off + bj * HALF + n * 16; const f32x4 r = *(const f32x4*)(out + o); const h16x4 p = *(const h16x4*)(pu + o);
;                         const f32x4 a = acc[ai][bj][m][n] * rs; f32x4 v;
;                         v.x = r.x + sigmoidf_(a.x) * (float)p.x; v.y = r.y + sigmoidf_(a.y) * (float)p.y; v.z = r.z + sigmoidf_(a.z) * (float)p.z; v.w = r.w + sigmoidf_(a.w) * (float)p.w;
;                         *(f32x4*)(out + o) = v; u32x2 w; w.x = pk2h(v.x, v.y); w.y = pk2h(v.z, v.w); *(u32x2*)(o16 + o) = w; sq += (v.x * v.x + v.y * v.y) + (v.z * v.z + v.w * v.w); }
;                 sq += __shfl_xor(sq, 16); sq += __shfl_xor(sq, 32);
;                 if (fq == 0) ssw[(size_t)row * 16 + u.pn * 4 + wc] = sq;
;                 asm volatile("" ::: "memory");
;             }
	v_cvt_f32_f16_e32 v88, v90
	v_cvt_f32_f16_sdwa v89, v90 dst_sel:DWORD dst_unused:UNUSED_PAD src0_sel:WORD_1
	s_waitcnt vmcnt(0)
	v_pk_fma_f32 v[64:65], v[64:65], v[88:89], v[72:73]
	v_cvt_f32_f16_e32 v72, v91
	v_cvt_f32_f16_sdwa v73, v91 dst_sel:DWORD dst_unused:UNUSED_PAD src0_sel:WORD_1
	v_pk_fma_f32 v[66:67], v[66:67], v[72:73], v[74:75]
	v_cvt_pk_f16_f32 v72, v64, v65
	v_cvt_pk_f16_f32 v73, v66, v67
	v_lshl_add_u64 v[74:75], s[24:25], 0, v[86:87]
	global_store_dwordx4 v[84:85], v[64:67], off offset:576 nt
	global_store_dwordx2 v[74:75], v[72:73], off
	v_add_f32_e32 v72, v82, v83
	v_add_f32_e32 v73, v80, v81
	v_add_f32_e32 v72, v73, v72
	v_add_f32_e32 v73, v78, v79
	v_add_f32_e32 v74, v76, v77
	v_pk_mul_f32 v[64:65], v[64:65], v[64:65]
	v_pk_mul_f32 v[66:67], v[66:67], v[66:67]
	v_add_f32_e32 v73, v74, v73
	v_add_f32_e32 v72, v72, v73
	v_add_f32_e32 v66, v66, v67
	v_add_f32_e32 v64, v64, v65
	v_add_f32_e32 v68, v72, v68
	v_add_f32_e32 v64, v64, v66
	v_add_f32_e32 v64, v68, v64
	ds_bpermute_b32 v65, v214, v64
	s_waitcnt lgkmcnt(0)
	v_add_f32_e32 v64, v64, v65
	ds_bpermute_b32 v65, v213, v64
	s_and_saveexec_b64 s[2:3], s[8:9]
	s_cbranch_execz .LBB0_1028
	s_waitcnt lgkmcnt(0)
	v_add_f32_e32 v66, v64, v65
	v_lshl_add_u64 v[64:65], s[70:71], 0, v[172:173]
	v_lshl_add_u64 v[64:65], s[22:23], 2, v[64:65]
	s_lshl_b32 s92, s38, 2
	v_lshl_add_u64 v[64:65], v[64:65], 0, s[92:93]
	global_store_dword v[64:65], v66, off
.LBB0_1028:
	s_or_b64 exec, exec, s[2:3]
	v_add_f32_e32 v64, v221, v222
	v_fmamk_f32 v64, v64, 0x3a800000, v201
	v_rsq_f32_e32 v72, v64
	s_waitcnt lgkmcnt(0)
	v_lshlrev_b64 v[64:65], 10, v[170:171]
	v_readlane_b32 s52, v248, 48
	v_lshl_add_u64 v[70:71], v[64:65], 0, v[138:139]
	v_readlane_b32 s66, v248, 62
	v_readlane_b32 s67, v248, 63
	v_pk_mul_f32 v[60:61], v[60:61], v[72:73] op_sel_hi:[1,0]
	v_pk_mul_f32 v[62:63], v[62:63], v[72:73] op_sel_hi:[1,0]
	v_lshl_add_u64 v[68:69], v[70:71], 2, s[66:67]
	v_lshlrev_b64 v[70:71], 1, v[70:71]
	v_lshl_add_u64 v[74:75], s[40:41], 0, v[70:71]
	global_load_dwordx2 v[74:75], v[74:75], off
	v_mul_f32_e32 v60, 0xbfb8aa3b, v60
	global_load_dwordx4 v[64:67], v[68:69], off
	v_mul_f32_e32 v61, 0xbfb8aa3b, v61
	v_exp_f32_e32 v60, v60
	v_exp_f32_e32 v61, v61
	v_mul_f32_e32 v62, 0xbfb8aa3b, v62
	v_mul_f32_e32 v63, 0xbfb8aa3b, v63
	v_add_f32_e32 v60, 1.0, v60
	v_add_f32_e32 v61, 1.0, v61
	v_exp_f32_e32 v62, v62
	v_exp_f32_e32 v63, v63
	v_rcp_f32_e32 v60, v60
	v_rcp_f32_e32 v61, v61
	v_add_f32_e32 v62, 1.0, v62
	v_add_f32_e32 v63, 1.0, v63
	v_rcp_f32_e32 v62, v62
	v_rcp_f32_e32 v63, v63
	v_pk_mul_f32 v[56:57], v[56:57], v[72:73] op_sel_hi:[1,0]
	v_pk_mul_f32 v[58:59], v[58:59], v[72:73] op_sel_hi:[1,0]
	v_mul_f32_e32 v56, 0xbfb8aa3b, v56
	v_mul_f32_e32 v57, 0xbfb8aa3b, v57
	v_exp_f32_e32 v56, v56
	v_exp_f32_e32 v57, v57
	v_mul_f32_e32 v58, 0xbfb8aa3b, v58
	v_mul_f32_e32 v59, 0xbfb8aa3b, v59
	v_add_f32_e32 v56, 1.0, v56
	v_add_f32_e32 v57, 1.0, v57
	v_exp_f32_e32 v58, v58
	v_exp_f32_e32 v59, v59
	v_rcp_f32_e32 v56, v56
	v_rcp_f32_e32 v57, v57
	v_add_f32_e32 v58, 1.0, v58
	v_add_f32_e32 v59, 1.0, v59
	v_rcp_f32_e32 v58, v58
	v_rcp_f32_e32 v59, v59
	v_pk_mul_f32 v[52:53], v[52:53], v[72:73] op_sel_hi:[1,0]
	v_pk_mul_f32 v[54:55], v[54:55], v[72:73] op_sel_hi:[1,0]
	v_mul_f32_e32 v52, 0xbfb8aa3b, v52
	v_mul_f32_e32 v53, 0xbfb8aa3b, v53
	v_exp_f32_e32 v52, v52
	v_exp_f32_e32 v53, v53
	v_mul_f32_e32 v54, 0xbfb8aa3b, v54
	v_mul_f32_e32 v55, 0xbfb8aa3b, v55
	v_add_f32_e32 v52, 1.0, v52
	v_add_f32_e32 v53, 1.0, v53
	v_exp_f32_e32 v54, v54
	v_exp_f32_e32 v55, v55
	v_rcp_f32_e32 v52, v52
	v_rcp_f32_e32 v53, v53
	v_add_f32_e32 v54, 1.0, v54
	v_add_f32_e32 v55, 1.0, v55
	v_rcp_f32_e32 v54, v54
	v_rcp_f32_e32 v55, v55
	v_pk_mul_f32 v[48:49], v[48:49], v[72:73] op_sel_hi:[1,0]
	v_pk_mul_f32 v[50:51], v[50:51], v[72:73] op_sel_hi:[1,0]
	v_mul_f32_e32 v48, 0xbfb8aa3b, v48
	v_mul_f32_e32 v49, 0xbfb8aa3b, v49
	v_exp_f32_e32 v48, v48
	v_exp_f32_e32 v49, v49
	v_mul_f32_e32 v50, 0xbfb8aa3b, v50
	v_mul_f32_e32 v51, 0xbfb8aa3b, v51
	v_add_f32_e32 v48, 1.0, v48
	v_add_f32_e32 v49, 1.0, v49
	v_exp_f32_e32 v50, v50
	v_exp_f32_e32 v51, v51
	v_rcp_f32_e32 v48, v48
	v_rcp_f32_e32 v49, v49
	v_add_f32_e32 v50, 1.0, v50
	v_add_f32_e32 v51, 1.0, v51
	v_rcp_f32_e32 v50, v50
	v_rcp_f32_e32 v51, v51
	v_readlane_b32 s53, v248, 49
	v_readlane_b32 s54, v248, 50
	v_readlane_b32 s55, v248, 51
	v_readlane_b32 s56, v248, 52
	v_readlane_b32 s57, v248, 53
	v_readlane_b32 s58, v248, 54
	v_readlane_b32 s59, v248, 55
	v_readlane_b32 s60, v248, 56
	s_waitcnt vmcnt(1)
	v_cvt_f32_f16_e32 v76, v74
	v_cvt_f32_f16_sdwa v77, v74 dst_sel:DWORD dst_unused:UNUSED_PAD src0_sel:WORD_1
	v_or_b32_e32 v74, 32, v70
	v_readlane_b32 s61, v248, 57
	v_readlane_b32 s62, v248, 58
	s_waitcnt vmcnt(0)
	v_pk_fma_f32 v[60:61], v[60:61], v[76:77], v[64:65]
	v_cvt_f32_f16_e32 v64, v75
	v_cvt_f32_f16_sdwa v65, v75 dst_sel:DWORD dst_unused:UNUSED_PAD src0_sel:WORD_1
	v_mov_b32_e32 v75, v71
	v_lshl_add_u64 v[76:77], s[40:41], 0, v[74:75]
	v_readlane_b32 s63, v248, 59
	v_pk_fma_f32 v[62:63], v[62:63], v[64:65], v[66:67]
	global_store_dwordx4 v[68:69], v[60:63], off nt
	global_load_dwordx2 v[76:77], v[76:77], off
	v_cvt_pk_f16_f32 v64, v60, v61
	v_cvt_pk_f16_f32 v65, v62, v63
	v_lshl_add_u64 v[66:67], s[24:25], 0, v[70:71]
	global_store_dwordx2 v[66:67], v[64:65], off
	v_pk_mul_f32 v[64:65], v[60:61], v[60:61]
	v_pk_mul_f32 v[66:67], v[62:63], v[62:63]
	global_load_dwordx4 v[60:63], v[68:69], off offset:64
	v_readlane_b32 s64, v248, 60
	v_readlane_b32 s65, v248, 61
	s_waitcnt vmcnt(2)
	v_cvt_f32_f16_e32 v78, v76
	v_cvt_f32_f16_sdwa v79, v76 dst_sel:DWORD dst_unused:UNUSED_PAD src0_sel:WORD_1
	s_waitcnt vmcnt(0)
; __device__ __forceinline__ float sigmoidf_(float x) { return __builtin_amdgcn_rcpf(1.0f + __expf(-x)); }
;     __device__ __forceinline__ void operator()(const Acc& acc, const Unit& u, int wr, int wc, int fr, int fq) const {
;     ...
;                 const int row = row0 + ai * HALF + m * 16; const size_t off = (size_t)row * D + col0; float sq = 0.f; const float rs = rs8[ai][m];
; #pragma unroll
;                 for (int bj = 0; bj < 2; ++bj)
; #pragma unroll
;                     for (int n = 0; n < 2; ++n) { const size_t o = off + bj * HALF + n * 16; const f32x4 r = *(const f32x4*)(out + o); const h16x4 p = *(const h16x4*)(pu + o);
;                         const f32x4 a = acc[ai][bj][m][n] * rs; f32x4 v;
;                         v.x = r.x + sigmoidf_(a.x) * (float)p.x; v.y = r.y + sigmoidf_(a.y) * (float)p.y; v.z = r.z + sigmoidf_(a.z) * (float)p.z; v.w = r.w + sigmoidf_(a.w) * (float)p.w;
;                         *(f32x4*)(out + o) = v; u32x2 w; w.x = pk2h(v.x, v.y); w.y = pk2h(v.z, v.w); *(u32x2*)(o16 + o) = w; sq += (v.x * v.x + v.y * v.y) + (v.z * v.z + v.w * v.w); }
;                 sq += __shfl_xor(sq, 16); sq += __shfl_xor(sq, 32);
;                 if (fq == 0) ssw[(size_t)row * 16 + u.pn * 4 + wc] = sq;
;                 asm volatile("" ::: "memory");
;             }
	v_pk_fma_f32 v[56:57], v[56:57], v[78:79], v[60:61]
	v_cvt_f32_f16_e32 v60, v77
	v_cvt_f32_f16_sdwa v61, v77 dst_sel:DWORD dst_unused:UNUSED_PAD src0_sel:WORD_1
	v_pk_fma_f32 v[58:59], v[58:59], v[60:61], v[62:63]
	v_lshl_add_u64 v[62:63], s[24:25], 0, v[74:75]
	v_or_b32_e32 v74, 0x100, v70
	global_store_dwordx4 v[68:69], v[56:59], off offset:64 nt
	v_lshl_add_u64 v[76:77], s[40:41], 0, v[74:75]
	global_load_dwordx2 v[76:77], v[76:77], off
	v_cvt_pk_f16_f32 v60, v56, v57
	v_cvt_pk_f16_f32 v61, v58, v59
	global_store_dwordx2 v[62:63], v[60:61], off
	v_pk_mul_f32 v[60:61], v[56:57], v[56:57]
	v_pk_mul_f32 v[62:63], v[58:59], v[58:59]
	global_load_dwordx4 v[56:59], v[68:69], off offset:512
	v_or_b32_e32 v70, 0x120, v70
	s_waitcnt vmcnt(2)
	v_cvt_f32_f16_e32 v78, v76
	v_cvt_f32_f16_sdwa v79, v76 dst_sel:DWORD dst_unused:UNUSED_PAD src0_sel:WORD_1
	s_waitcnt vmcnt(0)
	v_pk_fma_f32 v[52:53], v[52:53], v[78:79], v[56:57]
	v_cvt_f32_f16_e32 v56, v77
	v_cvt_f32_f16_sdwa v57, v77 dst_sel:DWORD dst_unused:UNUSED_PAD src0_sel:WORD_1
	v_pk_fma_f32 v[54:55], v[54:55], v[56:57], v[58:59]
	global_store_dwordx4 v[68:69], v[52:55], off offset:512 nt
	v_lshl_add_u64 v[58:59], s[24:25], 0, v[74:75]
	v_lshl_add_u64 v[74:75], s[40:41], 0, v[70:71]
	global_load_dwordx2 v[74:75], v[74:75], off
	v_cvt_pk_f16_f32 v56, v52, v53
	v_cvt_pk_f16_f32 v57, v54, v55
	global_store_dwordx2 v[58:59], v[56:57], off
	global_load_dwordx4 v[56:59], v[68:69], off offset:576
	v_pk_mul_f32 v[52:53], v[52:53], v[52:53]
	v_pk_mul_f32 v[54:55], v[54:55], v[54:55]
	v_add_f32_e32 v52, v52, v53
	v_add_f32_e32 v54, v54, v55
	v_add_f32_e32 v52, v52, v54
	s_waitcnt vmcnt(2)
	v_cvt_f32_f16_e32 v72, v74
	v_cvt_f32_f16_sdwa v73, v74 dst_sel:DWORD dst_unused:UNUSED_PAD src0_sel:WORD_1
	s_waitcnt vmcnt(0)
	v_pk_fma_f32 v[48:49], v[48:49], v[72:73], v[56:57]
	v_cvt_f32_f16_e32 v56, v75
	v_cvt_f32_f16_sdwa v57, v75 dst_sel:DWORD dst_unused:UNUSED_PAD src0_sel:WORD_1
	v_pk_fma_f32 v[50:51], v[50:51], v[56:57], v[58:59]
	v_cvt_pk_f16_f32 v56, v48, v49
	v_cvt_pk_f16_f32 v57, v50, v51
	v_lshl_add_u64 v[58:59], s[24:25], 0, v[70:71]
	global_store_dwordx4 v[68:69], v[48:51], off offset:576 nt
	global_store_dwordx2 v[58:59], v[56:57], off
	v_add_f32_e32 v56, v66, v67
	v_add_f32_e32 v57, v64, v65
	v_add_f32_e32 v56, v57, v56
	v_add_f32_e32 v57, v62, v63
	v_add_f32_e32 v58, v60, v61
	v_pk_mul_f32 v[48:49], v[48:49], v[48:49]
	v_pk_mul_f32 v[50:51], v[50:51], v[50:51]
	v_add_f32_e32 v57, v58, v57
	v_add_f32_e32 v56, v56, v57
	v_add_f32_e32 v50, v50, v51
	v_add_f32_e32 v48, v48, v49
	v_add_f32_e32 v52, v56, v52
	v_add_f32_e32 v48, v48, v50
	v_add_f32_e32 v48, v52, v48
	ds_bpermute_b32 v49, v214, v48
	s_waitcnt lgkmcnt(0)
	v_add_f32_e32 v48, v48, v49
	ds_bpermute_b32 v49, v213, v48
	s_and_saveexec_b64 s[2:3], s[8:9]
	s_cbranch_execz .LBB0_1030
	s_waitcnt lgkmcnt(0)
	v_add_f32_e32 v50, v48, v49
	v_lshl_add_u64 v[48:49], s[70:71], 0, v[150:151]
	v_lshl_add_u64 v[48:49], s[22:23], 2, v[48:49]
	s_lshl_b32 s92, s38, 2
	v_lshl_add_u64 v[48:49], v[48:49], 0, s[92:93]
	global_store_dword v[48:49], v50, off
.LBB0_1030:
	s_or_b64 exec, exec, s[2:3]
	v_add_f32_e32 v48, v219, v220
	v_fmamk_f32 v48, v48, 0x3a800000, v201
	v_rsq_f32_e32 v56, v48
	s_waitcnt lgkmcnt(0)
	v_lshlrev_b64 v[48:49], 10, v[148:149]
	v_readlane_b32 s52, v248, 48
	v_lshl_add_u64 v[54:55], v[48:49], 0, v[138:139]
	v_readlane_b32 s66, v248, 62
	v_readlane_b32 s67, v248, 63
	v_pk_mul_f32 v[44:45], v[44:45], v[56:57] op_sel_hi:[1,0]
	v_pk_mul_f32 v[46:47], v[46:47], v[56:57] op_sel_hi:[1,0]
	v_lshl_add_u64 v[52:53], v[54:55], 2, s[66:67]
	v_lshlrev_b64 v[54:55], 1, v[54:55]
	v_lshl_add_u64 v[58:59], s[40:41], 0, v[54:55]
	global_load_dwordx2 v[58:59], v[58:59], off
	v_mul_f32_e32 v44, 0xbfb8aa3b, v44
	global_load_dwordx4 v[48:51], v[52:53], off
	v_mul_f32_e32 v45, 0xbfb8aa3b, v45
	v_exp_f32_e32 v44, v44
	v_exp_f32_e32 v45, v45
	v_mul_f32_e32 v46, 0xbfb8aa3b, v46
	v_mul_f32_e32 v47, 0xbfb8aa3b, v47
	v_add_f32_e32 v44, 1.0, v44
	v_add_f32_e32 v45, 1.0, v45
	v_exp_f32_e32 v46, v46
	v_exp_f32_e32 v47, v47
	v_rcp_f32_e32 v44, v44
	v_rcp_f32_e32 v45, v45
	v_add_f32_e32 v46, 1.0, v46
	v_add_f32_e32 v47, 1.0, v47
	v_rcp_f32_e32 v46, v46
	v_rcp_f32_e32 v47, v47
	v_pk_mul_f32 v[40:41], v[40:41], v[56:57] op_sel_hi:[1,0]
	v_pk_mul_f32 v[42:43], v[42:43], v[56:57] op_sel_hi:[1,0]
	v_mul_f32_e32 v40, 0xbfb8aa3b, v40
	v_mul_f32_e32 v41, 0xbfb8aa3b, v41
	v_exp_f32_e32 v40, v40
	v_exp_f32_e32 v41, v41
	v_mul_f32_e32 v42, 0xbfb8aa3b, v42
	v_mul_f32_e32 v43, 0xbfb8aa3b, v43
	v_add_f32_e32 v40, 1.0, v40
	v_add_f32_e32 v41, 1.0, v41
	v_exp_f32_e32 v42, v42
	v_exp_f32_e32 v43, v43
	v_rcp_f32_e32 v40, v40
	v_rcp_f32_e32 v41, v41
	v_add_f32_e32 v42, 1.0, v42
	v_add_f32_e32 v43, 1.0, v43
	v_rcp_f32_e32 v42, v42
	v_rcp_f32_e32 v43, v43
	v_pk_mul_f32 v[36:37], v[36:37], v[56:57] op_sel_hi:[1,0]
	v_pk_mul_f32 v[38:39], v[38:39], v[56:57] op_sel_hi:[1,0]
	v_mul_f32_e32 v36, 0xbfb8aa3b, v36
	v_mul_f32_e32 v37, 0xbfb8aa3b, v37
	v_exp_f32_e32 v36, v36
	v_exp_f32_e32 v37, v37
	v_mul_f32_e32 v38, 0xbfb8aa3b, v38
	v_mul_f32_e32 v39, 0xbfb8aa3b, v39
	v_add_f32_e32 v36, 1.0, v36
	v_add_f32_e32 v37, 1.0, v37
	v_exp_f32_e32 v38, v38
	v_exp_f32_e32 v39, v39
	v_rcp_f32_e32 v36, v36
	v_rcp_f32_e32 v37, v37
	v_add_f32_e32 v38, 1.0, v38
	v_add_f32_e32 v39, 1.0, v39
	v_rcp_f32_e32 v38, v38
	v_rcp_f32_e32 v39, v39
	v_pk_mul_f32 v[32:33], v[32:33], v[56:57] op_sel_hi:[1,0]
	v_pk_mul_f32 v[34:35], v[34:35], v[56:57] op_sel_hi:[1,0]
	v_mul_f32_e32 v32, 0xbfb8aa3b, v32
	v_mul_f32_e32 v33, 0xbfb8aa3b, v33
	v_exp_f32_e32 v32, v32
	v_exp_f32_e32 v33, v33
	v_mul_f32_e32 v34, 0xbfb8aa3b, v34
	v_mul_f32_e32 v35, 0xbfb8aa3b, v35
	v_add_f32_e32 v32, 1.0, v32
	v_add_f32_e32 v33, 1.0, v33
	v_exp_f32_e32 v34, v34
	v_exp_f32_e32 v35, v35
	v_rcp_f32_e32 v32, v32
	v_rcp_f32_e32 v33, v33
	v_add_f32_e32 v34, 1.0, v34
	v_add_f32_e32 v35, 1.0, v35
	v_rcp_f32_e32 v34, v34
	v_rcp_f32_e32 v35, v35
	v_readlane_b32 s53, v248, 49
	v_readlane_b32 s54, v248, 50
	v_readlane_b32 s55, v248, 51
	v_readlane_b32 s56, v248, 52
	v_readlane_b32 s57, v248, 53
	v_readlane_b32 s58, v248, 54
	v_readlane_b32 s59, v248, 55
	v_readlane_b32 s60, v248, 56
	s_waitcnt vmcnt(1)
; __device__ __forceinline__ float sigmoidf_(float x) { return __builtin_amdgcn_rcpf(1.0f + __expf(-x)); }
;     __device__ __forceinline__ void operator()(const Acc& acc, const Unit& u, int wr, int wc, int fr, int fq) const {
;     ...
;                 const int row = row0 + ai * HALF + m * 16; const size_t off = (size_t)row * D + col0; float sq = 0.f; const float rs = rs8[ai][m];
; #pragma unroll
;                 for (int bj = 0; bj < 2; ++bj)
; #pragma unroll
;                     for (int n = 0; n < 2; ++n) { const size_t o = off + bj * HALF + n * 16; const f32x4 r = *(const f32x4*)(out + o); const h16x4 p = *(const h16x4*)(pu + o);
;                         const f32x4 a = acc[ai][bj][m][n] * rs; f32x4 v;
;                         v.x = r.x + sigmoidf_(a.x) * (float)p.x; v.y = r.y + sigmoidf_(a.y) * (float)p.y; v.z = r.z + sigmoidf_(a.z) * (float)p.z; v.w = r.w + sigmoidf_(a.w) * (float)p.w;
;                         *(f32x4*)(out + o) = v; u32x2 w; w.x = pk2h(v.x, v.y); w.y = pk2h(v.z, v.w); *(u32x2*)(o16 + o) = w; sq += (v.x * v.x + v.y * v.y) + (v.z * v.z + v.w * v.w); }
;                 sq += __shfl_xor(sq, 16); sq += __shfl_xor(sq, 32);
;                 if (fq == 0) ssw[(size_t)row * 16 + u.pn * 4 + wc] = sq;
;                 asm volatile("" ::: "memory");
;             }
	v_cvt_f32_f16_e32 v60, v58
	v_cvt_f32_f16_sdwa v61, v58 dst_sel:DWORD dst_unused:UNUSED_PAD src0_sel:WORD_1
	v_or_b32_e32 v58, 32, v54
	v_readlane_b32 s61, v248, 57
	v_readlane_b32 s62, v248, 58
	s_waitcnt vmcnt(0)
	v_pk_fma_f32 v[44:45], v[44:45], v[60:61], v[48:49]
	v_cvt_f32_f16_e32 v48, v59
	v_cvt_f32_f16_sdwa v49, v59 dst_sel:DWORD dst_unused:UNUSED_PAD src0_sel:WORD_1
	v_mov_b32_e32 v59, v55
	v_lshl_add_u64 v[60:61], s[40:41], 0, v[58:59]
	v_readlane_b32 s63, v248, 59
	v_pk_fma_f32 v[46:47], v[46:47], v[48:49], v[50:51]
	global_store_dwordx4 v[52:53], v[44:47], off nt
	global_load_dwordx2 v[60:61], v[60:61], off
	v_cvt_pk_f16_f32 v48, v44, v45
	v_cvt_pk_f16_f32 v49, v46, v47
	v_lshl_add_u64 v[50:51], s[24:25], 0, v[54:55]
	global_store_dwordx2 v[50:51], v[48:49], off
	v_pk_mul_f32 v[48:49], v[44:45], v[44:45]
	v_pk_mul_f32 v[50:51], v[46:47], v[46:47]
	global_load_dwordx4 v[44:47], v[52:53], off offset:64
	v_readlane_b32 s64, v248, 60
	v_readlane_b32 s65, v248, 61
	s_waitcnt vmcnt(2)
	v_cvt_f32_f16_e32 v62, v60
	v_cvt_f32_f16_sdwa v63, v60 dst_sel:DWORD dst_unused:UNUSED_PAD src0_sel:WORD_1
	s_waitcnt vmcnt(0)
	v_pk_fma_f32 v[40:41], v[40:41], v[62:63], v[44:45]
	v_cvt_f32_f16_e32 v44, v61
	v_cvt_f32_f16_sdwa v45, v61 dst_sel:DWORD dst_unused:UNUSED_PAD src0_sel:WORD_1
	v_pk_fma_f32 v[42:43], v[42:43], v[44:45], v[46:47]
	v_lshl_add_u64 v[46:47], s[24:25], 0, v[58:59]
	v_or_b32_e32 v58, 0x100, v54
	global_store_dwordx4 v[52:53], v[40:43], off offset:64 nt
	v_lshl_add_u64 v[60:61], s[40:41], 0, v[58:59]
	global_load_dwordx2 v[60:61], v[60:61], off
	v_cvt_pk_f16_f32 v44, v40, v41
	v_cvt_pk_f16_f32 v45, v42, v43
	global_store_dwordx2 v[46:47], v[44:45], off
	v_pk_mul_f32 v[44:45], v[40:41], v[40:41]
	v_pk_mul_f32 v[46:47], v[42:43], v[42:43]
	global_load_dwordx4 v[40:43], v[52:53], off offset:512
	v_or_b32_e32 v54, 0x120, v54
	s_waitcnt vmcnt(2)
	v_cvt_f32_f16_e32 v62, v60
	v_cvt_f32_f16_sdwa v63, v60 dst_sel:DWORD dst_unused:UNUSED_PAD src0_sel:WORD_1
	s_waitcnt vmcnt(0)
	v_pk_fma_f32 v[36:37], v[36:37], v[62:63], v[40:41]
	v_cvt_f32_f16_e32 v40, v61
	v_cvt_f32_f16_sdwa v41, v61 dst_sel:DWORD dst_unused:UNUSED_PAD src0_sel:WORD_1
	v_pk_fma_f32 v[38:39], v[38:39], v[40:41], v[42:43]
	global_store_dwordx4 v[52:53], v[36:39], off offset:512 nt
	v_lshl_add_u64 v[42:43], s[24:25], 0, v[58:59]
	v_lshl_add_u64 v[58:59], s[40:41], 0, v[54:55]
	global_load_dwordx2 v[58:59], v[58:59], off
	v_cvt_pk_f16_f32 v40, v36, v37
	v_cvt_pk_f16_f32 v41, v38, v39
	global_store_dwordx2 v[42:43], v[40:41], off
	global_load_dwordx4 v[40:43], v[52:53], off offset:576
	v_pk_mul_f32 v[36:37], v[36:37], v[36:37]
	v_pk_mul_f32 v[38:39], v[38:39], v[38:39]
	v_add_f32_e32 v36, v36, v37
	v_add_f32_e32 v38, v38, v39
	v_add_f32_e32 v36, v36, v38
	s_waitcnt vmcnt(2)
	v_cvt_f32_f16_e32 v56, v58
	v_cvt_f32_f16_sdwa v57, v58 dst_sel:DWORD dst_unused:UNUSED_PAD src0_sel:WORD_1
	s_waitcnt vmcnt(0)
	v_pk_fma_f32 v[32:33], v[32:33], v[56:57], v[40:41]
	v_cvt_f32_f16_e32 v40, v59
	v_cvt_f32_f16_sdwa v41, v59 dst_sel:DWORD dst_unused:UNUSED_PAD src0_sel:WORD_1
	v_pk_fma_f32 v[34:35], v[34:35], v[40:41], v[42:43]
	v_cvt_pk_f16_f32 v40, v32, v33
	v_cvt_pk_f16_f32 v41, v34, v35
	v_lshl_add_u64 v[42:43], s[24:25], 0, v[54:55]
	global_store_dwordx4 v[52:53], v[32:35], off offset:576 nt
	global_store_dwordx2 v[42:43], v[40:41], off
	v_add_f32_e32 v40, v50, v51
	v_add_f32_e32 v41, v48, v49
	v_add_f32_e32 v40, v41, v40
	v_add_f32_e32 v41, v46, v47
	v_add_f32_e32 v42, v44, v45
	v_pk_mul_f32 v[32:33], v[32:33], v[32:33]
	v_pk_mul_f32 v[34:35], v[34:35], v[34:35]
	v_add_f32_e32 v41, v42, v41
	v_add_f32_e32 v40, v40, v41
	v_add_f32_e32 v34, v34, v35
	v_add_f32_e32 v32, v32, v33
	v_add_f32_e32 v36, v40, v36
	v_add_f32_e32 v32, v32, v34
	v_add_f32_e32 v32, v36, v32
	ds_bpermute_b32 v33, v214, v32
	s_waitcnt lgkmcnt(0)
	v_add_f32_e32 v32, v32, v33
	ds_bpermute_b32 v33, v213, v32
	s_and_saveexec_b64 s[2:3], s[8:9]
	s_cbranch_execz .LBB0_1032
	s_waitcnt lgkmcnt(0)
	v_add_f32_e32 v34, v32, v33
	v_lshl_add_u64 v[32:33], s[70:71], 0, v[146:147]
	v_lshl_add_u64 v[32:33], s[22:23], 2, v[32:33]
	s_lshl_b32 s92, s38, 2
	v_lshl_add_u64 v[32:33], v[32:33], 0, s[92:93]
	global_store_dword v[32:33], v34, off
.LBB0_1032:
	s_or_b64 exec, exec, s[2:3]
	v_add_f32_e32 v32, v217, v218
	v_fmamk_f32 v32, v32, 0x3a800000, v201
	v_rsq_f32_e32 v40, v32
	s_waitcnt lgkmcnt(0)
; __device__ __forceinline__ float sigmoidf_(float x) { return __builtin_amdgcn_rcpf(1.0f + __expf(-x)); }
;     __device__ __forceinline__ void operator()(const Acc& acc, const Unit& u, int wr, int wc, int fr, int fq) const {
;     ...
;                 const int row = row0 + ai * HALF + m * 16; const size_t off = (size_t)row * D + col0; float sq = 0.f; const float rs = rs8[ai][m];
; #pragma unroll
;                 for (int bj = 0; bj < 2; ++bj)
; #pragma unroll
;                     for (int n = 0; n < 2; ++n) { const size_t o = off + bj * HALF + n * 16; const f32x4 r = *(const f32x4*)(out + o); const h16x4 p = *(const h16x4*)(pu + o);
;                         const f32x4 a = acc[ai][bj][m][n] * rs; f32x4 v;
;                         v.x = r.x + sigmoidf_(a.x) * (float)p.x; v.y = r.y + sigmoidf_(a.y) * (float)p.y; v.z = r.z + sigmoidf_(a.z) * (float)p.z; v.w = r.w + sigmoidf_(a.w) * (float)p.w;
;                         *(f32x4*)(out + o) = v; u32x2 w; w.x = pk2h(v.x, v.y); w.y = pk2h(v.z, v.w); *(u32x2*)(o16 + o) = w; sq += (v.x * v.x + v.y * v.y) + (v.z * v.z + v.w * v.w); }
;                 sq += __shfl_xor(sq, 16); sq += __shfl_xor(sq, 32);
;                 if (fq == 0) ssw[(size_t)row * 16 + u.pn * 4 + wc] = sq;
	v_lshlrev_b64 v[32:33], 10, v[144:145]
	v_readlane_b32 s52, v248, 48
	v_lshl_add_u64 v[38:39], v[32:33], 0, v[138:139]
	v_readlane_b32 s66, v248, 62
	v_readlane_b32 s67, v248, 63
	v_pk_mul_f32 v[28:29], v[28:29], v[40:41] op_sel_hi:[1,0]
	v_pk_mul_f32 v[30:31], v[30:31], v[40:41] op_sel_hi:[1,0]
	v_lshl_add_u64 v[36:37], v[38:39], 2, s[66:67]
	v_lshlrev_b64 v[38:39], 1, v[38:39]
	v_lshl_add_u64 v[42:43], s[40:41], 0, v[38:39]
	global_load_dwordx2 v[42:43], v[42:43], off
	v_mul_f32_e32 v28, 0xbfb8aa3b, v28
	global_load_dwordx4 v[32:35], v[36:37], off
	v_mul_f32_e32 v29, 0xbfb8aa3b, v29
	v_exp_f32_e32 v28, v28
	v_exp_f32_e32 v29, v29
	v_mul_f32_e32 v30, 0xbfb8aa3b, v30
	v_mul_f32_e32 v31, 0xbfb8aa3b, v31
	v_add_f32_e32 v28, 1.0, v28
	v_add_f32_e32 v29, 1.0, v29
	v_exp_f32_e32 v30, v30
	v_exp_f32_e32 v31, v31
	v_rcp_f32_e32 v28, v28
	v_rcp_f32_e32 v29, v29
	v_add_f32_e32 v30, 1.0, v30
	v_add_f32_e32 v31, 1.0, v31
	v_rcp_f32_e32 v30, v30
	v_rcp_f32_e32 v31, v31
	v_pk_mul_f32 v[24:25], v[24:25], v[40:41] op_sel_hi:[1,0]
	v_pk_mul_f32 v[26:27], v[26:27], v[40:41] op_sel_hi:[1,0]
	v_mul_f32_e32 v24, 0xbfb8aa3b, v24
	v_mul_f32_e32 v25, 0xbfb8aa3b, v25
	v_exp_f32_e32 v24, v24
	v_exp_f32_e32 v25, v25
	v_mul_f32_e32 v26, 0xbfb8aa3b, v26
	v_mul_f32_e32 v27, 0xbfb8aa3b, v27
	v_add_f32_e32 v24, 1.0, v24
	v_add_f32_e32 v25, 1.0, v25
	v_exp_f32_e32 v26, v26
	v_exp_f32_e32 v27, v27
	v_rcp_f32_e32 v24, v24
	v_rcp_f32_e32 v25, v25
	v_add_f32_e32 v26, 1.0, v26
	v_add_f32_e32 v27, 1.0, v27
	v_rcp_f32_e32 v26, v26
	v_rcp_f32_e32 v27, v27
	v_pk_mul_f32 v[20:21], v[20:21], v[40:41] op_sel_hi:[1,0]
	v_pk_mul_f32 v[22:23], v[22:23], v[40:41] op_sel_hi:[1,0]
	v_mul_f32_e32 v20, 0xbfb8aa3b, v20
	v_mul_f32_e32 v21, 0xbfb8aa3b, v21
	v_exp_f32_e32 v20, v20
	v_exp_f32_e32 v21, v21
	v_mul_f32_e32 v22, 0xbfb8aa3b, v22
	v_mul_f32_e32 v23, 0xbfb8aa3b, v23
	v_add_f32_e32 v20, 1.0, v20
	v_add_f32_e32 v21, 1.0, v21
	v_exp_f32_e32 v22, v22
	v_exp_f32_e32 v23, v23
	v_rcp_f32_e32 v20, v20
	v_rcp_f32_e32 v21, v21
	v_add_f32_e32 v22, 1.0, v22
	v_add_f32_e32 v23, 1.0, v23
	v_rcp_f32_e32 v22, v22
	v_rcp_f32_e32 v23, v23
	v_pk_mul_f32 v[16:17], v[16:17], v[40:41] op_sel_hi:[1,0]
	v_pk_mul_f32 v[18:19], v[18:19], v[40:41] op_sel_hi:[1,0]
	v_mul_f32_e32 v16, 0xbfb8aa3b, v16
	v_mul_f32_e32 v17, 0xbfb8aa3b, v17
	v_exp_f32_e32 v16, v16
	v_exp_f32_e32 v17, v17
	v_mul_f32_e32 v18, 0xbfb8aa3b, v18
	v_mul_f32_e32 v19, 0xbfb8aa3b, v19
	v_add_f32_e32 v16, 1.0, v16
	v_add_f32_e32 v17, 1.0, v17
	v_exp_f32_e32 v18, v18
	v_exp_f32_e32 v19, v19
	v_rcp_f32_e32 v16, v16
	v_rcp_f32_e32 v17, v17
	v_add_f32_e32 v18, 1.0, v18
	v_add_f32_e32 v19, 1.0, v19
	v_rcp_f32_e32 v18, v18
	v_rcp_f32_e32 v19, v19
	v_readlane_b32 s53, v248, 49
	v_readlane_b32 s54, v248, 50
	v_readlane_b32 s55, v248, 51
	v_readlane_b32 s56, v248, 52
	v_readlane_b32 s57, v248, 53
	v_readlane_b32 s58, v248, 54
	v_readlane_b32 s59, v248, 55
	v_readlane_b32 s60, v248, 56
	s_waitcnt vmcnt(1)
	v_cvt_f32_f16_e32 v44, v42
	v_cvt_f32_f16_sdwa v45, v42 dst_sel:DWORD dst_unused:UNUSED_PAD src0_sel:WORD_1
	v_or_b32_e32 v42, 32, v38
	v_readlane_b32 s61, v248, 57
	v_readlane_b32 s62, v248, 58
	s_waitcnt vmcnt(0)
	v_pk_fma_f32 v[28:29], v[28:29], v[44:45], v[32:33]
	v_cvt_f32_f16_e32 v32, v43
	v_cvt_f32_f16_sdwa v33, v43 dst_sel:DWORD dst_unused:UNUSED_PAD src0_sel:WORD_1
	v_mov_b32_e32 v43, v39
	v_lshl_add_u64 v[44:45], s[40:41], 0, v[42:43]
	v_readlane_b32 s63, v248, 59
	v_pk_fma_f32 v[30:31], v[30:31], v[32:33], v[34:35]
	global_store_dwordx4 v[36:37], v[28:31], off nt
	global_load_dwordx2 v[44:45], v[44:45], off
	v_cvt_pk_f16_f32 v32, v28, v29
	v_cvt_pk_f16_f32 v33, v30, v31
	v_lshl_add_u64 v[34:35], s[24:25], 0, v[38:39]
	global_store_dwordx2 v[34:35], v[32:33], off
	v_pk_mul_f32 v[32:33], v[28:29], v[28:29]
	v_pk_mul_f32 v[34:35], v[30:31], v[30:31]
	global_load_dwordx4 v[28:31], v[36:37], off offset:64
	v_readlane_b32 s64, v248, 60
	v_readlane_b32 s65, v248, 61
	s_waitcnt vmcnt(2)
	v_cvt_f32_f16_e32 v46, v44
	v_cvt_f32_f16_sdwa v47, v44 dst_sel:DWORD dst_unused:UNUSED_PAD src0_sel:WORD_1
	s_waitcnt vmcnt(0)
	v_pk_fma_f32 v[24:25], v[24:25], v[46:47], v[28:29]
	v_cvt_f32_f16_e32 v28, v45
	v_cvt_f32_f16_sdwa v29, v45 dst_sel:DWORD dst_unused:UNUSED_PAD src0_sel:WORD_1
	v_pk_fma_f32 v[26:27], v[26:27], v[28:29], v[30:31]
	v_lshl_add_u64 v[30:31], s[24:25], 0, v[42:43]
	v_or_b32_e32 v42, 0x100, v38
	global_store_dwordx4 v[36:37], v[24:27], off offset:64 nt
	v_lshl_add_u64 v[44:45], s[40:41], 0, v[42:43]
	global_load_dwordx2 v[44:45], v[44:45], off
	v_cvt_pk_f16_f32 v28, v24, v25
	v_cvt_pk_f16_f32 v29, v26, v27
	global_store_dwordx2 v[30:31], v[28:29], off
	v_pk_mul_f32 v[28:29], v[24:25], v[24:25]
	v_pk_mul_f32 v[30:31], v[26:27], v[26:27]
	global_load_dwordx4 v[24:27], v[36:37], off offset:512
	v_or_b32_e32 v38, 0x120, v38
	s_waitcnt vmcnt(2)
	v_cvt_f32_f16_e32 v46, v44
	v_cvt_f32_f16_sdwa v47, v44 dst_sel:DWORD dst_unused:UNUSED_PAD src0_sel:WORD_1
	s_waitcnt vmcnt(0)
	v_pk_fma_f32 v[20:21], v[20:21], v[46:47], v[24:25]
	v_cvt_f32_f16_e32 v24, v45
	v_cvt_f32_f16_sdwa v25, v45 dst_sel:DWORD dst_unused:UNUSED_PAD src0_sel:WORD_1
	v_pk_fma_f32 v[22:23], v[22:23], v[24:25], v[26:27]
	global_store_dwordx4 v[36:37], v[20:23], off offset:512 nt
	v_lshl_add_u64 v[26:27], s[24:25], 0, v[42:43]
	v_lshl_add_u64 v[42:43], s[40:41], 0, v[38:39]
	global_load_dwordx2 v[42:43], v[42:43], off
	v_cvt_pk_f16_f32 v24, v20, v21
	v_cvt_pk_f16_f32 v25, v22, v23
	global_store_dwordx2 v[26:27], v[24:25], off
	global_load_dwordx4 v[24:27], v[36:37], off offset:576
	v_pk_mul_f32 v[20:21], v[20:21], v[20:21]
	v_pk_mul_f32 v[22:23], v[22:23], v[22:23]
	v_add_f32_e32 v20, v20, v21
	v_add_f32_e32 v22, v22, v23
	v_add_f32_e32 v20, v20, v22
	s_waitcnt vmcnt(2)
	v_cvt_f32_f16_e32 v40, v42
	v_cvt_f32_f16_sdwa v41, v42 dst_sel:DWORD dst_unused:UNUSED_PAD src0_sel:WORD_1
	s_waitcnt vmcnt(0)
	v_pk_fma_f32 v[16:17], v[16:17], v[40:41], v[24:25]
	v_cvt_f32_f16_e32 v24, v43
	v_cvt_f32_f16_sdwa v25, v43 dst_sel:DWORD dst_unused:UNUSED_PAD src0_sel:WORD_1
	v_pk_fma_f32 v[18:19], v[18:19], v[24:25], v[26:27]
	v_cvt_pk_f16_f32 v24, v16, v17
	v_cvt_pk_f16_f32 v25, v18, v19
	v_lshl_add_u64 v[26:27], s[24:25], 0, v[38:39]
	global_store_dwordx4 v[36:37], v[16:19], off offset:576 nt
	global_store_dwordx2 v[26:27], v[24:25], off
	v_add_f32_e32 v24, v34, v35
	v_add_f32_e32 v25, v32, v33
	v_add_f32_e32 v24, v25, v24
	v_add_f32_e32 v25, v30, v31
	v_add_f32_e32 v26, v28, v29
	v_pk_mul_f32 v[16:17], v[16:17], v[16:17]
	v_pk_mul_f32 v[18:19], v[18:19], v[18:19]
	v_add_f32_e32 v25, v26, v25
	v_add_f32_e32 v24, v24, v25
	v_add_f32_e32 v18, v18, v19
	v_add_f32_e32 v16, v16, v17
	v_add_f32_e32 v20, v24, v20
	v_add_f32_e32 v16, v16, v18
	v_add_f32_e32 v16, v20, v16
	ds_bpermute_b32 v17, v214, v16
	s_waitcnt lgkmcnt(0)
	v_add_f32_e32 v16, v16, v17
	ds_bpermute_b32 v17, v213, v16
	s_and_saveexec_b64 s[2:3], s[8:9]
	s_cbranch_execz .LBB0_1034
; __device__ __forceinline__ float sigmoidf_(float x) { return __builtin_amdgcn_rcpf(1.0f + __expf(-x)); }
;     __device__ __forceinline__ void operator()(const Acc& acc, const Unit& u, int wr, int wc, int fr, int fq) const {
;     ...
;                 const int row = row0 + ai * HALF + m * 16; const size_t off = (size_t)row * D + col0; float sq = 0.f; const float rs = rs8[ai][m];
; #pragma unroll
;                 for (int bj = 0; bj < 2; ++bj)
; #pragma unroll
;                     for (int n = 0; n < 2; ++n) { const size_t o = off + bj * HALF + n * 16; const f32x4 r = *(const f32x4*)(out + o); const h16x4 p = *(const h16x4*)(pu + o);
;                         const f32x4 a = acc[ai][bj][m][n] * rs; f32x4 v;
;                         v.x = r.x + sigmoidf_(a.x) * (float)p.x; v.y = r.y + sigmoidf_(a.y) * (float)p.y; v.z = r.z + sigmoidf_(a.z) * (float)p.z; v.w = r.w + sigmoidf_(a.w) * (float)p.w;
;     ...
;                 sq += __shfl_xor(sq, 16); sq += __shfl_xor(sq, 32);
;                 if (fq == 0) ssw[(size_t)row * 16 + u.pn * 4 + wc] = sq;
	s_waitcnt lgkmcnt(0)
	v_add_f32_e32 v18, v16, v17
	v_lshl_add_u64 v[16:17], s[70:71], 0, v[142:143]
	v_lshl_add_u64 v[16:17], s[22:23], 2, v[16:17]
	s_lshl_b32 s92, s38, 2
	v_lshl_add_u64 v[16:17], v[16:17], 0, s[92:93]
	global_store_dword v[16:17], v18, off
.LBB0_1034:
	s_or_b64 exec, exec, s[2:3]
	v_add_f32_e32 v16, v215, v216
	v_fmamk_f32 v16, v16, 0x3a800000, v201
	v_rsq_f32_e32 v24, v16
	s_waitcnt lgkmcnt(0)
	v_lshlrev_b64 v[16:17], 10, v[140:141]
	v_readlane_b32 s52, v248, 48
	v_lshl_add_u64 v[22:23], v[16:17], 0, v[138:139]
	v_readlane_b32 s66, v248, 62
	v_readlane_b32 s67, v248, 63
	v_pk_mul_f32 v[12:13], v[12:13], v[24:25] op_sel_hi:[1,0]
	v_pk_mul_f32 v[14:15], v[14:15], v[24:25] op_sel_hi:[1,0]
	v_lshl_add_u64 v[20:21], v[22:23], 2, s[66:67]
	v_lshlrev_b64 v[22:23], 1, v[22:23]
	v_lshl_add_u64 v[26:27], s[40:41], 0, v[22:23]
	global_load_dwordx2 v[26:27], v[26:27], off
	v_mul_f32_e32 v12, 0xbfb8aa3b, v12
	global_load_dwordx4 v[16:19], v[20:21], off
	v_mul_f32_e32 v13, 0xbfb8aa3b, v13
	v_exp_f32_e32 v12, v12
	v_exp_f32_e32 v13, v13
	v_mul_f32_e32 v14, 0xbfb8aa3b, v14
	v_mul_f32_e32 v15, 0xbfb8aa3b, v15
	v_add_f32_e32 v12, 1.0, v12
	v_add_f32_e32 v13, 1.0, v13
	v_exp_f32_e32 v14, v14
	v_exp_f32_e32 v15, v15
	v_rcp_f32_e32 v12, v12
	v_rcp_f32_e32 v13, v13
	v_add_f32_e32 v14, 1.0, v14
	v_add_f32_e32 v15, 1.0, v15
	v_rcp_f32_e32 v14, v14
	v_rcp_f32_e32 v15, v15
	v_pk_mul_f32 v[8:9], v[8:9], v[24:25] op_sel_hi:[1,0]
	v_pk_mul_f32 v[10:11], v[10:11], v[24:25] op_sel_hi:[1,0]
	v_mul_f32_e32 v8, 0xbfb8aa3b, v8
	v_mul_f32_e32 v9, 0xbfb8aa3b, v9
	v_exp_f32_e32 v8, v8
	v_exp_f32_e32 v9, v9
	v_mul_f32_e32 v10, 0xbfb8aa3b, v10
	v_mul_f32_e32 v11, 0xbfb8aa3b, v11
	v_add_f32_e32 v8, 1.0, v8
	v_add_f32_e32 v9, 1.0, v9
	v_exp_f32_e32 v10, v10
	v_exp_f32_e32 v11, v11
	v_rcp_f32_e32 v8, v8
	v_rcp_f32_e32 v9, v9
	v_add_f32_e32 v10, 1.0, v10
	v_add_f32_e32 v11, 1.0, v11
	v_rcp_f32_e32 v10, v10
	v_rcp_f32_e32 v11, v11
	v_pk_mul_f32 v[4:5], v[4:5], v[24:25] op_sel_hi:[1,0]
	v_pk_mul_f32 v[6:7], v[6:7], v[24:25] op_sel_hi:[1,0]
	v_mul_f32_e32 v4, 0xbfb8aa3b, v4
	v_mul_f32_e32 v5, 0xbfb8aa3b, v5
	v_exp_f32_e32 v4, v4
	v_exp_f32_e32 v5, v5
	v_mul_f32_e32 v6, 0xbfb8aa3b, v6
	v_mul_f32_e32 v7, 0xbfb8aa3b, v7
	v_add_f32_e32 v4, 1.0, v4
	v_add_f32_e32 v5, 1.0, v5
	v_exp_f32_e32 v6, v6
	v_exp_f32_e32 v7, v7
	v_rcp_f32_e32 v4, v4
	v_rcp_f32_e32 v5, v5
	v_add_f32_e32 v6, 1.0, v6
	v_add_f32_e32 v7, 1.0, v7
	v_rcp_f32_e32 v6, v6
	v_rcp_f32_e32 v7, v7
	v_pk_mul_f32 v[0:1], v[0:1], v[24:25] op_sel_hi:[1,0]
	v_pk_mul_f32 v[2:3], v[2:3], v[24:25] op_sel_hi:[1,0]
	v_mul_f32_e32 v0, 0xbfb8aa3b, v0
	v_mul_f32_e32 v1, 0xbfb8aa3b, v1
	v_exp_f32_e32 v0, v0
	v_exp_f32_e32 v1, v1
	v_mul_f32_e32 v2, 0xbfb8aa3b, v2
	v_mul_f32_e32 v3, 0xbfb8aa3b, v3
	v_add_f32_e32 v0, 1.0, v0
	v_add_f32_e32 v1, 1.0, v1
	v_exp_f32_e32 v2, v2
	v_exp_f32_e32 v3, v3
	v_rcp_f32_e32 v0, v0
	v_rcp_f32_e32 v1, v1
	v_add_f32_e32 v2, 1.0, v2
	v_add_f32_e32 v3, 1.0, v3
	v_rcp_f32_e32 v2, v2
	v_rcp_f32_e32 v3, v3
	v_readlane_b32 s53, v248, 49
	v_readlane_b32 s54, v248, 50
	v_readlane_b32 s55, v248, 51
	v_readlane_b32 s56, v248, 52
	v_readlane_b32 s57, v248, 53
	v_readlane_b32 s58, v248, 54
	v_readlane_b32 s59, v248, 55
	v_readlane_b32 s60, v248, 56
	s_waitcnt vmcnt(1)
	v_cvt_f32_f16_e32 v28, v26
	v_cvt_f32_f16_sdwa v29, v26 dst_sel:DWORD dst_unused:UNUSED_PAD src0_sel:WORD_1
	v_or_b32_e32 v26, 32, v22
	v_readlane_b32 s61, v248, 57
	v_readlane_b32 s62, v248, 58
	s_waitcnt vmcnt(0)
; __device__ __forceinline__ float sigmoidf_(float x) { return __builtin_amdgcn_rcpf(1.0f + __expf(-x)); }
;     __device__ __forceinline__ void operator()(const Acc& acc, const Unit& u, int wr, int wc, int fr, int fq) const {
;     ...
;                 const int row = row0 + ai * HALF + m * 16; const size_t off = (size_t)row * D + col0; float sq = 0.f; const float rs = rs8[ai][m];
; #pragma unroll
;                 for (int bj = 0; bj < 2; ++bj)
; #pragma unroll
;                     for (int n = 0; n < 2; ++n) { const size_t o = off + bj * HALF + n * 16; const f32x4 r = *(const f32x4*)(out + o); const h16x4 p = *(const h16x4*)(pu + o);
;                         const f32x4 a = acc[ai][bj][m][n] * rs; f32x4 v;
;                         v.x = r.x + sigmoidf_(a.x) * (float)p.x; v.y = r.y + sigmoidf_(a.y) * (float)p.y; v.z = r.z + sigmoidf_(a.z) * (float)p.z; v.w = r.w + sigmoidf_(a.w) * (float)p.w;
;                         *(f32x4*)(out + o) = v; u32x2 w; w.x = pk2h(v.x, v.y); w.y = pk2h(v.z, v.w); *(u32x2*)(o16 + o) = w; sq += (v.x * v.x + v.y * v.y) + (v.z * v.z + v.w * v.w); }
;                 sq += __shfl_xor(sq, 16); sq += __shfl_xor(sq, 32);
;                 if (fq == 0) ssw[(size_t)row * 16 + u.pn * 4 + wc] = sq;
	v_pk_fma_f32 v[12:13], v[12:13], v[28:29], v[16:17]
	v_cvt_f32_f16_e32 v16, v27
	v_cvt_f32_f16_sdwa v17, v27 dst_sel:DWORD dst_unused:UNUSED_PAD src0_sel:WORD_1
	v_mov_b32_e32 v27, v23
	v_lshl_add_u64 v[28:29], s[40:41], 0, v[26:27]
	v_readlane_b32 s63, v248, 59
	v_pk_fma_f32 v[14:15], v[14:15], v[16:17], v[18:19]
	global_store_dwordx4 v[20:21], v[12:15], off nt
	global_load_dwordx2 v[28:29], v[28:29], off
	v_cvt_pk_f16_f32 v16, v12, v13
	v_cvt_pk_f16_f32 v17, v14, v15
	v_lshl_add_u64 v[18:19], s[24:25], 0, v[22:23]
	global_store_dwordx2 v[18:19], v[16:17], off
	v_pk_mul_f32 v[16:17], v[12:13], v[12:13]
	v_pk_mul_f32 v[18:19], v[14:15], v[14:15]
	global_load_dwordx4 v[12:15], v[20:21], off offset:64
	v_readlane_b32 s64, v248, 60
	v_readlane_b32 s65, v248, 61
	s_waitcnt vmcnt(2)
	v_cvt_f32_f16_e32 v30, v28
	v_cvt_f32_f16_sdwa v31, v28 dst_sel:DWORD dst_unused:UNUSED_PAD src0_sel:WORD_1
	s_waitcnt vmcnt(0)
	v_pk_fma_f32 v[8:9], v[8:9], v[30:31], v[12:13]
	v_cvt_f32_f16_e32 v12, v29
	v_cvt_f32_f16_sdwa v13, v29 dst_sel:DWORD dst_unused:UNUSED_PAD src0_sel:WORD_1
	v_pk_fma_f32 v[10:11], v[10:11], v[12:13], v[14:15]
	v_lshl_add_u64 v[14:15], s[24:25], 0, v[26:27]
	v_or_b32_e32 v26, 0x100, v22
	global_store_dwordx4 v[20:21], v[8:11], off offset:64 nt
	v_lshl_add_u64 v[28:29], s[40:41], 0, v[26:27]
	global_load_dwordx2 v[28:29], v[28:29], off
	v_cvt_pk_f16_f32 v12, v8, v9
	v_cvt_pk_f16_f32 v13, v10, v11
	global_store_dwordx2 v[14:15], v[12:13], off
	v_pk_mul_f32 v[12:13], v[8:9], v[8:9]
	v_pk_mul_f32 v[14:15], v[10:11], v[10:11]
	global_load_dwordx4 v[8:11], v[20:21], off offset:512
	v_or_b32_e32 v22, 0x120, v22
	s_waitcnt vmcnt(2)
	v_cvt_f32_f16_e32 v30, v28
	v_cvt_f32_f16_sdwa v31, v28 dst_sel:DWORD dst_unused:UNUSED_PAD src0_sel:WORD_1
	s_waitcnt vmcnt(0)
	v_pk_fma_f32 v[4:5], v[4:5], v[30:31], v[8:9]
	v_cvt_f32_f16_e32 v8, v29
	v_cvt_f32_f16_sdwa v9, v29 dst_sel:DWORD dst_unused:UNUSED_PAD src0_sel:WORD_1
	v_pk_fma_f32 v[6:7], v[6:7], v[8:9], v[10:11]
	global_store_dwordx4 v[20:21], v[4:7], off offset:512 nt
	v_lshl_add_u64 v[10:11], s[24:25], 0, v[26:27]
	v_lshl_add_u64 v[26:27], s[40:41], 0, v[22:23]
	global_load_dwordx2 v[26:27], v[26:27], off
	v_cvt_pk_f16_f32 v8, v4, v5
	v_cvt_pk_f16_f32 v9, v6, v7
	global_store_dwordx2 v[10:11], v[8:9], off
	global_load_dwordx4 v[8:11], v[20:21], off offset:576
	v_pk_mul_f32 v[4:5], v[4:5], v[4:5]
	v_pk_mul_f32 v[6:7], v[6:7], v[6:7]
	v_add_f32_e32 v4, v4, v5
	v_add_f32_e32 v6, v6, v7
	v_add_f32_e32 v4, v4, v6
	s_waitcnt vmcnt(2)
	v_cvt_f32_f16_e32 v24, v26
	v_cvt_f32_f16_sdwa v25, v26 dst_sel:DWORD dst_unused:UNUSED_PAD src0_sel:WORD_1
	s_waitcnt vmcnt(0)
	v_pk_fma_f32 v[0:1], v[0:1], v[24:25], v[8:9]
	v_cvt_f32_f16_e32 v8, v27
	v_cvt_f32_f16_sdwa v9, v27 dst_sel:DWORD dst_unused:UNUSED_PAD src0_sel:WORD_1
	v_pk_fma_f32 v[2:3], v[2:3], v[8:9], v[10:11]
	v_cvt_pk_f16_f32 v8, v0, v1
	v_cvt_pk_f16_f32 v9, v2, v3
	v_lshl_add_u64 v[10:11], s[24:25], 0, v[22:23]
	global_store_dwordx4 v[20:21], v[0:3], off offset:576 nt
	global_store_dwordx2 v[10:11], v[8:9], off
	v_add_f32_e32 v8, v18, v19
	v_add_f32_e32 v9, v16, v17
	v_add_f32_e32 v8, v9, v8
	v_add_f32_e32 v9, v14, v15
	v_add_f32_e32 v10, v12, v13
	v_pk_mul_f32 v[0:1], v[0:1], v[0:1]
	v_pk_mul_f32 v[2:3], v[2:3], v[2:3]
	v_add_f32_e32 v9, v10, v9
	v_add_f32_e32 v8, v8, v9
	v_add_f32_e32 v2, v2, v3
	v_add_f32_e32 v0, v0, v1
	v_add_f32_e32 v4, v8, v4
	v_add_f32_e32 v0, v0, v2
	v_add_f32_e32 v0, v4, v0
	ds_bpermute_b32 v1, v214, v0
	s_waitcnt lgkmcnt(0)
	v_add_f32_e32 v0, v0, v1
	ds_bpermute_b32 v1, v213, v0
	s_and_saveexec_b64 s[2:3], s[8:9]
	s_cbranch_execz .LBB0_1036
	s_waitcnt lgkmcnt(0)
	v_add_f32_e32 v2, v0, v1
	v_lshl_add_u64 v[0:1], s[70:71], 0, v[136:137]
	v_lshl_add_u64 v[0:1], s[22:23], 2, v[0:1]
	s_lshl_b32 s92, s38, 2
	v_lshl_add_u64 v[0:1], v[0:1], 0, s[92:93]
	global_store_dword v[0:1], v2, off
